# GEMM K-loop restructured from 8 to 4 barrier phases per K-tile: 32-MFMA segments (M1+M2, M3+M4), B0/B1/A reads merged into one load segment, LDS-DMA stages regrouped with per-segment vmcnt(8) waits
# speedup vs baseline: 1.0202x; 1.0202x over previous
; #define PG8_STAGE(bufoff, gbase, voff) do { _Pragma("unroll") for (int _i = 0; _i < 2; ++_i) \
;         __builtin_amdgcn_global_load_lds((const unsigned*)((const char*)(gbase) + (voff)[_i]), (LAS unsigned*)(lds + (bufoff) + ldsw + _i * 8192), 16, 0, 0); } while (0)
; #define PG8_WAIT_V(n) asm volatile("s_waitcnt vmcnt(" #n ")" ::: "memory")
; #define PG8_BAR __builtin_amdgcn_s_barrier()
; template <class Epi>
; __device__ __forceinline__ void gemm_phase(LAS unsigned char* lds, const Gemm g, const StaticOrder& S, const Epi& E) {
;     const int tid = threadIdx.x, wid = __builtin_amdgcn_readfirstlane(tid >> 6), lane = tid & 63, wr = wid >> 2, wc = wid & 3, fr = lane & 15, fq = lane >> 4;
;     const int K = g.K, nt = K / BK;
;     unsigned voffA[2], voffB[2];
; #pragma unroll
;     for (int i = 0; i < 2; ++i) { int R, C; stage_rc(tid * 16 + i * 8192, R, C); const int Rb = Epi::PERM ? ((R & ~31) + perm32(R & 31)) : R;
;         voffA[i] = (unsigned)(R * K + C) * 2u; voffB[i] = (unsigned)(Rb * K + C) * 2u; }
;     const size_t kstep = (size_t)(BK * 2);
;     const size_t hstep = (size_t)HALF * K * 2;
;     const size_t tstep = 2 * hstep;
;     const unsigned ldsw = (unsigned)wid * 1024u;
;     const int aoff = lds_byte(wr * 64 + fr, fq * 8), boff = lds_byte(wc * 32 + fr, fq * 8);
;     ...
;     PG8_STAGE(PG8_SB(0, 0), cB, voffB); PG8_STAGE(PG8_SA(0, 0), cA, voffA); PG8_STAGE(PG8_SB(0, 1), cB + hstep, voffB); PG8_STAGE(PG8_SA(0, 1), cA + hstep, voffA);
;     if (wr == 1) PG8_BAR;
;     PG8_WAIT_V(4); PG8_BAR;
;     PG8_STAGE(PG8_SB(1, 0), cB + kstep, voffB); PG8_STAGE(PG8_SA(1, 0), cA + kstep, voffA); PG8_STAGE(PG8_SB(1, 1), cB + hstep + kstep, voffB);
;     PG8_WAIT_V(6); PG8_BAR;
.LBB0_254:
	s_lshl_b32 s4, s4, 5
	s_lshl_b32 s7, s5, 13
	s_and_b32 s10, s4, 0x60
	s_mov_b64 s[4:5], 0x80
	s_add_i32 m0, s35, 0x18000
	v_lshl_add_u64 v[6:7], v[6:7], 0, s[4:5]
	s_lshl_b32 s11, s10, 7
	s_waitcnt vmcnt(2)
	s_barrier
	global_load_lds_dwordx4 v[6:7], off
	v_lshl_add_u64 v[4:5], v[4:5], 0, s[4:5]
	s_add_i32 m0, s35, 0x1a000
	s_add_i32 s56, s35, 0x8000
	s_add_i32 s57, s35, 0xa000
	global_load_lds_dwordx4 v[4:5], off
	v_lshl_add_u64 v[2:3], v[2:3], 0, s[4:5]
	s_mov_b32 m0, s56
	s_add_u32 s8, s18, 0x80080
	global_load_lds_dwordx4 v[2:3], off
	v_lshl_add_u64 v[0:1], v[0:1], 0, s[4:5]
	s_mov_b32 m0, s57
	s_addc_u32 s9, s19, 0
	global_load_lds_dwordx4 v[0:1], off
	s_add_i32 m0, s35, 0x1c000
	v_lshl_add_u64 v[0:1], s[8:9], 0, v[132:133]
	global_load_lds_dwordx4 v[0:1], off
	v_lshl_add_u64 v[0:1], s[8:9], 0, v[128:129]
	s_add_i32 m0, s35, 0x1e000
	s_sext_i32_i16 s15, s6
	global_load_lds_dwordx4 v[0:1], off
	v_lshlrev_b32_e32 v0, 6, v13
	v_lshlrev_b32_e32 v1, 1, v11
	s_movk_i32 s6, 0x3c0
	v_lshlrev_b32_e32 v2, 2, v13
	v_and_or_b32 v0, v0, s6, v1
	v_and_b32_e32 v2, 32, v2
	v_bitop3_b32 v0, v0, s7, v2 bitop3:0xde
	v_lshlrev_b32_e32 v2, 6, v178
	v_and_or_b32 v1, v2, s6, v1
	v_lshlrev_b32_e32 v2, 2, v178
	v_and_b32_e32 v2, 32, v2
	v_bitop3_b32 v146, s11, v1, v2 bitop3:0xf6
	v_lshlrev_b32_e32 v1, 9, v178
	v_and_b32_e32 v1, 0x70000, v1
	v_lshlrev_b32_e32 v2, 12, v12
	v_or3_b32 v1, v9, v1, v2
	v_add_u32_e32 v136, v1, v10
	v_lshlrev_b32_e32 v1, 5, v8
	s_waitcnt vmcnt(6)
	v_and_b32_e32 v1, 0xf0000, v1
	v_or3_b32 v1, v9, v1, v2
	s_add_i32 s60, 0, 0x10000
	s_add_i32 s61, 0, 0x14000
	s_ashr_i32 s58, s54, 31
	s_mov_b32 s59, s54
	v_or_b32_e32 v147, s10, v11
	v_mov_b32_e32 v137, v133
	v_add_u32_e32 v138, v1, v10
	v_mov_b32_e32 v139, v133
	v_mov_b64_e32 v[140:141], 0xac0
	v_mov_b64_e32 v[142:143], 0xabf
	v_add_u32_e32 v148, s60, v146
	v_add_u32_e32 v149, 0, v0
	v_add_u32_e32 v150, s61, v146
	v_mov_b32_e32 v151, 0x358637bd
	s_movk_i32 s62, 0x2b00
	s_barrier
	s_branch .LBB0_256

; #define PG8_STAGE(bufoff, gbase, voff) do { _Pragma("unroll") for (int _i = 0; _i < 2; ++_i) \
;         __builtin_amdgcn_global_load_lds((const unsigned*)((const char*)(gbase) + (voff)[_i]), (LAS unsigned*)(lds + (bufoff) + ldsw + _i * 8192), 16, 0, 0); } while (0)
; #define PG8_LDA(dst, b, h) do { _Pragma("unroll") for (int m = 0; m < 4; ++m) _Pragma("unroll") for (int k = 0; k < 2; ++k) dst[m][k] = *(const LAS bf16x8*)(lds + PG8_SA(b, h) + aoff + m * 2048 + k * 1024); } while (0)
; #define PG8_LDB(dst, b, h) do { _Pragma("unroll") for (int n = 0; n < 2; ++n) _Pragma("unroll") for (int k = 0; k < 2; ++k) dst[n][k] = *(const LAS bf16x8*)(lds + PG8_SB(b, h) + boff + n * 2048 + k * 1024); } while (0)
; #define PG8_MMA(ai, bj, At, Bt) do { __builtin_amdgcn_s_setprio(1); _Pragma("unroll") for (int m = 0; m < 4; ++m) _Pragma("unroll") for (int n = 0; n < 2; ++n) _Pragma("unroll") for (int k = 0; k < 2; ++k) \
;         acc[ai][bj][m][n] = __builtin_amdgcn_mfma_f32_16x16x32_bf16(Bt[n][k], At[m][k], acc[ai][bj][m][n], 0, 0, 0); __builtin_amdgcn_s_setprio(0); } while (0)
; #define PG8_WAIT_L(n) asm volatile("s_waitcnt lgkmcnt(" #n ")" ::: "memory")
; #define PG8_BAR __builtin_amdgcn_s_barrier()
; #define PG8_SCHED __builtin_amdgcn_sched_barrier(0)
; template <class Epi>
; __device__ __forceinline__ void gemm_phase(LAS unsigned char* lds, const Gemm g, const StaticOrder& S, const Epi& E) {
;     ...
;             PG8_LDB(B0, 0, 0); PG8_SCHED; PG8_LDA(At, 0, 0); PG8_STAGE(PG8_SA(1, 1), a1 + hstep, voffA);
;             PG8_WAIT_L(8); PG8_BAR; PG8_WAIT_L(0); PG8_MMA(0, 0, At, B0); PG8_BAR; PG8_SCHED;
;             PG8_LDB(B1, 0, 1); PG8_STAGE(PG8_SB(0, 0), b2, voffB);
;             PG8_BAR; PG8_WAIT_L(0); PG8_MMA(0, 1, At, B1); PG8_BAR;
;             PG8_LDA(At, 0, 1); PG8_STAGE(PG8_SA(0, 0), a2, voffA);
;             PG8_BAR; PG8_WAIT_L(0); PG8_MMA(1, 0, At, B0); PG8_BAR; PG8_SCHED;
;             PG8_STAGE(PG8_SB(0, 1), b2 + hstep, voffB);
.LBB0_259:
	ds_read_b128 v[160:163], v148
	ds_read_b128 v[166:169], v148 offset:1024
	ds_read_b128 v[170:173], v148 offset:2048
	ds_read_b128 v[174:177], v148 offset:3072
	s_add_u32 s18, s16, 0xfff80080
	s_addc_u32 s19, s17, -1
	s_cmp_eq_u32 s67, 28
	s_cselect_b32 s21, s9, s19
	s_cselect_b32 s20, s63, s18
	s_cselect_b32 s19, s7, s66
	s_cselect_b32 s18, s64, s65
	v_lshl_add_u64 v[212:213], s[16:17], 0, v[136:137]
	s_add_i32 m0, s35, 0xc000
	ds_read_b128 v[180:183], v149
	ds_read_b128 v[184:187], v149 offset:1024
	ds_read_b128 v[188:191], v149 offset:2048
	ds_read_b128 v[192:195], v149 offset:3072
	ds_read_b128 v[196:199], v149 offset:4096
	ds_read_b128 v[200:203], v149 offset:5120
	ds_read_b128 v[204:207], v149 offset:6144
	ds_read_b128 v[208:211], v149 offset:7168
	global_load_lds_dwordx4 v[212:213], off
	v_lshl_add_u64 v[212:213], s[16:17], 0, v[138:139]
	s_add_i32 m0, s35, 0xe000
	s_nop 0
	global_load_lds_dwordx4 v[212:213], off
	ds_read_b128 v[212:215], v150
	ds_read_b128 v[216:219], v150 offset:1024
	ds_read_b128 v[220:223], v150 offset:2048
	ds_read_b128 v[224:227], v150 offset:3072
	s_waitcnt lgkmcnt(0)
	s_waitcnt vmcnt(8)
	s_setprio 1
	s_barrier
	v_mfma_f32_16x16x32_bf16 v[124:127], v[160:163], v[180:183], v[124:127]
	v_mfma_f32_16x16x32_bf16 v[116:119], v[170:173], v[180:183], v[116:119]
	v_mfma_f32_16x16x32_bf16 v[108:111], v[160:163], v[188:191], v[108:111]
	v_mfma_f32_16x16x32_bf16 v[100:103], v[170:173], v[188:191], v[100:103]
	v_mfma_f32_16x16x32_bf16 v[92:95], v[160:163], v[196:199], v[92:95]
	v_mfma_f32_16x16x32_bf16 v[84:87], v[170:173], v[196:199], v[84:87]
	v_mfma_f32_16x16x32_bf16 v[76:79], v[160:163], v[204:207], v[76:79]
	v_mfma_f32_16x16x32_bf16 v[68:71], v[170:173], v[204:207], v[68:71]
	v_mfma_f32_16x16x32_bf16 v[124:127], v[166:169], v[184:187], v[124:127]
	v_mfma_f32_16x16x32_bf16 v[116:119], v[174:177], v[184:187], v[116:119]
	v_mfma_f32_16x16x32_bf16 v[108:111], v[166:169], v[192:195], v[108:111]
	v_mfma_f32_16x16x32_bf16 v[100:103], v[174:177], v[192:195], v[100:103]
	v_mfma_f32_16x16x32_bf16 v[92:95], v[166:169], v[200:203], v[92:95]
	v_mfma_f32_16x16x32_bf16 v[84:87], v[174:177], v[200:203], v[84:87]
	v_mfma_f32_16x16x32_bf16 v[76:79], v[166:169], v[208:211], v[76:79]
	v_mfma_f32_16x16x32_bf16 v[68:71], v[174:177], v[208:211], v[68:71]
	v_mfma_f32_16x16x32_bf16 v[120:123], v[212:215], v[180:183], v[120:123]
	v_mfma_f32_16x16x32_bf16 v[112:115], v[220:223], v[180:183], v[112:115]
	v_mfma_f32_16x16x32_bf16 v[104:107], v[212:215], v[188:191], v[104:107]
	v_mfma_f32_16x16x32_bf16 v[96:99], v[220:223], v[188:191], v[96:99]
	v_mfma_f32_16x16x32_bf16 v[88:91], v[212:215], v[196:199], v[88:91]
	v_mfma_f32_16x16x32_bf16 v[80:83], v[220:223], v[196:199], v[80:83]
	v_mfma_f32_16x16x32_bf16 v[72:75], v[212:215], v[204:207], v[72:75]
	v_mfma_f32_16x16x32_bf16 v[64:67], v[220:223], v[204:207], v[64:67]
	v_mfma_f32_16x16x32_bf16 v[120:123], v[216:219], v[184:187], v[120:123]
	v_mfma_f32_16x16x32_bf16 v[112:115], v[224:227], v[184:187], v[112:115]
	v_mfma_f32_16x16x32_bf16 v[104:107], v[216:219], v[192:195], v[104:107]
	v_mfma_f32_16x16x32_bf16 v[96:99], v[224:227], v[192:195], v[96:99]
	v_mfma_f32_16x16x32_bf16 v[88:91], v[216:219], v[200:203], v[88:91]
	v_mfma_f32_16x16x32_bf16 v[80:83], v[224:227], v[200:203], v[80:83]
	v_mfma_f32_16x16x32_bf16 v[72:75], v[216:219], v[208:211], v[72:75]
	v_mfma_f32_16x16x32_bf16 v[64:67], v[224:227], v[208:211], v[64:67]
	s_barrier
	s_setprio 0
	s_add_i32 s68, s60, s31
	v_lshl_add_u64 v[228:229], s[18:19], 0, v[132:133]
	s_mov_b32 m0, s68
	s_nop 0
	global_load_lds_dwordx4 v[228:229], off
	v_lshl_add_u64 v[230:231], s[18:19], 0, v[128:129]
	s_add_i32 m0, s68, 0x2000
	s_nop 0
	global_load_lds_dwordx4 v[230:231], off
	s_mov_b32 m0, s35
	v_lshl_add_u64 v[232:233], s[20:21], 0, v[134:135]
	ds_read_b128 v[180:183], v149 offset:16384
	ds_read_b128 v[184:187], v149 offset:17408
	ds_read_b128 v[188:191], v149 offset:18432
	ds_read_b128 v[192:195], v149 offset:19456
	ds_read_b128 v[196:199], v149 offset:20480
	ds_read_b128 v[200:203], v149 offset:21504
	ds_read_b128 v[204:207], v149 offset:22528
	ds_read_b128 v[208:211], v149 offset:23552
	global_load_lds_dwordx4 v[232:233], off
	v_lshl_add_u64 v[234:235], s[20:21], 0, v[130:131]
	s_mov_b32 m0, s38
	s_nop 0
	global_load_lds_dwordx4 v[234:235], off
	s_add_u32 s68, s18, 0x80000
	s_addc_u32 s69, s19, 0
	s_add_i32 s70, s61, s31
	v_lshl_add_u64 v[252:253], s[68:69], 0, v[132:133]
	s_mov_b32 m0, s70
	s_nop 0
	global_load_lds_dwordx4 v[252:253], off
	v_lshl_add_u64 v[252:253], s[68:69], 0, v[128:129]
	s_add_i32 m0, s70, 0x2000
	s_nop 0
	global_load_lds_dwordx4 v[252:253], off
	s_waitcnt lgkmcnt(0)
	s_waitcnt vmcnt(8)
	s_setprio 1
	s_barrier
; #define PG8_STAGE(bufoff, gbase, voff) do { _Pragma("unroll") for (int _i = 0; _i < 2; ++_i) \
;         __builtin_amdgcn_global_load_lds((const unsigned*)((const char*)(gbase) + (voff)[_i]), (LAS unsigned*)(lds + (bufoff) + ldsw + _i * 8192), 16, 0, 0); } while (0)
; #define PG8_LDA(dst, b, h) do { _Pragma("unroll") for (int m = 0; m < 4; ++m) _Pragma("unroll") for (int k = 0; k < 2; ++k) dst[m][k] = *(const LAS bf16x8*)(lds + PG8_SA(b, h) + aoff + m * 2048 + k * 1024); } while (0)
; #define PG8_LDB(dst, b, h) do { _Pragma("unroll") for (int n = 0; n < 2; ++n) _Pragma("unroll") for (int k = 0; k < 2; ++k) dst[n][k] = *(const LAS bf16x8*)(lds + PG8_SB(b, h) + boff + n * 2048 + k * 1024); } while (0)
; #define PG8_MMA(ai, bj, At, Bt) do { __builtin_amdgcn_s_setprio(1); _Pragma("unroll") for (int m = 0; m < 4; ++m) _Pragma("unroll") for (int n = 0; n < 2; ++n) _Pragma("unroll") for (int k = 0; k < 2; ++k) \
;         acc[ai][bj][m][n] = __builtin_amdgcn_mfma_f32_16x16x32_bf16(Bt[n][k], At[m][k], acc[ai][bj][m][n], 0, 0, 0); __builtin_amdgcn_s_setprio(0); } while (0)
; #define PG8_WAIT_V(n) asm volatile("s_waitcnt vmcnt(" #n ")" ::: "memory")
; #define PG8_WAIT_L(n) asm volatile("s_waitcnt lgkmcnt(" #n ")" ::: "memory")
; #define PG8_BAR __builtin_amdgcn_s_barrier()
; #define PG8_SCHED __builtin_amdgcn_sched_barrier(0)
; template <class Epi>
; __device__ __forceinline__ void gemm_phase(LAS unsigned char* lds, const Gemm g, const StaticOrder& S, const Epi& E) {
;     ...
;             PG8_BAR; PG8_WAIT_L(0); PG8_MMA(1, 0, At, B0); PG8_BAR; PG8_SCHED;
;             PG8_STAGE(PG8_SB(0, 1), b2 + hstep, voffB);
;             PG8_WAIT_V(6); PG8_BAR; PG8_MMA(1, 1, At, B1); PG8_BAR;
;             PG8_LDB(B0, 1, 0); PG8_SCHED; PG8_LDA(At, 1, 0); PG8_STAGE(PG8_SA(0, 1), a2 + hstep, voffA);
;             PG8_WAIT_L(8); PG8_BAR; PG8_WAIT_L(0); PG8_MMA(0, 0, At, B0); PG8_BAR; PG8_SCHED;
;             PG8_LDB(B1, 1, 1); PG8_STAGE(PG8_SB(1, 0), b3, voffB);
	v_mfma_f32_16x16x32_bf16 v[60:63], v[160:163], v[180:183], v[60:63]
	v_mfma_f32_16x16x32_bf16 v[52:55], v[170:173], v[180:183], v[52:55]
	v_mfma_f32_16x16x32_bf16 v[44:47], v[160:163], v[188:191], v[44:47]
	v_mfma_f32_16x16x32_bf16 v[36:39], v[170:173], v[188:191], v[36:39]
	v_mfma_f32_16x16x32_bf16 v[28:31], v[160:163], v[196:199], v[28:31]
	v_mfma_f32_16x16x32_bf16 v[20:23], v[170:173], v[196:199], v[20:23]
	v_mfma_f32_16x16x32_bf16 v[12:15], v[160:163], v[204:207], v[12:15]
	v_mfma_f32_16x16x32_bf16 v[4:7], v[170:173], v[204:207], v[4:7]
	v_mfma_f32_16x16x32_bf16 v[60:63], v[166:169], v[184:187], v[60:63]
	v_mfma_f32_16x16x32_bf16 v[52:55], v[174:177], v[184:187], v[52:55]
	v_mfma_f32_16x16x32_bf16 v[44:47], v[166:169], v[192:195], v[44:47]
	v_mfma_f32_16x16x32_bf16 v[36:39], v[174:177], v[192:195], v[36:39]
	v_mfma_f32_16x16x32_bf16 v[28:31], v[166:169], v[200:203], v[28:31]
	v_mfma_f32_16x16x32_bf16 v[20:23], v[174:177], v[200:203], v[20:23]
	v_mfma_f32_16x16x32_bf16 v[12:15], v[166:169], v[208:211], v[12:15]
	v_mfma_f32_16x16x32_bf16 v[4:7], v[174:177], v[208:211], v[4:7]
	v_mfma_f32_16x16x32_bf16 v[56:59], v[212:215], v[180:183], v[56:59]
	v_mfma_f32_16x16x32_bf16 v[48:51], v[220:223], v[180:183], v[48:51]
	v_mfma_f32_16x16x32_bf16 v[40:43], v[212:215], v[188:191], v[40:43]
	v_mfma_f32_16x16x32_bf16 v[32:35], v[220:223], v[188:191], v[32:35]
	v_mfma_f32_16x16x32_bf16 v[24:27], v[212:215], v[196:199], v[24:27]
	v_mfma_f32_16x16x32_bf16 v[16:19], v[220:223], v[196:199], v[16:19]
	v_mfma_f32_16x16x32_bf16 v[8:11], v[212:215], v[204:207], v[8:11]
	v_mfma_f32_16x16x32_bf16 v[0:3], v[220:223], v[204:207], v[0:3]
	v_mfma_f32_16x16x32_bf16 v[56:59], v[216:219], v[184:187], v[56:59]
	v_mfma_f32_16x16x32_bf16 v[48:51], v[224:227], v[184:187], v[48:51]
	v_mfma_f32_16x16x32_bf16 v[40:43], v[216:219], v[192:195], v[40:43]
	v_mfma_f32_16x16x32_bf16 v[32:35], v[224:227], v[192:195], v[32:35]
	v_mfma_f32_16x16x32_bf16 v[24:27], v[216:219], v[200:203], v[24:27]
	v_mfma_f32_16x16x32_bf16 v[16:19], v[224:227], v[200:203], v[16:19]
	v_mfma_f32_16x16x32_bf16 v[8:11], v[216:219], v[208:211], v[8:11]
	v_mfma_f32_16x16x32_bf16 v[0:3], v[224:227], v[208:211], v[0:3]
	s_barrier
	s_setprio 0
	s_add_i32 s68, 0, 0x18000
	v_add_u32_e32 v165, s68, v146
	ds_read_b128 v[160:163], v165
	ds_read_b128 v[166:169], v165 offset:1024
	ds_read_b128 v[170:173], v165 offset:2048
	ds_read_b128 v[174:177], v165 offset:3072
	s_add_u32 s20, s20, 0x80000
	s_addc_u32 s21, s21, 0
	s_mov_b32 m0, s39
	v_lshl_add_u64 v[212:213], s[20:21], 0, v[134:135]
	ds_read_b128 v[180:183], v149 offset:32768
	ds_read_b128 v[184:187], v149 offset:33792
	ds_read_b128 v[188:191], v149 offset:34816
	ds_read_b128 v[192:195], v149 offset:35840
	ds_read_b128 v[196:199], v149 offset:36864
	ds_read_b128 v[200:203], v149 offset:37888
	ds_read_b128 v[204:207], v149 offset:38912
	ds_read_b128 v[208:211], v149 offset:39936
	global_load_lds_dwordx4 v[212:213], off
	v_lshl_add_u64 v[212:213], s[20:21], 0, v[130:131]
	s_mov_b32 m0, s42
	s_nop 0
	global_load_lds_dwordx4 v[212:213], off
	s_add_i32 s20, 0, 0x1c000
	v_add_u32_e32 v165, s20, v146
	ds_read_b128 v[212:215], v165
	ds_read_b128 v[216:219], v165 offset:1024
	ds_read_b128 v[220:223], v165 offset:2048
	ds_read_b128 v[224:227], v165 offset:3072
	s_waitcnt lgkmcnt(0)
	s_waitcnt vmcnt(8)
	s_setprio 1
	s_barrier
	v_mfma_f32_16x16x32_bf16 v[124:127], v[160:163], v[180:183], v[124:127]
	v_mfma_f32_16x16x32_bf16 v[116:119], v[170:173], v[180:183], v[116:119]
	v_mfma_f32_16x16x32_bf16 v[108:111], v[160:163], v[188:191], v[108:111]
	v_mfma_f32_16x16x32_bf16 v[100:103], v[170:173], v[188:191], v[100:103]
	v_mfma_f32_16x16x32_bf16 v[92:95], v[160:163], v[196:199], v[92:95]
	v_mfma_f32_16x16x32_bf16 v[84:87], v[170:173], v[196:199], v[84:87]
	v_mfma_f32_16x16x32_bf16 v[76:79], v[160:163], v[204:207], v[76:79]
	v_mfma_f32_16x16x32_bf16 v[68:71], v[170:173], v[204:207], v[68:71]
	v_mfma_f32_16x16x32_bf16 v[124:127], v[166:169], v[184:187], v[124:127]
	v_mfma_f32_16x16x32_bf16 v[116:119], v[174:177], v[184:187], v[116:119]
	v_mfma_f32_16x16x32_bf16 v[108:111], v[166:169], v[192:195], v[108:111]
	v_mfma_f32_16x16x32_bf16 v[100:103], v[174:177], v[192:195], v[100:103]
	v_mfma_f32_16x16x32_bf16 v[92:95], v[166:169], v[200:203], v[92:95]
	v_mfma_f32_16x16x32_bf16 v[84:87], v[174:177], v[200:203], v[84:87]
	v_mfma_f32_16x16x32_bf16 v[76:79], v[166:169], v[208:211], v[76:79]
	v_mfma_f32_16x16x32_bf16 v[68:71], v[174:177], v[208:211], v[68:71]
	v_mfma_f32_16x16x32_bf16 v[120:123], v[212:215], v[180:183], v[120:123]
	v_mfma_f32_16x16x32_bf16 v[112:115], v[220:223], v[180:183], v[112:115]
	v_mfma_f32_16x16x32_bf16 v[104:107], v[212:215], v[188:191], v[104:107]
	v_mfma_f32_16x16x32_bf16 v[96:99], v[220:223], v[188:191], v[96:99]
	v_mfma_f32_16x16x32_bf16 v[88:91], v[212:215], v[196:199], v[88:91]
	v_mfma_f32_16x16x32_bf16 v[80:83], v[220:223], v[196:199], v[80:83]
	v_mfma_f32_16x16x32_bf16 v[72:75], v[212:215], v[204:207], v[72:75]
	v_mfma_f32_16x16x32_bf16 v[64:67], v[220:223], v[204:207], v[64:67]
	v_mfma_f32_16x16x32_bf16 v[120:123], v[216:219], v[184:187], v[120:123]
	v_mfma_f32_16x16x32_bf16 v[112:115], v[224:227], v[184:187], v[112:115]
	v_mfma_f32_16x16x32_bf16 v[104:107], v[216:219], v[192:195], v[104:107]
	v_mfma_f32_16x16x32_bf16 v[96:99], v[224:227], v[192:195], v[96:99]
	v_mfma_f32_16x16x32_bf16 v[88:91], v[216:219], v[200:203], v[88:91]
	v_mfma_f32_16x16x32_bf16 v[80:83], v[224:227], v[200:203], v[80:83]
	v_mfma_f32_16x16x32_bf16 v[72:75], v[216:219], v[208:211], v[72:75]
	v_mfma_f32_16x16x32_bf16 v[64:67], v[224:227], v[208:211], v[64:67]
	s_barrier
; __device__ __forceinline__ float sigmoidf_(float x) { return __builtin_amdgcn_rcpf(1.0f + fexp(-x)); }
; #define PG8_STAGE(bufoff, gbase, voff) do { _Pragma("unroll") for (int _i = 0; _i < 2; ++_i) \
;         __builtin_amdgcn_global_load_lds((const unsigned*)((const char*)(gbase) + (voff)[_i]), (LAS unsigned*)(lds + (bufoff) + ldsw + _i * 8192), 16, 0, 0); } while (0)
; #define PG8_LDA(dst, b, h) do { _Pragma("unroll") for (int m = 0; m < 4; ++m) _Pragma("unroll") for (int k = 0; k < 2; ++k) dst[m][k] = *(const LAS bf16x8*)(lds + PG8_SA(b, h) + aoff + m * 2048 + k * 1024); } while (0)
; #define PG8_LDB(dst, b, h) do { _Pragma("unroll") for (int n = 0; n < 2; ++n) _Pragma("unroll") for (int k = 0; k < 2; ++k) dst[n][k] = *(const LAS bf16x8*)(lds + PG8_SB(b, h) + boff + n * 2048 + k * 1024); } while (0)
; #define PG8_WAIT_V(n) asm volatile("s_waitcnt vmcnt(" #n ")" ::: "memory")
; #define PG8_WAIT_L(n) asm volatile("s_waitcnt lgkmcnt(" #n ")" ::: "memory")
; #define PG8_BAR __builtin_amdgcn_s_barrier()
; #define PG8_SCHED __builtin_amdgcn_sched_barrier(0)
; template <class Epi>
; __device__ __forceinline__ void gemm_phase(LAS unsigned char* lds, const Gemm g, const StaticOrder& S, const Epi& E) {
;     ...
;             PG8_LDB(B1, 1, 1); PG8_STAGE(PG8_SB(1, 0), b3, voffB);
;             PG8_BAR; PG8_WAIT_L(0); PG8_MMA(0, 1, At, B1); PG8_BAR;
;             PG8_LDA(At, 1, 1); PG8_STAGE(PG8_SA(1, 0), a3, voffA);
;             PG8_BAR; PG8_WAIT_L(0); PG8_MMA(1, 0, At, B0); PG8_BAR; PG8_SCHED;
;             PG8_STAGE(PG8_SB(1, 1), b3 + hstep, voffB);
;             PG8_WAIT_V(6); PG8_BAR; PG8_MMA(1, 1, At, B1); PG8_BAR;
;     __device__ __forceinline__ void operator()(const f32x4 (&acc)[2][2][4][2], const Unit& u, int wr, int wc, int fr, int fq, const Pre& P) const {
;         const int row0 = ROW_X + u.pm * BM + wr * 64 + fr, col0 = u.pn * HALF + wc * 32 + 8 * fq;
; #pragma unroll
;         for (int ai = 0; ai < 2; ++ai)
; #pragma unroll
;             for (int m = 0; m < 4; ++m) { const int r = row0 + ai * HALF + m * 16; const float rs = __builtin_amdgcn_rsqf(P.rs[ai * 4 + m] * (1.0f / DM) + RMS_EPS);
;                 float y[8];
; #pragma unroll
;                 for (int n = 0; n < 2; ++n)
; #pragma unroll
;                     for (int j = 0; j < 4; ++j) { const float a = acc[ai][0][m][n][j] * rs, b = acc[ai][1][m][n][j] * rs; y[n * 4 + j] = a * b * sigmoidf_(a); }
	s_setprio 0
	s_add_i32 s21, s68, s31
	v_lshl_add_u64 v[228:229], v[228:229], 0, s[4:5]
	s_mov_b32 m0, s21
	s_nop 0
	global_load_lds_dwordx4 v[228:229], off
	v_lshl_add_u64 v[228:229], v[230:231], 0, s[4:5]
	s_add_i32 m0, s21, 0x2000
	s_nop 0
	global_load_lds_dwordx4 v[228:229], off
	s_mov_b32 m0, s56
	v_lshl_add_u64 v[228:229], v[232:233], 0, s[4:5]
	ds_read_b128 v[180:183], v149 offset:49152
	ds_read_b128 v[184:187], v149 offset:50176
	ds_read_b128 v[188:191], v149 offset:51200
	ds_read_b128 v[192:195], v149 offset:52224
	ds_read_b128 v[196:199], v149 offset:53248
	ds_read_b128 v[200:203], v149 offset:54272
	ds_read_b128 v[204:207], v149 offset:55296
	ds_read_b128 v[208:211], v149 offset:56320
	global_load_lds_dwordx4 v[228:229], off
	v_lshl_add_u64 v[228:229], v[234:235], 0, s[4:5]
	s_mov_b32 m0, s57
	s_nop 0
	global_load_lds_dwordx4 v[228:229], off
	s_add_u32 s18, s18, 0x80080
	s_addc_u32 s19, s19, 0
	s_add_i32 s20, s20, s31
	v_lshl_add_u64 v[252:253], s[18:19], 0, v[132:133]
	s_mov_b32 m0, s20
	s_nop 0
	global_load_lds_dwordx4 v[252:253], off
	v_lshl_add_u64 v[252:253], s[18:19], 0, v[128:129]
	s_add_i32 m0, s20, 0x2000
	s_nop 0
	global_load_lds_dwordx4 v[252:253], off
	s_waitcnt lgkmcnt(0)
	s_waitcnt vmcnt(8)
	s_setprio 1
	s_barrier
	v_mfma_f32_16x16x32_bf16 v[60:63], v[160:163], v[180:183], v[60:63]
	v_mfma_f32_16x16x32_bf16 v[52:55], v[170:173], v[180:183], v[52:55]
	v_mfma_f32_16x16x32_bf16 v[44:47], v[160:163], v[188:191], v[44:47]
	v_mfma_f32_16x16x32_bf16 v[36:39], v[170:173], v[188:191], v[36:39]
	v_mfma_f32_16x16x32_bf16 v[28:31], v[160:163], v[196:199], v[28:31]
	v_mfma_f32_16x16x32_bf16 v[20:23], v[170:173], v[196:199], v[20:23]
	v_mfma_f32_16x16x32_bf16 v[12:15], v[160:163], v[204:207], v[12:15]
	v_mfma_f32_16x16x32_bf16 v[4:7], v[170:173], v[204:207], v[4:7]
	v_mfma_f32_16x16x32_bf16 v[60:63], v[166:169], v[184:187], v[60:63]
	v_mfma_f32_16x16x32_bf16 v[52:55], v[174:177], v[184:187], v[52:55]
	v_mfma_f32_16x16x32_bf16 v[44:47], v[166:169], v[192:195], v[44:47]
	v_mfma_f32_16x16x32_bf16 v[36:39], v[174:177], v[192:195], v[36:39]
	v_mfma_f32_16x16x32_bf16 v[28:31], v[166:169], v[200:203], v[28:31]
	v_mfma_f32_16x16x32_bf16 v[20:23], v[174:177], v[200:203], v[20:23]
	v_mfma_f32_16x16x32_bf16 v[12:15], v[166:169], v[208:211], v[12:15]
	v_mfma_f32_16x16x32_bf16 v[4:7], v[174:177], v[208:211], v[4:7]
	v_mfma_f32_16x16x32_bf16 v[56:59], v[212:215], v[180:183], v[56:59]
	v_mfma_f32_16x16x32_bf16 v[48:51], v[220:223], v[180:183], v[48:51]
	v_mfma_f32_16x16x32_bf16 v[40:43], v[212:215], v[188:191], v[40:43]
	v_mfma_f32_16x16x32_bf16 v[32:35], v[220:223], v[188:191], v[32:35]
	v_mfma_f32_16x16x32_bf16 v[24:27], v[212:215], v[196:199], v[24:27]
	v_mfma_f32_16x16x32_bf16 v[16:19], v[220:223], v[196:199], v[16:19]
	v_mfma_f32_16x16x32_bf16 v[8:11], v[212:215], v[204:207], v[8:11]
	v_mfma_f32_16x16x32_bf16 v[0:3], v[220:223], v[204:207], v[0:3]
	v_mfma_f32_16x16x32_bf16 v[56:59], v[216:219], v[184:187], v[56:59]
	v_mfma_f32_16x16x32_bf16 v[48:51], v[224:227], v[184:187], v[48:51]
	v_mfma_f32_16x16x32_bf16 v[40:43], v[216:219], v[192:195], v[40:43]
	v_mfma_f32_16x16x32_bf16 v[32:35], v[224:227], v[192:195], v[32:35]
	v_mfma_f32_16x16x32_bf16 v[24:27], v[216:219], v[200:203], v[24:27]
	v_mfma_f32_16x16x32_bf16 v[16:19], v[224:227], v[200:203], v[16:19]
	v_mfma_f32_16x16x32_bf16 v[8:11], v[216:219], v[208:211], v[8:11]
	v_mfma_f32_16x16x32_bf16 v[0:3], v[224:227], v[208:211], v[0:3]
	s_barrier
	s_setprio 0
	s_add_i32 s67, s67, 2
	s_add_u32 s16, s16, 0x100
	s_addc_u32 s17, s17, 0
	s_add_u32 s65, s65, 0x100
	s_addc_u32 s66, s66, 0
	s_cmp_gt_u32 s67, 29
	s_cbranch_scc0 .LBB0_259
	s_waitcnt vmcnt(0)
	v_fmamk_f32 v159, v159, 0x3a000000, v151
	v_rsq_f32_e32 v166, v159
	v_lshl_or_b32 v162, s15, 7, v147
	v_lshl_add_u32 v160, s14, 8, v145
	v_ashrrev_i32_e32 v163, 31, v162
	v_pk_mul_f32 v[124:125], v[166:167], v[124:125] op_sel_hi:[0,1]
	v_pk_mul_f32 v[120:121], v[166:167], v[120:121] op_sel_hi:[0,1]
	v_mul_f32_e32 v159, 0xbfb8aa3b, v124
	v_pk_mul_f32 v[120:121], v[124:125], v[120:121]
	v_mul_f32_e32 v124, 0xbfb8aa3b, v125
	v_exp_f32_e32 v159, v159
	v_exp_f32_e32 v124, v124
	v_pk_mul_f32 v[122:123], v[166:167], v[122:123] op_sel_hi:[0,1]
	v_pk_mul_f32 v[116:117], v[166:167], v[116:117] op_sel_hi:[0,1]
	v_add_f32_e32 v159, 1.0, v159
	v_add_f32_e32 v124, 1.0, v124
	v_rcp_f32_e32 v168, v159
	v_rcp_f32_e32 v169, v124
	v_pk_mul_f32 v[124:125], v[166:167], v[126:127] op_sel_hi:[0,1]
	v_pk_mul_f32 v[122:123], v[124:125], v[122:123]
	v_pk_mul_f32 v[112:113], v[166:167], v[112:113] op_sel_hi:[0,1]
	v_pk_mul_f32 v[120:121], v[168:169], v[120:121]
	v_pk_mul_f32 v[112:113], v[116:117], v[112:113]
	v_cvt_pk_bf16_f32 v120, v120, v121
	v_mul_f32_e32 v121, 0xbfb8aa3b, v124
	v_exp_f32_e32 v121, v121
	v_pk_mul_f32 v[114:115], v[166:167], v[114:115] op_sel_hi:[0,1]
	s_and_b64 vcc, vcc, exec
	v_add_f32_e32 v121, 1.0, v121
	v_rcp_f32_e32 v126, v121
	v_mul_f32_e32 v121, 0xbfb8aa3b, v125
	v_exp_f32_e32 v121, v121
	s_nop 0
	v_add_f32_e32 v121, 1.0, v121
	v_rcp_f32_e32 v127, v121
	s_nop 0
	v_pk_mul_f32 v[122:123], v[126:127], v[122:123]
	s_nop 0
	v_cvt_pk_bf16_f32 v121, v122, v123
	v_mul_f32_e32 v122, 0xbfb8aa3b, v116
	v_mul_f32_e32 v116, 0xbfb8aa3b, v117
	v_exp_f32_e32 v122, v122
	v_exp_f32_e32 v116, v116
	v_add_f32_e32 v122, 1.0, v122
	v_add_f32_e32 v116, 1.0, v116
	v_rcp_f32_e32 v122, v122
	v_rcp_f32_e32 v123, v116
	s_nop 0
	v_pk_mul_f32 v[112:113], v[122:123], v[112:113]
	s_nop 0
	v_cvt_pk_bf16_f32 v122, v112, v113
	v_pk_mul_f32 v[112:113], v[166:167], v[118:119] op_sel_hi:[0,1]
	v_mul_f32_e32 v116, 0xbfb8aa3b, v112
	v_pk_mul_f32 v[114:115], v[112:113], v[114:115]
; __device__ __forceinline__ float sigmoidf_(float x) { return __builtin_amdgcn_rcpf(1.0f + fexp(-x)); }
;     __device__ __forceinline__ void operator()(const f32x4 (&acc)[2][2][4][2], const Unit& u, int wr, int wc, int fr, int fq, const Pre& P) const {
;         const int row0 = ROW_X + u.pm * BM + wr * 64 + fr, col0 = u.pn * HALF + wc * 32 + 8 * fq;
; #pragma unroll
;         for (int ai = 0; ai < 2; ++ai)
; #pragma unroll
;             for (int m = 0; m < 4; ++m) { const int r = row0 + ai * HALF + m * 16; const float rs = __builtin_amdgcn_rsqf(P.rs[ai * 4 + m] * (1.0f / DM) + RMS_EPS);
;                 float y[8];
; #pragma unroll
;                 for (int n = 0; n < 2; ++n)
; #pragma unroll
;                     for (int j = 0; j < 4; ++j) { const float a = acc[ai][0][m][n][j] * rs, b = acc[ai][1][m][n][j] * rs; y[n * 4 + j] = a * b * sigmoidf_(a); }
;                 u32x4 w; w.x = cvtpk(y[0], y[1]); w.y = cvtpk(y[2], y[3]); w.z = cvtpk(y[4], y[5]); w.w = cvtpk(y[6], y[7]);
;                 *(u32x4*)(O + (size_t)r * FF + col0) = w; }
	v_mul_f32_e32 v112, 0xbfb8aa3b, v113
	v_exp_f32_e32 v116, v116
	v_exp_f32_e32 v112, v112
	v_add_f32_e32 v116, 1.0, v116
	v_add_f32_e32 v112, 1.0, v112
	v_rcp_f32_e32 v116, v116
	v_rcp_f32_e32 v117, v112
	s_nop 0
	v_pk_mul_f32 v[112:113], v[116:117], v[114:115]
	s_nop 0
	v_cvt_pk_bf16_f32 v123, v112, v113
	v_mov_b64_e32 v[112:113], s[0:1]
	v_mad_i64_i32 v[116:117], s[14:15], v160, s62, v[112:113]
	v_lshlrev_b64 v[114:115], 1, v[162:163]
	v_lshl_add_u64 v[116:117], v[116:117], 0, v[114:115]
	global_store_dwordx4 v[116:117], v[120:123], off
	v_fmamk_f32 v116, v158, 0x3a000000, v151
	v_rsq_f32_e32 v116, v116
	v_or_b32_e32 v117, 16, v160
	v_pk_mul_f32 v[108:109], v[116:117], v[108:109] op_sel_hi:[0,1]
	v_pk_mul_f32 v[104:105], v[116:117], v[104:105] op_sel_hi:[0,1]
	v_mul_f32_e32 v118, 0xbfb8aa3b, v108
	v_pk_mul_f32 v[104:105], v[108:109], v[104:105]
	v_mul_f32_e32 v108, 0xbfb8aa3b, v109
	v_exp_f32_e32 v118, v118
	v_exp_f32_e32 v108, v108
	v_pk_mul_f32 v[106:107], v[116:117], v[106:107] op_sel_hi:[0,1]
	v_pk_mul_f32 v[100:101], v[116:117], v[100:101] op_sel_hi:[0,1]
	v_add_f32_e32 v118, 1.0, v118
	v_add_f32_e32 v108, 1.0, v108
	v_rcp_f32_e32 v118, v118
	v_rcp_f32_e32 v119, v108
	v_pk_mul_f32 v[108:109], v[116:117], v[110:111] op_sel_hi:[0,1]
	v_pk_mul_f32 v[106:107], v[108:109], v[106:107]
	v_pk_mul_f32 v[96:97], v[116:117], v[96:97] op_sel_hi:[0,1]
	v_pk_mul_f32 v[104:105], v[118:119], v[104:105]
	v_pk_mul_f32 v[96:97], v[100:101], v[96:97]
	v_cvt_pk_bf16_f32 v104, v104, v105
	v_mul_f32_e32 v105, 0xbfb8aa3b, v108
	v_exp_f32_e32 v105, v105
	v_pk_mul_f32 v[98:99], v[116:117], v[98:99] op_sel_hi:[0,1]
	v_add_f32_e32 v105, 1.0, v105
	v_rcp_f32_e32 v110, v105
	v_mul_f32_e32 v105, 0xbfb8aa3b, v109
	v_exp_f32_e32 v105, v105
	s_nop 0
	v_add_f32_e32 v105, 1.0, v105
	v_rcp_f32_e32 v111, v105
	s_nop 0
	v_pk_mul_f32 v[106:107], v[110:111], v[106:107]
	s_nop 0
	v_cvt_pk_bf16_f32 v105, v106, v107
	v_mul_f32_e32 v106, 0xbfb8aa3b, v100
	v_mul_f32_e32 v100, 0xbfb8aa3b, v101
	v_exp_f32_e32 v106, v106
	v_exp_f32_e32 v100, v100
	v_add_f32_e32 v106, 1.0, v106
	v_add_f32_e32 v100, 1.0, v100
	v_rcp_f32_e32 v106, v106
	v_rcp_f32_e32 v107, v100
	s_nop 0
	v_pk_mul_f32 v[96:97], v[106:107], v[96:97]
	s_nop 0
	v_cvt_pk_bf16_f32 v106, v96, v97
	v_pk_mul_f32 v[96:97], v[116:117], v[102:103] op_sel_hi:[0,1]
	v_mul_f32_e32 v100, 0xbfb8aa3b, v96
	v_pk_mul_f32 v[98:99], v[96:97], v[98:99]
	v_mul_f32_e32 v96, 0xbfb8aa3b, v97
	v_exp_f32_e32 v100, v100
	v_exp_f32_e32 v96, v96
	v_add_f32_e32 v100, 1.0, v100
	v_add_f32_e32 v96, 1.0, v96
	v_rcp_f32_e32 v100, v100
	v_rcp_f32_e32 v101, v96
	s_nop 0
	v_pk_mul_f32 v[96:97], v[100:101], v[98:99]
	s_nop 0
	v_cvt_pk_bf16_f32 v107, v96, v97
	v_mad_i64_i32 v[96:97], s[14:15], v117, s62, v[112:113]
	v_lshl_add_u64 v[96:97], v[96:97], 0, v[114:115]
	global_store_dwordx4 v[96:97], v[104:107], off
	v_fmamk_f32 v96, v157, 0x3a000000, v151
	v_rsq_f32_e32 v96, v96
	v_or_b32_e32 v97, 32, v160
	v_pk_mul_f32 v[92:93], v[96:97], v[92:93] op_sel_hi:[0,1]
	v_pk_mul_f32 v[88:89], v[96:97], v[88:89] op_sel_hi:[0,1]
	v_mul_f32_e32 v98, 0xbfb8aa3b, v92
	v_pk_mul_f32 v[88:89], v[92:93], v[88:89]
	v_mul_f32_e32 v92, 0xbfb8aa3b, v93
	v_exp_f32_e32 v98, v98
	v_exp_f32_e32 v92, v92
	v_pk_mul_f32 v[90:91], v[96:97], v[90:91] op_sel_hi:[0,1]
	v_pk_mul_f32 v[84:85], v[96:97], v[84:85] op_sel_hi:[0,1]
	v_add_f32_e32 v98, 1.0, v98
	v_add_f32_e32 v92, 1.0, v92
	v_rcp_f32_e32 v98, v98
	v_rcp_f32_e32 v99, v92
	v_pk_mul_f32 v[92:93], v[96:97], v[94:95] op_sel_hi:[0,1]
	v_pk_mul_f32 v[90:91], v[92:93], v[90:91]
	v_pk_mul_f32 v[80:81], v[96:97], v[80:81] op_sel_hi:[0,1]
	v_pk_mul_f32 v[88:89], v[98:99], v[88:89]
	v_pk_mul_f32 v[80:81], v[84:85], v[80:81]
	v_cvt_pk_bf16_f32 v88, v88, v89
	v_mul_f32_e32 v89, 0xbfb8aa3b, v92
	v_exp_f32_e32 v89, v89
	v_pk_mul_f32 v[82:83], v[96:97], v[82:83] op_sel_hi:[0,1]
	v_add_f32_e32 v89, 1.0, v89
	v_rcp_f32_e32 v94, v89
	v_mul_f32_e32 v89, 0xbfb8aa3b, v93
	v_exp_f32_e32 v89, v89
	s_nop 0
	v_add_f32_e32 v89, 1.0, v89
	v_rcp_f32_e32 v95, v89
	s_nop 0
	v_pk_mul_f32 v[90:91], v[94:95], v[90:91]
	s_nop 0
	v_cvt_pk_bf16_f32 v89, v90, v91
	v_mul_f32_e32 v90, 0xbfb8aa3b, v84
	v_mul_f32_e32 v84, 0xbfb8aa3b, v85
	v_exp_f32_e32 v90, v90
	v_exp_f32_e32 v84, v84
	v_add_f32_e32 v90, 1.0, v90
	v_add_f32_e32 v84, 1.0, v84
	v_rcp_f32_e32 v90, v90
	v_rcp_f32_e32 v91, v84
	s_nop 0
	v_pk_mul_f32 v[80:81], v[90:91], v[80:81]
	s_nop 0
	v_cvt_pk_bf16_f32 v90, v80, v81
	v_pk_mul_f32 v[80:81], v[96:97], v[86:87] op_sel_hi:[0,1]
	v_mul_f32_e32 v84, 0xbfb8aa3b, v80
	v_pk_mul_f32 v[82:83], v[80:81], v[82:83]
	v_mul_f32_e32 v80, 0xbfb8aa3b, v81
	v_exp_f32_e32 v84, v84
	v_exp_f32_e32 v80, v80
	v_add_f32_e32 v84, 1.0, v84
	v_add_f32_e32 v80, 1.0, v80
	v_rcp_f32_e32 v84, v84
	v_rcp_f32_e32 v85, v80
	s_nop 0
	v_pk_mul_f32 v[80:81], v[84:85], v[82:83]
	s_nop 0
	v_cvt_pk_bf16_f32 v91, v80, v81
	v_mad_i64_i32 v[80:81], s[14:15], v97, s62, v[112:113]
	v_lshl_add_u64 v[80:81], v[80:81], 0, v[114:115]
	global_store_dwordx4 v[80:81], v[88:91], off
	v_fmamk_f32 v80, v156, 0x3a000000, v151
	v_rsq_f32_e32 v80, v80
	v_or_b32_e32 v81, 48, v160
	v_pk_mul_f32 v[76:77], v[80:81], v[76:77] op_sel_hi:[0,1]
	v_pk_mul_f32 v[72:73], v[80:81], v[72:73] op_sel_hi:[0,1]
	v_mul_f32_e32 v82, 0xbfb8aa3b, v76
	v_pk_mul_f32 v[72:73], v[76:77], v[72:73]
	v_mul_f32_e32 v76, 0xbfb8aa3b, v77
	v_exp_f32_e32 v82, v82
	v_exp_f32_e32 v76, v76
	v_pk_mul_f32 v[74:75], v[80:81], v[74:75] op_sel_hi:[0,1]
	v_pk_mul_f32 v[68:69], v[80:81], v[68:69] op_sel_hi:[0,1]
	v_add_f32_e32 v82, 1.0, v82
	v_add_f32_e32 v76, 1.0, v76
	v_rcp_f32_e32 v82, v82
	v_rcp_f32_e32 v83, v76
	v_pk_mul_f32 v[76:77], v[80:81], v[78:79] op_sel_hi:[0,1]
; __device__ __forceinline__ float sigmoidf_(float x) { return __builtin_amdgcn_rcpf(1.0f + fexp(-x)); }
;     __device__ __forceinline__ void operator()(const f32x4 (&acc)[2][2][4][2], const Unit& u, int wr, int wc, int fr, int fq, const Pre& P) const {
;         const int row0 = ROW_X + u.pm * BM + wr * 64 + fr, col0 = u.pn * HALF + wc * 32 + 8 * fq;
; #pragma unroll
;         for (int ai = 0; ai < 2; ++ai)
; #pragma unroll
;             for (int m = 0; m < 4; ++m) { const int r = row0 + ai * HALF + m * 16; const float rs = __builtin_amdgcn_rsqf(P.rs[ai * 4 + m] * (1.0f / DM) + RMS_EPS);
;                 float y[8];
; #pragma unroll
;                 for (int n = 0; n < 2; ++n)
; #pragma unroll
;                     for (int j = 0; j < 4; ++j) { const float a = acc[ai][0][m][n][j] * rs, b = acc[ai][1][m][n][j] * rs; y[n * 4 + j] = a * b * sigmoidf_(a); }
;                 u32x4 w; w.x = cvtpk(y[0], y[1]); w.y = cvtpk(y[2], y[3]); w.z = cvtpk(y[4], y[5]); w.w = cvtpk(y[6], y[7]);
;                 *(u32x4*)(O + (size_t)r * FF + col0) = w; }
	v_pk_mul_f32 v[74:75], v[76:77], v[74:75]
	v_pk_mul_f32 v[64:65], v[80:81], v[64:65] op_sel_hi:[0,1]
	v_pk_mul_f32 v[72:73], v[82:83], v[72:73]
	v_pk_mul_f32 v[64:65], v[68:69], v[64:65]
	v_cvt_pk_bf16_f32 v72, v72, v73
	v_mul_f32_e32 v73, 0xbfb8aa3b, v76
	v_exp_f32_e32 v73, v73
	v_pk_mul_f32 v[66:67], v[80:81], v[66:67] op_sel_hi:[0,1]
	v_add_f32_e32 v73, 1.0, v73
	v_rcp_f32_e32 v78, v73
	v_mul_f32_e32 v73, 0xbfb8aa3b, v77
	v_exp_f32_e32 v73, v73
	s_nop 0
	v_add_f32_e32 v73, 1.0, v73
	v_rcp_f32_e32 v79, v73
	s_nop 0
	v_pk_mul_f32 v[74:75], v[78:79], v[74:75]
	s_nop 0
	v_cvt_pk_bf16_f32 v73, v74, v75
	v_mul_f32_e32 v74, 0xbfb8aa3b, v68
	v_mul_f32_e32 v68, 0xbfb8aa3b, v69
	v_exp_f32_e32 v74, v74
	v_exp_f32_e32 v68, v68
	v_add_f32_e32 v74, 1.0, v74
	v_add_f32_e32 v68, 1.0, v68
	v_rcp_f32_e32 v74, v74
	v_rcp_f32_e32 v75, v68
	s_nop 0
	v_pk_mul_f32 v[64:65], v[74:75], v[64:65]
	s_nop 0
	v_cvt_pk_bf16_f32 v74, v64, v65
	v_pk_mul_f32 v[64:65], v[80:81], v[70:71] op_sel_hi:[0,1]
	v_mul_f32_e32 v68, 0xbfb8aa3b, v64
	v_pk_mul_f32 v[66:67], v[64:65], v[66:67]
	v_mul_f32_e32 v64, 0xbfb8aa3b, v65
	v_exp_f32_e32 v68, v68
	v_exp_f32_e32 v64, v64
	v_add_f32_e32 v68, 1.0, v68
	v_add_f32_e32 v64, 1.0, v64
	v_rcp_f32_e32 v68, v68
	v_rcp_f32_e32 v69, v64
	s_nop 0
	v_pk_mul_f32 v[64:65], v[68:69], v[66:67]
	s_nop 0
	v_cvt_pk_bf16_f32 v75, v64, v65
	v_mad_i64_i32 v[64:65], s[14:15], v81, s62, v[112:113]
	v_lshl_add_u64 v[64:65], v[64:65], 0, v[114:115]
	global_store_dwordx4 v[64:65], v[72:75], off
	v_fmamk_f32 v64, v155, 0x3a000000, v151
	v_rsq_f32_e32 v64, v64
	v_add_u32_e32 v65, 0x80, v160
	v_pk_mul_f32 v[60:61], v[64:65], v[60:61] op_sel_hi:[0,1]
	v_pk_mul_f32 v[56:57], v[64:65], v[56:57] op_sel_hi:[0,1]
	v_mul_f32_e32 v66, 0xbfb8aa3b, v60
	v_pk_mul_f32 v[56:57], v[60:61], v[56:57]
	v_mul_f32_e32 v60, 0xbfb8aa3b, v61
	v_exp_f32_e32 v66, v66
	v_exp_f32_e32 v60, v60
	v_pk_mul_f32 v[58:59], v[64:65], v[58:59] op_sel_hi:[0,1]
	v_pk_mul_f32 v[52:53], v[64:65], v[52:53] op_sel_hi:[0,1]
	v_add_f32_e32 v66, 1.0, v66
	v_add_f32_e32 v60, 1.0, v60
	v_rcp_f32_e32 v66, v66
	v_rcp_f32_e32 v67, v60
	v_pk_mul_f32 v[60:61], v[64:65], v[62:63] op_sel_hi:[0,1]
	v_pk_mul_f32 v[58:59], v[60:61], v[58:59]
	v_pk_mul_f32 v[48:49], v[64:65], v[48:49] op_sel_hi:[0,1]
	v_pk_mul_f32 v[56:57], v[66:67], v[56:57]
	v_pk_mul_f32 v[48:49], v[52:53], v[48:49]
	v_cvt_pk_bf16_f32 v56, v56, v57
	v_mul_f32_e32 v57, 0xbfb8aa3b, v60
	v_exp_f32_e32 v57, v57
	v_pk_mul_f32 v[50:51], v[64:65], v[50:51] op_sel_hi:[0,1]
	v_add_f32_e32 v57, 1.0, v57
	v_rcp_f32_e32 v62, v57
	v_mul_f32_e32 v57, 0xbfb8aa3b, v61
	v_exp_f32_e32 v57, v57
	s_nop 0
	v_add_f32_e32 v57, 1.0, v57
	v_rcp_f32_e32 v63, v57
	s_nop 0
	v_pk_mul_f32 v[58:59], v[62:63], v[58:59]
	s_nop 0
	v_cvt_pk_bf16_f32 v57, v58, v59
	v_mul_f32_e32 v58, 0xbfb8aa3b, v52
	v_mul_f32_e32 v52, 0xbfb8aa3b, v53
	v_exp_f32_e32 v58, v58
	v_exp_f32_e32 v52, v52
	v_add_f32_e32 v58, 1.0, v58
	v_add_f32_e32 v52, 1.0, v52
	v_rcp_f32_e32 v58, v58
	v_rcp_f32_e32 v59, v52
	s_nop 0
	v_pk_mul_f32 v[48:49], v[58:59], v[48:49]
	s_nop 0
	v_cvt_pk_bf16_f32 v58, v48, v49
	v_pk_mul_f32 v[48:49], v[64:65], v[54:55] op_sel_hi:[0,1]
	v_mul_f32_e32 v52, 0xbfb8aa3b, v48
	v_pk_mul_f32 v[50:51], v[48:49], v[50:51]
	v_mul_f32_e32 v48, 0xbfb8aa3b, v49
	v_exp_f32_e32 v52, v52
	v_exp_f32_e32 v48, v48
	v_add_f32_e32 v52, 1.0, v52
	v_add_f32_e32 v48, 1.0, v48
	v_rcp_f32_e32 v52, v52
	v_rcp_f32_e32 v53, v48
	s_nop 0
	v_pk_mul_f32 v[48:49], v[52:53], v[50:51]
	s_nop 0
	v_cvt_pk_bf16_f32 v59, v48, v49
	v_mad_i64_i32 v[48:49], s[14:15], v65, s62, v[112:113]
	v_lshl_add_u64 v[48:49], v[48:49], 0, v[114:115]
	global_store_dwordx4 v[48:49], v[56:59], off
	v_fmamk_f32 v48, v154, 0x3a000000, v151
	v_rsq_f32_e32 v48, v48
	v_add_u32_e32 v49, 0x90, v160
	v_pk_mul_f32 v[44:45], v[48:49], v[44:45] op_sel_hi:[0,1]
	v_pk_mul_f32 v[40:41], v[48:49], v[40:41] op_sel_hi:[0,1]
	v_mul_f32_e32 v50, 0xbfb8aa3b, v44
	v_pk_mul_f32 v[40:41], v[44:45], v[40:41]
	v_mul_f32_e32 v44, 0xbfb8aa3b, v45
	v_exp_f32_e32 v50, v50
	v_exp_f32_e32 v44, v44
	v_pk_mul_f32 v[42:43], v[48:49], v[42:43] op_sel_hi:[0,1]
	v_pk_mul_f32 v[36:37], v[48:49], v[36:37] op_sel_hi:[0,1]
	v_add_f32_e32 v50, 1.0, v50
	v_add_f32_e32 v44, 1.0, v44
	v_rcp_f32_e32 v50, v50
	v_rcp_f32_e32 v51, v44
	v_pk_mul_f32 v[44:45], v[48:49], v[46:47] op_sel_hi:[0,1]
	v_pk_mul_f32 v[42:43], v[44:45], v[42:43]
	v_pk_mul_f32 v[32:33], v[48:49], v[32:33] op_sel_hi:[0,1]
	v_pk_mul_f32 v[40:41], v[50:51], v[40:41]
	v_pk_mul_f32 v[32:33], v[36:37], v[32:33]
	v_cvt_pk_bf16_f32 v40, v40, v41
	v_mul_f32_e32 v41, 0xbfb8aa3b, v44
	v_exp_f32_e32 v41, v41
	v_pk_mul_f32 v[34:35], v[48:49], v[34:35] op_sel_hi:[0,1]
	v_add_f32_e32 v41, 1.0, v41
	v_rcp_f32_e32 v46, v41
	v_mul_f32_e32 v41, 0xbfb8aa3b, v45
	v_exp_f32_e32 v41, v41
	s_nop 0
	v_add_f32_e32 v41, 1.0, v41
	v_rcp_f32_e32 v47, v41
	s_nop 0
	v_pk_mul_f32 v[42:43], v[46:47], v[42:43]
	s_nop 0
	v_cvt_pk_bf16_f32 v41, v42, v43
	v_mul_f32_e32 v42, 0xbfb8aa3b, v36
	v_mul_f32_e32 v36, 0xbfb8aa3b, v37
	v_exp_f32_e32 v42, v42
	v_exp_f32_e32 v36, v36
	v_add_f32_e32 v42, 1.0, v42
	v_add_f32_e32 v36, 1.0, v36
	v_rcp_f32_e32 v42, v42
	v_rcp_f32_e32 v43, v36
	s_nop 0
	v_pk_mul_f32 v[32:33], v[42:43], v[32:33]
	s_nop 0
	v_cvt_pk_bf16_f32 v42, v32, v33
	v_pk_mul_f32 v[32:33], v[48:49], v[38:39] op_sel_hi:[0,1]
	v_mul_f32_e32 v36, 0xbfb8aa3b, v32
	v_pk_mul_f32 v[34:35], v[32:33], v[34:35]
	v_mul_f32_e32 v32, 0xbfb8aa3b, v33
	v_exp_f32_e32 v36, v36
	v_exp_f32_e32 v32, v32
; __device__ __forceinline__ float sigmoidf_(float x) { return __builtin_amdgcn_rcpf(1.0f + fexp(-x)); }
; __device__ __forceinline__ PreRs load_rs(const float* ssq, int pm, int wr, int fr) { PreRs p;
; #pragma unroll
;     for (int ai = 0; ai < 2; ++ai)
; #pragma unroll
;         for (int m = 0; m < 4; ++m) p.rs[ai * 4 + m] = ssq[ROW_X + pm * BM + ai * HALF + wr * 64 + m * 16 + fr];
;     return p; }
;     __device__ __forceinline__ void operator()(const f32x4 (&acc)[2][2][4][2], const Unit& u, int wr, int wc, int fr, int fq, const Pre& P) const {
;         const int row0 = ROW_X + u.pm * BM + wr * 64 + fr, col0 = u.pn * HALF + wc * 32 + 8 * fq;
; #pragma unroll
;         for (int ai = 0; ai < 2; ++ai)
; #pragma unroll
;             for (int m = 0; m < 4; ++m) { const int r = row0 + ai * HALF + m * 16; const float rs = __builtin_amdgcn_rsqf(P.rs[ai * 4 + m] * (1.0f / DM) + RMS_EPS);
;                 float y[8];
; #pragma unroll
;                 for (int n = 0; n < 2; ++n)
; #pragma unroll
;                     for (int j = 0; j < 4; ++j) { const float a = acc[ai][0][m][n][j] * rs, b = acc[ai][1][m][n][j] * rs; y[n * 4 + j] = a * b * sigmoidf_(a); }
;                 u32x4 w; w.x = cvtpk(y[0], y[1]); w.y = cvtpk(y[2], y[3]); w.z = cvtpk(y[4], y[5]); w.w = cvtpk(y[6], y[7]);
;                 *(u32x4*)(O + (size_t)r * FF + col0) = w; }
	v_add_f32_e32 v36, 1.0, v36
	v_add_f32_e32 v32, 1.0, v32
	v_rcp_f32_e32 v36, v36
	v_rcp_f32_e32 v37, v32
	s_nop 0
	v_pk_mul_f32 v[32:33], v[36:37], v[34:35]
	s_nop 0
	v_cvt_pk_bf16_f32 v43, v32, v33
	v_mad_i64_i32 v[32:33], s[14:15], v49, s62, v[112:113]
	v_lshl_add_u64 v[32:33], v[32:33], 0, v[114:115]
	global_store_dwordx4 v[32:33], v[40:43], off
	v_fmamk_f32 v32, v153, 0x3a000000, v151
	v_rsq_f32_e32 v32, v32
	v_add_u32_e32 v33, 0xa0, v160
	v_pk_mul_f32 v[28:29], v[32:33], v[28:29] op_sel_hi:[0,1]
	v_pk_mul_f32 v[24:25], v[32:33], v[24:25] op_sel_hi:[0,1]
	v_mul_f32_e32 v34, 0xbfb8aa3b, v28
	v_pk_mul_f32 v[24:25], v[28:29], v[24:25]
	v_mul_f32_e32 v28, 0xbfb8aa3b, v29
	v_exp_f32_e32 v34, v34
	v_exp_f32_e32 v28, v28
	v_pk_mul_f32 v[26:27], v[32:33], v[26:27] op_sel_hi:[0,1]
	v_pk_mul_f32 v[20:21], v[32:33], v[20:21] op_sel_hi:[0,1]
	v_add_f32_e32 v34, 1.0, v34
	v_add_f32_e32 v28, 1.0, v28
	v_rcp_f32_e32 v34, v34
	v_rcp_f32_e32 v35, v28
	v_pk_mul_f32 v[28:29], v[32:33], v[30:31] op_sel_hi:[0,1]
	v_pk_mul_f32 v[26:27], v[28:29], v[26:27]
	v_pk_mul_f32 v[16:17], v[32:33], v[16:17] op_sel_hi:[0,1]
	v_pk_mul_f32 v[24:25], v[34:35], v[24:25]
	v_pk_mul_f32 v[16:17], v[20:21], v[16:17]
	v_cvt_pk_bf16_f32 v24, v24, v25
	v_mul_f32_e32 v25, 0xbfb8aa3b, v28
	v_exp_f32_e32 v25, v25
	v_pk_mul_f32 v[18:19], v[32:33], v[18:19] op_sel_hi:[0,1]
	v_add_f32_e32 v25, 1.0, v25
	v_rcp_f32_e32 v30, v25
	v_mul_f32_e32 v25, 0xbfb8aa3b, v29
	v_exp_f32_e32 v25, v25
	s_nop 0
	v_add_f32_e32 v25, 1.0, v25
	v_rcp_f32_e32 v31, v25
	s_nop 0
	v_pk_mul_f32 v[26:27], v[30:31], v[26:27]
	s_nop 0
	v_cvt_pk_bf16_f32 v25, v26, v27
	v_mul_f32_e32 v26, 0xbfb8aa3b, v20
	v_mul_f32_e32 v20, 0xbfb8aa3b, v21
	v_exp_f32_e32 v26, v26
	v_exp_f32_e32 v20, v20
	v_add_f32_e32 v26, 1.0, v26
	v_add_f32_e32 v20, 1.0, v20
	v_rcp_f32_e32 v26, v26
	v_rcp_f32_e32 v27, v20
	s_nop 0
	v_pk_mul_f32 v[16:17], v[26:27], v[16:17]
	s_nop 0
	v_cvt_pk_bf16_f32 v26, v16, v17
	v_pk_mul_f32 v[16:17], v[32:33], v[22:23] op_sel_hi:[0,1]
	v_mul_f32_e32 v20, 0xbfb8aa3b, v16
	v_pk_mul_f32 v[18:19], v[16:17], v[18:19]
	v_mul_f32_e32 v16, 0xbfb8aa3b, v17
	v_exp_f32_e32 v20, v20
	v_exp_f32_e32 v16, v16
	v_add_f32_e32 v20, 1.0, v20
	v_add_f32_e32 v16, 1.0, v16
	v_rcp_f32_e32 v20, v20
	v_rcp_f32_e32 v21, v16
	s_nop 0
	v_pk_mul_f32 v[16:17], v[20:21], v[18:19]
	s_nop 0
	v_cvt_pk_bf16_f32 v27, v16, v17
	v_mad_i64_i32 v[16:17], s[14:15], v33, s62, v[112:113]
	v_lshl_add_u64 v[16:17], v[16:17], 0, v[114:115]
	global_store_dwordx4 v[16:17], v[24:27], off
	v_fmamk_f32 v16, v152, 0x3a000000, v151
	v_rsq_f32_e32 v16, v16
	v_add_u32_e32 v17, 0xb0, v160
	v_pk_mul_f32 v[12:13], v[16:17], v[12:13] op_sel_hi:[0,1]
	v_pk_mul_f32 v[8:9], v[16:17], v[8:9] op_sel_hi:[0,1]
	v_mul_f32_e32 v18, 0xbfb8aa3b, v12
	v_pk_mul_f32 v[8:9], v[12:13], v[8:9]
	v_mul_f32_e32 v12, 0xbfb8aa3b, v13
	v_exp_f32_e32 v18, v18
	v_exp_f32_e32 v12, v12
	v_pk_mul_f32 v[10:11], v[16:17], v[10:11] op_sel_hi:[0,1]
	v_pk_mul_f32 v[4:5], v[16:17], v[4:5] op_sel_hi:[0,1]
	v_add_f32_e32 v18, 1.0, v18
	v_add_f32_e32 v12, 1.0, v12
	v_rcp_f32_e32 v18, v18
	v_rcp_f32_e32 v19, v12
	v_pk_mul_f32 v[12:13], v[16:17], v[14:15] op_sel_hi:[0,1]
	v_pk_mul_f32 v[10:11], v[12:13], v[10:11]
	v_pk_mul_f32 v[0:1], v[16:17], v[0:1] op_sel_hi:[0,1]
	v_pk_mul_f32 v[8:9], v[18:19], v[8:9]
	v_pk_mul_f32 v[0:1], v[4:5], v[0:1]
	v_cvt_pk_bf16_f32 v8, v8, v9
	v_mul_f32_e32 v9, 0xbfb8aa3b, v12
	v_exp_f32_e32 v9, v9
	v_pk_mul_f32 v[2:3], v[16:17], v[2:3] op_sel_hi:[0,1]
	v_add_f32_e32 v9, 1.0, v9
	v_rcp_f32_e32 v14, v9
	v_mul_f32_e32 v9, 0xbfb8aa3b, v13
	v_exp_f32_e32 v9, v9
	s_nop 0
	v_add_f32_e32 v9, 1.0, v9
	v_rcp_f32_e32 v15, v9
	s_nop 0
	v_pk_mul_f32 v[10:11], v[14:15], v[10:11]
	s_nop 0
	v_cvt_pk_bf16_f32 v9, v10, v11
	v_mul_f32_e32 v10, 0xbfb8aa3b, v4
	v_mul_f32_e32 v4, 0xbfb8aa3b, v5
	v_exp_f32_e32 v10, v10
	v_exp_f32_e32 v4, v4
	v_add_f32_e32 v10, 1.0, v10
	v_add_f32_e32 v4, 1.0, v4
	v_rcp_f32_e32 v10, v10
	v_rcp_f32_e32 v11, v4
	s_nop 0
	v_pk_mul_f32 v[0:1], v[10:11], v[0:1]
	s_nop 0
	v_cvt_pk_bf16_f32 v10, v0, v1
	v_pk_mul_f32 v[0:1], v[16:17], v[6:7] op_sel_hi:[0,1]
	v_mul_f32_e32 v4, 0xbfb8aa3b, v0
	v_pk_mul_f32 v[2:3], v[0:1], v[2:3]
	v_mul_f32_e32 v0, 0xbfb8aa3b, v1
	v_exp_f32_e32 v4, v4
	v_exp_f32_e32 v0, v0
	v_add_f32_e32 v4, 1.0, v4
	v_add_f32_e32 v0, 1.0, v0
	v_rcp_f32_e32 v4, v4
	v_rcp_f32_e32 v5, v0
	s_nop 0
	v_pk_mul_f32 v[0:1], v[4:5], v[2:3]
	s_nop 0
	v_cvt_pk_bf16_f32 v11, v0, v1
	v_mad_i64_i32 v[0:1], s[14:15], v17, s62, v[112:113]
	v_lshl_add_u64 v[0:1], v[0:1], 0, v[114:115]
	s_mov_b64 s[14:15], -1
	global_store_dwordx4 v[0:1], v[8:11], off
	s_cbranch_vccz .LBB0_255
	v_lshl_add_u32 v0, s8, 8, v145
	v_ashrrev_i32_e32 v1, 31, v0
	v_lshl_add_u64 v[2:3], v[0:1], 2, s[2:3]
	v_add_u32_e32 v4, 0x80, v0
	v_add_u32_e32 v6, 0x90, v0
	v_add_u32_e32 v8, 0xa0, v0
	v_add_u32_e32 v0, 0xb0, v0
	v_ashrrev_i32_e32 v5, 31, v4
	v_ashrrev_i32_e32 v7, 31, v6
	v_ashrrev_i32_e32 v9, 31, v8
	v_ashrrev_i32_e32 v1, 31, v0
	v_lshl_add_u64 v[4:5], v[4:5], 2, s[2:3]
	v_lshl_add_u64 v[6:7], v[6:7], 2, s[2:3]
	v_lshl_add_u64 v[8:9], v[8:9], 2, s[2:3]
	v_lshl_add_u64 v[0:1], v[0:1], 2, s[2:3]
	global_load_dword v159, v[2:3], off
	global_load_dword v158, v[2:3], off offset:64
	global_load_dword v157, v[2:3], off offset:128
	global_load_dword v156, v[2:3], off offset:192
	global_load_dword v155, v[4:5], off
	global_load_dword v154, v[6:7], off
	global_load_dword v153, v[8:9], off
	global_load_dword v152, v[0:1], off
	s_mov_b64 s[14:15], 0
	s_branch .LBB0_255

; #define PG8_STAGE(bufoff, gbase, voff) do { _Pragma("unroll") for (int _i = 0; _i < 2; ++_i) \
;         __builtin_amdgcn_global_load_lds((const unsigned*)((const char*)(gbase) + (voff)[_i]), (LAS unsigned*)(lds + (bufoff) + ldsw + _i * 8192), 16, 0, 0); } while (0)
; #define PG8_WAIT_V(n) asm volatile("s_waitcnt vmcnt(" #n ")" ::: "memory")
; #define PG8_BAR __builtin_amdgcn_s_barrier()
; template <class Epi>
; __device__ __forceinline__ void gemm_phase(LAS unsigned char* lds, const Gemm g, const StaticOrder& S, const Epi& E) {
;     const int tid = threadIdx.x, wid = __builtin_amdgcn_readfirstlane(tid >> 6), lane = tid & 63, wr = wid >> 2, wc = wid & 3, fr = lane & 15, fq = lane >> 4;
;     const int K = g.K, nt = K / BK;
;     unsigned voffA[2], voffB[2];
; #pragma unroll
;     for (int i = 0; i < 2; ++i) { int R, C; stage_rc(tid * 16 + i * 8192, R, C); const int Rb = Epi::PERM ? ((R & ~31) + perm32(R & 31)) : R;
;         voffA[i] = (unsigned)(R * K + C) * 2u; voffB[i] = (unsigned)(Rb * K + C) * 2u; }
;     const size_t kstep = (size_t)(BK * 2);
;     const size_t hstep = (size_t)HALF * K * 2;
;     const size_t tstep = 2 * hstep;
;     const unsigned ldsw = (unsigned)wid * 1024u;
;     const int aoff = lds_byte(wr * 64 + fr, fq * 8), boff = lds_byte(wc * 32 + fr, fq * 8);
;     ...
;     PG8_STAGE(PG8_SB(0, 0), cB, voffB); PG8_STAGE(PG8_SA(0, 0), cA, voffA); PG8_STAGE(PG8_SB(0, 1), cB + hstep, voffB); PG8_STAGE(PG8_SA(0, 1), cA + hstep, voffA);
;     if (wr == 1) PG8_BAR;
;     PG8_WAIT_V(4); PG8_BAR;
;     PG8_STAGE(PG8_SB(1, 0), cB + kstep, voffB); PG8_STAGE(PG8_SA(1, 0), cA + kstep, voffA); PG8_STAGE(PG8_SB(1, 1), cB + hstep + kstep, voffB);
;     PG8_WAIT_V(6); PG8_BAR;
.LBB0_351:
	s_lshl_b32 s1, s1, 5
	s_mov_b64 s[12:13], 0x80
	s_and_b32 s1, s1, 0x60
	s_add_i32 m0, s30, 0x18000
	v_lshl_add_u64 v[6:7], v[6:7], 0, s[12:13]
	s_lshl_b32 s4, s0, 13
	s_lshl_b32 s5, s1, 7
	s_waitcnt vmcnt(2)
	s_barrier
	global_load_lds_dwordx4 v[6:7], off
	v_lshl_add_u64 v[4:5], v[4:5], 0, s[12:13]
	s_add_i32 m0, s30, 0x1a000
	s_add_i32 s38, s30, 0x8000
	s_add_i32 s39, s30, 0xa000
	global_load_lds_dwordx4 v[4:5], off
	v_lshl_add_u64 v[2:3], v[2:3], 0, s[12:13]
	s_mov_b32 m0, s38
	s_add_u32 s2, s16, 0x158080
	global_load_lds_dwordx4 v[2:3], off
	v_lshl_add_u64 v[0:1], v[0:1], 0, s[12:13]
	s_mov_b32 m0, s39
	s_addc_u32 s3, s17, 0
	global_load_lds_dwordx4 v[0:1], off
	s_add_i32 m0, s30, 0x1c000
	v_lshl_add_u64 v[0:1], s[2:3], 0, v[138:139]
	global_load_lds_dwordx4 v[0:1], off
	v_lshl_add_u64 v[0:1], s[2:3], 0, v[142:143]
	s_add_i32 m0, s30, 0x1e000
	v_lshlrev_b32_e32 v4, 2, v148
	global_load_lds_dwordx4 v[0:1], off
	v_bfe_u32 v0, v178, 4, 2
	v_lshlrev_b32_e32 v2, 4, v0
	v_lshl_or_b32 v3, v148, 6, v2
	v_and_b32_e32 v4, 32, v4
	v_lshl_or_b32 v1, s0, 6, v148
	v_bitop3_b32 v3, v3, s4, v4 bitop3:0xde
	v_lshlrev_b32_e32 v4, 6, v178
	s_movk_i32 s0, 0x3c0
	v_and_or_b32 v2, v4, s0, v2
	v_lshlrev_b32_e32 v4, 2, v178
	v_cmp_eq_u32_e64 s[2:3], 0, v0
	v_lshl_or_b32 v160, v0, 3, s1
	v_add_u16_e32 v0, v8, v9
	v_and_b32_e32 v4, 32, v4
	s_waitcnt vmcnt(6)
	v_lshrrev_b16_e32 v0, 1, v0
	s_waitcnt vmcnt(0)
	v_bitop3_b32 v158, s5, v2, v4 bitop3:0xf6
	v_add_lshl_u32 v144, v10, v0, 1
	v_add_lshl_u32 v146, v11, v0, 1
	s_add_i32 s57, 0, 0x10000
	s_add_i32 s58, 0, 0x14000
	v_mbcnt_lo_u32_b32 v0, -1, 0
	v_add_u32_e32 v159, 0x100, v1
	s_ashr_i32 s42, s54, 31
	s_mov_b32 s43, s54
	s_ashr_i32 s56, s28, 31
	v_mov_b32_e32 v145, v139
	v_mov_b32_e32 v147, v139
	v_mov_b64_e32 v[148:149], 0x200
	v_mov_b64_e32 v[150:151], 0x1ff
	v_add_u32_e32 v161, s57, v158
	v_add_u32_e32 v162, 0, v3
	v_add_u32_e32 v163, s58, v158
	v_mbcnt_hi_u32_b32 v165, -1, v0
	s_barrier
	s_branch .LBB0_353

; #define PG8_STAGE(bufoff, gbase, voff) do { _Pragma("unroll") for (int _i = 0; _i < 2; ++_i) \
;         __builtin_amdgcn_global_load_lds((const unsigned*)((const char*)(gbase) + (voff)[_i]), (LAS unsigned*)(lds + (bufoff) + ldsw + _i * 8192), 16, 0, 0); } while (0)
; #define PG8_LDA(dst, b, h) do { _Pragma("unroll") for (int m = 0; m < 4; ++m) _Pragma("unroll") for (int k = 0; k < 2; ++k) dst[m][k] = *(const LAS bf16x8*)(lds + PG8_SA(b, h) + aoff + m * 2048 + k * 1024); } while (0)
; #define PG8_LDB(dst, b, h) do { _Pragma("unroll") for (int n = 0; n < 2; ++n) _Pragma("unroll") for (int k = 0; k < 2; ++k) dst[n][k] = *(const LAS bf16x8*)(lds + PG8_SB(b, h) + boff + n * 2048 + k * 1024); } while (0)
; #define PG8_MMA(ai, bj, At, Bt) do { __builtin_amdgcn_s_setprio(1); _Pragma("unroll") for (int m = 0; m < 4; ++m) _Pragma("unroll") for (int n = 0; n < 2; ++n) _Pragma("unroll") for (int k = 0; k < 2; ++k) \
;         acc[ai][bj][m][n] = __builtin_amdgcn_mfma_f32_16x16x32_bf16(Bt[n][k], At[m][k], acc[ai][bj][m][n], 0, 0, 0); __builtin_amdgcn_s_setprio(0); } while (0)
; #define PG8_WAIT_L(n) asm volatile("s_waitcnt lgkmcnt(" #n ")" ::: "memory")
; #define PG8_BAR __builtin_amdgcn_s_barrier()
; #define PG8_SCHED __builtin_amdgcn_sched_barrier(0)
; template <class Epi>
; __device__ __forceinline__ void gemm_phase(LAS unsigned char* lds, const Gemm g, const StaticOrder& S, const Epi& E) {
;     ...
;             PG8_LDB(B0, 0, 0); PG8_SCHED; PG8_LDA(At, 0, 0); PG8_STAGE(PG8_SA(1, 1), a1 + hstep, voffA);
;             PG8_WAIT_L(8); PG8_BAR; PG8_WAIT_L(0); PG8_MMA(0, 0, At, B0); PG8_BAR; PG8_SCHED;
;             PG8_LDB(B1, 0, 1); PG8_STAGE(PG8_SB(0, 0), b2, voffB);
;             PG8_BAR; PG8_WAIT_L(0); PG8_MMA(0, 1, At, B1); PG8_BAR;
;             PG8_LDA(At, 0, 1); PG8_STAGE(PG8_SA(0, 0), a2, voffA);
;             PG8_BAR; PG8_WAIT_L(0); PG8_MMA(1, 0, At, B0); PG8_BAR; PG8_SCHED;
;             PG8_STAGE(PG8_SB(0, 1), b2 + hstep, voffB);
.LBB0_364:
	ds_read_b128 v[128:131], v161
	ds_read_b128 v[132:135], v161 offset:1024
	ds_read_b128 v[152:155], v161 offset:2048
	ds_read_b128 v[166:169], v161 offset:3072
	s_add_u32 s16, s14, 0xffea8080
	s_addc_u32 s17, s15, -1
	s_cmpk_eq_i32 s65, 0x52
	s_cselect_b32 s19, s1, s17
	s_cselect_b32 s18, s0, s16
	s_cselect_b32 s17, s7, s64
	s_cselect_b32 s16, s6, s63
	v_lshl_add_u64 v[156:157], s[14:15], 0, v[144:145]
	s_add_i32 m0, s30, 0xc000
	ds_read_b128 v[170:173], v162
	ds_read_b128 v[174:177], v162 offset:1024
	ds_read_b128 v[180:183], v162 offset:2048
	ds_read_b128 v[184:187], v162 offset:3072
	ds_read_b128 v[188:191], v162 offset:4096
	ds_read_b128 v[192:195], v162 offset:5120
	ds_read_b128 v[196:199], v162 offset:6144
	ds_read_b128 v[200:203], v162 offset:7168
	global_load_lds_dwordx4 v[156:157], off
	v_lshl_add_u64 v[156:157], s[14:15], 0, v[146:147]
	s_add_i32 m0, s30, 0xe000
	s_nop 0
	global_load_lds_dwordx4 v[156:157], off
	ds_read_b128 v[204:207], v163
	ds_read_b128 v[208:211], v163 offset:1024
	ds_read_b128 v[212:215], v163 offset:2048
	ds_read_b128 v[216:219], v163 offset:3072
	s_waitcnt lgkmcnt(0)
	s_waitcnt vmcnt(8)
	s_setprio 1
	s_barrier
	v_mfma_f32_16x16x32_bf16 v[124:127], v[128:131], v[170:173], v[124:127]
	v_mfma_f32_16x16x32_bf16 v[120:123], v[152:155], v[170:173], v[120:123]
	v_mfma_f32_16x16x32_bf16 v[108:111], v[128:131], v[180:183], v[108:111]
	v_mfma_f32_16x16x32_bf16 v[104:107], v[152:155], v[180:183], v[104:107]
	v_mfma_f32_16x16x32_bf16 v[92:95], v[128:131], v[188:191], v[92:95]
	v_mfma_f32_16x16x32_bf16 v[88:91], v[152:155], v[188:191], v[88:91]
	v_mfma_f32_16x16x32_bf16 v[76:79], v[128:131], v[196:199], v[76:79]
	v_mfma_f32_16x16x32_bf16 v[72:75], v[152:155], v[196:199], v[72:75]
	v_mfma_f32_16x16x32_bf16 v[124:127], v[132:135], v[174:177], v[124:127]
	v_mfma_f32_16x16x32_bf16 v[120:123], v[166:169], v[174:177], v[120:123]
	v_mfma_f32_16x16x32_bf16 v[108:111], v[132:135], v[184:187], v[108:111]
	v_mfma_f32_16x16x32_bf16 v[104:107], v[166:169], v[184:187], v[104:107]
	v_mfma_f32_16x16x32_bf16 v[92:95], v[132:135], v[192:195], v[92:95]
	v_mfma_f32_16x16x32_bf16 v[88:91], v[166:169], v[192:195], v[88:91]
	v_mfma_f32_16x16x32_bf16 v[76:79], v[132:135], v[200:203], v[76:79]
	v_mfma_f32_16x16x32_bf16 v[72:75], v[166:169], v[200:203], v[72:75]
	v_mfma_f32_16x16x32_bf16 v[116:119], v[204:207], v[170:173], v[116:119]
	v_mfma_f32_16x16x32_bf16 v[112:115], v[212:215], v[170:173], v[112:115]
	v_mfma_f32_16x16x32_bf16 v[100:103], v[204:207], v[180:183], v[100:103]
	v_mfma_f32_16x16x32_bf16 v[96:99], v[212:215], v[180:183], v[96:99]
	v_mfma_f32_16x16x32_bf16 v[84:87], v[204:207], v[188:191], v[84:87]
	v_mfma_f32_16x16x32_bf16 v[80:83], v[212:215], v[188:191], v[80:83]
	v_mfma_f32_16x16x32_bf16 v[68:71], v[204:207], v[196:199], v[68:71]
	v_mfma_f32_16x16x32_bf16 v[64:67], v[212:215], v[196:199], v[64:67]
	v_mfma_f32_16x16x32_bf16 v[116:119], v[208:211], v[174:177], v[116:119]
	v_mfma_f32_16x16x32_bf16 v[112:115], v[216:219], v[174:177], v[112:115]
	v_mfma_f32_16x16x32_bf16 v[100:103], v[208:211], v[184:187], v[100:103]
	v_mfma_f32_16x16x32_bf16 v[96:99], v[216:219], v[184:187], v[96:99]
	v_mfma_f32_16x16x32_bf16 v[84:87], v[208:211], v[192:195], v[84:87]
	v_mfma_f32_16x16x32_bf16 v[80:83], v[216:219], v[192:195], v[80:83]
	v_mfma_f32_16x16x32_bf16 v[68:71], v[208:211], v[200:203], v[68:71]
	v_mfma_f32_16x16x32_bf16 v[64:67], v[216:219], v[200:203], v[64:67]
	s_barrier
	s_setprio 0
	s_add_i32 s66, s57, s21
	v_lshl_add_u64 v[156:157], s[16:17], 0, v[138:139]
	s_mov_b32 m0, s66
	s_nop 0
	global_load_lds_dwordx4 v[156:157], off
	v_lshl_add_u64 v[220:221], s[16:17], 0, v[142:143]
	s_add_i32 m0, s66, 0x2000
	s_nop 0
	global_load_lds_dwordx4 v[220:221], off
	s_mov_b32 m0, s30
	v_lshl_add_u64 v[222:223], s[18:19], 0, v[136:137]
	ds_read_b128 v[170:173], v162 offset:16384
	ds_read_b128 v[174:177], v162 offset:17408
	ds_read_b128 v[180:183], v162 offset:18432
	ds_read_b128 v[184:187], v162 offset:19456
	ds_read_b128 v[188:191], v162 offset:20480
	ds_read_b128 v[192:195], v162 offset:21504
	ds_read_b128 v[196:199], v162 offset:22528
	ds_read_b128 v[200:203], v162 offset:23552
	global_load_lds_dwordx4 v[222:223], off
	v_lshl_add_u64 v[224:225], s[18:19], 0, v[140:141]
	s_mov_b32 m0, s31
	s_nop 0
	global_load_lds_dwordx4 v[224:225], off
	s_add_u32 s66, s16, 0x158000
	s_addc_u32 s67, s17, 0
	s_add_i32 s68, s58, s21
	v_lshl_add_u64 v[252:253], s[66:67], 0, v[138:139]
	s_mov_b32 m0, s68
	s_nop 0
	global_load_lds_dwordx4 v[252:253], off
	v_lshl_add_u64 v[252:253], s[66:67], 0, v[142:143]
	s_add_i32 m0, s68, 0x2000
	s_nop 0
	global_load_lds_dwordx4 v[252:253], off
	s_waitcnt lgkmcnt(0)
	s_waitcnt vmcnt(8)
	s_setprio 1
	s_barrier
; #define PG8_STAGE(bufoff, gbase, voff) do { _Pragma("unroll") for (int _i = 0; _i < 2; ++_i) \
;         __builtin_amdgcn_global_load_lds((const unsigned*)((const char*)(gbase) + (voff)[_i]), (LAS unsigned*)(lds + (bufoff) + ldsw + _i * 8192), 16, 0, 0); } while (0)
; #define PG8_LDA(dst, b, h) do { _Pragma("unroll") for (int m = 0; m < 4; ++m) _Pragma("unroll") for (int k = 0; k < 2; ++k) dst[m][k] = *(const LAS bf16x8*)(lds + PG8_SA(b, h) + aoff + m * 2048 + k * 1024); } while (0)
; #define PG8_LDB(dst, b, h) do { _Pragma("unroll") for (int n = 0; n < 2; ++n) _Pragma("unroll") for (int k = 0; k < 2; ++k) dst[n][k] = *(const LAS bf16x8*)(lds + PG8_SB(b, h) + boff + n * 2048 + k * 1024); } while (0)
; #define PG8_MMA(ai, bj, At, Bt) do { __builtin_amdgcn_s_setprio(1); _Pragma("unroll") for (int m = 0; m < 4; ++m) _Pragma("unroll") for (int n = 0; n < 2; ++n) _Pragma("unroll") for (int k = 0; k < 2; ++k) \
;         acc[ai][bj][m][n] = __builtin_amdgcn_mfma_f32_16x16x32_bf16(Bt[n][k], At[m][k], acc[ai][bj][m][n], 0, 0, 0); __builtin_amdgcn_s_setprio(0); } while (0)
; #define PG8_WAIT_V(n) asm volatile("s_waitcnt vmcnt(" #n ")" ::: "memory")
; #define PG8_WAIT_L(n) asm volatile("s_waitcnt lgkmcnt(" #n ")" ::: "memory")
; #define PG8_BAR __builtin_amdgcn_s_barrier()
; #define PG8_SCHED __builtin_amdgcn_sched_barrier(0)
; template <class Epi>
; __device__ __forceinline__ void gemm_phase(LAS unsigned char* lds, const Gemm g, const StaticOrder& S, const Epi& E) {
;     ...
;             PG8_LDA(At, 0, 1); PG8_STAGE(PG8_SA(0, 0), a2, voffA);
;             PG8_BAR; PG8_WAIT_L(0); PG8_MMA(1, 0, At, B0); PG8_BAR; PG8_SCHED;
;             PG8_STAGE(PG8_SB(0, 1), b2 + hstep, voffB);
;             PG8_WAIT_V(6); PG8_BAR; PG8_MMA(1, 1, At, B1); PG8_BAR;
;             PG8_LDB(B0, 1, 0); PG8_SCHED; PG8_LDA(At, 1, 0); PG8_STAGE(PG8_SA(0, 1), a2 + hstep, voffA);
;             PG8_WAIT_L(8); PG8_BAR; PG8_WAIT_L(0); PG8_MMA(0, 0, At, B0); PG8_BAR; PG8_SCHED;
;             PG8_LDB(B1, 1, 1); PG8_STAGE(PG8_SB(1, 0), b3, voffB);
;             PG8_BAR; PG8_WAIT_L(0); PG8_MMA(0, 1, At, B1); PG8_BAR;
	v_mfma_f32_16x16x32_bf16 v[60:63], v[128:131], v[170:173], v[60:63]
	v_mfma_f32_16x16x32_bf16 v[56:59], v[152:155], v[170:173], v[56:59]
	v_mfma_f32_16x16x32_bf16 v[44:47], v[128:131], v[180:183], v[44:47]
	v_mfma_f32_16x16x32_bf16 v[40:43], v[152:155], v[180:183], v[40:43]
	v_mfma_f32_16x16x32_bf16 v[28:31], v[128:131], v[188:191], v[28:31]
	v_mfma_f32_16x16x32_bf16 v[24:27], v[152:155], v[188:191], v[24:27]
	v_mfma_f32_16x16x32_bf16 v[12:15], v[128:131], v[196:199], v[12:15]
	v_mfma_f32_16x16x32_bf16 v[8:11], v[152:155], v[196:199], v[8:11]
	v_mfma_f32_16x16x32_bf16 v[60:63], v[132:135], v[174:177], v[60:63]
	v_mfma_f32_16x16x32_bf16 v[56:59], v[166:169], v[174:177], v[56:59]
	v_mfma_f32_16x16x32_bf16 v[44:47], v[132:135], v[184:187], v[44:47]
	v_mfma_f32_16x16x32_bf16 v[40:43], v[166:169], v[184:187], v[40:43]
	v_mfma_f32_16x16x32_bf16 v[28:31], v[132:135], v[192:195], v[28:31]
	v_mfma_f32_16x16x32_bf16 v[24:27], v[166:169], v[192:195], v[24:27]
	v_mfma_f32_16x16x32_bf16 v[12:15], v[132:135], v[200:203], v[12:15]
	v_mfma_f32_16x16x32_bf16 v[8:11], v[166:169], v[200:203], v[8:11]
	v_mfma_f32_16x16x32_bf16 v[52:55], v[204:207], v[170:173], v[52:55]
	v_mfma_f32_16x16x32_bf16 v[48:51], v[212:215], v[170:173], v[48:51]
	v_mfma_f32_16x16x32_bf16 v[36:39], v[204:207], v[180:183], v[36:39]
	v_mfma_f32_16x16x32_bf16 v[32:35], v[212:215], v[180:183], v[32:35]
	v_mfma_f32_16x16x32_bf16 v[20:23], v[204:207], v[188:191], v[20:23]
	v_mfma_f32_16x16x32_bf16 v[16:19], v[212:215], v[188:191], v[16:19]
	v_mfma_f32_16x16x32_bf16 v[4:7], v[204:207], v[196:199], v[4:7]
	v_mfma_f32_16x16x32_bf16 v[0:3], v[212:215], v[196:199], v[0:3]
	v_mfma_f32_16x16x32_bf16 v[52:55], v[208:211], v[174:177], v[52:55]
	v_mfma_f32_16x16x32_bf16 v[48:51], v[216:219], v[174:177], v[48:51]
	v_mfma_f32_16x16x32_bf16 v[36:39], v[208:211], v[184:187], v[36:39]
	v_mfma_f32_16x16x32_bf16 v[32:35], v[216:219], v[184:187], v[32:35]
	v_mfma_f32_16x16x32_bf16 v[20:23], v[208:211], v[192:195], v[20:23]
	v_mfma_f32_16x16x32_bf16 v[16:19], v[216:219], v[192:195], v[16:19]
	v_mfma_f32_16x16x32_bf16 v[4:7], v[208:211], v[200:203], v[4:7]
	v_mfma_f32_16x16x32_bf16 v[0:3], v[216:219], v[200:203], v[0:3]
	s_barrier
	s_setprio 0
	s_add_i32 s66, 0, 0x18000
	v_add_u32_e32 v166, s66, v158
	ds_read_b128 v[128:131], v166
	ds_read_b128 v[132:135], v166 offset:1024
	ds_read_b128 v[152:155], v166 offset:2048
	ds_read_b128 v[166:169], v166 offset:3072
	s_add_u32 s18, s18, 0x158000
	s_addc_u32 s19, s19, 0
	s_mov_b32 m0, s33
	v_lshl_add_u64 v[204:205], s[18:19], 0, v[136:137]
	ds_read_b128 v[170:173], v162 offset:32768
	ds_read_b128 v[174:177], v162 offset:33792
	ds_read_b128 v[180:183], v162 offset:34816
	ds_read_b128 v[184:187], v162 offset:35840
	ds_read_b128 v[188:191], v162 offset:36864
	ds_read_b128 v[192:195], v162 offset:37888
	ds_read_b128 v[196:199], v162 offset:38912
	ds_read_b128 v[200:203], v162 offset:39936
	global_load_lds_dwordx4 v[204:205], off
	v_lshl_add_u64 v[204:205], s[18:19], 0, v[140:141]
	s_mov_b32 m0, s34
	s_nop 0
	global_load_lds_dwordx4 v[204:205], off
	s_add_i32 s18, 0, 0x1c000
	v_add_u32_e32 v179, s18, v158
	ds_read_b128 v[204:207], v179
	ds_read_b128 v[208:211], v179 offset:1024
	ds_read_b128 v[212:215], v179 offset:2048
	ds_read_b128 v[216:219], v179 offset:3072
	s_waitcnt lgkmcnt(0)
	s_waitcnt vmcnt(8)
	s_setprio 1
	s_barrier
	v_mfma_f32_16x16x32_bf16 v[124:127], v[128:131], v[170:173], v[124:127]
	v_mfma_f32_16x16x32_bf16 v[120:123], v[152:155], v[170:173], v[120:123]
	v_mfma_f32_16x16x32_bf16 v[108:111], v[128:131], v[180:183], v[108:111]
	v_mfma_f32_16x16x32_bf16 v[104:107], v[152:155], v[180:183], v[104:107]
	v_mfma_f32_16x16x32_bf16 v[92:95], v[128:131], v[188:191], v[92:95]
	v_mfma_f32_16x16x32_bf16 v[88:91], v[152:155], v[188:191], v[88:91]
	v_mfma_f32_16x16x32_bf16 v[76:79], v[128:131], v[196:199], v[76:79]
	v_mfma_f32_16x16x32_bf16 v[72:75], v[152:155], v[196:199], v[72:75]
	v_mfma_f32_16x16x32_bf16 v[124:127], v[132:135], v[174:177], v[124:127]
	v_mfma_f32_16x16x32_bf16 v[120:123], v[166:169], v[174:177], v[120:123]
	v_mfma_f32_16x16x32_bf16 v[108:111], v[132:135], v[184:187], v[108:111]
	v_mfma_f32_16x16x32_bf16 v[104:107], v[166:169], v[184:187], v[104:107]
	v_mfma_f32_16x16x32_bf16 v[92:95], v[132:135], v[192:195], v[92:95]
	v_mfma_f32_16x16x32_bf16 v[88:91], v[166:169], v[192:195], v[88:91]
	v_mfma_f32_16x16x32_bf16 v[76:79], v[132:135], v[200:203], v[76:79]
	v_mfma_f32_16x16x32_bf16 v[72:75], v[166:169], v[200:203], v[72:75]
	v_mfma_f32_16x16x32_bf16 v[116:119], v[204:207], v[170:173], v[116:119]
	v_mfma_f32_16x16x32_bf16 v[112:115], v[212:215], v[170:173], v[112:115]
	v_mfma_f32_16x16x32_bf16 v[100:103], v[204:207], v[180:183], v[100:103]
	v_mfma_f32_16x16x32_bf16 v[96:99], v[212:215], v[180:183], v[96:99]
	v_mfma_f32_16x16x32_bf16 v[84:87], v[204:207], v[188:191], v[84:87]
	v_mfma_f32_16x16x32_bf16 v[80:83], v[212:215], v[188:191], v[80:83]
	v_mfma_f32_16x16x32_bf16 v[68:71], v[204:207], v[196:199], v[68:71]
	v_mfma_f32_16x16x32_bf16 v[64:67], v[212:215], v[196:199], v[64:67]
	v_mfma_f32_16x16x32_bf16 v[116:119], v[208:211], v[174:177], v[116:119]
	v_mfma_f32_16x16x32_bf16 v[112:115], v[216:219], v[174:177], v[112:115]
	v_mfma_f32_16x16x32_bf16 v[100:103], v[208:211], v[184:187], v[100:103]
	v_mfma_f32_16x16x32_bf16 v[96:99], v[216:219], v[184:187], v[96:99]
	v_mfma_f32_16x16x32_bf16 v[84:87], v[208:211], v[192:195], v[84:87]
	v_mfma_f32_16x16x32_bf16 v[80:83], v[216:219], v[192:195], v[80:83]
	v_mfma_f32_16x16x32_bf16 v[68:71], v[208:211], v[200:203], v[68:71]
	v_mfma_f32_16x16x32_bf16 v[64:67], v[216:219], v[200:203], v[64:67]
	s_barrier
; #define PG8_STAGE(bufoff, gbase, voff) do { _Pragma("unroll") for (int _i = 0; _i < 2; ++_i) \
;         __builtin_amdgcn_global_load_lds((const unsigned*)((const char*)(gbase) + (voff)[_i]), (LAS unsigned*)(lds + (bufoff) + ldsw + _i * 8192), 16, 0, 0); } while (0)
; #define PG8_LDA(dst, b, h) do { _Pragma("unroll") for (int m = 0; m < 4; ++m) _Pragma("unroll") for (int k = 0; k < 2; ++k) dst[m][k] = *(const LAS bf16x8*)(lds + PG8_SA(b, h) + aoff + m * 2048 + k * 1024); } while (0)
; #define PG8_LDB(dst, b, h) do { _Pragma("unroll") for (int n = 0; n < 2; ++n) _Pragma("unroll") for (int k = 0; k < 2; ++k) dst[n][k] = *(const LAS bf16x8*)(lds + PG8_SB(b, h) + boff + n * 2048 + k * 1024); } while (0)
; #define PG8_MMA(ai, bj, At, Bt) do { __builtin_amdgcn_s_setprio(1); _Pragma("unroll") for (int m = 0; m < 4; ++m) _Pragma("unroll") for (int n = 0; n < 2; ++n) _Pragma("unroll") for (int k = 0; k < 2; ++k) \
;         acc[ai][bj][m][n] = __builtin_amdgcn_mfma_f32_16x16x32_bf16(Bt[n][k], At[m][k], acc[ai][bj][m][n], 0, 0, 0); __builtin_amdgcn_s_setprio(0); } while (0)
; #define PG8_WAIT_V(n) asm volatile("s_waitcnt vmcnt(" #n ")" ::: "memory")
; #define PG8_WAIT_L(n) asm volatile("s_waitcnt lgkmcnt(" #n ")" ::: "memory")
; #define PG8_BAR __builtin_amdgcn_s_barrier()
; #define PG8_SCHED __builtin_amdgcn_sched_barrier(0)
; template <class Epi>
; __device__ __forceinline__ void gemm_phase(LAS unsigned char* lds, const Gemm g, const StaticOrder& S, const Epi& E) {
;     ...
;             PG8_LDB(B0, 1, 0); PG8_SCHED; PG8_LDA(At, 1, 0); PG8_STAGE(PG8_SA(0, 1), a2 + hstep, voffA);
;             PG8_WAIT_L(8); PG8_BAR; PG8_WAIT_L(0); PG8_MMA(0, 0, At, B0); PG8_BAR; PG8_SCHED;
;             PG8_LDB(B1, 1, 1); PG8_STAGE(PG8_SB(1, 0), b3, voffB);
;             PG8_BAR; PG8_WAIT_L(0); PG8_MMA(0, 1, At, B1); PG8_BAR;
;             PG8_LDA(At, 1, 1); PG8_STAGE(PG8_SA(1, 0), a3, voffA);
;             PG8_BAR; PG8_WAIT_L(0); PG8_MMA(1, 0, At, B0); PG8_BAR; PG8_SCHED;
;             PG8_STAGE(PG8_SB(1, 1), b3 + hstep, voffB);
;             PG8_WAIT_V(6); PG8_BAR; PG8_MMA(1, 1, At, B1); PG8_BAR;
;         }
	s_setprio 0
	s_add_i32 s19, s66, s21
	v_lshl_add_u64 v[156:157], v[156:157], 0, s[12:13]
	s_mov_b32 m0, s19
	s_nop 0
	global_load_lds_dwordx4 v[156:157], off
	v_lshl_add_u64 v[156:157], v[220:221], 0, s[12:13]
	s_add_i32 m0, s19, 0x2000
	s_nop 0
	global_load_lds_dwordx4 v[156:157], off
	s_mov_b32 m0, s38
	v_lshl_add_u64 v[156:157], v[222:223], 0, s[12:13]
	ds_read_b128 v[170:173], v162 offset:49152
	ds_read_b128 v[174:177], v162 offset:50176
	ds_read_b128 v[180:183], v162 offset:51200
	ds_read_b128 v[184:187], v162 offset:52224
	ds_read_b128 v[188:191], v162 offset:53248
	ds_read_b128 v[192:195], v162 offset:54272
	ds_read_b128 v[196:199], v162 offset:55296
	ds_read_b128 v[200:203], v162 offset:56320
	global_load_lds_dwordx4 v[156:157], off
	v_lshl_add_u64 v[156:157], v[224:225], 0, s[12:13]
	s_mov_b32 m0, s39
	s_nop 0
	global_load_lds_dwordx4 v[156:157], off
	s_add_u32 s16, s16, 0x158080
	s_addc_u32 s17, s17, 0
	s_add_i32 s18, s18, s21
	v_lshl_add_u64 v[252:253], s[16:17], 0, v[138:139]
	s_mov_b32 m0, s18
	s_nop 0
	global_load_lds_dwordx4 v[252:253], off
	v_lshl_add_u64 v[252:253], s[16:17], 0, v[142:143]
	s_add_i32 m0, s18, 0x2000
	s_nop 0
	global_load_lds_dwordx4 v[252:253], off
	s_waitcnt lgkmcnt(0)
	s_waitcnt vmcnt(8)
	s_setprio 1
	s_barrier
	v_mfma_f32_16x16x32_bf16 v[60:63], v[128:131], v[170:173], v[60:63]
	v_mfma_f32_16x16x32_bf16 v[56:59], v[152:155], v[170:173], v[56:59]
	v_mfma_f32_16x16x32_bf16 v[44:47], v[128:131], v[180:183], v[44:47]
	v_mfma_f32_16x16x32_bf16 v[40:43], v[152:155], v[180:183], v[40:43]
	v_mfma_f32_16x16x32_bf16 v[28:31], v[128:131], v[188:191], v[28:31]
	v_mfma_f32_16x16x32_bf16 v[24:27], v[152:155], v[188:191], v[24:27]
	v_mfma_f32_16x16x32_bf16 v[12:15], v[128:131], v[196:199], v[12:15]
	v_mfma_f32_16x16x32_bf16 v[8:11], v[152:155], v[196:199], v[8:11]
	v_mfma_f32_16x16x32_bf16 v[60:63], v[132:135], v[174:177], v[60:63]
	v_mfma_f32_16x16x32_bf16 v[56:59], v[166:169], v[174:177], v[56:59]
	v_mfma_f32_16x16x32_bf16 v[44:47], v[132:135], v[184:187], v[44:47]
	v_mfma_f32_16x16x32_bf16 v[40:43], v[166:169], v[184:187], v[40:43]
	v_mfma_f32_16x16x32_bf16 v[28:31], v[132:135], v[192:195], v[28:31]
	v_mfma_f32_16x16x32_bf16 v[24:27], v[166:169], v[192:195], v[24:27]
	v_mfma_f32_16x16x32_bf16 v[12:15], v[132:135], v[200:203], v[12:15]
	v_mfma_f32_16x16x32_bf16 v[8:11], v[166:169], v[200:203], v[8:11]
	v_mfma_f32_16x16x32_bf16 v[52:55], v[204:207], v[170:173], v[52:55]
	v_mfma_f32_16x16x32_bf16 v[48:51], v[212:215], v[170:173], v[48:51]
	v_mfma_f32_16x16x32_bf16 v[36:39], v[204:207], v[180:183], v[36:39]
	v_mfma_f32_16x16x32_bf16 v[32:35], v[212:215], v[180:183], v[32:35]
	v_mfma_f32_16x16x32_bf16 v[20:23], v[204:207], v[188:191], v[20:23]
	v_mfma_f32_16x16x32_bf16 v[16:19], v[212:215], v[188:191], v[16:19]
	v_mfma_f32_16x16x32_bf16 v[4:7], v[204:207], v[196:199], v[4:7]
	v_mfma_f32_16x16x32_bf16 v[0:3], v[212:215], v[196:199], v[0:3]
	v_mfma_f32_16x16x32_bf16 v[52:55], v[208:211], v[174:177], v[52:55]
	v_mfma_f32_16x16x32_bf16 v[48:51], v[216:219], v[174:177], v[48:51]
	v_mfma_f32_16x16x32_bf16 v[36:39], v[208:211], v[184:187], v[36:39]
	v_mfma_f32_16x16x32_bf16 v[32:35], v[216:219], v[184:187], v[32:35]
	v_mfma_f32_16x16x32_bf16 v[20:23], v[208:211], v[192:195], v[20:23]
	v_mfma_f32_16x16x32_bf16 v[16:19], v[216:219], v[192:195], v[16:19]
	v_mfma_f32_16x16x32_bf16 v[4:7], v[208:211], v[200:203], v[4:7]
	v_mfma_f32_16x16x32_bf16 v[0:3], v[216:219], v[200:203], v[0:3]
	s_barrier
	s_setprio 0
	s_add_i32 s65, s65, 2
	s_add_u32 s14, s14, 0x100
	s_addc_u32 s15, s15, 0
	s_add_u32 s63, s63, 0x100
	s_addc_u32 s64, s64, 0
	s_cmpk_gt_u32 s65, 0x53
	s_cbranch_scc0 .LBB0_364
; __device__ __forceinline__ float bflo(unsigned w) { return __uint_as_float(w << 16); }
; __device__ __forceinline__ float bfhi(unsigned w) { return __uint_as_float(w & 0xffff0000u); }
; #define ER_LOAD(g_, set_) do { const size_t off_ = (size_t)(row0 + ((g_) >> 2) * HALF + ((g_) & 3) * 16) * DM + col0; \
;         hv[set_][0] = *(const u32x4*)(HB + off_); hv[set_][1] = *(const u32x4*)(HB + off_ + HALF); } while (0)
;     __device__ __forceinline__ void operator()(const f32x4 (&acc)[2][2][4][2], const Unit& u, int wr, int wc, int fr, int fq, const Pre&) const {
;         const int row0 = ROW_X + u.pm * BM + wr * 64 + fr, col0 = u.pn * BM + wc * 32 + 8 * fq;
;         u32x4 hv[2][2]; float sprev = 0.f;
;     ...
;         ER_LOAD(0, 0);
; #pragma unroll
;         for (int g = 0; g < 8; ++g) { const int ai = g >> 2, m = g & 3; const int r = row0 + ai * HALF + m * 16; const size_t off = (size_t)r * DM + col0; float s = 0.f;
;             if (g + 1 < 8) ER_LOAD(g + 1, (g + 1) & 1);
; #pragma unroll
;             for (int bj = 0; bj < 2; ++bj) { const u32x4 w = hv[g & 1][bj];
;                 const f32x4 h0 = {bflo(w.x), bfhi(w.x), bflo(w.y), bfhi(w.y)}, h1 = {bflo(w.z), bfhi(w.z), bflo(w.w), bfhi(w.w)};
;                 const f32x4 o0 = h0 + acc[ai][bj][m][0] * alpha, o1 = h1 + acc[ai][bj][m][1] * alpha;
;                 if (FINAL) { float* op = OUT + (size_t)(r - ROW_X) * DM + col0 + bj * HALF; *(f32x4*)op = o0; *(f32x4*)(op + 4) = o1; }
;                 else { u32x4 q; q.x = cvtpk(o0[0], o0[1]); q.y = cvtpk(o0[2], o0[3]); q.z = cvtpk(o1[0], o1[1]); q.w = cvtpk(o1[2], o1[3]); *(u32x4*)(HB + off + bj * HALF) = q;
;                        s += ((o0[0] * o0[0] + o0[1] * o0[1]) + (o0[2] * o0[2] + o0[3] * o0[3])) + ((o1[0] * o1[0] + o1[1] * o1[1]) + (o1[2] * o1[2] + o1[3] * o1[3])); } }
;             if (!FINAL) { if (g > 0) { float t = sprev; t += __shfl_xor(t, 16); t += __shfl_xor(t, 32);
;                     if (fq == 0) __hip_atomic_fetch_add(ssq_out + row0 + ((g - 1) >> 2) * HALF + ((g - 1) & 3) * 16, t, __ATOMIC_RELAXED, __HIP_MEMORY_SCOPE_AGENT); }
;                 sprev = s; } }
;     ...
;         if (!FINAL) { float t = sprev; t += __shfl_xor(t, 16); t += __shfl_xor(t, 32);
;             if (fq == 0) __hip_atomic_fetch_add(ssq_out + row0 + HALF + 48, t, __ATOMIC_RELAXED, __HIP_MEMORY_SCOPE_AGENT); }
	v_lshl_add_u32 v154, s61, 8, v159
	v_lshl_or_b32 v152, s62, 8, v160
	v_ashrrev_i32_e32 v155, 31, v154
	v_ashrrev_i32_e32 v153, 31, v152
	v_lshlrev_b64 v[128:129], 12, v[154:155]
	v_lshl_add_u64 v[128:129], s[8:9], 0, v[128:129]
	v_lshlrev_b64 v[130:131], 1, v[152:153]
	v_lshl_add_u64 v[184:185], v[128:129], 0, v[130:131]
	v_or_b32_e32 v128, 16, v154
	v_ashrrev_i32_e32 v129, 31, v128
	global_load_dwordx4 v[166:169], v[184:185], off
	global_load_dwordx4 v[170:173], v[184:185], off offset:256
	v_lshlrev_b64 v[128:129], 12, v[128:129]
	v_lshl_add_u64 v[128:129], s[8:9], 0, v[128:129]
	v_lshl_add_u64 v[186:187], v[128:129], 0, v[130:131]
	global_load_dwordx4 v[174:177], v[186:187], off
	global_load_dwordx4 v[180:183], v[186:187], off offset:256
	v_or_b32_e32 v128, 32, v154
	v_ashrrev_i32_e32 v129, 31, v128
	v_lshlrev_b64 v[128:129], 12, v[128:129]
	v_lshl_add_u64 v[128:129], s[8:9], 0, v[128:129]
	v_lshl_add_u64 v[156:157], v[128:129], 0, v[130:131]
	global_load_dwordx4 v[132:135], v[156:157], off
	global_load_dwordx4 v[128:131], v[156:157], off offset:256
	s_waitcnt vmcnt(0)
	v_lshlrev_b32_e32 v188, 16, v166
	v_and_b32_e32 v189, 0xffff0000, v166
	v_lshlrev_b32_e32 v166, 16, v167
	v_and_b32_e32 v167, 0xffff0000, v167
	v_lshlrev_b32_e32 v190, 16, v168
	v_and_b32_e32 v191, 0xffff0000, v168
	v_lshlrev_b32_e32 v168, 16, v169
	v_and_b32_e32 v169, 0xffff0000, v169
	v_lshlrev_b32_e32 v192, 16, v170
	v_and_b32_e32 v193, 0xffff0000, v170
	v_lshlrev_b32_e32 v170, 16, v171
	v_and_b32_e32 v171, 0xffff0000, v171
	v_lshlrev_b32_e32 v194, 16, v172
	v_and_b32_e32 v195, 0xffff0000, v172
	v_lshlrev_b32_e32 v172, 16, v173
	v_and_b32_e32 v173, 0xffff0000, v173
	v_pk_fma_f32 v[126:127], v[126:127], 0.5, v[166:167] op_sel_hi:[1,0,1]
	v_pk_fma_f32 v[124:125], v[124:125], 0.5, v[188:189] op_sel_hi:[1,0,1]
	v_pk_fma_f32 v[122:123], v[122:123], 0.5, v[168:169] op_sel_hi:[1,0,1]
	v_pk_fma_f32 v[166:167], v[120:121], 0.5, v[190:191] op_sel_hi:[1,0,1]
	v_pk_fma_f32 v[168:169], v[118:119], 0.5, v[170:171] op_sel_hi:[1,0,1]
	v_pk_fma_f32 v[170:171], v[116:117], 0.5, v[192:193] op_sel_hi:[1,0,1]
	v_pk_fma_f32 v[172:173], v[114:115], 0.5, v[172:173] op_sel_hi:[1,0,1]
	v_pk_fma_f32 v[188:189], v[112:113], 0.5, v[194:195] op_sel_hi:[1,0,1]
	v_cvt_pk_bf16_f32 v114, v124, v125
	v_cvt_pk_bf16_f32 v115, v126, v127
	v_cvt_pk_bf16_f32 v116, v166, v167
	v_cvt_pk_bf16_f32 v117, v122, v123
	v_mul_f32_e32 v125, v125, v125
	v_mul_f32_e32 v127, v127, v127
	v_mul_f32_e32 v167, v167, v167
	v_mul_f32_e32 v123, v123, v123
	v_cvt_pk_bf16_f32 v118, v170, v171
	v_cvt_pk_bf16_f32 v119, v168, v169
	v_cvt_pk_bf16_f32 v121, v172, v173
	v_mul_f32_e32 v171, v171, v171
	v_mul_f32_e32 v169, v169, v169
	v_mul_f32_e32 v179, v189, v189
	v_mul_f32_e32 v173, v173, v173
	v_lshlrev_b32_e32 v112, 16, v174
	v_and_b32_e32 v113, 0xffff0000, v174
	v_lshlrev_b32_e32 v190, 16, v176
	v_and_b32_e32 v191, 0xffff0000, v176
	v_lshlrev_b32_e32 v176, 16, v177
	v_and_b32_e32 v177, 0xffff0000, v177
	v_fmac_f32_e32 v125, v124, v124
	v_fmac_f32_e32 v127, v126, v126
	v_fmac_f32_e32 v167, v166, v166
	v_fmac_f32_e32 v123, v122, v122
	v_fmac_f32_e32 v171, v170, v170
	v_fmac_f32_e32 v169, v168, v168
	v_fmac_f32_e32 v179, v188, v188
	v_fmac_f32_e32 v173, v172, v172
	v_lshlrev_b32_e32 v174, 16, v175
	v_and_b32_e32 v175, 0xffff0000, v175
	v_pk_fma_f32 v[112:113], v[108:109], 0.5, v[112:113] op_sel_hi:[1,0,1]
	v_pk_fma_f32 v[108:109], v[106:107], 0.5, v[176:177] op_sel_hi:[1,0,1]
	global_store_dwordx4 v[184:185], v[114:117], off
	v_add_f32_e32 v106, v125, v127
	v_add_f32_e32 v107, v167, v123
	v_add_f32_e32 v114, v171, v169
	v_add_f32_e32 v115, v179, v173
	v_pk_fma_f32 v[110:111], v[110:111], 0.5, v[174:175] op_sel_hi:[1,0,1]
	v_add_f32_e32 v106, v106, v107
	v_add_f32_e32 v107, v114, v115
	v_pk_fma_f32 v[114:115], v[104:105], 0.5, v[190:191] op_sel_hi:[1,0,1]
	v_add_f32_e32 v125, v106, v107
	v_cvt_pk_bf16_f32 v104, v112, v113
	v_cvt_pk_bf16_f32 v105, v110, v111
	v_cvt_pk_bf16_f32 v106, v114, v115
	v_cvt_pk_bf16_f32 v107, v108, v109
	v_cvt_pk_bf16_f32 v120, v188, v189
	global_store_dwordx4 v[186:187], v[104:107], off
	global_store_dwordx4 v[184:185], v[118:121], off offset:256
	v_lshlrev_b32_e32 v122, 16, v182
	v_lshlrev_b32_e32 v104, 16, v180
	v_and_b32_e32 v105, 0xffff0000, v180
	v_pk_fma_f32 v[118:119], v[100:101], 0.5, v[104:105] op_sel_hi:[1,0,1]
	v_and_b32_e32 v101, 64, v165
	v_xor_b32_e32 v100, 16, v165
	v_add_u32_e32 v101, 64, v101
	v_cmp_lt_i32_e32 vcc, v100, v101
	v_and_b32_e32 v123, 0xffff0000, v182
	v_pk_fma_f32 v[122:123], v[96:97], 0.5, v[122:123] op_sel_hi:[1,0,1]
	v_cndmask_b32_e32 v100, v165, v100, vcc
	v_lshlrev_b32_e32 v124, 2, v100
	ds_bpermute_b32 v100, v124, v125
	v_xor_b32_e32 v97, 32, v165
	v_cmp_lt_i32_e32 vcc, v97, v101
	v_lshlrev_b32_e32 v106, 16, v181
	v_and_b32_e32 v107, 0xffff0000, v181
	v_cndmask_b32_e32 v97, v165, v97, vcc
	s_waitcnt lgkmcnt(0)
	v_add_f32_e32 v96, v125, v100
	v_lshlrev_b32_e32 v125, 2, v97
	ds_bpermute_b32 v97, v125, v96
	v_lshlrev_b32_e32 v120, 16, v183
	v_and_b32_e32 v121, 0xffff0000, v183
	v_pk_fma_f32 v[116:117], v[102:103], 0.5, v[106:107] op_sel_hi:[1,0,1]
	v_pk_fma_f32 v[120:121], v[98:99], 0.5, v[120:121] op_sel_hi:[1,0,1]
	v_cvt_pk_bf16_f32 v98, v118, v119
	v_cvt_pk_bf16_f32 v99, v116, v117
	v_cvt_pk_bf16_f32 v100, v122, v123
	v_cvt_pk_bf16_f32 v101, v120, v121
	v_lshl_add_u64 v[104:105], v[154:155], 2, s[10:11]
	global_store_dwordx4 v[186:187], v[98:101], off offset:256
	s_and_saveexec_b64 s[14:15], s[2:3]
	s_cbranch_execz .LBB0_367
	s_waitcnt lgkmcnt(0)
	v_add_f32_e32 v96, v96, v97
	global_atomic_add_f32 v[104:105], v96, off

; #define PG8_STAGE(bufoff, gbase, voff) do { _Pragma("unroll") for (int _i = 0; _i < 2; ++_i) \
;         __builtin_amdgcn_global_load_lds((const unsigned*)((const char*)(gbase) + (voff)[_i]), (LAS unsigned*)(lds + (bufoff) + ldsw + _i * 8192), 16, 0, 0); } while (0)
; #define PG8_WAIT_V(n) asm volatile("s_waitcnt vmcnt(" #n ")" ::: "memory")
; #define PG8_BAR __builtin_amdgcn_s_barrier()
; template <class Epi>
; __device__ __forceinline__ void gemm_phase(LAS unsigned char* lds, const Gemm g, const StaticOrder& S, const Epi& E) {
;     const int tid = threadIdx.x, wid = __builtin_amdgcn_readfirstlane(tid >> 6), lane = tid & 63, wr = wid >> 2, wc = wid & 3, fr = lane & 15, fq = lane >> 4;
;     const int K = g.K, nt = K / BK;
;     unsigned voffA[2], voffB[2];
; #pragma unroll
;     for (int i = 0; i < 2; ++i) { int R, C; stage_rc(tid * 16 + i * 8192, R, C); const int Rb = Epi::PERM ? ((R & ~31) + perm32(R & 31)) : R;
;         voffA[i] = (unsigned)(R * K + C) * 2u; voffB[i] = (unsigned)(Rb * K + C) * 2u; }
;     const size_t kstep = (size_t)(BK * 2);
;     const size_t hstep = (size_t)HALF * K * 2;
;     const size_t tstep = 2 * hstep;
;     const unsigned ldsw = (unsigned)wid * 1024u;
;     const int aoff = lds_byte(wr * 64 + fr, fq * 8), boff = lds_byte(wc * 32 + fr, fq * 8);
;     ...
;     Unit cur, nxt; int ui = 0;
;     if (!S.next(0, cur)) return;
;     f32x4 acc[2][2][4][2];
; #pragma unroll
;     for (int a = 0; a < 2; ++a)
; #pragma unroll
;         for (int b = 0; b < 2; ++b)
; #pragma unroll
;             for (int m = 0; m < 4; ++m)
; #pragma unroll
;                 for (int n = 0; n < 2; ++n) acc[a][b][m][n] = (f32x4){0.f, 0.f, 0.f, 0.f};
;     bf16x8 At[4][2], B0[2][2], B1[2][2];
;     const char* cA = (const char*)g.A + (size_t)cur.pm * tstep; const char* cB = (const char*)g.Bt + (size_t)cur.pn * tstep;
;     typename Epi::Pre pre = E.pre(cur, wr, fr);
;     PG8_STAGE(PG8_SB(0, 0), cB, voffB); PG8_STAGE(PG8_SA(0, 0), cA, voffA); PG8_STAGE(PG8_SB(0, 1), cB + hstep, voffB); PG8_STAGE(PG8_SA(0, 1), cA + hstep, voffA);
;     if (wr == 1) PG8_BAR;
;     PG8_WAIT_V(4); PG8_BAR;
;     PG8_STAGE(PG8_SB(1, 0), cB + kstep, voffB); PG8_STAGE(PG8_SA(1, 0), cA + kstep, voffA); PG8_STAGE(PG8_SB(1, 1), cB + hstep + kstep, voffB);
;     PG8_WAIT_V(6); PG8_BAR;
.LBB0_682:
	s_lshl_b32 s1, s2, 13
	s_lshl_b32 s2, s3, 5
	s_mov_b64 s[34:35], 0x80
	s_and_b32 s5, s2, 0x60
	s_add_i32 m0, s74, 0x18000
	v_lshl_add_u64 v[6:7], v[6:7], 0, s[34:35]
	s_lshl_b32 s10, s5, 7
	s_waitcnt vmcnt(2)
	s_barrier
	global_load_lds_dwordx4 v[6:7], off
	v_lshl_add_u64 v[4:5], v[4:5], 0, s[34:35]
	s_add_i32 m0, s74, 0x1a000
	s_add_i32 s79, s74, 0x8000
	s_add_i32 s80, s74, 0xa000
	global_load_lds_dwordx4 v[4:5], off
	v_lshl_add_u64 v[2:3], v[2:3], 0, s[34:35]
	s_mov_b32 m0, s79
	s_add_u32 s2, s8, 0x80080
	global_load_lds_dwordx4 v[2:3], off
	v_lshl_add_u64 v[0:1], v[0:1], 0, s[34:35]
	s_mov_b32 m0, s80
	s_addc_u32 s3, s9, 0
	global_load_lds_dwordx4 v[0:1], off
	s_add_i32 m0, s74, 0x1c000
	v_lshl_add_u64 v[0:1], s[2:3], 0, v[130:131]
	global_load_lds_dwordx4 v[0:1], off
	v_lshl_add_u64 v[0:1], s[2:3], 0, v[134:135]
	s_add_i32 m0, s74, 0x1e000
	s_movk_i32 s2, 0x3c0
	global_load_lds_dwordx4 v[0:1], off
	v_lshlrev_b32_e32 v0, 6, v13
	v_lshlrev_b32_e32 v1, 1, v11
	v_lshlrev_b32_e32 v2, 2, v13
	v_and_or_b32 v0, v0, s2, v1
	v_and_b32_e32 v2, 32, v2
	v_bitop3_b32 v0, v0, s1, v2 bitop3:0xde
	v_lshlrev_b32_e32 v2, 6, v178
	v_and_or_b32 v1, v2, s2, v1
	v_lshlrev_b32_e32 v2, 2, v178
	v_and_b32_e32 v2, 32, v2
	v_bitop3_b32 v165, s10, v1, v2 bitop3:0xf6
	v_lshlrev_b32_e32 v1, 9, v178
	v_and_b32_e32 v1, 0x70000, v1
	v_lshlrev_b32_e32 v2, 12, v10
	v_or3_b32 v1, v8, v1, v2
	v_add_u32_e32 v140, v1, v9
	v_lshlrev_b32_e32 v1, 5, v12
	s_waitcnt vmcnt(6)
	v_and_b32_e32 v1, 0xf0000, v1
	v_or3_b32 v1, v8, v1, v2
	s_add_i32 s84, 0, 0x10000
	s_add_i32 s85, 0, 0x14000
	s_ashr_i32 s81, s54, 31
	s_mov_b32 s82, s54
	s_ashr_i32 s83, s28, 31
	v_or_b32_e32 v166, s5, v11
	v_mov_b32_e32 v141, v139
	v_add_u32_e32 v142, v1, v9
	v_mov_b32_e32 v143, v139
	v_mov_b64_e32 v[144:145], 0x800
	v_mov_b64_e32 v[146:147], 0x7ff
	v_add_u32_e32 v167, s84, v165
	v_add_u32_e32 v168, 0, v0
	v_add_u32_e32 v169, s85, v165
	v_mov_b32_e32 v170, 0x358637bd
	s_mov_b32 s86, 0x800000
	s_mov_b32 s87, 0x3f317217
	s_mov_b32 s88, 0x7f800000
	s_mov_b64 s[38:39], 0x40000
	s_mov_b64 s[42:43], 0x48000
	s_mov_b64 s[56:57], 0x50000
	s_mov_b64 s[58:59], 0x58000
	v_mov_b32_e32 v171, 0x41b17218
	s_barrier
	s_branch .LBB0_684

; #define PG8_STAGE(bufoff, gbase, voff) do { _Pragma("unroll") for (int _i = 0; _i < 2; ++_i) \
;         __builtin_amdgcn_global_load_lds((const unsigned*)((const char*)(gbase) + (voff)[_i]), (LAS unsigned*)(lds + (bufoff) + ldsw + _i * 8192), 16, 0, 0); } while (0)
; #define PG8_LDA(dst, b, h) do { _Pragma("unroll") for (int m = 0; m < 4; ++m) _Pragma("unroll") for (int k = 0; k < 2; ++k) dst[m][k] = *(const LAS bf16x8*)(lds + PG8_SA(b, h) + aoff + m * 2048 + k * 1024); } while (0)
; #define PG8_LDB(dst, b, h) do { _Pragma("unroll") for (int n = 0; n < 2; ++n) _Pragma("unroll") for (int k = 0; k < 2; ++k) dst[n][k] = *(const LAS bf16x8*)(lds + PG8_SB(b, h) + boff + n * 2048 + k * 1024); } while (0)
; #define PG8_MMA(ai, bj, At, Bt) do { __builtin_amdgcn_s_setprio(1); _Pragma("unroll") for (int m = 0; m < 4; ++m) _Pragma("unroll") for (int n = 0; n < 2; ++n) _Pragma("unroll") for (int k = 0; k < 2; ++k) \
;         acc[ai][bj][m][n] = __builtin_amdgcn_mfma_f32_16x16x32_bf16(Bt[n][k], At[m][k], acc[ai][bj][m][n], 0, 0, 0); __builtin_amdgcn_s_setprio(0); } while (0)
; #define PG8_WAIT_V(n) asm volatile("s_waitcnt vmcnt(" #n ")" ::: "memory")
; #define PG8_WAIT_L(n) asm volatile("s_waitcnt lgkmcnt(" #n ")" ::: "memory")
; #define PG8_BAR __builtin_amdgcn_s_barrier()
; #define PG8_SCHED __builtin_amdgcn_sched_barrier(0)
; template <class Epi>
; __device__ __forceinline__ void gemm_phase(LAS unsigned char* lds, const Gemm g, const StaticOrder& S, const Epi& E) {
;     ...
;             const char* a2 = last ? nA : cA + (size_t)(t + 2) * kstep; const char* b2 = last ? nB : cB + (size_t)(t + 2) * kstep;
;             const char* a3 = a2 + kstep; const char* b3 = b2 + kstep;
;             PG8_LDB(B0, 0, 0); PG8_SCHED; PG8_LDA(At, 0, 0); PG8_STAGE(PG8_SA(1, 1), a1 + hstep, voffA);
;             PG8_WAIT_L(8); PG8_BAR; PG8_WAIT_L(0); PG8_MMA(0, 0, At, B0); PG8_BAR; PG8_SCHED;
;             PG8_LDB(B1, 0, 1); PG8_STAGE(PG8_SB(0, 0), b2, voffB);
;             PG8_BAR; PG8_WAIT_L(0); PG8_MMA(0, 1, At, B1); PG8_BAR;
;             PG8_LDA(At, 0, 1); PG8_STAGE(PG8_SA(0, 0), a2, voffA);
;             PG8_BAR; PG8_WAIT_L(0); PG8_MMA(1, 0, At, B0); PG8_BAR; PG8_SCHED;
;             PG8_STAGE(PG8_SB(0, 1), b2 + hstep, voffB);
;             PG8_WAIT_V(6); PG8_BAR; PG8_MMA(1, 1, At, B1); PG8_BAR;
.LBB0_691:
	ds_read_b128 v[150:153], v167
	ds_read_b128 v[154:157], v167 offset:1024
	ds_read_b128 v[158:161], v167 offset:2048
	ds_read_b128 v[180:183], v167 offset:3072
	s_add_u32 s8, s6, 0xfff80080
	s_addc_u32 s9, s7, -1
	s_cmp_eq_u32 s63, 28
	s_cselect_b32 s11, s1, s9
	s_cselect_b32 s10, s5, s8
	s_cselect_b32 s9, s12, s61
	s_cselect_b32 s8, s13, s33
	v_lshl_add_u64 v[162:163], s[6:7], 0, v[140:141]
	s_add_i32 m0, s74, 0xc000
	ds_read_b128 v[184:187], v168
	ds_read_b128 v[188:191], v168 offset:1024
	ds_read_b128 v[192:195], v168 offset:2048
	ds_read_b128 v[196:199], v168 offset:3072
	ds_read_b128 v[200:203], v168 offset:4096
	ds_read_b128 v[204:207], v168 offset:5120
	ds_read_b128 v[208:211], v168 offset:6144
	ds_read_b128 v[212:215], v168 offset:7168
	global_load_lds_dwordx4 v[162:163], off
	v_lshl_add_u64 v[162:163], s[6:7], 0, v[142:143]
	s_add_i32 m0, s74, 0xe000
	s_nop 0
	global_load_lds_dwordx4 v[162:163], off
	ds_read_b128 v[216:219], v169
	ds_read_b128 v[220:223], v169 offset:1024
	ds_read_b128 v[224:227], v169 offset:2048
	ds_read_b128 v[228:231], v169 offset:3072
	s_waitcnt lgkmcnt(0)
	s_waitcnt vmcnt(8)
	s_setprio 1
	s_barrier
	v_mfma_f32_16x16x32_bf16 v[124:127], v[150:153], v[184:187], v[124:127]
	v_mfma_f32_16x16x32_bf16 v[120:123], v[158:161], v[184:187], v[120:123]
	v_mfma_f32_16x16x32_bf16 v[108:111], v[150:153], v[192:195], v[108:111]
	v_mfma_f32_16x16x32_bf16 v[104:107], v[158:161], v[192:195], v[104:107]
	v_mfma_f32_16x16x32_bf16 v[92:95], v[150:153], v[200:203], v[92:95]
	v_mfma_f32_16x16x32_bf16 v[88:91], v[158:161], v[200:203], v[88:91]
	v_mfma_f32_16x16x32_bf16 v[76:79], v[150:153], v[208:211], v[76:79]
	v_mfma_f32_16x16x32_bf16 v[72:75], v[158:161], v[208:211], v[72:75]
	v_mfma_f32_16x16x32_bf16 v[124:127], v[154:157], v[188:191], v[124:127]
	v_mfma_f32_16x16x32_bf16 v[120:123], v[180:183], v[188:191], v[120:123]
	v_mfma_f32_16x16x32_bf16 v[108:111], v[154:157], v[196:199], v[108:111]
	v_mfma_f32_16x16x32_bf16 v[104:107], v[180:183], v[196:199], v[104:107]
	v_mfma_f32_16x16x32_bf16 v[92:95], v[154:157], v[204:207], v[92:95]
	v_mfma_f32_16x16x32_bf16 v[88:91], v[180:183], v[204:207], v[88:91]
	v_mfma_f32_16x16x32_bf16 v[76:79], v[154:157], v[212:215], v[76:79]
	v_mfma_f32_16x16x32_bf16 v[72:75], v[180:183], v[212:215], v[72:75]
	v_mfma_f32_16x16x32_bf16 v[116:119], v[216:219], v[184:187], v[116:119]
	v_mfma_f32_16x16x32_bf16 v[112:115], v[224:227], v[184:187], v[112:115]
	v_mfma_f32_16x16x32_bf16 v[100:103], v[216:219], v[192:195], v[100:103]
	v_mfma_f32_16x16x32_bf16 v[96:99], v[224:227], v[192:195], v[96:99]
	v_mfma_f32_16x16x32_bf16 v[84:87], v[216:219], v[200:203], v[84:87]
	v_mfma_f32_16x16x32_bf16 v[80:83], v[224:227], v[200:203], v[80:83]
	v_mfma_f32_16x16x32_bf16 v[68:71], v[216:219], v[208:211], v[68:71]
	v_mfma_f32_16x16x32_bf16 v[64:67], v[224:227], v[208:211], v[64:67]
	v_mfma_f32_16x16x32_bf16 v[116:119], v[220:223], v[188:191], v[116:119]
	v_mfma_f32_16x16x32_bf16 v[112:115], v[228:231], v[188:191], v[112:115]
	v_mfma_f32_16x16x32_bf16 v[100:103], v[220:223], v[196:199], v[100:103]
	v_mfma_f32_16x16x32_bf16 v[96:99], v[228:231], v[196:199], v[96:99]
	v_mfma_f32_16x16x32_bf16 v[84:87], v[220:223], v[204:207], v[84:87]
	v_mfma_f32_16x16x32_bf16 v[80:83], v[228:231], v[204:207], v[80:83]
	v_mfma_f32_16x16x32_bf16 v[68:71], v[220:223], v[212:215], v[68:71]
	v_mfma_f32_16x16x32_bf16 v[64:67], v[228:231], v[212:215], v[64:67]
	s_barrier
	s_setprio 0
	s_add_i32 s89, s84, s69
	v_lshl_add_u64 v[162:163], s[8:9], 0, v[130:131]
	s_mov_b32 m0, s89
	s_nop 0
	global_load_lds_dwordx4 v[162:163], off
	v_lshl_add_u64 v[232:233], s[8:9], 0, v[134:135]
	s_add_i32 m0, s89, 0x2000
	s_nop 0
	global_load_lds_dwordx4 v[232:233], off
	s_mov_b32 m0, s74
	v_lshl_add_u64 v[234:235], s[10:11], 0, v[128:129]
	ds_read_b128 v[184:187], v168 offset:16384
	ds_read_b128 v[188:191], v168 offset:17408
	ds_read_b128 v[192:195], v168 offset:18432
	ds_read_b128 v[196:199], v168 offset:19456
	ds_read_b128 v[200:203], v168 offset:20480
	ds_read_b128 v[204:207], v168 offset:21504
	ds_read_b128 v[208:211], v168 offset:22528
	ds_read_b128 v[212:215], v168 offset:23552
	global_load_lds_dwordx4 v[234:235], off
	v_lshl_add_u64 v[236:237], s[10:11], 0, v[132:133]
	s_mov_b32 m0, s75
	s_nop 0
	global_load_lds_dwordx4 v[236:237], off
	s_add_u32 s90, s8, 0x80000
	s_addc_u32 s91, s9, 0
	s_add_i32 s89, s85, s69
	v_lshl_add_u64 v[252:253], s[90:91], 0, v[130:131]
	s_mov_b32 m0, s89
	s_nop 0
	global_load_lds_dwordx4 v[252:253], off
	v_lshl_add_u64 v[252:253], s[90:91], 0, v[134:135]
	s_add_i32 m0, s89, 0x2000
	s_nop 0
	global_load_lds_dwordx4 v[252:253], off
	s_waitcnt lgkmcnt(0)
	s_waitcnt vmcnt(8)
	s_setprio 1
	s_barrier
; #define PG8_STAGE(bufoff, gbase, voff) do { _Pragma("unroll") for (int _i = 0; _i < 2; ++_i) \
;         __builtin_amdgcn_global_load_lds((const unsigned*)((const char*)(gbase) + (voff)[_i]), (LAS unsigned*)(lds + (bufoff) + ldsw + _i * 8192), 16, 0, 0); } while (0)
; #define PG8_LDA(dst, b, h) do { _Pragma("unroll") for (int m = 0; m < 4; ++m) _Pragma("unroll") for (int k = 0; k < 2; ++k) dst[m][k] = *(const LAS bf16x8*)(lds + PG8_SA(b, h) + aoff + m * 2048 + k * 1024); } while (0)
; #define PG8_LDB(dst, b, h) do { _Pragma("unroll") for (int n = 0; n < 2; ++n) _Pragma("unroll") for (int k = 0; k < 2; ++k) dst[n][k] = *(const LAS bf16x8*)(lds + PG8_SB(b, h) + boff + n * 2048 + k * 1024); } while (0)
; #define PG8_MMA(ai, bj, At, Bt) do { __builtin_amdgcn_s_setprio(1); _Pragma("unroll") for (int m = 0; m < 4; ++m) _Pragma("unroll") for (int n = 0; n < 2; ++n) _Pragma("unroll") for (int k = 0; k < 2; ++k) \
;         acc[ai][bj][m][n] = __builtin_amdgcn_mfma_f32_16x16x32_bf16(Bt[n][k], At[m][k], acc[ai][bj][m][n], 0, 0, 0); __builtin_amdgcn_s_setprio(0); } while (0)
; #define PG8_WAIT_V(n) asm volatile("s_waitcnt vmcnt(" #n ")" ::: "memory")
; #define PG8_WAIT_L(n) asm volatile("s_waitcnt lgkmcnt(" #n ")" ::: "memory")
; #define PG8_BAR __builtin_amdgcn_s_barrier()
; #define PG8_SCHED __builtin_amdgcn_sched_barrier(0)
; template <class Epi>
; __device__ __forceinline__ void gemm_phase(LAS unsigned char* lds, const Gemm g, const StaticOrder& S, const Epi& E) {
;     ...
;             PG8_LDA(At, 0, 1); PG8_STAGE(PG8_SA(0, 0), a2, voffA);
;             PG8_BAR; PG8_WAIT_L(0); PG8_MMA(1, 0, At, B0); PG8_BAR; PG8_SCHED;
;             PG8_STAGE(PG8_SB(0, 1), b2 + hstep, voffB);
;             PG8_WAIT_V(6); PG8_BAR; PG8_MMA(1, 1, At, B1); PG8_BAR;
;             PG8_LDB(B0, 1, 0); PG8_SCHED; PG8_LDA(At, 1, 0); PG8_STAGE(PG8_SA(0, 1), a2 + hstep, voffA);
;             PG8_WAIT_L(8); PG8_BAR; PG8_WAIT_L(0); PG8_MMA(0, 0, At, B0); PG8_BAR; PG8_SCHED;
;             PG8_LDB(B1, 1, 1); PG8_STAGE(PG8_SB(1, 0), b3, voffB);
;             PG8_BAR; PG8_WAIT_L(0); PG8_MMA(0, 1, At, B1); PG8_BAR;
	v_mfma_f32_16x16x32_bf16 v[60:63], v[150:153], v[184:187], v[60:63]
	v_mfma_f32_16x16x32_bf16 v[56:59], v[158:161], v[184:187], v[56:59]
	v_mfma_f32_16x16x32_bf16 v[44:47], v[150:153], v[192:195], v[44:47]
	v_mfma_f32_16x16x32_bf16 v[40:43], v[158:161], v[192:195], v[40:43]
	v_mfma_f32_16x16x32_bf16 v[28:31], v[150:153], v[200:203], v[28:31]
	v_mfma_f32_16x16x32_bf16 v[24:27], v[158:161], v[200:203], v[24:27]
	v_mfma_f32_16x16x32_bf16 v[12:15], v[150:153], v[208:211], v[12:15]
	v_mfma_f32_16x16x32_bf16 v[8:11], v[158:161], v[208:211], v[8:11]
	v_mfma_f32_16x16x32_bf16 v[60:63], v[154:157], v[188:191], v[60:63]
	v_mfma_f32_16x16x32_bf16 v[56:59], v[180:183], v[188:191], v[56:59]
	v_mfma_f32_16x16x32_bf16 v[44:47], v[154:157], v[196:199], v[44:47]
	v_mfma_f32_16x16x32_bf16 v[40:43], v[180:183], v[196:199], v[40:43]
	v_mfma_f32_16x16x32_bf16 v[28:31], v[154:157], v[204:207], v[28:31]
	v_mfma_f32_16x16x32_bf16 v[24:27], v[180:183], v[204:207], v[24:27]
	v_mfma_f32_16x16x32_bf16 v[12:15], v[154:157], v[212:215], v[12:15]
	v_mfma_f32_16x16x32_bf16 v[8:11], v[180:183], v[212:215], v[8:11]
	v_mfma_f32_16x16x32_bf16 v[52:55], v[216:219], v[184:187], v[52:55]
	v_mfma_f32_16x16x32_bf16 v[48:51], v[224:227], v[184:187], v[48:51]
	v_mfma_f32_16x16x32_bf16 v[36:39], v[216:219], v[192:195], v[36:39]
	v_mfma_f32_16x16x32_bf16 v[32:35], v[224:227], v[192:195], v[32:35]
	v_mfma_f32_16x16x32_bf16 v[20:23], v[216:219], v[200:203], v[20:23]
	v_mfma_f32_16x16x32_bf16 v[16:19], v[224:227], v[200:203], v[16:19]
	v_mfma_f32_16x16x32_bf16 v[4:7], v[216:219], v[208:211], v[4:7]
	v_mfma_f32_16x16x32_bf16 v[0:3], v[224:227], v[208:211], v[0:3]
	v_mfma_f32_16x16x32_bf16 v[52:55], v[220:223], v[188:191], v[52:55]
	v_mfma_f32_16x16x32_bf16 v[48:51], v[228:231], v[188:191], v[48:51]
	v_mfma_f32_16x16x32_bf16 v[36:39], v[220:223], v[196:199], v[36:39]
	v_mfma_f32_16x16x32_bf16 v[32:35], v[228:231], v[196:199], v[32:35]
	v_mfma_f32_16x16x32_bf16 v[20:23], v[220:223], v[204:207], v[20:23]
	v_mfma_f32_16x16x32_bf16 v[16:19], v[228:231], v[204:207], v[16:19]
	v_mfma_f32_16x16x32_bf16 v[4:7], v[220:223], v[212:215], v[4:7]
	v_mfma_f32_16x16x32_bf16 v[0:3], v[228:231], v[212:215], v[0:3]
	s_barrier
	s_setprio 0
	s_add_i32 s89, 0, 0x18000
	v_add_u32_e32 v138, s89, v165
	ds_read_b128 v[150:153], v138
	ds_read_b128 v[154:157], v138 offset:1024
	ds_read_b128 v[158:161], v138 offset:2048
	ds_read_b128 v[180:183], v138 offset:3072
	s_add_u32 s10, s10, 0x80000
	s_addc_u32 s11, s11, 0
	s_mov_b32 m0, s76
	v_lshl_add_u64 v[216:217], s[10:11], 0, v[128:129]
	ds_read_b128 v[184:187], v168 offset:32768
	ds_read_b128 v[188:191], v168 offset:33792
	ds_read_b128 v[192:195], v168 offset:34816
	ds_read_b128 v[196:199], v168 offset:35840
	ds_read_b128 v[200:203], v168 offset:36864
	ds_read_b128 v[204:207], v168 offset:37888
	ds_read_b128 v[208:211], v168 offset:38912
	ds_read_b128 v[212:215], v168 offset:39936
	global_load_lds_dwordx4 v[216:217], off
	v_lshl_add_u64 v[216:217], s[10:11], 0, v[132:133]
	s_mov_b32 m0, s77
	s_nop 0
	global_load_lds_dwordx4 v[216:217], off
	s_add_i32 s10, 0, 0x1c000
	v_add_u32_e32 v138, s10, v165
	ds_read_b128 v[216:219], v138
	ds_read_b128 v[220:223], v138 offset:1024
	ds_read_b128 v[224:227], v138 offset:2048
	ds_read_b128 v[228:231], v138 offset:3072
	s_waitcnt lgkmcnt(0)
	s_waitcnt vmcnt(8)
	s_setprio 1
	s_barrier
	v_mfma_f32_16x16x32_bf16 v[124:127], v[150:153], v[184:187], v[124:127]
	v_mfma_f32_16x16x32_bf16 v[120:123], v[158:161], v[184:187], v[120:123]
	v_mfma_f32_16x16x32_bf16 v[108:111], v[150:153], v[192:195], v[108:111]
	v_mfma_f32_16x16x32_bf16 v[104:107], v[158:161], v[192:195], v[104:107]
	v_mfma_f32_16x16x32_bf16 v[92:95], v[150:153], v[200:203], v[92:95]
	v_mfma_f32_16x16x32_bf16 v[88:91], v[158:161], v[200:203], v[88:91]
	v_mfma_f32_16x16x32_bf16 v[76:79], v[150:153], v[208:211], v[76:79]
	v_mfma_f32_16x16x32_bf16 v[72:75], v[158:161], v[208:211], v[72:75]
	v_mfma_f32_16x16x32_bf16 v[124:127], v[154:157], v[188:191], v[124:127]
	v_mfma_f32_16x16x32_bf16 v[120:123], v[180:183], v[188:191], v[120:123]
	v_mfma_f32_16x16x32_bf16 v[108:111], v[154:157], v[196:199], v[108:111]
	v_mfma_f32_16x16x32_bf16 v[104:107], v[180:183], v[196:199], v[104:107]
	v_mfma_f32_16x16x32_bf16 v[92:95], v[154:157], v[204:207], v[92:95]
	v_mfma_f32_16x16x32_bf16 v[88:91], v[180:183], v[204:207], v[88:91]
	v_mfma_f32_16x16x32_bf16 v[76:79], v[154:157], v[212:215], v[76:79]
	v_mfma_f32_16x16x32_bf16 v[72:75], v[180:183], v[212:215], v[72:75]
	v_mfma_f32_16x16x32_bf16 v[116:119], v[216:219], v[184:187], v[116:119]
	v_mfma_f32_16x16x32_bf16 v[112:115], v[224:227], v[184:187], v[112:115]
	v_mfma_f32_16x16x32_bf16 v[100:103], v[216:219], v[192:195], v[100:103]
	v_mfma_f32_16x16x32_bf16 v[96:99], v[224:227], v[192:195], v[96:99]
	v_mfma_f32_16x16x32_bf16 v[84:87], v[216:219], v[200:203], v[84:87]
	v_mfma_f32_16x16x32_bf16 v[80:83], v[224:227], v[200:203], v[80:83]
	v_mfma_f32_16x16x32_bf16 v[68:71], v[216:219], v[208:211], v[68:71]
	v_mfma_f32_16x16x32_bf16 v[64:67], v[224:227], v[208:211], v[64:67]
	v_mfma_f32_16x16x32_bf16 v[116:119], v[220:223], v[188:191], v[116:119]
	v_mfma_f32_16x16x32_bf16 v[112:115], v[228:231], v[188:191], v[112:115]
	v_mfma_f32_16x16x32_bf16 v[100:103], v[220:223], v[196:199], v[100:103]
	v_mfma_f32_16x16x32_bf16 v[96:99], v[228:231], v[196:199], v[96:99]
	v_mfma_f32_16x16x32_bf16 v[84:87], v[220:223], v[204:207], v[84:87]
	v_mfma_f32_16x16x32_bf16 v[80:83], v[228:231], v[204:207], v[80:83]
	v_mfma_f32_16x16x32_bf16 v[68:71], v[220:223], v[212:215], v[68:71]
	v_mfma_f32_16x16x32_bf16 v[64:67], v[228:231], v[212:215], v[64:67]
	s_barrier
; __device__ __forceinline__ float sigmoidf_(float x) { return __builtin_amdgcn_rcpf(1.0f + fexp(-x)); }
; #define PG8_STAGE(bufoff, gbase, voff) do { _Pragma("unroll") for (int _i = 0; _i < 2; ++_i) \
;         __builtin_amdgcn_global_load_lds((const unsigned*)((const char*)(gbase) + (voff)[_i]), (LAS unsigned*)(lds + (bufoff) + ldsw + _i * 8192), 16, 0, 0); } while (0)
; #define PG8_WAIT_V(n) asm volatile("s_waitcnt vmcnt(" #n ")" ::: "memory")
; #define PG8_WAIT_L(n) asm volatile("s_waitcnt lgkmcnt(" #n ")" ::: "memory")
; template <class Epi>
; __device__ __forceinline__ void gemm_phase(LAS unsigned char* lds, const Gemm g, const StaticOrder& S, const Epi& E) {
;     ...
;             PG8_LDA(At, 1, 1); PG8_STAGE(PG8_SA(1, 0), a3, voffA);
;             PG8_BAR; PG8_WAIT_L(0); PG8_MMA(1, 0, At, B0); PG8_BAR; PG8_SCHED;
;             PG8_STAGE(PG8_SB(1, 1), b3 + hstep, voffB);
;             PG8_WAIT_V(6); PG8_BAR; PG8_MMA(1, 1, At, B1); PG8_BAR;
;         }
;     __device__ __forceinline__ void operator()(const f32x4 (&acc)[2][2][4][2], const Unit& u, int wr, int wc, int fr, int fq, const Pre& P) const {
;         const int sec = u.pn >> 3, row0 = ROW_X + u.pm * BM + wr * 64 + fr, colb = (u.pn & 7) * BM + wc * 32 + 8 * fq;
; #pragma unroll
;         for (int ai = 0; ai < 2; ++ai)
; #pragma unroll
;             for (int m = 0; m < 4; ++m) { const int r = row0 + ai * HALF + m * 16; const float rs = __builtin_amdgcn_rsqf(P.rs[ai * 4 + m] * (1.0f / DM) + RMS_EPS);
; #pragma unroll
;                 for (int bj = 0; bj < 2; ++bj) { const int c = colb + bj * HALF; const size_t off = (size_t)r * DM + c; float x[8], y[8];
; #pragma unroll
;                     for (int n = 0; n < 2; ++n)
; #pragma unroll
;                         for (int j = 0; j < 4; ++j) x[n * 4 + j] = acc[ai][bj][m][n][j] * rs;
;                     bf16_t* dst;
;                     if (sec == 0) { dst = QB;
; #pragma unroll
;                         for (int j = 0; j < 8; ++j) y[j] = x[j] * sigmoidf_(x[j]); }
;                     else if (sec == 1) { dst = KB; const f32x4 l0 = *(const f32x4*)(LBv + c), l1 = *(const f32x4*)(LBv + c + 4); float lf[8];
; #pragma unroll
;                         for (int j = 0; j < 8; ++j) { const float lb = j < 4 ? l0[j] : l1[j - 4]; const float fg = lb + (1.0f - lb) * sigmoidf_(x[j]); y[j] = 1.0f - fg; lf[j] = __logf(fg); }
	s_setprio 0
	s_add_i32 s11, s89, s69
	v_lshl_add_u64 v[162:163], v[162:163], 0, s[34:35]
	s_mov_b32 m0, s11
	s_nop 0
	global_load_lds_dwordx4 v[162:163], off
	v_lshl_add_u64 v[162:163], v[232:233], 0, s[34:35]
	s_add_i32 m0, s11, 0x2000
	s_nop 0
	global_load_lds_dwordx4 v[162:163], off
	s_mov_b32 m0, s79
	v_lshl_add_u64 v[162:163], v[234:235], 0, s[34:35]
	ds_read_b128 v[184:187], v168 offset:49152
	ds_read_b128 v[188:191], v168 offset:50176
	ds_read_b128 v[192:195], v168 offset:51200
	ds_read_b128 v[196:199], v168 offset:52224
	ds_read_b128 v[200:203], v168 offset:53248
	ds_read_b128 v[204:207], v168 offset:54272
	ds_read_b128 v[208:211], v168 offset:55296
	ds_read_b128 v[212:215], v168 offset:56320
	global_load_lds_dwordx4 v[162:163], off
	v_lshl_add_u64 v[162:163], v[236:237], 0, s[34:35]
	s_mov_b32 m0, s80
	s_nop 0
	global_load_lds_dwordx4 v[162:163], off
	s_add_u32 s8, s8, 0x80080
	s_addc_u32 s9, s9, 0
	s_add_i32 s10, s10, s69
	v_lshl_add_u64 v[252:253], s[8:9], 0, v[130:131]
	s_mov_b32 m0, s10
	s_nop 0
	global_load_lds_dwordx4 v[252:253], off
	v_lshl_add_u64 v[252:253], s[8:9], 0, v[134:135]
	s_add_i32 m0, s10, 0x2000
	s_nop 0
	global_load_lds_dwordx4 v[252:253], off
	s_waitcnt lgkmcnt(0)
	s_waitcnt vmcnt(8)
	s_setprio 1
	s_barrier
	v_mfma_f32_16x16x32_bf16 v[60:63], v[150:153], v[184:187], v[60:63]
	v_mfma_f32_16x16x32_bf16 v[56:59], v[158:161], v[184:187], v[56:59]
	v_mfma_f32_16x16x32_bf16 v[44:47], v[150:153], v[192:195], v[44:47]
	v_mfma_f32_16x16x32_bf16 v[40:43], v[158:161], v[192:195], v[40:43]
	v_mfma_f32_16x16x32_bf16 v[28:31], v[150:153], v[200:203], v[28:31]
	v_mfma_f32_16x16x32_bf16 v[24:27], v[158:161], v[200:203], v[24:27]
	v_mfma_f32_16x16x32_bf16 v[12:15], v[150:153], v[208:211], v[12:15]
	v_mfma_f32_16x16x32_bf16 v[8:11], v[158:161], v[208:211], v[8:11]
	v_mfma_f32_16x16x32_bf16 v[60:63], v[154:157], v[188:191], v[60:63]
	v_mfma_f32_16x16x32_bf16 v[56:59], v[180:183], v[188:191], v[56:59]
	v_mfma_f32_16x16x32_bf16 v[44:47], v[154:157], v[196:199], v[44:47]
	v_mfma_f32_16x16x32_bf16 v[40:43], v[180:183], v[196:199], v[40:43]
	v_mfma_f32_16x16x32_bf16 v[28:31], v[154:157], v[204:207], v[28:31]
	v_mfma_f32_16x16x32_bf16 v[24:27], v[180:183], v[204:207], v[24:27]
	v_mfma_f32_16x16x32_bf16 v[12:15], v[154:157], v[212:215], v[12:15]
	v_mfma_f32_16x16x32_bf16 v[8:11], v[180:183], v[212:215], v[8:11]
	v_mfma_f32_16x16x32_bf16 v[52:55], v[216:219], v[184:187], v[52:55]
	v_mfma_f32_16x16x32_bf16 v[48:51], v[224:227], v[184:187], v[48:51]
	v_mfma_f32_16x16x32_bf16 v[36:39], v[216:219], v[192:195], v[36:39]
	v_mfma_f32_16x16x32_bf16 v[32:35], v[224:227], v[192:195], v[32:35]
	v_mfma_f32_16x16x32_bf16 v[20:23], v[216:219], v[200:203], v[20:23]
	v_mfma_f32_16x16x32_bf16 v[16:19], v[224:227], v[200:203], v[16:19]
	v_mfma_f32_16x16x32_bf16 v[4:7], v[216:219], v[208:211], v[4:7]
	v_mfma_f32_16x16x32_bf16 v[0:3], v[224:227], v[208:211], v[0:3]
	v_mfma_f32_16x16x32_bf16 v[52:55], v[220:223], v[188:191], v[52:55]
	v_mfma_f32_16x16x32_bf16 v[48:51], v[228:231], v[188:191], v[48:51]
	v_mfma_f32_16x16x32_bf16 v[36:39], v[220:223], v[196:199], v[36:39]
	v_mfma_f32_16x16x32_bf16 v[32:35], v[228:231], v[196:199], v[32:35]
	v_mfma_f32_16x16x32_bf16 v[20:23], v[220:223], v[204:207], v[20:23]
	v_mfma_f32_16x16x32_bf16 v[16:19], v[228:231], v[204:207], v[16:19]
	v_mfma_f32_16x16x32_bf16 v[4:7], v[220:223], v[212:215], v[4:7]
	v_mfma_f32_16x16x32_bf16 v[0:3], v[228:231], v[212:215], v[0:3]
	s_barrier
	s_setprio 0
	s_add_i32 s63, s63, 2
	s_add_u32 s6, s6, 0x100
	s_addc_u32 s7, s7, 0
	s_add_u32 s33, s33, 0x100
	s_addc_u32 s61, s61, 0
	s_cmp_gt_u32 s63, 29
	s_cbranch_scc0 .LBB0_691
	v_fmamk_f32 v149, v149, 0x3a000000, v170
	s_lshl_b32 s1, s0, 8
	v_rsq_f32_e32 v152, v149
	s_ashr_i32 s61, s0, 3
	v_lshl_add_u32 v148, s4, 8, v137
	s_and_b32 s1, s1, 0x700
	s_cmp_gt_u32 s0, 7
	v_ashrrev_i32_e32 v149, 31, v148
	v_or_b32_e32 v138, s1, v166
	v_lshlrev_b32_e32 v254, 2, v138
	global_load_dwordx4 v[238:241], v254, s[24:25]
	global_load_dwordx4 v[242:245], v254, s[24:25] offset:16
	global_load_dwordx4 v[246:249], v254, s[24:25] offset:512
	global_load_dwordx4 v[250:253], v254, s[24:25] offset:528
	s_cselect_b64 s[12:13], -1, 0
	v_lshlrev_b64 v[150:151], 11, v[148:149]
	v_pk_mul_f32 v[124:125], v[152:153], v[124:125] op_sel_hi:[0,1]
	v_pk_mul_f32 v[126:127], v[152:153], v[126:127] op_sel_hi:[0,1]
	v_pk_mul_f32 v[154:155], v[152:153], v[120:121] op_sel_hi:[0,1]
	v_pk_mul_f32 v[122:123], v[152:153], v[122:123] op_sel_hi:[0,1]
	v_or_b32_e32 v120, v150, v138
	v_mov_b32_e32 v121, v151
	s_mov_b64 s[0:1], -1
	s_and_b64 vcc, exec, s[12:13]
	s_cbranch_vccz .LBB0_704
	s_mov_b64 s[6:7], -1
	s_mov_b64 s[0:1], 0
	s_cmp_lt_i32 s61, 2
	s_mov_b64 s[4:5], 0
	s_cbranch_scc1 .LBB0_699
	s_cmp_eq_u32 s61, 2
	s_mov_b64 s[4:5], -1
	s_cbranch_scc0 .LBB0_696
	s_mov_b64 s[4:5], 0
	v_mov_b32_e32 v161, v123
	v_mov_b32_e32 v160, v122
	v_mov_b32_e32 v163, v155
	v_mov_b32_e32 v162, v154
	v_mov_b32_e32 v157, v127
	v_mov_b32_e32 v156, v126
	v_mov_b32_e32 v159, v125
	v_mov_b32_e32 v158, v124

; #define PG8_STAGE(bufoff, gbase, voff) do { _Pragma("unroll") for (int _i = 0; _i < 2; ++_i) \
;         __builtin_amdgcn_global_load_lds((const unsigned*)((const char*)(gbase) + (voff)[_i]), (LAS unsigned*)(lds + (bufoff) + ldsw + _i * 8192), 16, 0, 0); } while (0)
; #define PG8_WAIT_V(n) asm volatile("s_waitcnt vmcnt(" #n ")" ::: "memory")
; #define PG8_BAR __builtin_amdgcn_s_barrier()
; template <class Epi>
; __device__ __forceinline__ void gemm_phase(LAS unsigned char* lds, const Gemm g, const StaticOrder& S, const Epi& E) {
;     const int tid = threadIdx.x, wid = __builtin_amdgcn_readfirstlane(tid >> 6), lane = tid & 63, wr = wid >> 2, wc = wid & 3, fr = lane & 15, fq = lane >> 4;
;     const int K = g.K, nt = K / BK;
;     unsigned voffA[2], voffB[2];
; #pragma unroll
;     for (int i = 0; i < 2; ++i) { int R, C; stage_rc(tid * 16 + i * 8192, R, C); const int Rb = Epi::PERM ? ((R & ~31) + perm32(R & 31)) : R;
;         voffA[i] = (unsigned)(R * K + C) * 2u; voffB[i] = (unsigned)(Rb * K + C) * 2u; }
;     const size_t kstep = (size_t)(BK * 2);
;     const size_t hstep = (size_t)HALF * K * 2;
;     const size_t tstep = 2 * hstep;
;     const unsigned ldsw = (unsigned)wid * 1024u;
;     const int aoff = lds_byte(wr * 64 + fr, fq * 8), boff = lds_byte(wc * 32 + fr, fq * 8);
;     ...
;     Unit cur, nxt; int ui = 0;
;     if (!S.next(0, cur)) return;
;     f32x4 acc[2][2][4][2];
; #pragma unroll
;     for (int a = 0; a < 2; ++a)
; #pragma unroll
;         for (int b = 0; b < 2; ++b)
; #pragma unroll
;             for (int m = 0; m < 4; ++m)
; #pragma unroll
;                 for (int n = 0; n < 2; ++n) acc[a][b][m][n] = (f32x4){0.f, 0.f, 0.f, 0.f};
;     bf16x8 At[4][2], B0[2][2], B1[2][2];
;     const char* cA = (const char*)g.A + (size_t)cur.pm * tstep; const char* cB = (const char*)g.Bt + (size_t)cur.pn * tstep;
;     typename Epi::Pre pre = E.pre(cur, wr, fr);
;     PG8_STAGE(PG8_SB(0, 0), cB, voffB); PG8_STAGE(PG8_SA(0, 0), cA, voffA); PG8_STAGE(PG8_SB(0, 1), cB + hstep, voffB); PG8_STAGE(PG8_SA(0, 1), cA + hstep, voffA);
;     if (wr == 1) PG8_BAR;
;     PG8_WAIT_V(4); PG8_BAR;
;     PG8_STAGE(PG8_SB(1, 0), cB + kstep, voffB); PG8_STAGE(PG8_SA(1, 0), cA + kstep, voffA); PG8_STAGE(PG8_SB(1, 1), cB + hstep + kstep, voffB);
;     PG8_WAIT_V(6); PG8_BAR;
.LBB0_1211:
	s_lshl_b32 s3, s3, 5
	s_mov_b64 s[8:9], 0x80
	s_and_b32 s11, s3, 0x60
	s_add_i32 m0, s21, 0x18000
	v_lshl_add_u64 v[6:7], v[6:7], 0, s[8:9]
	s_lshl_b32 s10, s2, 13
	s_lshl_b32 s3, s11, 7
	s_waitcnt vmcnt(2)
	s_barrier
	global_load_lds_dwordx4 v[6:7], off
	v_lshl_add_u64 v[4:5], v[4:5], 0, s[8:9]
	s_add_i32 m0, s21, 0x1a000
	s_add_i32 s57, s21, 0x8000
	s_add_i32 s58, s21, 0xa000
	global_load_lds_dwordx4 v[4:5], off
	v_lshl_add_u64 v[2:3], v[2:3], 0, s[8:9]
	s_mov_b32 m0, s57
	s_add_u32 s4, s24, 0x80080
	global_load_lds_dwordx4 v[2:3], off
	v_lshl_add_u64 v[0:1], v[0:1], 0, s[8:9]
	s_mov_b32 m0, s58
	s_addc_u32 s5, s25, 0
	global_load_lds_dwordx4 v[0:1], off
	s_add_i32 m0, s21, 0x1c000
	v_lshl_add_u64 v[0:1], s[4:5], 0, v[140:141]
	global_load_lds_dwordx4 v[0:1], off
	v_lshl_add_u64 v[0:1], s[4:5], 0, v[144:145]
	s_add_i32 m0, s21, 0x1e000
	v_lshlrev_b32_e32 v4, 2, v137
	global_load_lds_dwordx4 v[0:1], off
	v_bfe_u32 v0, v178, 4, 2
	v_lshlrev_b32_e32 v2, 4, v0
	v_lshl_or_b32 v3, v137, 6, v2
	v_and_b32_e32 v4, 32, v4
	v_lshl_or_b32 v1, s2, 6, v137
	v_bitop3_b32 v3, v3, s10, v4 bitop3:0xde
	v_lshlrev_b32_e32 v4, 6, v178
	s_movk_i32 s2, 0x3c0
	v_and_or_b32 v2, v4, s2, v2
	v_lshlrev_b32_e32 v4, 2, v178
	v_and_b32_e32 v4, 32, v4
	v_bitop3_b32 v137, s3, v2, v4 bitop3:0xf6
	v_cmp_eq_u32_e64 s[2:3], 0, v0
	v_lshl_or_b32 v161, v0, 3, s11
	v_lshlrev_b32_e32 v0, 9, v178
	v_add_u32_e32 v160, 0x100, v1
	v_and_b32_e32 v0, 0x70000, v0
	v_lshlrev_b32_e32 v1, 12, v10
	v_or3_b32 v0, v8, v0, v1
	v_add_u32_e32 v146, v0, v9
	v_lshlrev_b32_e32 v0, 5, v11
	v_and_b32_e32 v0, 0xf0000, v0
	s_waitcnt vmcnt(6)
	v_or3_b32 v0, v8, v0, v1
	v_add_u32_e32 v148, v0, v9
	s_add_i32 s62, 0, 0x10000
	s_add_i32 s63, 0, 0x14000
	v_mbcnt_lo_u32_b32 v0, -1, 0
	s_ashr_i32 s59, s54, 31
	s_mov_b32 s60, s54
	s_ashr_i32 s61, s28, 31
	v_mov_b32_e32 v147, v141
	s_waitcnt vmcnt(0)
	v_mov_b32_e32 v149, v141
	v_mov_b64_e32 v[150:151], 0x200
	v_mov_b64_e32 v[152:153], 0x1ff
	v_add_u32_e32 v162, s62, v137
	v_add_u32_e32 v163, 0, v3
	v_add_u32_e32 v165, s63, v137
	v_mbcnt_hi_u32_b32 v166, -1, v0
	s_barrier
	s_branch .LBB0_1213

; #define PG8_STAGE(bufoff, gbase, voff) do { _Pragma("unroll") for (int _i = 0; _i < 2; ++_i) \
;         __builtin_amdgcn_global_load_lds((const unsigned*)((const char*)(gbase) + (voff)[_i]), (LAS unsigned*)(lds + (bufoff) + ldsw + _i * 8192), 16, 0, 0); } while (0)
; #define PG8_LDA(dst, b, h) do { _Pragma("unroll") for (int m = 0; m < 4; ++m) _Pragma("unroll") for (int k = 0; k < 2; ++k) dst[m][k] = *(const LAS bf16x8*)(lds + PG8_SA(b, h) + aoff + m * 2048 + k * 1024); } while (0)
; #define PG8_LDB(dst, b, h) do { _Pragma("unroll") for (int n = 0; n < 2; ++n) _Pragma("unroll") for (int k = 0; k < 2; ++k) dst[n][k] = *(const LAS bf16x8*)(lds + PG8_SB(b, h) + boff + n * 2048 + k * 1024); } while (0)
; #define PG8_MMA(ai, bj, At, Bt) do { __builtin_amdgcn_s_setprio(1); _Pragma("unroll") for (int m = 0; m < 4; ++m) _Pragma("unroll") for (int n = 0; n < 2; ++n) _Pragma("unroll") for (int k = 0; k < 2; ++k) \
;         acc[ai][bj][m][n] = __builtin_amdgcn_mfma_f32_16x16x32_bf16(Bt[n][k], At[m][k], acc[ai][bj][m][n], 0, 0, 0); __builtin_amdgcn_s_setprio(0); } while (0)
; #define PG8_WAIT_V(n) asm volatile("s_waitcnt vmcnt(" #n ")" ::: "memory")
; #define PG8_WAIT_L(n) asm volatile("s_waitcnt lgkmcnt(" #n ")" ::: "memory")
; #define PG8_BAR __builtin_amdgcn_s_barrier()
; #define PG8_SCHED __builtin_amdgcn_sched_barrier(0)
; template <class Epi>
; __device__ __forceinline__ void gemm_phase(LAS unsigned char* lds, const Gemm g, const StaticOrder& S, const Epi& E) {
;     ...
;             const char* a2 = last ? nA : cA + (size_t)(t + 2) * kstep; const char* b2 = last ? nB : cB + (size_t)(t + 2) * kstep;
;             const char* a3 = a2 + kstep; const char* b3 = b2 + kstep;
;             PG8_LDB(B0, 0, 0); PG8_SCHED; PG8_LDA(At, 0, 0); PG8_STAGE(PG8_SA(1, 1), a1 + hstep, voffA);
;             PG8_WAIT_L(8); PG8_BAR; PG8_WAIT_L(0); PG8_MMA(0, 0, At, B0); PG8_BAR; PG8_SCHED;
;             PG8_LDB(B1, 0, 1); PG8_STAGE(PG8_SB(0, 0), b2, voffB);
;             PG8_BAR; PG8_WAIT_L(0); PG8_MMA(0, 1, At, B1); PG8_BAR;
;             PG8_LDA(At, 0, 1); PG8_STAGE(PG8_SA(0, 0), a2, voffA);
;             PG8_BAR; PG8_WAIT_L(0); PG8_MMA(1, 0, At, B0); PG8_BAR; PG8_SCHED;
;             PG8_STAGE(PG8_SB(0, 1), b2 + hstep, voffB);
;             PG8_WAIT_V(6); PG8_BAR; PG8_MMA(1, 1, At, B1); PG8_BAR;
.LBB0_1220:
	ds_read_b128 v[128:131], v162
	ds_read_b128 v[132:135], v162 offset:1024
	ds_read_b128 v[154:157], v162 offset:2048
	ds_read_b128 v[168:171], v162 offset:3072
	s_add_u32 s24, s22, 0xfff80080
	s_addc_u32 s25, s23, -1
	s_cmp_eq_u32 s67, 28
	s_cselect_b32 s31, s13, s25
	s_cselect_b32 s30, s19, s24
	s_cselect_b32 s25, s11, s66
	s_cselect_b32 s24, s64, s65
	v_lshl_add_u64 v[158:159], s[22:23], 0, v[146:147]
	s_add_i32 m0, s21, 0xc000
	ds_read_b128 v[172:175], v163
	ds_read_b128 v[180:183], v163 offset:1024
	ds_read_b128 v[184:187], v163 offset:2048
	ds_read_b128 v[188:191], v163 offset:3072
	ds_read_b128 v[192:195], v163 offset:4096
	ds_read_b128 v[196:199], v163 offset:5120
	ds_read_b128 v[200:203], v163 offset:6144
	ds_read_b128 v[204:207], v163 offset:7168
	global_load_lds_dwordx4 v[158:159], off
	v_lshl_add_u64 v[158:159], s[22:23], 0, v[148:149]
	s_add_i32 m0, s21, 0xe000
	s_nop 0
	global_load_lds_dwordx4 v[158:159], off
	ds_read_b128 v[208:211], v165
	ds_read_b128 v[212:215], v165 offset:1024
	ds_read_b128 v[216:219], v165 offset:2048
	ds_read_b128 v[220:223], v165 offset:3072
	s_waitcnt lgkmcnt(0)
	s_waitcnt vmcnt(8)
	s_setprio 1
	s_barrier
	v_mfma_f32_16x16x32_bf16 v[124:127], v[128:131], v[172:175], v[124:127]
	v_mfma_f32_16x16x32_bf16 v[120:123], v[154:157], v[172:175], v[120:123]
	v_mfma_f32_16x16x32_bf16 v[108:111], v[128:131], v[184:187], v[108:111]
	v_mfma_f32_16x16x32_bf16 v[104:107], v[154:157], v[184:187], v[104:107]
	v_mfma_f32_16x16x32_bf16 v[92:95], v[128:131], v[192:195], v[92:95]
	v_mfma_f32_16x16x32_bf16 v[88:91], v[154:157], v[192:195], v[88:91]
	v_mfma_f32_16x16x32_bf16 v[76:79], v[128:131], v[200:203], v[76:79]
	v_mfma_f32_16x16x32_bf16 v[72:75], v[154:157], v[200:203], v[72:75]
	v_mfma_f32_16x16x32_bf16 v[124:127], v[132:135], v[180:183], v[124:127]
	v_mfma_f32_16x16x32_bf16 v[120:123], v[168:171], v[180:183], v[120:123]
	v_mfma_f32_16x16x32_bf16 v[108:111], v[132:135], v[188:191], v[108:111]
	v_mfma_f32_16x16x32_bf16 v[104:107], v[168:171], v[188:191], v[104:107]
	v_mfma_f32_16x16x32_bf16 v[92:95], v[132:135], v[196:199], v[92:95]
	v_mfma_f32_16x16x32_bf16 v[88:91], v[168:171], v[196:199], v[88:91]
	v_mfma_f32_16x16x32_bf16 v[76:79], v[132:135], v[204:207], v[76:79]
	v_mfma_f32_16x16x32_bf16 v[72:75], v[168:171], v[204:207], v[72:75]
	v_mfma_f32_16x16x32_bf16 v[116:119], v[208:211], v[172:175], v[116:119]
	v_mfma_f32_16x16x32_bf16 v[112:115], v[216:219], v[172:175], v[112:115]
	v_mfma_f32_16x16x32_bf16 v[100:103], v[208:211], v[184:187], v[100:103]
	v_mfma_f32_16x16x32_bf16 v[96:99], v[216:219], v[184:187], v[96:99]
	v_mfma_f32_16x16x32_bf16 v[84:87], v[208:211], v[192:195], v[84:87]
	v_mfma_f32_16x16x32_bf16 v[80:83], v[216:219], v[192:195], v[80:83]
	v_mfma_f32_16x16x32_bf16 v[68:71], v[208:211], v[200:203], v[68:71]
	v_mfma_f32_16x16x32_bf16 v[64:67], v[216:219], v[200:203], v[64:67]
	v_mfma_f32_16x16x32_bf16 v[116:119], v[212:215], v[180:183], v[116:119]
	v_mfma_f32_16x16x32_bf16 v[112:115], v[220:223], v[180:183], v[112:115]
	v_mfma_f32_16x16x32_bf16 v[100:103], v[212:215], v[188:191], v[100:103]
	v_mfma_f32_16x16x32_bf16 v[96:99], v[220:223], v[188:191], v[96:99]
	v_mfma_f32_16x16x32_bf16 v[84:87], v[212:215], v[196:199], v[84:87]
	v_mfma_f32_16x16x32_bf16 v[80:83], v[220:223], v[196:199], v[80:83]
	v_mfma_f32_16x16x32_bf16 v[68:71], v[212:215], v[204:207], v[68:71]
	v_mfma_f32_16x16x32_bf16 v[64:67], v[220:223], v[204:207], v[64:67]
	s_barrier
	s_setprio 0
	s_add_i32 s68, s62, s36
	v_lshl_add_u64 v[158:159], s[24:25], 0, v[140:141]
	s_mov_b32 m0, s68
	s_nop 0
	global_load_lds_dwordx4 v[158:159], off
	v_lshl_add_u64 v[176:177], s[24:25], 0, v[144:145]
	s_add_i32 m0, s68, 0x2000
	s_nop 0
	global_load_lds_dwordx4 v[176:177], off
	s_mov_b32 m0, s21
	v_lshl_add_u64 v[224:225], s[30:31], 0, v[138:139]
	ds_read_b128 v[172:175], v163 offset:16384
	ds_read_b128 v[180:183], v163 offset:17408
	ds_read_b128 v[184:187], v163 offset:18432
	ds_read_b128 v[188:191], v163 offset:19456
	ds_read_b128 v[192:195], v163 offset:20480
	ds_read_b128 v[196:199], v163 offset:21504
	ds_read_b128 v[200:203], v163 offset:22528
	ds_read_b128 v[204:207], v163 offset:23552
	global_load_lds_dwordx4 v[224:225], off
	v_lshl_add_u64 v[226:227], s[30:31], 0, v[142:143]
	s_mov_b32 m0, s39
	s_nop 0
	global_load_lds_dwordx4 v[226:227], off
	s_add_u32 s68, s24, 0x80000
	s_addc_u32 s69, s25, 0
	s_add_i32 s70, s63, s36
	v_lshl_add_u64 v[252:253], s[68:69], 0, v[140:141]
	s_mov_b32 m0, s70
	s_nop 0
	global_load_lds_dwordx4 v[252:253], off
	v_lshl_add_u64 v[252:253], s[68:69], 0, v[144:145]
	s_add_i32 m0, s70, 0x2000
	s_nop 0
	global_load_lds_dwordx4 v[252:253], off
	s_waitcnt lgkmcnt(0)
	s_waitcnt vmcnt(8)
	s_setprio 1
	s_barrier
; #define PG8_STAGE(bufoff, gbase, voff) do { _Pragma("unroll") for (int _i = 0; _i < 2; ++_i) \
;         __builtin_amdgcn_global_load_lds((const unsigned*)((const char*)(gbase) + (voff)[_i]), (LAS unsigned*)(lds + (bufoff) + ldsw + _i * 8192), 16, 0, 0); } while (0)
; #define PG8_LDA(dst, b, h) do { _Pragma("unroll") for (int m = 0; m < 4; ++m) _Pragma("unroll") for (int k = 0; k < 2; ++k) dst[m][k] = *(const LAS bf16x8*)(lds + PG8_SA(b, h) + aoff + m * 2048 + k * 1024); } while (0)
; #define PG8_LDB(dst, b, h) do { _Pragma("unroll") for (int n = 0; n < 2; ++n) _Pragma("unroll") for (int k = 0; k < 2; ++k) dst[n][k] = *(const LAS bf16x8*)(lds + PG8_SB(b, h) + boff + n * 2048 + k * 1024); } while (0)
; #define PG8_MMA(ai, bj, At, Bt) do { __builtin_amdgcn_s_setprio(1); _Pragma("unroll") for (int m = 0; m < 4; ++m) _Pragma("unroll") for (int n = 0; n < 2; ++n) _Pragma("unroll") for (int k = 0; k < 2; ++k) \
;         acc[ai][bj][m][n] = __builtin_amdgcn_mfma_f32_16x16x32_bf16(Bt[n][k], At[m][k], acc[ai][bj][m][n], 0, 0, 0); __builtin_amdgcn_s_setprio(0); } while (0)
; #define PG8_WAIT_V(n) asm volatile("s_waitcnt vmcnt(" #n ")" ::: "memory")
; #define PG8_WAIT_L(n) asm volatile("s_waitcnt lgkmcnt(" #n ")" ::: "memory")
; #define PG8_BAR __builtin_amdgcn_s_barrier()
; #define PG8_SCHED __builtin_amdgcn_sched_barrier(0)
; template <class Epi>
; __device__ __forceinline__ void gemm_phase(LAS unsigned char* lds, const Gemm g, const StaticOrder& S, const Epi& E) {
;     ...
;             PG8_LDA(At, 0, 1); PG8_STAGE(PG8_SA(0, 0), a2, voffA);
;             PG8_BAR; PG8_WAIT_L(0); PG8_MMA(1, 0, At, B0); PG8_BAR; PG8_SCHED;
;             PG8_STAGE(PG8_SB(0, 1), b2 + hstep, voffB);
;             PG8_WAIT_V(6); PG8_BAR; PG8_MMA(1, 1, At, B1); PG8_BAR;
;             PG8_LDB(B0, 1, 0); PG8_SCHED; PG8_LDA(At, 1, 0); PG8_STAGE(PG8_SA(0, 1), a2 + hstep, voffA);
;             PG8_WAIT_L(8); PG8_BAR; PG8_WAIT_L(0); PG8_MMA(0, 0, At, B0); PG8_BAR; PG8_SCHED;
;             PG8_LDB(B1, 1, 1); PG8_STAGE(PG8_SB(1, 0), b3, voffB);
;             PG8_BAR; PG8_WAIT_L(0); PG8_MMA(0, 1, At, B1); PG8_BAR;
	v_mfma_f32_16x16x32_bf16 v[60:63], v[128:131], v[172:175], v[60:63]
	v_mfma_f32_16x16x32_bf16 v[56:59], v[154:157], v[172:175], v[56:59]
	v_mfma_f32_16x16x32_bf16 v[44:47], v[128:131], v[184:187], v[44:47]
	v_mfma_f32_16x16x32_bf16 v[40:43], v[154:157], v[184:187], v[40:43]
	v_mfma_f32_16x16x32_bf16 v[28:31], v[128:131], v[192:195], v[28:31]
	v_mfma_f32_16x16x32_bf16 v[24:27], v[154:157], v[192:195], v[24:27]
	v_mfma_f32_16x16x32_bf16 v[12:15], v[128:131], v[200:203], v[12:15]
	v_mfma_f32_16x16x32_bf16 v[8:11], v[154:157], v[200:203], v[8:11]
	v_mfma_f32_16x16x32_bf16 v[60:63], v[132:135], v[180:183], v[60:63]
	v_mfma_f32_16x16x32_bf16 v[56:59], v[168:171], v[180:183], v[56:59]
	v_mfma_f32_16x16x32_bf16 v[44:47], v[132:135], v[188:191], v[44:47]
	v_mfma_f32_16x16x32_bf16 v[40:43], v[168:171], v[188:191], v[40:43]
	v_mfma_f32_16x16x32_bf16 v[28:31], v[132:135], v[196:199], v[28:31]
	v_mfma_f32_16x16x32_bf16 v[24:27], v[168:171], v[196:199], v[24:27]
	v_mfma_f32_16x16x32_bf16 v[12:15], v[132:135], v[204:207], v[12:15]
	v_mfma_f32_16x16x32_bf16 v[8:11], v[168:171], v[204:207], v[8:11]
	v_mfma_f32_16x16x32_bf16 v[52:55], v[208:211], v[172:175], v[52:55]
	v_mfma_f32_16x16x32_bf16 v[48:51], v[216:219], v[172:175], v[48:51]
	v_mfma_f32_16x16x32_bf16 v[36:39], v[208:211], v[184:187], v[36:39]
	v_mfma_f32_16x16x32_bf16 v[32:35], v[216:219], v[184:187], v[32:35]
	v_mfma_f32_16x16x32_bf16 v[20:23], v[208:211], v[192:195], v[20:23]
	v_mfma_f32_16x16x32_bf16 v[16:19], v[216:219], v[192:195], v[16:19]
	v_mfma_f32_16x16x32_bf16 v[4:7], v[208:211], v[200:203], v[4:7]
	v_mfma_f32_16x16x32_bf16 v[0:3], v[216:219], v[200:203], v[0:3]
	v_mfma_f32_16x16x32_bf16 v[52:55], v[212:215], v[180:183], v[52:55]
	v_mfma_f32_16x16x32_bf16 v[48:51], v[220:223], v[180:183], v[48:51]
	v_mfma_f32_16x16x32_bf16 v[36:39], v[212:215], v[188:191], v[36:39]
	v_mfma_f32_16x16x32_bf16 v[32:35], v[220:223], v[188:191], v[32:35]
	v_mfma_f32_16x16x32_bf16 v[20:23], v[212:215], v[196:199], v[20:23]
	v_mfma_f32_16x16x32_bf16 v[16:19], v[220:223], v[196:199], v[16:19]
	v_mfma_f32_16x16x32_bf16 v[4:7], v[212:215], v[204:207], v[4:7]
	v_mfma_f32_16x16x32_bf16 v[0:3], v[220:223], v[204:207], v[0:3]
	s_barrier
	s_setprio 0
	s_add_i32 s68, 0, 0x18000
	v_add_u32_e32 v167, s68, v137
	ds_read_b128 v[128:131], v167
	ds_read_b128 v[132:135], v167 offset:1024
	ds_read_b128 v[154:157], v167 offset:2048
	ds_read_b128 v[168:171], v167 offset:3072
	s_add_u32 s30, s30, 0x80000
	s_addc_u32 s31, s31, 0
	s_mov_b32 m0, s42
	v_lshl_add_u64 v[208:209], s[30:31], 0, v[138:139]
	ds_read_b128 v[172:175], v163 offset:32768
	ds_read_b128 v[180:183], v163 offset:33792
	ds_read_b128 v[184:187], v163 offset:34816
	ds_read_b128 v[188:191], v163 offset:35840
	ds_read_b128 v[192:195], v163 offset:36864
	ds_read_b128 v[196:199], v163 offset:37888
	ds_read_b128 v[200:203], v163 offset:38912
	ds_read_b128 v[204:207], v163 offset:39936
	global_load_lds_dwordx4 v[208:209], off
	v_lshl_add_u64 v[208:209], s[30:31], 0, v[142:143]
	s_mov_b32 m0, s43
	s_nop 0
	global_load_lds_dwordx4 v[208:209], off
	s_add_i32 s30, 0, 0x1c000
	v_add_u32_e32 v167, s30, v137
	ds_read_b128 v[208:211], v167
	ds_read_b128 v[212:215], v167 offset:1024
	ds_read_b128 v[216:219], v167 offset:2048
	ds_read_b128 v[220:223], v167 offset:3072
	s_waitcnt lgkmcnt(0)
	s_waitcnt vmcnt(8)
	s_setprio 1
	s_barrier
	v_mfma_f32_16x16x32_bf16 v[124:127], v[128:131], v[172:175], v[124:127]
	v_mfma_f32_16x16x32_bf16 v[120:123], v[154:157], v[172:175], v[120:123]
	v_mfma_f32_16x16x32_bf16 v[108:111], v[128:131], v[184:187], v[108:111]
	v_mfma_f32_16x16x32_bf16 v[104:107], v[154:157], v[184:187], v[104:107]
	v_mfma_f32_16x16x32_bf16 v[92:95], v[128:131], v[192:195], v[92:95]
	v_mfma_f32_16x16x32_bf16 v[88:91], v[154:157], v[192:195], v[88:91]
	v_mfma_f32_16x16x32_bf16 v[76:79], v[128:131], v[200:203], v[76:79]
	v_mfma_f32_16x16x32_bf16 v[72:75], v[154:157], v[200:203], v[72:75]
	v_mfma_f32_16x16x32_bf16 v[124:127], v[132:135], v[180:183], v[124:127]
	v_mfma_f32_16x16x32_bf16 v[120:123], v[168:171], v[180:183], v[120:123]
	v_mfma_f32_16x16x32_bf16 v[108:111], v[132:135], v[188:191], v[108:111]
	v_mfma_f32_16x16x32_bf16 v[104:107], v[168:171], v[188:191], v[104:107]
	v_mfma_f32_16x16x32_bf16 v[92:95], v[132:135], v[196:199], v[92:95]
	v_mfma_f32_16x16x32_bf16 v[88:91], v[168:171], v[196:199], v[88:91]
	v_mfma_f32_16x16x32_bf16 v[76:79], v[132:135], v[204:207], v[76:79]
	v_mfma_f32_16x16x32_bf16 v[72:75], v[168:171], v[204:207], v[72:75]
	v_mfma_f32_16x16x32_bf16 v[116:119], v[208:211], v[172:175], v[116:119]
	v_mfma_f32_16x16x32_bf16 v[112:115], v[216:219], v[172:175], v[112:115]
	v_mfma_f32_16x16x32_bf16 v[100:103], v[208:211], v[184:187], v[100:103]
	v_mfma_f32_16x16x32_bf16 v[96:99], v[216:219], v[184:187], v[96:99]
	v_mfma_f32_16x16x32_bf16 v[84:87], v[208:211], v[192:195], v[84:87]
	v_mfma_f32_16x16x32_bf16 v[80:83], v[216:219], v[192:195], v[80:83]
	v_mfma_f32_16x16x32_bf16 v[68:71], v[208:211], v[200:203], v[68:71]
	v_mfma_f32_16x16x32_bf16 v[64:67], v[216:219], v[200:203], v[64:67]
	v_mfma_f32_16x16x32_bf16 v[116:119], v[212:215], v[180:183], v[116:119]
	v_mfma_f32_16x16x32_bf16 v[112:115], v[220:223], v[180:183], v[112:115]
	v_mfma_f32_16x16x32_bf16 v[100:103], v[212:215], v[188:191], v[100:103]
	v_mfma_f32_16x16x32_bf16 v[96:99], v[220:223], v[188:191], v[96:99]
	v_mfma_f32_16x16x32_bf16 v[84:87], v[212:215], v[196:199], v[84:87]
	v_mfma_f32_16x16x32_bf16 v[80:83], v[220:223], v[196:199], v[80:83]
	v_mfma_f32_16x16x32_bf16 v[68:71], v[212:215], v[204:207], v[68:71]
	v_mfma_f32_16x16x32_bf16 v[64:67], v[220:223], v[204:207], v[64:67]
	s_barrier
; #define PG8_STAGE(bufoff, gbase, voff) do { _Pragma("unroll") for (int _i = 0; _i < 2; ++_i) \
;         __builtin_amdgcn_global_load_lds((const unsigned*)((const char*)(gbase) + (voff)[_i]), (LAS unsigned*)(lds + (bufoff) + ldsw + _i * 8192), 16, 0, 0); } while (0)
; #define PG8_LDA(dst, b, h) do { _Pragma("unroll") for (int m = 0; m < 4; ++m) _Pragma("unroll") for (int k = 0; k < 2; ++k) dst[m][k] = *(const LAS bf16x8*)(lds + PG8_SA(b, h) + aoff + m * 2048 + k * 1024); } while (0)
; #define PG8_MMA(ai, bj, At, Bt) do { __builtin_amdgcn_s_setprio(1); _Pragma("unroll") for (int m = 0; m < 4; ++m) _Pragma("unroll") for (int n = 0; n < 2; ++n) _Pragma("unroll") for (int k = 0; k < 2; ++k) \
;         acc[ai][bj][m][n] = __builtin_amdgcn_mfma_f32_16x16x32_bf16(Bt[n][k], At[m][k], acc[ai][bj][m][n], 0, 0, 0); __builtin_amdgcn_s_setprio(0); } while (0)
; #define PG8_WAIT_V(n) asm volatile("s_waitcnt vmcnt(" #n ")" ::: "memory")
; #define PG8_WAIT_L(n) asm volatile("s_waitcnt lgkmcnt(" #n ")" ::: "memory")
; #define PG8_BAR __builtin_amdgcn_s_barrier()
; #define PG8_SCHED __builtin_amdgcn_sched_barrier(0)
; template <class Epi>
; __device__ __forceinline__ void gemm_phase(LAS unsigned char* lds, const Gemm g, const StaticOrder& S, const Epi& E) {
;     ...
;             PG8_LDA(At, 1, 1); PG8_STAGE(PG8_SA(1, 0), a3, voffA);
;             PG8_BAR; PG8_WAIT_L(0); PG8_MMA(1, 0, At, B0); PG8_BAR; PG8_SCHED;
;             PG8_STAGE(PG8_SB(1, 1), b3 + hstep, voffB);
;             PG8_WAIT_V(6); PG8_BAR; PG8_MMA(1, 1, At, B1); PG8_BAR;
;         }
	s_setprio 0
	s_add_i32 s31, s68, s36
	v_lshl_add_u64 v[158:159], v[158:159], 0, s[8:9]
	s_mov_b32 m0, s31
	s_nop 0
	global_load_lds_dwordx4 v[158:159], off
	v_lshl_add_u64 v[158:159], v[176:177], 0, s[8:9]
	s_add_i32 m0, s31, 0x2000
	s_nop 0
	global_load_lds_dwordx4 v[158:159], off
	s_mov_b32 m0, s57
	v_lshl_add_u64 v[158:159], v[224:225], 0, s[8:9]
	ds_read_b128 v[172:175], v163 offset:49152
	ds_read_b128 v[180:183], v163 offset:50176
	ds_read_b128 v[184:187], v163 offset:51200
	ds_read_b128 v[188:191], v163 offset:52224
	ds_read_b128 v[192:195], v163 offset:53248
	ds_read_b128 v[196:199], v163 offset:54272
	ds_read_b128 v[200:203], v163 offset:55296
	ds_read_b128 v[204:207], v163 offset:56320
	global_load_lds_dwordx4 v[158:159], off
	v_lshl_add_u64 v[158:159], v[226:227], 0, s[8:9]
	s_mov_b32 m0, s58
	s_nop 0
	global_load_lds_dwordx4 v[158:159], off
	s_add_u32 s24, s24, 0x80080
	s_addc_u32 s25, s25, 0
	s_add_i32 s30, s30, s36
	v_lshl_add_u64 v[252:253], s[24:25], 0, v[140:141]
	s_mov_b32 m0, s30
	s_nop 0
	global_load_lds_dwordx4 v[252:253], off
	v_lshl_add_u64 v[252:253], s[24:25], 0, v[144:145]
	s_add_i32 m0, s30, 0x2000
	s_nop 0
	global_load_lds_dwordx4 v[252:253], off
	s_waitcnt lgkmcnt(0)
	s_waitcnt vmcnt(8)
	s_setprio 1
	s_barrier
	v_mfma_f32_16x16x32_bf16 v[60:63], v[128:131], v[172:175], v[60:63]
	v_mfma_f32_16x16x32_bf16 v[56:59], v[154:157], v[172:175], v[56:59]
	v_mfma_f32_16x16x32_bf16 v[44:47], v[128:131], v[184:187], v[44:47]
	v_mfma_f32_16x16x32_bf16 v[40:43], v[154:157], v[184:187], v[40:43]
	v_mfma_f32_16x16x32_bf16 v[28:31], v[128:131], v[192:195], v[28:31]
	v_mfma_f32_16x16x32_bf16 v[24:27], v[154:157], v[192:195], v[24:27]
	v_mfma_f32_16x16x32_bf16 v[12:15], v[128:131], v[200:203], v[12:15]
	v_mfma_f32_16x16x32_bf16 v[8:11], v[154:157], v[200:203], v[8:11]
	v_mfma_f32_16x16x32_bf16 v[60:63], v[132:135], v[180:183], v[60:63]
	v_mfma_f32_16x16x32_bf16 v[56:59], v[168:171], v[180:183], v[56:59]
	v_mfma_f32_16x16x32_bf16 v[44:47], v[132:135], v[188:191], v[44:47]
	v_mfma_f32_16x16x32_bf16 v[40:43], v[168:171], v[188:191], v[40:43]
	v_mfma_f32_16x16x32_bf16 v[28:31], v[132:135], v[196:199], v[28:31]
	v_mfma_f32_16x16x32_bf16 v[24:27], v[168:171], v[196:199], v[24:27]
	v_mfma_f32_16x16x32_bf16 v[12:15], v[132:135], v[204:207], v[12:15]
	v_mfma_f32_16x16x32_bf16 v[8:11], v[168:171], v[204:207], v[8:11]
	v_mfma_f32_16x16x32_bf16 v[52:55], v[208:211], v[172:175], v[52:55]
	v_mfma_f32_16x16x32_bf16 v[48:51], v[216:219], v[172:175], v[48:51]
	v_mfma_f32_16x16x32_bf16 v[36:39], v[208:211], v[184:187], v[36:39]
	v_mfma_f32_16x16x32_bf16 v[32:35], v[216:219], v[184:187], v[32:35]
	v_mfma_f32_16x16x32_bf16 v[20:23], v[208:211], v[192:195], v[20:23]
	v_mfma_f32_16x16x32_bf16 v[16:19], v[216:219], v[192:195], v[16:19]
	v_mfma_f32_16x16x32_bf16 v[4:7], v[208:211], v[200:203], v[4:7]
	v_mfma_f32_16x16x32_bf16 v[0:3], v[216:219], v[200:203], v[0:3]
	v_mfma_f32_16x16x32_bf16 v[52:55], v[212:215], v[180:183], v[52:55]
	v_mfma_f32_16x16x32_bf16 v[48:51], v[220:223], v[180:183], v[48:51]
	v_mfma_f32_16x16x32_bf16 v[36:39], v[212:215], v[188:191], v[36:39]
	v_mfma_f32_16x16x32_bf16 v[32:35], v[220:223], v[188:191], v[32:35]
	v_mfma_f32_16x16x32_bf16 v[20:23], v[212:215], v[196:199], v[20:23]
	v_mfma_f32_16x16x32_bf16 v[16:19], v[220:223], v[196:199], v[16:19]
	v_mfma_f32_16x16x32_bf16 v[4:7], v[212:215], v[204:207], v[4:7]
	v_mfma_f32_16x16x32_bf16 v[0:3], v[220:223], v[204:207], v[0:3]
	s_barrier
	s_setprio 0
	s_add_i32 s67, s67, 2
	s_add_u32 s22, s22, 0x100
	s_addc_u32 s23, s23, 0
	s_add_u32 s65, s65, 0x100
	s_addc_u32 s66, s66, 0
	s_cmp_gt_u32 s67, 29
	s_cbranch_scc0 .LBB0_1220
; __device__ __forceinline__ float bflo(unsigned w) { return __uint_as_float(w << 16); }
; __device__ __forceinline__ float bfhi(unsigned w) { return __uint_as_float(w & 0xffff0000u); }
; #define ER_LOAD(g_, set_) do { const size_t off_ = (size_t)(row0 + ((g_) >> 2) * HALF + ((g_) & 3) * 16) * DM + col0; \
;         hv[set_][0] = *(const u32x4*)(HB + off_); hv[set_][1] = *(const u32x4*)(HB + off_ + HALF); } while (0)
;     __device__ __forceinline__ void operator()(const f32x4 (&acc)[2][2][4][2], const Unit& u, int wr, int wc, int fr, int fq, const Pre&) const {
;         const int row0 = ROW_X + u.pm * BM + wr * 64 + fr, col0 = u.pn * BM + wc * 32 + 8 * fq;
;         u32x4 hv[2][2]; float sprev = 0.f;
;     ...
;         ER_LOAD(0, 0);
; #pragma unroll
;         for (int g = 0; g < 8; ++g) { const int ai = g >> 2, m = g & 3; const int r = row0 + ai * HALF + m * 16; const size_t off = (size_t)r * DM + col0; float s = 0.f;
;             if (g + 1 < 8) ER_LOAD(g + 1, (g + 1) & 1);
; #pragma unroll
;             for (int bj = 0; bj < 2; ++bj) { const u32x4 w = hv[g & 1][bj];
;                 const f32x4 h0 = {bflo(w.x), bfhi(w.x), bflo(w.y), bfhi(w.y)}, h1 = {bflo(w.z), bfhi(w.z), bflo(w.w), bfhi(w.w)};
;                 const f32x4 o0 = h0 + acc[ai][bj][m][0] * alpha, o1 = h1 + acc[ai][bj][m][1] * alpha;
;                 if (FINAL) { float* op = OUT + (size_t)(r - ROW_X) * DM + col0 + bj * HALF; *(f32x4*)op = o0; *(f32x4*)(op + 4) = o1; }
;                 else { u32x4 q; q.x = cvtpk(o0[0], o0[1]); q.y = cvtpk(o0[2], o0[3]); q.z = cvtpk(o1[0], o1[1]); q.w = cvtpk(o1[2], o1[3]); *(u32x4*)(HB + off + bj * HALF) = q;
;                        s += ((o0[0] * o0[0] + o0[1] * o0[1]) + (o0[2] * o0[2] + o0[3] * o0[3])) + ((o1[0] * o1[0] + o1[1] * o1[1]) + (o1[2] * o1[2] + o1[3] * o1[3])); } }
;             if (!FINAL) { if (g > 0) { float t = sprev; t += __shfl_xor(t, 16); t += __shfl_xor(t, 32);
;                     if (fq == 0) __hip_atomic_fetch_add(ssq_out + row0 + ((g - 1) >> 2) * HALF + ((g - 1) & 3) * 16, t, __ATOMIC_RELAXED, __HIP_MEMORY_SCOPE_AGENT); }
;                 sprev = s; } }
;     ...
;         if (!FINAL) { float t = sprev; t += __shfl_xor(t, 16); t += __shfl_xor(t, 32);
;             if (fq == 0) __hip_atomic_fetch_add(ssq_out + row0 + HALF + 48, t, __ATOMIC_RELAXED, __HIP_MEMORY_SCOPE_AGENT); }
	v_lshl_add_u32 v156, s18, 8, v160
	v_lshl_or_b32 v154, s20, 8, v161
	v_ashrrev_i32_e32 v157, 31, v156
	v_ashrrev_i32_e32 v155, 31, v154
	v_lshlrev_b64 v[128:129], 12, v[156:157]
	v_lshl_add_u64 v[128:129], s[0:1], 0, v[128:129]
	v_lshlrev_b64 v[130:131], 1, v[154:155]
	v_lshl_add_u64 v[176:177], v[128:129], 0, v[130:131]
	v_or_b32_e32 v128, 16, v156
	v_ashrrev_i32_e32 v129, 31, v128
	global_load_dwordx4 v[168:171], v[176:177], off
	global_load_dwordx4 v[172:175], v[176:177], off offset:256
	v_lshlrev_b64 v[128:129], 12, v[128:129]
	v_lshl_add_u64 v[128:129], s[0:1], 0, v[128:129]
	v_lshl_add_u64 v[188:189], v[128:129], 0, v[130:131]
	global_load_dwordx4 v[180:183], v[188:189], off
	global_load_dwordx4 v[184:187], v[188:189], off offset:256
	v_or_b32_e32 v128, 32, v156
	v_ashrrev_i32_e32 v129, 31, v128
	v_lshlrev_b64 v[128:129], 12, v[128:129]
	v_lshl_add_u64 v[128:129], s[0:1], 0, v[128:129]
	v_lshl_add_u64 v[158:159], v[128:129], 0, v[130:131]
	global_load_dwordx4 v[132:135], v[158:159], off
	global_load_dwordx4 v[128:131], v[158:159], off offset:256
	s_waitcnt vmcnt(0)
	v_lshlrev_b32_e32 v190, 16, v168
	v_and_b32_e32 v191, 0xffff0000, v168
	v_lshlrev_b32_e32 v168, 16, v169
	v_and_b32_e32 v169, 0xffff0000, v169
	v_lshlrev_b32_e32 v192, 16, v170
	v_and_b32_e32 v193, 0xffff0000, v170
	v_lshlrev_b32_e32 v170, 16, v171
	v_and_b32_e32 v171, 0xffff0000, v171
	v_lshlrev_b32_e32 v194, 16, v172
	v_and_b32_e32 v195, 0xffff0000, v172
	v_lshlrev_b32_e32 v172, 16, v173
	v_and_b32_e32 v173, 0xffff0000, v173
	v_lshlrev_b32_e32 v196, 16, v174
	v_and_b32_e32 v197, 0xffff0000, v174
	v_lshlrev_b32_e32 v174, 16, v175
	v_and_b32_e32 v175, 0xffff0000, v175
	v_pk_add_f32 v[126:127], v[126:127], v[168:169]
	v_pk_add_f32 v[124:125], v[124:125], v[190:191]
	v_pk_add_f32 v[122:123], v[122:123], v[170:171]
	v_pk_add_f32 v[168:169], v[120:121], v[192:193]
	v_pk_add_f32 v[170:171], v[118:119], v[172:173]
	v_pk_add_f32 v[172:173], v[116:117], v[194:195]
	v_pk_add_f32 v[174:175], v[114:115], v[174:175]
	v_pk_add_f32 v[190:191], v[112:113], v[196:197]
	v_cvt_pk_bf16_f32 v114, v124, v125
	v_cvt_pk_bf16_f32 v115, v126, v127
	v_cvt_pk_bf16_f32 v116, v168, v169
	v_cvt_pk_bf16_f32 v117, v122, v123
	v_mul_f32_e32 v125, v125, v125
	v_mul_f32_e32 v127, v127, v127
	v_mul_f32_e32 v167, v169, v169
	v_mul_f32_e32 v123, v123, v123
	v_cvt_pk_bf16_f32 v118, v172, v173
	v_cvt_pk_bf16_f32 v119, v170, v171
	v_cvt_pk_bf16_f32 v121, v174, v175
	v_mul_f32_e32 v169, v173, v173
	v_mul_f32_e32 v171, v171, v171
	v_mul_f32_e32 v173, v191, v191
	v_mul_f32_e32 v175, v175, v175
	v_lshlrev_b32_e32 v112, 16, v180
	v_and_b32_e32 v113, 0xffff0000, v180
	v_lshlrev_b32_e32 v192, 16, v182
	v_and_b32_e32 v193, 0xffff0000, v182
	v_lshlrev_b32_e32 v182, 16, v183
	v_and_b32_e32 v183, 0xffff0000, v183
	v_fmac_f32_e32 v125, v124, v124
	v_fmac_f32_e32 v127, v126, v126
	v_fmac_f32_e32 v167, v168, v168
	v_fmac_f32_e32 v123, v122, v122
	v_fmac_f32_e32 v169, v172, v172
	v_fmac_f32_e32 v171, v170, v170
	v_fmac_f32_e32 v173, v190, v190
	v_fmac_f32_e32 v175, v174, v174
	v_lshlrev_b32_e32 v180, 16, v181
	v_and_b32_e32 v181, 0xffff0000, v181
	v_pk_add_f32 v[112:113], v[108:109], v[112:113]
	v_pk_add_f32 v[108:109], v[106:107], v[182:183]
	global_store_dwordx4 v[176:177], v[114:117], off
	v_add_f32_e32 v106, v125, v127
	v_add_f32_e32 v107, v167, v123
	v_add_f32_e32 v114, v169, v171
	v_add_f32_e32 v115, v173, v175
	v_pk_add_f32 v[110:111], v[110:111], v[180:181]
	v_add_f32_e32 v106, v106, v107
	v_add_f32_e32 v107, v114, v115
	v_pk_add_f32 v[114:115], v[104:105], v[192:193]
	v_add_f32_e32 v125, v106, v107
	v_cvt_pk_bf16_f32 v104, v112, v113
	v_cvt_pk_bf16_f32 v105, v110, v111
	v_cvt_pk_bf16_f32 v106, v114, v115
	v_cvt_pk_bf16_f32 v107, v108, v109
	v_cvt_pk_bf16_f32 v120, v190, v191
	global_store_dwordx4 v[188:189], v[104:107], off
	global_store_dwordx4 v[176:177], v[118:121], off offset:256
	v_lshlrev_b32_e32 v122, 16, v186
	v_lshlrev_b32_e32 v104, 16, v184
	v_and_b32_e32 v105, 0xffff0000, v184
	v_pk_add_f32 v[118:119], v[100:101], v[104:105]
	v_and_b32_e32 v101, 64, v166
	v_xor_b32_e32 v100, 16, v166
	v_add_u32_e32 v101, 64, v101
	v_cmp_lt_i32_e32 vcc, v100, v101
	v_and_b32_e32 v123, 0xffff0000, v186
	v_pk_add_f32 v[122:123], v[96:97], v[122:123]
	v_cndmask_b32_e32 v100, v166, v100, vcc
	v_lshlrev_b32_e32 v124, 2, v100
	ds_bpermute_b32 v100, v124, v125
	v_xor_b32_e32 v97, 32, v166
	v_cmp_lt_i32_e32 vcc, v97, v101
	v_lshlrev_b32_e32 v106, 16, v185
	v_and_b32_e32 v107, 0xffff0000, v185
	v_cndmask_b32_e32 v97, v166, v97, vcc
	s_waitcnt lgkmcnt(0)
	v_add_f32_e32 v96, v125, v100
	v_lshlrev_b32_e32 v125, 2, v97
	ds_bpermute_b32 v97, v125, v96
	v_lshlrev_b32_e32 v120, 16, v187
	v_and_b32_e32 v121, 0xffff0000, v187
	v_pk_add_f32 v[116:117], v[102:103], v[106:107]
	v_pk_add_f32 v[120:121], v[98:99], v[120:121]
	v_cvt_pk_bf16_f32 v98, v118, v119
	v_cvt_pk_bf16_f32 v99, v116, v117
	v_cvt_pk_bf16_f32 v100, v122, v123
	v_cvt_pk_bf16_f32 v101, v120, v121
	v_lshl_add_u64 v[104:105], v[156:157], 2, s[6:7]
	global_store_dwordx4 v[188:189], v[98:101], off offset:256
	s_and_saveexec_b64 s[18:19], s[2:3]
	s_cbranch_execz .LBB0_1223
	s_waitcnt lgkmcnt(0)
	v_add_f32_e32 v96, v96, v97
	global_atomic_add_f32 v[104:105], v96, off

; #define PG8_STAGE(bufoff, gbase, voff) do { _Pragma("unroll") for (int _i = 0; _i < 2; ++_i) \
;         __builtin_amdgcn_global_load_lds((const unsigned*)((const char*)(gbase) + (voff)[_i]), (LAS unsigned*)(lds + (bufoff) + ldsw + _i * 8192), 16, 0, 0); } while (0)
; #define PG8_WAIT_V(n) asm volatile("s_waitcnt vmcnt(" #n ")" ::: "memory")
; #define PG8_BAR __builtin_amdgcn_s_barrier()
; template <class Epi>
; __device__ __forceinline__ void gemm_phase(LAS unsigned char* lds, const Gemm g, const StaticOrder& S, const Epi& E) {
;     const int tid = threadIdx.x, wid = __builtin_amdgcn_readfirstlane(tid >> 6), lane = tid & 63, wr = wid >> 2, wc = wid & 3, fr = lane & 15, fq = lane >> 4;
;     const int K = g.K, nt = K / BK;
;     unsigned voffA[2], voffB[2];
; #pragma unroll
;     for (int i = 0; i < 2; ++i) { int R, C; stage_rc(tid * 16 + i * 8192, R, C); const int Rb = Epi::PERM ? ((R & ~31) + perm32(R & 31)) : R;
;         voffA[i] = (unsigned)(R * K + C) * 2u; voffB[i] = (unsigned)(Rb * K + C) * 2u; }
;     const size_t kstep = (size_t)(BK * 2);
;     const size_t hstep = (size_t)HALF * K * 2;
;     const size_t tstep = 2 * hstep;
;     const unsigned ldsw = (unsigned)wid * 1024u;
;     const int aoff = lds_byte(wr * 64 + fr, fq * 8), boff = lds_byte(wc * 32 + fr, fq * 8);
;     ...
;     Unit cur, nxt; int ui = 0;
;     if (!S.next(0, cur)) return;
;     f32x4 acc[2][2][4][2];
; #pragma unroll
;     for (int a = 0; a < 2; ++a)
; #pragma unroll
;         for (int b = 0; b < 2; ++b)
; #pragma unroll
;             for (int m = 0; m < 4; ++m)
; #pragma unroll
;                 for (int n = 0; n < 2; ++n) acc[a][b][m][n] = (f32x4){0.f, 0.f, 0.f, 0.f};
;     bf16x8 At[4][2], B0[2][2], B1[2][2];
;     const char* cA = (const char*)g.A + (size_t)cur.pm * tstep; const char* cB = (const char*)g.Bt + (size_t)cur.pn * tstep;
;     typename Epi::Pre pre = E.pre(cur, wr, fr);
;     PG8_STAGE(PG8_SB(0, 0), cB, voffB); PG8_STAGE(PG8_SA(0, 0), cA, voffA); PG8_STAGE(PG8_SB(0, 1), cB + hstep, voffB); PG8_STAGE(PG8_SA(0, 1), cA + hstep, voffA);
;     if (wr == 1) PG8_BAR;
;     PG8_WAIT_V(4); PG8_BAR;
;     PG8_STAGE(PG8_SB(1, 0), cB + kstep, voffB); PG8_STAGE(PG8_SA(1, 0), cA + kstep, voffA); PG8_STAGE(PG8_SB(1, 1), cB + hstep + kstep, voffB);
;     PG8_WAIT_V(6); PG8_BAR;
.LBB0_1301:
	s_lshl_b32 s4, s4, 5
	s_lshl_b32 s7, s5, 13
	s_and_b32 s10, s4, 0x60
	s_mov_b64 s[4:5], 0x80
	s_add_i32 m0, s35, 0x18000
	v_lshl_add_u64 v[6:7], v[6:7], 0, s[4:5]
	s_lshl_b32 s11, s10, 7
	s_waitcnt vmcnt(2)
	s_barrier
	global_load_lds_dwordx4 v[6:7], off
	v_lshl_add_u64 v[4:5], v[4:5], 0, s[4:5]
	s_add_i32 m0, s35, 0x1a000
	s_add_i32 s42, s35, 0x8000
	s_add_i32 s43, s35, 0xa000
	global_load_lds_dwordx4 v[4:5], off
	v_lshl_add_u64 v[2:3], v[2:3], 0, s[4:5]
	s_mov_b32 m0, s42
	s_add_u32 s8, s18, 0x80080
	global_load_lds_dwordx4 v[2:3], off
	v_lshl_add_u64 v[0:1], v[0:1], 0, s[4:5]
	s_mov_b32 m0, s43
	s_addc_u32 s9, s19, 0
	global_load_lds_dwordx4 v[0:1], off
	s_add_i32 m0, s35, 0x1c000
	v_lshl_add_u64 v[0:1], s[8:9], 0, v[132:133]
	global_load_lds_dwordx4 v[0:1], off
	v_lshl_add_u64 v[0:1], s[8:9], 0, v[128:129]
	s_add_i32 m0, s35, 0x1e000
	s_sext_i32_i16 s15, s6
	global_load_lds_dwordx4 v[0:1], off
	v_lshlrev_b32_e32 v0, 6, v13
	v_lshlrev_b32_e32 v1, 1, v11
	s_movk_i32 s6, 0x3c0
	v_lshlrev_b32_e32 v2, 2, v13
	v_and_or_b32 v0, v0, s6, v1
	v_and_b32_e32 v2, 32, v2
	v_bitop3_b32 v0, v0, s7, v2 bitop3:0xde
	v_lshlrev_b32_e32 v2, 6, v178
	v_and_or_b32 v1, v2, s6, v1
	v_lshlrev_b32_e32 v2, 2, v178
	v_and_b32_e32 v2, 32, v2
	v_bitop3_b32 v147, s11, v1, v2 bitop3:0xf6
	v_lshlrev_b32_e32 v1, 9, v178
	v_and_b32_e32 v1, 0x70000, v1
	v_lshlrev_b32_e32 v2, 12, v12
	v_or3_b32 v1, v9, v1, v2
	v_add_u32_e32 v138, v1, v10
	v_lshlrev_b32_e32 v1, 5, v8
	s_waitcnt vmcnt(6)
	v_and_b32_e32 v1, 0xf0000, v1
	v_or3_b32 v1, v9, v1, v2
	s_add_i32 s58, 0, 0x10000
	s_add_i32 s59, 0, 0x14000
	s_ashr_i32 s56, s54, 31
	s_mov_b32 s57, s54
	v_or_b32_e32 v148, s10, v11
	v_mov_b32_e32 v139, v133
	v_add_u32_e32 v140, v1, v10
	v_mov_b32_e32 v141, v133
	v_mov_b64_e32 v[142:143], 0xac0
	v_mov_b64_e32 v[144:145], 0xabf
	s_waitcnt vmcnt(0)
	v_add_u32_e32 v149, s58, v147
	v_add_u32_e32 v150, 0, v0
	v_add_u32_e32 v152, s59, v147
	v_mov_b32_e32 v153, 0x358637bd
	s_movk_i32 s60, 0x2b00
	s_barrier
	s_branch .LBB0_1303

; #define PG8_STAGE(bufoff, gbase, voff) do { _Pragma("unroll") for (int _i = 0; _i < 2; ++_i) \
;         __builtin_amdgcn_global_load_lds((const unsigned*)((const char*)(gbase) + (voff)[_i]), (LAS unsigned*)(lds + (bufoff) + ldsw + _i * 8192), 16, 0, 0); } while (0)
; #define PG8_LDA(dst, b, h) do { _Pragma("unroll") for (int m = 0; m < 4; ++m) _Pragma("unroll") for (int k = 0; k < 2; ++k) dst[m][k] = *(const LAS bf16x8*)(lds + PG8_SA(b, h) + aoff + m * 2048 + k * 1024); } while (0)
; #define PG8_LDB(dst, b, h) do { _Pragma("unroll") for (int n = 0; n < 2; ++n) _Pragma("unroll") for (int k = 0; k < 2; ++k) dst[n][k] = *(const LAS bf16x8*)(lds + PG8_SB(b, h) + boff + n * 2048 + k * 1024); } while (0)
; #define PG8_MMA(ai, bj, At, Bt) do { __builtin_amdgcn_s_setprio(1); _Pragma("unroll") for (int m = 0; m < 4; ++m) _Pragma("unroll") for (int n = 0; n < 2; ++n) _Pragma("unroll") for (int k = 0; k < 2; ++k) \
;         acc[ai][bj][m][n] = __builtin_amdgcn_mfma_f32_16x16x32_bf16(Bt[n][k], At[m][k], acc[ai][bj][m][n], 0, 0, 0); __builtin_amdgcn_s_setprio(0); } while (0)
; #define PG8_WAIT_V(n) asm volatile("s_waitcnt vmcnt(" #n ")" ::: "memory")
; #define PG8_WAIT_L(n) asm volatile("s_waitcnt lgkmcnt(" #n ")" ::: "memory")
; #define PG8_BAR __builtin_amdgcn_s_barrier()
; #define PG8_SCHED __builtin_amdgcn_sched_barrier(0)
; template <class Epi>
; __device__ __forceinline__ void gemm_phase(LAS unsigned char* lds, const Gemm g, const StaticOrder& S, const Epi& E) {
;     ...
;             const char* a2 = last ? nA : cA + (size_t)(t + 2) * kstep; const char* b2 = last ? nB : cB + (size_t)(t + 2) * kstep;
;             const char* a3 = a2 + kstep; const char* b3 = b2 + kstep;
;             PG8_LDB(B0, 0, 0); PG8_SCHED; PG8_LDA(At, 0, 0); PG8_STAGE(PG8_SA(1, 1), a1 + hstep, voffA);
;             PG8_WAIT_L(8); PG8_BAR; PG8_WAIT_L(0); PG8_MMA(0, 0, At, B0); PG8_BAR; PG8_SCHED;
;             PG8_LDB(B1, 0, 1); PG8_STAGE(PG8_SB(0, 0), b2, voffB);
;             PG8_BAR; PG8_WAIT_L(0); PG8_MMA(0, 1, At, B1); PG8_BAR;
;             PG8_LDA(At, 0, 1); PG8_STAGE(PG8_SA(0, 0), a2, voffA);
;             PG8_BAR; PG8_WAIT_L(0); PG8_MMA(1, 0, At, B0); PG8_BAR; PG8_SCHED;
;             PG8_STAGE(PG8_SB(0, 1), b2 + hstep, voffB);
;             PG8_WAIT_V(6); PG8_BAR; PG8_MMA(1, 1, At, B1); PG8_BAR;
.LBB0_1306:
	ds_read_b128 v[166:169], v149
	ds_read_b128 v[170:173], v149 offset:1024
	ds_read_b128 v[174:177], v149 offset:2048
	ds_read_b128 v[180:183], v149 offset:3072
	s_add_u32 s18, s16, 0xfff80080
	s_addc_u32 s19, s17, -1
	s_cmp_eq_u32 s65, 28
	s_cselect_b32 s21, s9, s19
	s_cselect_b32 s20, s61, s18
	s_cselect_b32 s19, s7, s64
	s_cselect_b32 s18, s62, s63
	v_lshl_add_u64 v[162:163], s[16:17], 0, v[138:139]
	s_add_i32 m0, s35, 0xc000
	ds_read_b128 v[184:187], v150
	ds_read_b128 v[188:191], v150 offset:1024
	ds_read_b128 v[192:195], v150 offset:2048
	ds_read_b128 v[196:199], v150 offset:3072
	ds_read_b128 v[200:203], v150 offset:4096
	ds_read_b128 v[204:207], v150 offset:5120
	ds_read_b128 v[208:211], v150 offset:6144
	ds_read_b128 v[212:215], v150 offset:7168
	global_load_lds_dwordx4 v[162:163], off
	v_lshl_add_u64 v[162:163], s[16:17], 0, v[140:141]
	s_add_i32 m0, s35, 0xe000
	s_nop 0
	global_load_lds_dwordx4 v[162:163], off
	ds_read_b128 v[216:219], v152
	ds_read_b128 v[220:223], v152 offset:1024
	ds_read_b128 v[224:227], v152 offset:2048
	ds_read_b128 v[228:231], v152 offset:3072
	s_waitcnt lgkmcnt(0)
	s_waitcnt vmcnt(8)
	s_setprio 1
	s_barrier
	v_mfma_f32_16x16x32_bf16 v[124:127], v[166:169], v[184:187], v[124:127]
	v_mfma_f32_16x16x32_bf16 v[116:119], v[174:177], v[184:187], v[116:119]
	v_mfma_f32_16x16x32_bf16 v[108:111], v[166:169], v[192:195], v[108:111]
	v_mfma_f32_16x16x32_bf16 v[100:103], v[174:177], v[192:195], v[100:103]
	v_mfma_f32_16x16x32_bf16 v[92:95], v[166:169], v[200:203], v[92:95]
	v_mfma_f32_16x16x32_bf16 v[84:87], v[174:177], v[200:203], v[84:87]
	v_mfma_f32_16x16x32_bf16 v[76:79], v[166:169], v[208:211], v[76:79]
	v_mfma_f32_16x16x32_bf16 v[68:71], v[174:177], v[208:211], v[68:71]
	v_mfma_f32_16x16x32_bf16 v[124:127], v[170:173], v[188:191], v[124:127]
	v_mfma_f32_16x16x32_bf16 v[116:119], v[180:183], v[188:191], v[116:119]
	v_mfma_f32_16x16x32_bf16 v[108:111], v[170:173], v[196:199], v[108:111]
	v_mfma_f32_16x16x32_bf16 v[100:103], v[180:183], v[196:199], v[100:103]
	v_mfma_f32_16x16x32_bf16 v[92:95], v[170:173], v[204:207], v[92:95]
	v_mfma_f32_16x16x32_bf16 v[84:87], v[180:183], v[204:207], v[84:87]
	v_mfma_f32_16x16x32_bf16 v[76:79], v[170:173], v[212:215], v[76:79]
	v_mfma_f32_16x16x32_bf16 v[68:71], v[180:183], v[212:215], v[68:71]
	v_mfma_f32_16x16x32_bf16 v[120:123], v[216:219], v[184:187], v[120:123]
	v_mfma_f32_16x16x32_bf16 v[112:115], v[224:227], v[184:187], v[112:115]
	v_mfma_f32_16x16x32_bf16 v[104:107], v[216:219], v[192:195], v[104:107]
	v_mfma_f32_16x16x32_bf16 v[96:99], v[224:227], v[192:195], v[96:99]
	v_mfma_f32_16x16x32_bf16 v[88:91], v[216:219], v[200:203], v[88:91]
	v_mfma_f32_16x16x32_bf16 v[80:83], v[224:227], v[200:203], v[80:83]
	v_mfma_f32_16x16x32_bf16 v[72:75], v[216:219], v[208:211], v[72:75]
	v_mfma_f32_16x16x32_bf16 v[64:67], v[224:227], v[208:211], v[64:67]
	v_mfma_f32_16x16x32_bf16 v[120:123], v[220:223], v[188:191], v[120:123]
	v_mfma_f32_16x16x32_bf16 v[112:115], v[228:231], v[188:191], v[112:115]
	v_mfma_f32_16x16x32_bf16 v[104:107], v[220:223], v[196:199], v[104:107]
	v_mfma_f32_16x16x32_bf16 v[96:99], v[228:231], v[196:199], v[96:99]
	v_mfma_f32_16x16x32_bf16 v[88:91], v[220:223], v[204:207], v[88:91]
	v_mfma_f32_16x16x32_bf16 v[80:83], v[228:231], v[204:207], v[80:83]
	v_mfma_f32_16x16x32_bf16 v[72:75], v[220:223], v[212:215], v[72:75]
	v_mfma_f32_16x16x32_bf16 v[64:67], v[228:231], v[212:215], v[64:67]
	s_barrier
	s_setprio 0
	s_add_i32 s66, s58, s31
	v_lshl_add_u64 v[162:163], s[18:19], 0, v[132:133]
	s_mov_b32 m0, s66
	s_nop 0
	global_load_lds_dwordx4 v[162:163], off
	v_lshl_add_u64 v[232:233], s[18:19], 0, v[128:129]
	s_add_i32 m0, s66, 0x2000
	s_nop 0
	global_load_lds_dwordx4 v[232:233], off
	s_mov_b32 m0, s35
	v_lshl_add_u64 v[234:235], s[20:21], 0, v[134:135]
	ds_read_b128 v[184:187], v150 offset:16384
	ds_read_b128 v[188:191], v150 offset:17408
	ds_read_b128 v[192:195], v150 offset:18432
	ds_read_b128 v[196:199], v150 offset:19456
	ds_read_b128 v[200:203], v150 offset:20480
	ds_read_b128 v[204:207], v150 offset:21504
	ds_read_b128 v[208:211], v150 offset:22528
	ds_read_b128 v[212:215], v150 offset:23552
	global_load_lds_dwordx4 v[234:235], off
	v_lshl_add_u64 v[236:237], s[20:21], 0, v[130:131]
	s_mov_b32 m0, s36
	s_nop 0
	global_load_lds_dwordx4 v[236:237], off
	s_add_u32 s66, s18, 0x80000
	s_addc_u32 s67, s19, 0
	s_add_i32 s68, s59, s31
	v_lshl_add_u64 v[252:253], s[66:67], 0, v[132:133]
	s_mov_b32 m0, s68
	s_nop 0
	global_load_lds_dwordx4 v[252:253], off
	v_lshl_add_u64 v[252:253], s[66:67], 0, v[128:129]
	s_add_i32 m0, s68, 0x2000
	s_nop 0
	global_load_lds_dwordx4 v[252:253], off
	s_waitcnt lgkmcnt(0)
	s_waitcnt vmcnt(8)
	s_setprio 1
	s_barrier
; #define PG8_STAGE(bufoff, gbase, voff) do { _Pragma("unroll") for (int _i = 0; _i < 2; ++_i) \
;         __builtin_amdgcn_global_load_lds((const unsigned*)((const char*)(gbase) + (voff)[_i]), (LAS unsigned*)(lds + (bufoff) + ldsw + _i * 8192), 16, 0, 0); } while (0)
; #define PG8_LDA(dst, b, h) do { _Pragma("unroll") for (int m = 0; m < 4; ++m) _Pragma("unroll") for (int k = 0; k < 2; ++k) dst[m][k] = *(const LAS bf16x8*)(lds + PG8_SA(b, h) + aoff + m * 2048 + k * 1024); } while (0)
; #define PG8_LDB(dst, b, h) do { _Pragma("unroll") for (int n = 0; n < 2; ++n) _Pragma("unroll") for (int k = 0; k < 2; ++k) dst[n][k] = *(const LAS bf16x8*)(lds + PG8_SB(b, h) + boff + n * 2048 + k * 1024); } while (0)
; #define PG8_MMA(ai, bj, At, Bt) do { __builtin_amdgcn_s_setprio(1); _Pragma("unroll") for (int m = 0; m < 4; ++m) _Pragma("unroll") for (int n = 0; n < 2; ++n) _Pragma("unroll") for (int k = 0; k < 2; ++k) \
;         acc[ai][bj][m][n] = __builtin_amdgcn_mfma_f32_16x16x32_bf16(Bt[n][k], At[m][k], acc[ai][bj][m][n], 0, 0, 0); __builtin_amdgcn_s_setprio(0); } while (0)
; #define PG8_WAIT_V(n) asm volatile("s_waitcnt vmcnt(" #n ")" ::: "memory")
; #define PG8_WAIT_L(n) asm volatile("s_waitcnt lgkmcnt(" #n ")" ::: "memory")
; #define PG8_BAR __builtin_amdgcn_s_barrier()
; #define PG8_SCHED __builtin_amdgcn_sched_barrier(0)
; template <class Epi>
; __device__ __forceinline__ void gemm_phase(LAS unsigned char* lds, const Gemm g, const StaticOrder& S, const Epi& E) {
;     ...
;             PG8_LDA(At, 0, 1); PG8_STAGE(PG8_SA(0, 0), a2, voffA);
;             PG8_BAR; PG8_WAIT_L(0); PG8_MMA(1, 0, At, B0); PG8_BAR; PG8_SCHED;
;             PG8_STAGE(PG8_SB(0, 1), b2 + hstep, voffB);
;             PG8_WAIT_V(6); PG8_BAR; PG8_MMA(1, 1, At, B1); PG8_BAR;
;             PG8_LDB(B0, 1, 0); PG8_SCHED; PG8_LDA(At, 1, 0); PG8_STAGE(PG8_SA(0, 1), a2 + hstep, voffA);
;             PG8_WAIT_L(8); PG8_BAR; PG8_WAIT_L(0); PG8_MMA(0, 0, At, B0); PG8_BAR; PG8_SCHED;
;             PG8_LDB(B1, 1, 1); PG8_STAGE(PG8_SB(1, 0), b3, voffB);
;             PG8_BAR; PG8_WAIT_L(0); PG8_MMA(0, 1, At, B1); PG8_BAR;
	v_mfma_f32_16x16x32_bf16 v[60:63], v[166:169], v[184:187], v[60:63]
	v_mfma_f32_16x16x32_bf16 v[52:55], v[174:177], v[184:187], v[52:55]
	v_mfma_f32_16x16x32_bf16 v[44:47], v[166:169], v[192:195], v[44:47]
	v_mfma_f32_16x16x32_bf16 v[36:39], v[174:177], v[192:195], v[36:39]
	v_mfma_f32_16x16x32_bf16 v[28:31], v[166:169], v[200:203], v[28:31]
	v_mfma_f32_16x16x32_bf16 v[20:23], v[174:177], v[200:203], v[20:23]
	v_mfma_f32_16x16x32_bf16 v[12:15], v[166:169], v[208:211], v[12:15]
	v_mfma_f32_16x16x32_bf16 v[4:7], v[174:177], v[208:211], v[4:7]
	v_mfma_f32_16x16x32_bf16 v[60:63], v[170:173], v[188:191], v[60:63]
	v_mfma_f32_16x16x32_bf16 v[52:55], v[180:183], v[188:191], v[52:55]
	v_mfma_f32_16x16x32_bf16 v[44:47], v[170:173], v[196:199], v[44:47]
	v_mfma_f32_16x16x32_bf16 v[36:39], v[180:183], v[196:199], v[36:39]
	v_mfma_f32_16x16x32_bf16 v[28:31], v[170:173], v[204:207], v[28:31]
	v_mfma_f32_16x16x32_bf16 v[20:23], v[180:183], v[204:207], v[20:23]
	v_mfma_f32_16x16x32_bf16 v[12:15], v[170:173], v[212:215], v[12:15]
	v_mfma_f32_16x16x32_bf16 v[4:7], v[180:183], v[212:215], v[4:7]
	v_mfma_f32_16x16x32_bf16 v[56:59], v[216:219], v[184:187], v[56:59]
	v_mfma_f32_16x16x32_bf16 v[48:51], v[224:227], v[184:187], v[48:51]
	v_mfma_f32_16x16x32_bf16 v[40:43], v[216:219], v[192:195], v[40:43]
	v_mfma_f32_16x16x32_bf16 v[32:35], v[224:227], v[192:195], v[32:35]
	v_mfma_f32_16x16x32_bf16 v[24:27], v[216:219], v[200:203], v[24:27]
	v_mfma_f32_16x16x32_bf16 v[16:19], v[224:227], v[200:203], v[16:19]
	v_mfma_f32_16x16x32_bf16 v[8:11], v[216:219], v[208:211], v[8:11]
	v_mfma_f32_16x16x32_bf16 v[0:3], v[224:227], v[208:211], v[0:3]
	v_mfma_f32_16x16x32_bf16 v[56:59], v[220:223], v[188:191], v[56:59]
	v_mfma_f32_16x16x32_bf16 v[48:51], v[228:231], v[188:191], v[48:51]
	v_mfma_f32_16x16x32_bf16 v[40:43], v[220:223], v[196:199], v[40:43]
	v_mfma_f32_16x16x32_bf16 v[32:35], v[228:231], v[196:199], v[32:35]
	v_mfma_f32_16x16x32_bf16 v[24:27], v[220:223], v[204:207], v[24:27]
	v_mfma_f32_16x16x32_bf16 v[16:19], v[228:231], v[204:207], v[16:19]
	v_mfma_f32_16x16x32_bf16 v[8:11], v[220:223], v[212:215], v[8:11]
	v_mfma_f32_16x16x32_bf16 v[0:3], v[228:231], v[212:215], v[0:3]
	s_barrier
	s_setprio 0
	s_add_i32 s66, 0, 0x18000
	v_add_u32_e32 v161, s66, v147
	ds_read_b128 v[166:169], v161
	ds_read_b128 v[170:173], v161 offset:1024
	ds_read_b128 v[174:177], v161 offset:2048
	ds_read_b128 v[180:183], v161 offset:3072
	s_add_u32 s20, s20, 0x80000
	s_addc_u32 s21, s21, 0
	s_mov_b32 m0, s37
	v_lshl_add_u64 v[216:217], s[20:21], 0, v[134:135]
	ds_read_b128 v[184:187], v150 offset:32768
	ds_read_b128 v[188:191], v150 offset:33792
	ds_read_b128 v[192:195], v150 offset:34816
	ds_read_b128 v[196:199], v150 offset:35840
	ds_read_b128 v[200:203], v150 offset:36864
	ds_read_b128 v[204:207], v150 offset:37888
	ds_read_b128 v[208:211], v150 offset:38912
	ds_read_b128 v[212:215], v150 offset:39936
	global_load_lds_dwordx4 v[216:217], off
	v_lshl_add_u64 v[216:217], s[20:21], 0, v[130:131]
	s_mov_b32 m0, s38
	s_nop 0
	global_load_lds_dwordx4 v[216:217], off
	s_add_i32 s20, 0, 0x1c000
	v_add_u32_e32 v161, s20, v147
	ds_read_b128 v[216:219], v161
	ds_read_b128 v[220:223], v161 offset:1024
	ds_read_b128 v[224:227], v161 offset:2048
	ds_read_b128 v[228:231], v161 offset:3072
	s_waitcnt lgkmcnt(0)
	s_waitcnt vmcnt(8)
	s_setprio 1
	s_barrier
	v_mfma_f32_16x16x32_bf16 v[124:127], v[166:169], v[184:187], v[124:127]
	v_mfma_f32_16x16x32_bf16 v[116:119], v[174:177], v[184:187], v[116:119]
	v_mfma_f32_16x16x32_bf16 v[108:111], v[166:169], v[192:195], v[108:111]
	v_mfma_f32_16x16x32_bf16 v[100:103], v[174:177], v[192:195], v[100:103]
	v_mfma_f32_16x16x32_bf16 v[92:95], v[166:169], v[200:203], v[92:95]
	v_mfma_f32_16x16x32_bf16 v[84:87], v[174:177], v[200:203], v[84:87]
	v_mfma_f32_16x16x32_bf16 v[76:79], v[166:169], v[208:211], v[76:79]
	v_mfma_f32_16x16x32_bf16 v[68:71], v[174:177], v[208:211], v[68:71]
	v_mfma_f32_16x16x32_bf16 v[124:127], v[170:173], v[188:191], v[124:127]
	v_mfma_f32_16x16x32_bf16 v[116:119], v[180:183], v[188:191], v[116:119]
	v_mfma_f32_16x16x32_bf16 v[108:111], v[170:173], v[196:199], v[108:111]
	v_mfma_f32_16x16x32_bf16 v[100:103], v[180:183], v[196:199], v[100:103]
	v_mfma_f32_16x16x32_bf16 v[92:95], v[170:173], v[204:207], v[92:95]
	v_mfma_f32_16x16x32_bf16 v[84:87], v[180:183], v[204:207], v[84:87]
	v_mfma_f32_16x16x32_bf16 v[76:79], v[170:173], v[212:215], v[76:79]
	v_mfma_f32_16x16x32_bf16 v[68:71], v[180:183], v[212:215], v[68:71]
	v_mfma_f32_16x16x32_bf16 v[120:123], v[216:219], v[184:187], v[120:123]
	v_mfma_f32_16x16x32_bf16 v[112:115], v[224:227], v[184:187], v[112:115]
	v_mfma_f32_16x16x32_bf16 v[104:107], v[216:219], v[192:195], v[104:107]
	v_mfma_f32_16x16x32_bf16 v[96:99], v[224:227], v[192:195], v[96:99]
	v_mfma_f32_16x16x32_bf16 v[88:91], v[216:219], v[200:203], v[88:91]
	v_mfma_f32_16x16x32_bf16 v[80:83], v[224:227], v[200:203], v[80:83]
	v_mfma_f32_16x16x32_bf16 v[72:75], v[216:219], v[208:211], v[72:75]
	v_mfma_f32_16x16x32_bf16 v[64:67], v[224:227], v[208:211], v[64:67]
	v_mfma_f32_16x16x32_bf16 v[120:123], v[220:223], v[188:191], v[120:123]
	v_mfma_f32_16x16x32_bf16 v[112:115], v[228:231], v[188:191], v[112:115]
	v_mfma_f32_16x16x32_bf16 v[104:107], v[220:223], v[196:199], v[104:107]
	v_mfma_f32_16x16x32_bf16 v[96:99], v[228:231], v[196:199], v[96:99]
	v_mfma_f32_16x16x32_bf16 v[88:91], v[220:223], v[204:207], v[88:91]
	v_mfma_f32_16x16x32_bf16 v[80:83], v[228:231], v[204:207], v[80:83]
	v_mfma_f32_16x16x32_bf16 v[72:75], v[220:223], v[212:215], v[72:75]
	v_mfma_f32_16x16x32_bf16 v[64:67], v[228:231], v[212:215], v[64:67]
	s_barrier
; __device__ __forceinline__ float sigmoidf_(float x) { return __builtin_amdgcn_rcpf(1.0f + fexp(-x)); }
; #define PG8_STAGE(bufoff, gbase, voff) do { _Pragma("unroll") for (int _i = 0; _i < 2; ++_i) \
;         __builtin_amdgcn_global_load_lds((const unsigned*)((const char*)(gbase) + (voff)[_i]), (LAS unsigned*)(lds + (bufoff) + ldsw + _i * 8192), 16, 0, 0); } while (0)
; #define PG8_LDA(dst, b, h) do { _Pragma("unroll") for (int m = 0; m < 4; ++m) _Pragma("unroll") for (int k = 0; k < 2; ++k) dst[m][k] = *(const LAS bf16x8*)(lds + PG8_SA(b, h) + aoff + m * 2048 + k * 1024); } while (0)
; #define PG8_MMA(ai, bj, At, Bt) do { __builtin_amdgcn_s_setprio(1); _Pragma("unroll") for (int m = 0; m < 4; ++m) _Pragma("unroll") for (int n = 0; n < 2; ++n) _Pragma("unroll") for (int k = 0; k < 2; ++k) \
;         acc[ai][bj][m][n] = __builtin_amdgcn_mfma_f32_16x16x32_bf16(Bt[n][k], At[m][k], acc[ai][bj][m][n], 0, 0, 0); __builtin_amdgcn_s_setprio(0); } while (0)
; template <class Epi>
; __device__ __forceinline__ void gemm_phase(LAS unsigned char* lds, const Gemm g, const StaticOrder& S, const Epi& E) {
;     ...
;             PG8_LDA(At, 1, 1); PG8_STAGE(PG8_SA(1, 0), a3, voffA);
;             PG8_BAR; PG8_WAIT_L(0); PG8_MMA(1, 0, At, B0); PG8_BAR; PG8_SCHED;
;             PG8_STAGE(PG8_SB(1, 1), b3 + hstep, voffB);
;             PG8_WAIT_V(6); PG8_BAR; PG8_MMA(1, 1, At, B1); PG8_BAR;
;         }
;     __device__ __forceinline__ void operator()(const f32x4 (&acc)[2][2][4][2], const Unit& u, int wr, int wc, int fr, int fq, const Pre& P) const {
;         const int row0 = ROW_X + u.pm * BM + wr * 64 + fr, col0 = u.pn * HALF + wc * 32 + 8 * fq;
; #pragma unroll
;         for (int ai = 0; ai < 2; ++ai)
; #pragma unroll
;             for (int m = 0; m < 4; ++m) { const int r = row0 + ai * HALF + m * 16; const float rs = __builtin_amdgcn_rsqf(P.rs[ai * 4 + m] * (1.0f / DM) + RMS_EPS);
;                 float y[8];
; #pragma unroll
;                 for (int n = 0; n < 2; ++n)
; #pragma unroll
;                     for (int j = 0; j < 4; ++j) { const float a = acc[ai][0][m][n][j] * rs, b = acc[ai][1][m][n][j] * rs; y[n * 4 + j] = a * b * sigmoidf_(a); }
;                 u32x4 w; w.x = cvtpk(y[0], y[1]); w.y = cvtpk(y[2], y[3]); w.z = cvtpk(y[4], y[5]); w.w = cvtpk(y[6], y[7]);
;                 *(u32x4*)(O + (size_t)r * FF + col0) = w; }
	s_setprio 0
	s_add_i32 s21, s66, s31
	v_lshl_add_u64 v[162:163], v[162:163], 0, s[4:5]
	s_mov_b32 m0, s21
	s_nop 0
	global_load_lds_dwordx4 v[162:163], off
	v_lshl_add_u64 v[162:163], v[232:233], 0, s[4:5]
	s_add_i32 m0, s21, 0x2000
	s_nop 0
	global_load_lds_dwordx4 v[162:163], off
	s_mov_b32 m0, s42
	v_lshl_add_u64 v[162:163], v[234:235], 0, s[4:5]
	ds_read_b128 v[184:187], v150 offset:49152
	ds_read_b128 v[188:191], v150 offset:50176
	ds_read_b128 v[192:195], v150 offset:51200
	ds_read_b128 v[196:199], v150 offset:52224
	ds_read_b128 v[200:203], v150 offset:53248
	ds_read_b128 v[204:207], v150 offset:54272
	ds_read_b128 v[208:211], v150 offset:55296
	ds_read_b128 v[212:215], v150 offset:56320
	global_load_lds_dwordx4 v[162:163], off
	v_lshl_add_u64 v[162:163], v[236:237], 0, s[4:5]
	s_mov_b32 m0, s43
	s_nop 0
	global_load_lds_dwordx4 v[162:163], off
	s_add_u32 s18, s18, 0x80080
	s_addc_u32 s19, s19, 0
	s_add_i32 s20, s20, s31
	v_lshl_add_u64 v[162:163], s[18:19], 0, v[132:133]
	s_mov_b32 m0, s20
	s_nop 0
	global_load_lds_dwordx4 v[162:163], off
	v_lshl_add_u64 v[162:163], s[18:19], 0, v[128:129]
	s_add_i32 m0, s20, 0x2000
	s_nop 0
	global_load_lds_dwordx4 v[162:163], off
	s_waitcnt lgkmcnt(0)
	s_waitcnt vmcnt(8)
	s_setprio 1
	s_barrier
	v_mfma_f32_16x16x32_bf16 v[60:63], v[166:169], v[184:187], v[60:63]
	v_mfma_f32_16x16x32_bf16 v[52:55], v[174:177], v[184:187], v[52:55]
	v_mfma_f32_16x16x32_bf16 v[44:47], v[166:169], v[192:195], v[44:47]
	v_mfma_f32_16x16x32_bf16 v[36:39], v[174:177], v[192:195], v[36:39]
	v_mfma_f32_16x16x32_bf16 v[28:31], v[166:169], v[200:203], v[28:31]
	v_mfma_f32_16x16x32_bf16 v[20:23], v[174:177], v[200:203], v[20:23]
	v_mfma_f32_16x16x32_bf16 v[12:15], v[166:169], v[208:211], v[12:15]
	v_mfma_f32_16x16x32_bf16 v[4:7], v[174:177], v[208:211], v[4:7]
	v_mfma_f32_16x16x32_bf16 v[60:63], v[170:173], v[188:191], v[60:63]
	v_mfma_f32_16x16x32_bf16 v[52:55], v[180:183], v[188:191], v[52:55]
	v_mfma_f32_16x16x32_bf16 v[44:47], v[170:173], v[196:199], v[44:47]
	v_mfma_f32_16x16x32_bf16 v[36:39], v[180:183], v[196:199], v[36:39]
	v_mfma_f32_16x16x32_bf16 v[28:31], v[170:173], v[204:207], v[28:31]
	v_mfma_f32_16x16x32_bf16 v[20:23], v[180:183], v[204:207], v[20:23]
	v_mfma_f32_16x16x32_bf16 v[12:15], v[170:173], v[212:215], v[12:15]
	v_mfma_f32_16x16x32_bf16 v[4:7], v[180:183], v[212:215], v[4:7]
	v_mfma_f32_16x16x32_bf16 v[56:59], v[216:219], v[184:187], v[56:59]
	v_mfma_f32_16x16x32_bf16 v[48:51], v[224:227], v[184:187], v[48:51]
	v_mfma_f32_16x16x32_bf16 v[40:43], v[216:219], v[192:195], v[40:43]
	v_mfma_f32_16x16x32_bf16 v[32:35], v[224:227], v[192:195], v[32:35]
	v_mfma_f32_16x16x32_bf16 v[24:27], v[216:219], v[200:203], v[24:27]
	v_mfma_f32_16x16x32_bf16 v[16:19], v[224:227], v[200:203], v[16:19]
	v_mfma_f32_16x16x32_bf16 v[8:11], v[216:219], v[208:211], v[8:11]
	v_mfma_f32_16x16x32_bf16 v[0:3], v[224:227], v[208:211], v[0:3]
	v_mfma_f32_16x16x32_bf16 v[56:59], v[220:223], v[188:191], v[56:59]
	v_mfma_f32_16x16x32_bf16 v[48:51], v[228:231], v[188:191], v[48:51]
	v_mfma_f32_16x16x32_bf16 v[40:43], v[220:223], v[196:199], v[40:43]
	v_mfma_f32_16x16x32_bf16 v[32:35], v[228:231], v[196:199], v[32:35]
	v_mfma_f32_16x16x32_bf16 v[24:27], v[220:223], v[204:207], v[24:27]
	v_mfma_f32_16x16x32_bf16 v[16:19], v[228:231], v[204:207], v[16:19]
	v_mfma_f32_16x16x32_bf16 v[8:11], v[220:223], v[212:215], v[8:11]
	v_mfma_f32_16x16x32_bf16 v[0:3], v[228:231], v[212:215], v[0:3]
	s_barrier
	s_setprio 0
	s_add_i32 s65, s65, 2
	s_add_u32 s16, s16, 0x100
	s_addc_u32 s17, s17, 0
	s_add_u32 s63, s63, 0x100
	s_addc_u32 s64, s64, 0
	s_cmp_gt_u32 s65, 29
	s_cbranch_scc0 .LBB0_1306
	s_waitcnt vmcnt(0)
	v_fmamk_f32 v160, v160, 0x3a000000, v153
	v_rsq_f32_e32 v160, v160
	v_lshl_or_b32 v166, s15, 7, v148
	v_ashrrev_i32_e32 v167, 31, v166
	s_and_b64 vcc, vcc, exec
	v_pk_mul_f32 v[162:163], v[160:161], v[124:125] op_sel_hi:[0,1]
	v_mul_f32_e32 v124, 0xbfb8aa3b, v162
	v_mul_f32_e32 v125, 0xbfb8aa3b, v163
	v_exp_f32_e32 v161, v124
	v_exp_f32_e32 v125, v125
	v_lshl_add_u32 v124, s14, 8, v146
	v_add_f32_e32 v161, 1.0, v161
	v_add_f32_e32 v125, 1.0, v125
	v_rcp_f32_e32 v168, v161
	v_rcp_f32_e32 v169, v125
	v_pk_mul_f32 v[120:121], v[160:161], v[120:121] op_sel_hi:[0,1]
	v_pk_mul_f32 v[120:121], v[162:163], v[120:121]
	v_pk_mul_f32 v[126:127], v[160:161], v[126:127] op_sel_hi:[0,1]
	v_pk_mul_f32 v[120:121], v[168:169], v[120:121]
	v_mul_f32_e32 v125, 0xbfb8aa3b, v126
	v_cvt_pk_bf16_f32 v120, v120, v121
	v_mul_f32_e32 v121, 0xbfb8aa3b, v127
	v_exp_f32_e32 v125, v125
	v_exp_f32_e32 v121, v121
	v_pk_mul_f32 v[122:123], v[160:161], v[122:123] op_sel_hi:[0,1]
	v_pk_mul_f32 v[116:117], v[160:161], v[116:117] op_sel_hi:[0,1]
	v_add_f32_e32 v125, 1.0, v125
	v_add_f32_e32 v121, 1.0, v121
	v_rcp_f32_e32 v162, v125
	v_rcp_f32_e32 v163, v121
	v_pk_mul_f32 v[122:123], v[126:127], v[122:123]
	v_mul_f32_e32 v121, 0xbfb8aa3b, v116
	v_exp_f32_e32 v125, v121
	v_pk_mul_f32 v[122:123], v[162:163], v[122:123]
	v_pk_mul_f32 v[112:113], v[160:161], v[112:113] op_sel_hi:[0,1]
	v_cvt_pk_bf16_f32 v121, v122, v123
	v_mul_f32_e32 v123, 0xbfb8aa3b, v117
	v_exp_f32_e32 v123, v123
	v_add_f32_e32 v122, 1.0, v125
	v_pk_mul_f32 v[112:113], v[116:117], v[112:113]
	v_rcp_f32_e32 v122, v122
	v_add_f32_e32 v116, 1.0, v123
	v_rcp_f32_e32 v123, v116
	v_pk_mul_f32 v[116:117], v[160:161], v[118:119] op_sel_hi:[0,1]
	v_mul_f32_e32 v118, 0xbfb8aa3b, v116
	v_mul_f32_e32 v119, 0xbfb8aa3b, v117
	v_exp_f32_e32 v118, v118
	v_exp_f32_e32 v119, v119
	v_pk_mul_f32 v[112:113], v[122:123], v[112:113]
	v_add_f32_e32 v118, 1.0, v118
	v_cvt_pk_bf16_f32 v122, v112, v113
	v_pk_mul_f32 v[112:113], v[160:161], v[114:115] op_sel_hi:[0,1]
; __device__ __forceinline__ float sigmoidf_(float x) { return __builtin_amdgcn_rcpf(1.0f + fexp(-x)); }
;     __device__ __forceinline__ void operator()(const f32x4 (&acc)[2][2][4][2], const Unit& u, int wr, int wc, int fr, int fq, const Pre& P) const {
;         const int row0 = ROW_X + u.pm * BM + wr * 64 + fr, col0 = u.pn * HALF + wc * 32 + 8 * fq;
; #pragma unroll
;         for (int ai = 0; ai < 2; ++ai)
; #pragma unroll
;             for (int m = 0; m < 4; ++m) { const int r = row0 + ai * HALF + m * 16; const float rs = __builtin_amdgcn_rsqf(P.rs[ai * 4 + m] * (1.0f / DM) + RMS_EPS);
;                 float y[8];
; #pragma unroll
;                 for (int n = 0; n < 2; ++n)
; #pragma unroll
;                     for (int j = 0; j < 4; ++j) { const float a = acc[ai][0][m][n][j] * rs, b = acc[ai][1][m][n][j] * rs; y[n * 4 + j] = a * b * sigmoidf_(a); }
;                 u32x4 w; w.x = cvtpk(y[0], y[1]); w.y = cvtpk(y[2], y[3]); w.z = cvtpk(y[4], y[5]); w.w = cvtpk(y[6], y[7]);
;                 *(u32x4*)(O + (size_t)r * FF + col0) = w; }
	v_fmamk_f32 v114, v159, 0x3a000000, v153
	v_pk_mul_f32 v[112:113], v[116:117], v[112:113]
	v_rsq_f32_e32 v116, v114
	v_add_f32_e32 v119, 1.0, v119
	v_rcp_f32_e32 v118, v118
	v_rcp_f32_e32 v119, v119
	v_pk_mul_f32 v[108:109], v[116:117], v[108:109] op_sel_hi:[0,1]
	v_mul_f32_e32 v117, 0xbfb8aa3b, v108
	v_exp_f32_e32 v117, v117
	v_mul_f32_e32 v125, 0xbfb8aa3b, v109
	v_pk_mul_f32 v[112:113], v[118:119], v[112:113]
	v_exp_f32_e32 v125, v125
	v_cvt_pk_bf16_f32 v123, v112, v113
	v_mov_b64_e32 v[112:113], s[0:1]
	v_mad_i64_i32 v[118:119], s[14:15], v124, s60, v[112:113]
	v_lshlrev_b64 v[114:115], 1, v[166:167]
	v_lshl_add_u64 v[118:119], v[118:119], 0, v[114:115]
	v_add_f32_e32 v117, 1.0, v117
	global_store_dwordx4 v[118:119], v[120:123], off
	v_rcp_f32_e32 v118, v117
	v_add_f32_e32 v117, 1.0, v125
	v_rcp_f32_e32 v119, v117
	v_or_b32_e32 v117, 16, v124
	v_pk_mul_f32 v[104:105], v[116:117], v[104:105] op_sel_hi:[0,1]
	v_pk_mul_f32 v[104:105], v[108:109], v[104:105]
	v_pk_mul_f32 v[108:109], v[116:117], v[110:111] op_sel_hi:[0,1]
	v_pk_mul_f32 v[104:105], v[118:119], v[104:105]
	v_mul_f32_e32 v110, 0xbfb8aa3b, v108
	v_cvt_pk_bf16_f32 v104, v104, v105
	v_mul_f32_e32 v105, 0xbfb8aa3b, v109
	v_exp_f32_e32 v110, v110
	v_exp_f32_e32 v105, v105
	v_pk_mul_f32 v[106:107], v[116:117], v[106:107] op_sel_hi:[0,1]
	v_pk_mul_f32 v[100:101], v[116:117], v[100:101] op_sel_hi:[0,1]
	v_add_f32_e32 v110, 1.0, v110
	v_add_f32_e32 v105, 1.0, v105
	v_rcp_f32_e32 v110, v110
	v_rcp_f32_e32 v111, v105
	v_pk_mul_f32 v[106:107], v[108:109], v[106:107]
	v_mul_f32_e32 v105, 0xbfb8aa3b, v100
	v_exp_f32_e32 v118, v105
	v_pk_mul_f32 v[106:107], v[110:111], v[106:107]
	v_pk_mul_f32 v[96:97], v[116:117], v[96:97] op_sel_hi:[0,1]
	v_cvt_pk_bf16_f32 v105, v106, v107
	v_mul_f32_e32 v107, 0xbfb8aa3b, v101
	v_exp_f32_e32 v107, v107
	v_pk_mul_f32 v[96:97], v[100:101], v[96:97]
	v_add_f32_e32 v106, 1.0, v118
	v_rcp_f32_e32 v106, v106
	v_add_f32_e32 v100, 1.0, v107
	v_rcp_f32_e32 v107, v100
	v_pk_mul_f32 v[100:101], v[116:117], v[102:103] op_sel_hi:[0,1]
	v_mul_f32_e32 v102, 0xbfb8aa3b, v100
	v_mul_f32_e32 v103, 0xbfb8aa3b, v101
	v_exp_f32_e32 v102, v102
	v_exp_f32_e32 v103, v103
	v_pk_mul_f32 v[96:97], v[106:107], v[96:97]
	v_add_f32_e32 v102, 1.0, v102
	v_add_f32_e32 v103, 1.0, v103
	v_rcp_f32_e32 v102, v102
	v_rcp_f32_e32 v103, v103
	v_cvt_pk_bf16_f32 v106, v96, v97
	v_pk_mul_f32 v[96:97], v[116:117], v[98:99] op_sel_hi:[0,1]
	v_pk_mul_f32 v[96:97], v[100:101], v[96:97]
	v_mad_i64_i32 v[98:99], s[14:15], v117, s60, v[112:113]
	v_pk_mul_f32 v[96:97], v[102:103], v[96:97]
	v_lshl_add_u64 v[98:99], v[98:99], 0, v[114:115]
	v_cvt_pk_bf16_f32 v107, v96, v97
	v_fmamk_f32 v96, v158, 0x3a000000, v153
	v_rsq_f32_e32 v96, v96
	global_store_dwordx4 v[98:99], v[104:107], off
	v_pk_mul_f32 v[92:93], v[96:97], v[92:93] op_sel_hi:[0,1]
	v_mul_f32_e32 v97, 0xbfb8aa3b, v92
	v_exp_f32_e32 v97, v97
	v_mul_f32_e32 v100, 0xbfb8aa3b, v93
	v_exp_f32_e32 v100, v100
	v_add_f32_e32 v97, 1.0, v97
	v_rcp_f32_e32 v98, v97
	v_add_f32_e32 v97, 1.0, v100
	v_rcp_f32_e32 v99, v97
	v_or_b32_e32 v97, 32, v124
	v_pk_mul_f32 v[88:89], v[96:97], v[88:89] op_sel_hi:[0,1]
	v_pk_mul_f32 v[88:89], v[92:93], v[88:89]
	v_pk_mul_f32 v[92:93], v[96:97], v[94:95] op_sel_hi:[0,1]
	v_pk_mul_f32 v[88:89], v[98:99], v[88:89]
	v_mul_f32_e32 v94, 0xbfb8aa3b, v92
	v_cvt_pk_bf16_f32 v88, v88, v89
	v_mul_f32_e32 v89, 0xbfb8aa3b, v93
	v_exp_f32_e32 v94, v94
	v_exp_f32_e32 v89, v89
	v_pk_mul_f32 v[90:91], v[96:97], v[90:91] op_sel_hi:[0,1]
	v_pk_mul_f32 v[84:85], v[96:97], v[84:85] op_sel_hi:[0,1]
	v_add_f32_e32 v94, 1.0, v94
	v_add_f32_e32 v89, 1.0, v89
	v_rcp_f32_e32 v94, v94
	v_rcp_f32_e32 v95, v89
	v_pk_mul_f32 v[90:91], v[92:93], v[90:91]
	v_mul_f32_e32 v89, 0xbfb8aa3b, v84
	v_exp_f32_e32 v98, v89
	v_pk_mul_f32 v[90:91], v[94:95], v[90:91]
	v_pk_mul_f32 v[80:81], v[96:97], v[80:81] op_sel_hi:[0,1]
	v_cvt_pk_bf16_f32 v89, v90, v91
	v_mul_f32_e32 v91, 0xbfb8aa3b, v85
	v_exp_f32_e32 v91, v91
	v_pk_mul_f32 v[80:81], v[84:85], v[80:81]
	v_add_f32_e32 v90, 1.0, v98
	v_rcp_f32_e32 v90, v90
	v_add_f32_e32 v84, 1.0, v91
	v_rcp_f32_e32 v91, v84
	v_pk_mul_f32 v[84:85], v[96:97], v[86:87] op_sel_hi:[0,1]
	v_mul_f32_e32 v86, 0xbfb8aa3b, v84
	v_mul_f32_e32 v87, 0xbfb8aa3b, v85
	v_exp_f32_e32 v86, v86
	v_exp_f32_e32 v87, v87
	v_pk_mul_f32 v[80:81], v[90:91], v[80:81]
	v_add_f32_e32 v86, 1.0, v86
	v_add_f32_e32 v87, 1.0, v87
	v_rcp_f32_e32 v86, v86
	v_rcp_f32_e32 v87, v87
	v_cvt_pk_bf16_f32 v90, v80, v81
	v_pk_mul_f32 v[80:81], v[96:97], v[82:83] op_sel_hi:[0,1]
	v_pk_mul_f32 v[80:81], v[84:85], v[80:81]
	v_mad_i64_i32 v[82:83], s[14:15], v97, s60, v[112:113]
	v_pk_mul_f32 v[80:81], v[86:87], v[80:81]
	v_lshl_add_u64 v[82:83], v[82:83], 0, v[114:115]
	v_cvt_pk_bf16_f32 v91, v80, v81
	v_fmamk_f32 v80, v157, 0x3a000000, v153
	v_rsq_f32_e32 v80, v80
	global_store_dwordx4 v[82:83], v[88:91], off
	v_pk_mul_f32 v[76:77], v[80:81], v[76:77] op_sel_hi:[0,1]
	v_mul_f32_e32 v81, 0xbfb8aa3b, v76
	v_exp_f32_e32 v81, v81
	v_mul_f32_e32 v84, 0xbfb8aa3b, v77
	v_exp_f32_e32 v84, v84
	v_add_f32_e32 v81, 1.0, v81
	v_rcp_f32_e32 v82, v81
	v_add_f32_e32 v81, 1.0, v84
	v_rcp_f32_e32 v83, v81
	v_or_b32_e32 v81, 48, v124
	v_pk_mul_f32 v[72:73], v[80:81], v[72:73] op_sel_hi:[0,1]
	v_pk_mul_f32 v[72:73], v[76:77], v[72:73]
	v_pk_mul_f32 v[76:77], v[80:81], v[78:79] op_sel_hi:[0,1]
	v_pk_mul_f32 v[72:73], v[82:83], v[72:73]
	v_mul_f32_e32 v78, 0xbfb8aa3b, v76
	v_cvt_pk_bf16_f32 v72, v72, v73
	v_mul_f32_e32 v73, 0xbfb8aa3b, v77
	v_exp_f32_e32 v78, v78
	v_exp_f32_e32 v73, v73
	v_pk_mul_f32 v[74:75], v[80:81], v[74:75] op_sel_hi:[0,1]
	v_pk_mul_f32 v[68:69], v[80:81], v[68:69] op_sel_hi:[0,1]
; __device__ __forceinline__ float sigmoidf_(float x) { return __builtin_amdgcn_rcpf(1.0f + fexp(-x)); }
;     __device__ __forceinline__ void operator()(const f32x4 (&acc)[2][2][4][2], const Unit& u, int wr, int wc, int fr, int fq, const Pre& P) const {
;         const int row0 = ROW_X + u.pm * BM + wr * 64 + fr, col0 = u.pn * HALF + wc * 32 + 8 * fq;
; #pragma unroll
;         for (int ai = 0; ai < 2; ++ai)
; #pragma unroll
;             for (int m = 0; m < 4; ++m) { const int r = row0 + ai * HALF + m * 16; const float rs = __builtin_amdgcn_rsqf(P.rs[ai * 4 + m] * (1.0f / DM) + RMS_EPS);
;                 float y[8];
; #pragma unroll
;                 for (int n = 0; n < 2; ++n)
; #pragma unroll
;                     for (int j = 0; j < 4; ++j) { const float a = acc[ai][0][m][n][j] * rs, b = acc[ai][1][m][n][j] * rs; y[n * 4 + j] = a * b * sigmoidf_(a); }
;                 u32x4 w; w.x = cvtpk(y[0], y[1]); w.y = cvtpk(y[2], y[3]); w.z = cvtpk(y[4], y[5]); w.w = cvtpk(y[6], y[7]);
;                 *(u32x4*)(O + (size_t)r * FF + col0) = w; }
	v_add_f32_e32 v78, 1.0, v78
	v_add_f32_e32 v73, 1.0, v73
	v_rcp_f32_e32 v78, v78
	v_rcp_f32_e32 v79, v73
	v_pk_mul_f32 v[74:75], v[76:77], v[74:75]
	v_mul_f32_e32 v73, 0xbfb8aa3b, v68
	v_exp_f32_e32 v82, v73
	v_pk_mul_f32 v[74:75], v[78:79], v[74:75]
	v_pk_mul_f32 v[64:65], v[80:81], v[64:65] op_sel_hi:[0,1]
	v_cvt_pk_bf16_f32 v73, v74, v75
	v_mul_f32_e32 v75, 0xbfb8aa3b, v69
	v_exp_f32_e32 v75, v75
	v_pk_mul_f32 v[64:65], v[68:69], v[64:65]
	v_add_f32_e32 v74, 1.0, v82
	v_rcp_f32_e32 v74, v74
	v_add_f32_e32 v68, 1.0, v75
	v_rcp_f32_e32 v75, v68
	v_pk_mul_f32 v[68:69], v[80:81], v[70:71] op_sel_hi:[0,1]
	v_mul_f32_e32 v70, 0xbfb8aa3b, v68
	v_mul_f32_e32 v71, 0xbfb8aa3b, v69
	v_exp_f32_e32 v70, v70
	v_exp_f32_e32 v71, v71
	v_pk_mul_f32 v[64:65], v[74:75], v[64:65]
	v_add_f32_e32 v70, 1.0, v70
	v_add_f32_e32 v71, 1.0, v71
	v_rcp_f32_e32 v70, v70
	v_rcp_f32_e32 v71, v71
	v_cvt_pk_bf16_f32 v74, v64, v65
	v_pk_mul_f32 v[64:65], v[80:81], v[66:67] op_sel_hi:[0,1]
	v_pk_mul_f32 v[64:65], v[68:69], v[64:65]
	v_mad_i64_i32 v[66:67], s[14:15], v81, s60, v[112:113]
	v_pk_mul_f32 v[64:65], v[70:71], v[64:65]
	v_lshl_add_u64 v[66:67], v[66:67], 0, v[114:115]
	v_cvt_pk_bf16_f32 v75, v64, v65
	v_fmamk_f32 v64, v156, 0x3a000000, v153
	v_rsq_f32_e32 v64, v64
	global_store_dwordx4 v[66:67], v[72:75], off
	v_pk_mul_f32 v[60:61], v[64:65], v[60:61] op_sel_hi:[0,1]
	v_mul_f32_e32 v65, 0xbfb8aa3b, v60
	v_exp_f32_e32 v65, v65
	v_mul_f32_e32 v68, 0xbfb8aa3b, v61
	v_exp_f32_e32 v68, v68
	v_add_f32_e32 v65, 1.0, v65
	v_rcp_f32_e32 v66, v65
	v_add_f32_e32 v65, 1.0, v68
	v_rcp_f32_e32 v67, v65
	v_add_u32_e32 v65, 0x80, v124
	v_pk_mul_f32 v[56:57], v[64:65], v[56:57] op_sel_hi:[0,1]
	v_pk_mul_f32 v[56:57], v[60:61], v[56:57]
	v_pk_mul_f32 v[60:61], v[64:65], v[62:63] op_sel_hi:[0,1]
	v_pk_mul_f32 v[56:57], v[66:67], v[56:57]
	v_mul_f32_e32 v62, 0xbfb8aa3b, v60
	v_cvt_pk_bf16_f32 v56, v56, v57
	v_mul_f32_e32 v57, 0xbfb8aa3b, v61
	v_exp_f32_e32 v62, v62
	v_exp_f32_e32 v57, v57
	v_pk_mul_f32 v[58:59], v[64:65], v[58:59] op_sel_hi:[0,1]
	v_pk_mul_f32 v[52:53], v[64:65], v[52:53] op_sel_hi:[0,1]
	v_add_f32_e32 v62, 1.0, v62
	v_add_f32_e32 v57, 1.0, v57
	v_rcp_f32_e32 v62, v62
	v_rcp_f32_e32 v63, v57
	v_pk_mul_f32 v[58:59], v[60:61], v[58:59]
	v_mul_f32_e32 v57, 0xbfb8aa3b, v52
	v_exp_f32_e32 v66, v57
	v_pk_mul_f32 v[58:59], v[62:63], v[58:59]
	v_pk_mul_f32 v[48:49], v[64:65], v[48:49] op_sel_hi:[0,1]
	v_cvt_pk_bf16_f32 v57, v58, v59
	v_mul_f32_e32 v59, 0xbfb8aa3b, v53
	v_exp_f32_e32 v59, v59
	v_pk_mul_f32 v[48:49], v[52:53], v[48:49]
	v_add_f32_e32 v58, 1.0, v66
	v_rcp_f32_e32 v58, v58
	v_add_f32_e32 v52, 1.0, v59
	v_rcp_f32_e32 v59, v52
	v_pk_mul_f32 v[52:53], v[64:65], v[54:55] op_sel_hi:[0,1]
	v_mul_f32_e32 v54, 0xbfb8aa3b, v52
	v_mul_f32_e32 v55, 0xbfb8aa3b, v53
	v_exp_f32_e32 v54, v54
	v_exp_f32_e32 v55, v55
	v_pk_mul_f32 v[48:49], v[58:59], v[48:49]
	v_add_f32_e32 v54, 1.0, v54
	v_add_f32_e32 v55, 1.0, v55
	v_rcp_f32_e32 v54, v54
	v_rcp_f32_e32 v55, v55
	v_cvt_pk_bf16_f32 v58, v48, v49
	v_pk_mul_f32 v[48:49], v[64:65], v[50:51] op_sel_hi:[0,1]
	v_pk_mul_f32 v[48:49], v[52:53], v[48:49]
	v_mad_i64_i32 v[50:51], s[14:15], v65, s60, v[112:113]
	v_pk_mul_f32 v[48:49], v[54:55], v[48:49]
	v_lshl_add_u64 v[50:51], v[50:51], 0, v[114:115]
	v_cvt_pk_bf16_f32 v59, v48, v49
	v_fmamk_f32 v48, v155, 0x3a000000, v153
	v_rsq_f32_e32 v48, v48
	global_store_dwordx4 v[50:51], v[56:59], off
	v_pk_mul_f32 v[44:45], v[48:49], v[44:45] op_sel_hi:[0,1]
	v_mul_f32_e32 v49, 0xbfb8aa3b, v44
	v_exp_f32_e32 v49, v49
	v_mul_f32_e32 v52, 0xbfb8aa3b, v45
	v_exp_f32_e32 v52, v52
	v_add_f32_e32 v49, 1.0, v49
	v_rcp_f32_e32 v50, v49
	v_add_f32_e32 v49, 1.0, v52
	v_rcp_f32_e32 v51, v49
	v_add_u32_e32 v49, 0x90, v124
	v_pk_mul_f32 v[40:41], v[48:49], v[40:41] op_sel_hi:[0,1]
	v_pk_mul_f32 v[40:41], v[44:45], v[40:41]
	v_pk_mul_f32 v[44:45], v[48:49], v[46:47] op_sel_hi:[0,1]
	v_pk_mul_f32 v[40:41], v[50:51], v[40:41]
	v_mul_f32_e32 v46, 0xbfb8aa3b, v44
	v_cvt_pk_bf16_f32 v40, v40, v41
	v_mul_f32_e32 v41, 0xbfb8aa3b, v45
	v_exp_f32_e32 v46, v46
	v_exp_f32_e32 v41, v41
	v_pk_mul_f32 v[42:43], v[48:49], v[42:43] op_sel_hi:[0,1]
	v_pk_mul_f32 v[36:37], v[48:49], v[36:37] op_sel_hi:[0,1]
	v_add_f32_e32 v46, 1.0, v46
	v_add_f32_e32 v41, 1.0, v41
	v_rcp_f32_e32 v46, v46
	v_rcp_f32_e32 v47, v41
	v_pk_mul_f32 v[42:43], v[44:45], v[42:43]
	v_mul_f32_e32 v41, 0xbfb8aa3b, v36
	v_exp_f32_e32 v50, v41
	v_pk_mul_f32 v[42:43], v[46:47], v[42:43]
	v_pk_mul_f32 v[32:33], v[48:49], v[32:33] op_sel_hi:[0,1]
	v_cvt_pk_bf16_f32 v41, v42, v43
	v_mul_f32_e32 v43, 0xbfb8aa3b, v37
	v_exp_f32_e32 v43, v43
	v_pk_mul_f32 v[32:33], v[36:37], v[32:33]
	v_add_f32_e32 v42, 1.0, v50
	v_rcp_f32_e32 v42, v42
	v_add_f32_e32 v36, 1.0, v43
	v_rcp_f32_e32 v43, v36
	v_pk_mul_f32 v[36:37], v[48:49], v[38:39] op_sel_hi:[0,1]
	v_mul_f32_e32 v38, 0xbfb8aa3b, v36
	v_mul_f32_e32 v39, 0xbfb8aa3b, v37
	v_exp_f32_e32 v38, v38
	v_exp_f32_e32 v39, v39
	v_pk_mul_f32 v[32:33], v[42:43], v[32:33]
	v_add_f32_e32 v38, 1.0, v38
	v_add_f32_e32 v39, 1.0, v39
	v_rcp_f32_e32 v38, v38
	v_rcp_f32_e32 v39, v39
	v_cvt_pk_bf16_f32 v42, v32, v33
	v_pk_mul_f32 v[32:33], v[48:49], v[34:35] op_sel_hi:[0,1]
	v_pk_mul_f32 v[32:33], v[36:37], v[32:33]
	v_mad_i64_i32 v[34:35], s[14:15], v49, s60, v[112:113]
; __device__ __forceinline__ float sigmoidf_(float x) { return __builtin_amdgcn_rcpf(1.0f + fexp(-x)); }
;     __device__ __forceinline__ Pre pre(const Unit& u, int wr, int fr) const { return load_rs(ssq, u.pm, wr, fr); }
;     __device__ __forceinline__ Pre pre(const Unit& u, int wr, int fr) const { return load_rs(ssq, u.pm, wr, fr); }
;     __device__ __forceinline__ Pre pre(const Unit& u, int wr, int fr) const { return load_rs(ssq, u.pm, wr, fr); }
; template <class Epi>
; __device__ __forceinline__ void gemm_phase(LAS unsigned char* lds, const Gemm g, const StaticOrder& S, const Epi& E) {
;     ...
;         E(acc, cur, wr, wc, fr, fq, pre);
;         if (!has_next) break;
;         pre = E.pre(nxt, wr, fr);
;     __device__ __forceinline__ void operator()(const f32x4 (&acc)[2][2][4][2], const Unit& u, int wr, int wc, int fr, int fq, const Pre& P) const {
;         const int row0 = ROW_X + u.pm * BM + wr * 64 + fr, col0 = u.pn * HALF + wc * 32 + 8 * fq;
; #pragma unroll
;         for (int ai = 0; ai < 2; ++ai)
; #pragma unroll
;             for (int m = 0; m < 4; ++m) { const int r = row0 + ai * HALF + m * 16; const float rs = __builtin_amdgcn_rsqf(P.rs[ai * 4 + m] * (1.0f / DM) + RMS_EPS);
;                 float y[8];
; #pragma unroll
;                 for (int n = 0; n < 2; ++n)
; #pragma unroll
;                     for (int j = 0; j < 4; ++j) { const float a = acc[ai][0][m][n][j] * rs, b = acc[ai][1][m][n][j] * rs; y[n * 4 + j] = a * b * sigmoidf_(a); }
;                 u32x4 w; w.x = cvtpk(y[0], y[1]); w.y = cvtpk(y[2], y[3]); w.z = cvtpk(y[4], y[5]); w.w = cvtpk(y[6], y[7]);
;                 *(u32x4*)(O + (size_t)r * FF + col0) = w; }
	v_pk_mul_f32 v[32:33], v[38:39], v[32:33]
	v_lshl_add_u64 v[34:35], v[34:35], 0, v[114:115]
	v_cvt_pk_bf16_f32 v43, v32, v33
	v_fmamk_f32 v32, v154, 0x3a000000, v153
	v_rsq_f32_e32 v32, v32
	global_store_dwordx4 v[34:35], v[40:43], off
	v_pk_mul_f32 v[28:29], v[32:33], v[28:29] op_sel_hi:[0,1]
	v_mul_f32_e32 v33, 0xbfb8aa3b, v28
	v_exp_f32_e32 v33, v33
	v_mul_f32_e32 v36, 0xbfb8aa3b, v29
	v_exp_f32_e32 v36, v36
	v_add_f32_e32 v33, 1.0, v33
	v_rcp_f32_e32 v34, v33
	v_add_f32_e32 v33, 1.0, v36
	v_rcp_f32_e32 v35, v33
	v_add_u32_e32 v33, 0xa0, v124
	v_pk_mul_f32 v[24:25], v[32:33], v[24:25] op_sel_hi:[0,1]
	v_pk_mul_f32 v[24:25], v[28:29], v[24:25]
	v_pk_mul_f32 v[28:29], v[32:33], v[30:31] op_sel_hi:[0,1]
	v_pk_mul_f32 v[24:25], v[34:35], v[24:25]
	v_mul_f32_e32 v30, 0xbfb8aa3b, v28
	v_cvt_pk_bf16_f32 v24, v24, v25
	v_mul_f32_e32 v25, 0xbfb8aa3b, v29
	v_exp_f32_e32 v30, v30
	v_exp_f32_e32 v25, v25
	v_pk_mul_f32 v[26:27], v[32:33], v[26:27] op_sel_hi:[0,1]
	v_pk_mul_f32 v[20:21], v[32:33], v[20:21] op_sel_hi:[0,1]
	v_add_f32_e32 v30, 1.0, v30
	v_add_f32_e32 v25, 1.0, v25
	v_rcp_f32_e32 v30, v30
	v_rcp_f32_e32 v31, v25
	v_pk_mul_f32 v[26:27], v[28:29], v[26:27]
	v_mul_f32_e32 v25, 0xbfb8aa3b, v20
	v_exp_f32_e32 v34, v25
	v_pk_mul_f32 v[26:27], v[30:31], v[26:27]
	v_pk_mul_f32 v[16:17], v[32:33], v[16:17] op_sel_hi:[0,1]
	v_cvt_pk_bf16_f32 v25, v26, v27
	v_mul_f32_e32 v27, 0xbfb8aa3b, v21
	v_exp_f32_e32 v27, v27
	v_pk_mul_f32 v[16:17], v[20:21], v[16:17]
	v_add_f32_e32 v26, 1.0, v34
	v_rcp_f32_e32 v26, v26
	v_add_f32_e32 v20, 1.0, v27
	v_rcp_f32_e32 v27, v20
	v_pk_mul_f32 v[20:21], v[32:33], v[22:23] op_sel_hi:[0,1]
	v_mul_f32_e32 v22, 0xbfb8aa3b, v20
	v_mul_f32_e32 v23, 0xbfb8aa3b, v21
	v_exp_f32_e32 v22, v22
	v_exp_f32_e32 v23, v23
	v_pk_mul_f32 v[16:17], v[26:27], v[16:17]
	v_add_f32_e32 v22, 1.0, v22
	v_add_f32_e32 v23, 1.0, v23
	v_rcp_f32_e32 v22, v22
	v_rcp_f32_e32 v23, v23
	v_cvt_pk_bf16_f32 v26, v16, v17
	v_pk_mul_f32 v[16:17], v[32:33], v[18:19] op_sel_hi:[0,1]
	v_pk_mul_f32 v[16:17], v[20:21], v[16:17]
	v_mad_i64_i32 v[18:19], s[14:15], v33, s60, v[112:113]
	v_pk_mul_f32 v[16:17], v[22:23], v[16:17]
	v_lshl_add_u64 v[18:19], v[18:19], 0, v[114:115]
	v_cvt_pk_bf16_f32 v27, v16, v17
	v_fmamk_f32 v16, v151, 0x3a000000, v153
	v_rsq_f32_e32 v16, v16
	global_store_dwordx4 v[18:19], v[24:27], off
	v_pk_mul_f32 v[12:13], v[16:17], v[12:13] op_sel_hi:[0,1]
	v_mul_f32_e32 v17, 0xbfb8aa3b, v12
	v_exp_f32_e32 v17, v17
	v_mul_f32_e32 v20, 0xbfb8aa3b, v13
	v_exp_f32_e32 v20, v20
	v_add_f32_e32 v17, 1.0, v17
	v_rcp_f32_e32 v18, v17
	v_add_f32_e32 v17, 1.0, v20
	v_rcp_f32_e32 v19, v17
	v_add_u32_e32 v17, 0xb0, v124
	v_pk_mul_f32 v[8:9], v[16:17], v[8:9] op_sel_hi:[0,1]
	v_pk_mul_f32 v[8:9], v[12:13], v[8:9]
	v_pk_mul_f32 v[12:13], v[16:17], v[14:15] op_sel_hi:[0,1]
	v_pk_mul_f32 v[8:9], v[18:19], v[8:9]
	v_mul_f32_e32 v14, 0xbfb8aa3b, v12
	v_cvt_pk_bf16_f32 v8, v8, v9
	v_mul_f32_e32 v9, 0xbfb8aa3b, v13
	v_exp_f32_e32 v14, v14
	v_exp_f32_e32 v9, v9
	v_pk_mul_f32 v[10:11], v[16:17], v[10:11] op_sel_hi:[0,1]
	v_pk_mul_f32 v[4:5], v[16:17], v[4:5] op_sel_hi:[0,1]
	v_add_f32_e32 v14, 1.0, v14
	v_add_f32_e32 v9, 1.0, v9
	v_rcp_f32_e32 v14, v14
	v_rcp_f32_e32 v15, v9
	v_pk_mul_f32 v[10:11], v[12:13], v[10:11]
	v_mul_f32_e32 v9, 0xbfb8aa3b, v4
	v_exp_f32_e32 v18, v9
	v_pk_mul_f32 v[10:11], v[14:15], v[10:11]
	v_pk_mul_f32 v[0:1], v[16:17], v[0:1] op_sel_hi:[0,1]
	v_cvt_pk_bf16_f32 v9, v10, v11
	v_mul_f32_e32 v11, 0xbfb8aa3b, v5
	v_exp_f32_e32 v11, v11
	v_pk_mul_f32 v[0:1], v[4:5], v[0:1]
	v_add_f32_e32 v10, 1.0, v18
	v_rcp_f32_e32 v10, v10
	v_add_f32_e32 v4, 1.0, v11
	v_rcp_f32_e32 v11, v4
	v_pk_mul_f32 v[4:5], v[16:17], v[6:7] op_sel_hi:[0,1]
	v_mul_f32_e32 v6, 0xbfb8aa3b, v4
	v_mul_f32_e32 v7, 0xbfb8aa3b, v5
	v_exp_f32_e32 v6, v6
	v_exp_f32_e32 v7, v7
	v_pk_mul_f32 v[0:1], v[10:11], v[0:1]
	v_add_f32_e32 v6, 1.0, v6
	v_add_f32_e32 v7, 1.0, v7
	v_rcp_f32_e32 v6, v6
	v_rcp_f32_e32 v7, v7
	v_cvt_pk_bf16_f32 v10, v0, v1
	v_pk_mul_f32 v[0:1], v[16:17], v[2:3] op_sel_hi:[0,1]
	v_pk_mul_f32 v[0:1], v[4:5], v[0:1]
	s_nop 0
	v_pk_mul_f32 v[0:1], v[6:7], v[0:1]
	s_nop 0
	v_cvt_pk_bf16_f32 v11, v0, v1
	v_mad_i64_i32 v[0:1], s[14:15], v17, s60, v[112:113]
	v_lshl_add_u64 v[0:1], v[0:1], 0, v[114:115]
	s_mov_b64 s[14:15], -1
	global_store_dwordx4 v[0:1], v[8:11], off
	s_cbranch_vccz .LBB0_1302
	v_lshl_add_u32 v0, s8, 8, v146
	v_ashrrev_i32_e32 v1, 31, v0
	v_lshl_add_u64 v[2:3], v[0:1], 2, s[2:3]
	v_add_u32_e32 v4, 0x80, v0
	v_add_u32_e32 v6, 0x90, v0
	v_add_u32_e32 v8, 0xa0, v0
	v_add_u32_e32 v0, 0xb0, v0
	v_ashrrev_i32_e32 v5, 31, v4
	v_ashrrev_i32_e32 v7, 31, v6
	v_ashrrev_i32_e32 v9, 31, v8
	v_ashrrev_i32_e32 v1, 31, v0
	v_lshl_add_u64 v[4:5], v[4:5], 2, s[2:3]
	v_lshl_add_u64 v[6:7], v[6:7], 2, s[2:3]
	v_lshl_add_u64 v[8:9], v[8:9], 2, s[2:3]
	v_lshl_add_u64 v[0:1], v[0:1], 2, s[2:3]
	global_load_dword v160, v[2:3], off
	global_load_dword v159, v[2:3], off offset:64
	global_load_dword v158, v[2:3], off offset:128
	global_load_dword v157, v[2:3], off offset:192
	global_load_dword v156, v[4:5], off
	global_load_dword v155, v[6:7], off
	global_load_dword v154, v[8:9], off
	global_load_dword v151, v[0:1], off
	s_mov_b64 s[14:15], 0
	s_branch .LBB0_1302

; #define PG8_STAGE(bufoff, gbase, voff) do { _Pragma("unroll") for (int _i = 0; _i < 2; ++_i) \
;         __builtin_amdgcn_global_load_lds((const unsigned*)((const char*)(gbase) + (voff)[_i]), (LAS unsigned*)(lds + (bufoff) + ldsw + _i * 8192), 16, 0, 0); } while (0)
; #define PG8_WAIT_V(n) asm volatile("s_waitcnt vmcnt(" #n ")" ::: "memory")
; #define PG8_BAR __builtin_amdgcn_s_barrier()
; template <class Epi>
; __device__ __forceinline__ void gemm_phase(LAS unsigned char* lds, const Gemm g, const StaticOrder& S, const Epi& E) {
;     const int tid = threadIdx.x, wid = __builtin_amdgcn_readfirstlane(tid >> 6), lane = tid & 63, wr = wid >> 2, wc = wid & 3, fr = lane & 15, fq = lane >> 4;
;     const int K = g.K, nt = K / BK;
;     unsigned voffA[2], voffB[2];
; #pragma unroll
;     for (int i = 0; i < 2; ++i) { int R, C; stage_rc(tid * 16 + i * 8192, R, C); const int Rb = Epi::PERM ? ((R & ~31) + perm32(R & 31)) : R;
;         voffA[i] = (unsigned)(R * K + C) * 2u; voffB[i] = (unsigned)(Rb * K + C) * 2u; }
;     const size_t kstep = (size_t)(BK * 2);
;     const size_t hstep = (size_t)HALF * K * 2;
;     const size_t tstep = 2 * hstep;
;     const unsigned ldsw = (unsigned)wid * 1024u;
;     const int aoff = lds_byte(wr * 64 + fr, fq * 8), boff = lds_byte(wc * 32 + fr, fq * 8);
;     ...
;     Unit cur, nxt; int ui = 0;
;     if (!S.next(0, cur)) return;
;     f32x4 acc[2][2][4][2];
; #pragma unroll
;     for (int a = 0; a < 2; ++a)
; #pragma unroll
;         for (int b = 0; b < 2; ++b)
; #pragma unroll
;             for (int m = 0; m < 4; ++m)
; #pragma unroll
;                 for (int n = 0; n < 2; ++n) acc[a][b][m][n] = (f32x4){0.f, 0.f, 0.f, 0.f};
;     bf16x8 At[4][2], B0[2][2], B1[2][2];
;     const char* cA = (const char*)g.A + (size_t)cur.pm * tstep; const char* cB = (const char*)g.Bt + (size_t)cur.pn * tstep;
;     typename Epi::Pre pre = E.pre(cur, wr, fr);
;     PG8_STAGE(PG8_SB(0, 0), cB, voffB); PG8_STAGE(PG8_SA(0, 0), cA, voffA); PG8_STAGE(PG8_SB(0, 1), cB + hstep, voffB); PG8_STAGE(PG8_SA(0, 1), cA + hstep, voffA);
;     if (wr == 1) PG8_BAR;
;     PG8_WAIT_V(4); PG8_BAR;
;     PG8_STAGE(PG8_SB(1, 0), cB + kstep, voffB); PG8_STAGE(PG8_SA(1, 0), cA + kstep, voffA); PG8_STAGE(PG8_SB(1, 1), cB + hstep + kstep, voffB);
;     PG8_WAIT_V(6); PG8_BAR;
.LBB0_1398:
	s_lshl_b32 s1, s1, 5
	s_mov_b64 s[12:13], 0x80
	s_and_b32 s1, s1, 0x60
	s_add_i32 m0, s30, 0x18000
	v_lshl_add_u64 v[6:7], v[6:7], 0, s[12:13]
	s_lshl_b32 s4, s0, 13
	s_lshl_b32 s5, s1, 7
	s_waitcnt vmcnt(2)
	s_barrier
	global_load_lds_dwordx4 v[6:7], off
	v_lshl_add_u64 v[4:5], v[4:5], 0, s[12:13]
	s_add_i32 m0, s30, 0x1a000
	s_add_i32 s36, s30, 0x8000
	s_add_i32 s37, s30, 0xa000
	global_load_lds_dwordx4 v[4:5], off
	v_lshl_add_u64 v[2:3], v[2:3], 0, s[12:13]
	s_mov_b32 m0, s36
	s_add_u32 s2, s16, 0x158080
	global_load_lds_dwordx4 v[2:3], off
	v_lshl_add_u64 v[0:1], v[0:1], 0, s[12:13]
	s_mov_b32 m0, s37
	s_addc_u32 s3, s17, 0
	global_load_lds_dwordx4 v[0:1], off
	s_add_i32 m0, s30, 0x1c000
	v_lshl_add_u64 v[0:1], s[2:3], 0, v[140:141]
	global_load_lds_dwordx4 v[0:1], off
	v_lshl_add_u64 v[0:1], s[2:3], 0, v[144:145]
	s_add_i32 m0, s30, 0x1e000
	v_lshlrev_b32_e32 v4, 2, v137
	global_load_lds_dwordx4 v[0:1], off
	v_bfe_u32 v0, v178, 4, 2
	v_lshlrev_b32_e32 v2, 4, v0
	v_lshl_or_b32 v3, v137, 6, v2
	v_and_b32_e32 v4, 32, v4
	v_lshl_or_b32 v1, s0, 6, v137
	v_bitop3_b32 v3, v3, s4, v4 bitop3:0xde
	v_lshlrev_b32_e32 v4, 6, v178
	s_movk_i32 s0, 0x3c0
	v_and_or_b32 v2, v4, s0, v2
	v_lshlrev_b32_e32 v4, 2, v178
	v_cmp_eq_u32_e64 s[2:3], 0, v0
	v_lshl_or_b32 v161, v0, 3, s1
	v_add_u16_e32 v0, v8, v9
	v_and_b32_e32 v4, 32, v4
	s_waitcnt vmcnt(6)
	v_lshrrev_b16_e32 v0, 1, v0
	v_bitop3_b32 v137, s5, v2, v4 bitop3:0xf6
	v_add_lshl_u32 v146, v10, v0, 1
	v_add_lshl_u32 v148, v11, v0, 1
	s_add_i32 s43, 0, 0x10000
	s_add_i32 s56, 0, 0x14000
	v_mbcnt_lo_u32_b32 v0, -1, 0
	s_waitcnt vmcnt(0)
	v_add_u32_e32 v160, 0x100, v1
	s_ashr_i32 s38, s54, 31
	s_mov_b32 s39, s54
	s_ashr_i32 s42, s28, 31
	v_mov_b32_e32 v147, v141
	v_mov_b32_e32 v149, v141
	v_mov_b64_e32 v[150:151], 0x200
	v_mov_b64_e32 v[152:153], 0x1ff
	v_add_u32_e32 v162, s43, v137
	v_add_u32_e32 v163, 0, v3
	v_add_u32_e32 v165, s56, v137
	v_mbcnt_hi_u32_b32 v166, -1, v0
	s_barrier
	s_branch .LBB0_1400

; #define PG8_STAGE(bufoff, gbase, voff) do { _Pragma("unroll") for (int _i = 0; _i < 2; ++_i) \
;         __builtin_amdgcn_global_load_lds((const unsigned*)((const char*)(gbase) + (voff)[_i]), (LAS unsigned*)(lds + (bufoff) + ldsw + _i * 8192), 16, 0, 0); } while (0)
; #define PG8_LDA(dst, b, h) do { _Pragma("unroll") for (int m = 0; m < 4; ++m) _Pragma("unroll") for (int k = 0; k < 2; ++k) dst[m][k] = *(const LAS bf16x8*)(lds + PG8_SA(b, h) + aoff + m * 2048 + k * 1024); } while (0)
; #define PG8_LDB(dst, b, h) do { _Pragma("unroll") for (int n = 0; n < 2; ++n) _Pragma("unroll") for (int k = 0; k < 2; ++k) dst[n][k] = *(const LAS bf16x8*)(lds + PG8_SB(b, h) + boff + n * 2048 + k * 1024); } while (0)
; #define PG8_MMA(ai, bj, At, Bt) do { __builtin_amdgcn_s_setprio(1); _Pragma("unroll") for (int m = 0; m < 4; ++m) _Pragma("unroll") for (int n = 0; n < 2; ++n) _Pragma("unroll") for (int k = 0; k < 2; ++k) \
;         acc[ai][bj][m][n] = __builtin_amdgcn_mfma_f32_16x16x32_bf16(Bt[n][k], At[m][k], acc[ai][bj][m][n], 0, 0, 0); __builtin_amdgcn_s_setprio(0); } while (0)
; #define PG8_WAIT_V(n) asm volatile("s_waitcnt vmcnt(" #n ")" ::: "memory")
; #define PG8_WAIT_L(n) asm volatile("s_waitcnt lgkmcnt(" #n ")" ::: "memory")
; #define PG8_BAR __builtin_amdgcn_s_barrier()
; #define PG8_SCHED __builtin_amdgcn_sched_barrier(0)
; template <class Epi>
; __device__ __forceinline__ void gemm_phase(LAS unsigned char* lds, const Gemm g, const StaticOrder& S, const Epi& E) {
;     ...
;             const char* a2 = last ? nA : cA + (size_t)(t + 2) * kstep; const char* b2 = last ? nB : cB + (size_t)(t + 2) * kstep;
;             const char* a3 = a2 + kstep; const char* b3 = b2 + kstep;
;             PG8_LDB(B0, 0, 0); PG8_SCHED; PG8_LDA(At, 0, 0); PG8_STAGE(PG8_SA(1, 1), a1 + hstep, voffA);
;             PG8_WAIT_L(8); PG8_BAR; PG8_WAIT_L(0); PG8_MMA(0, 0, At, B0); PG8_BAR; PG8_SCHED;
;             PG8_LDB(B1, 0, 1); PG8_STAGE(PG8_SB(0, 0), b2, voffB);
;             PG8_BAR; PG8_WAIT_L(0); PG8_MMA(0, 1, At, B1); PG8_BAR;
;             PG8_LDA(At, 0, 1); PG8_STAGE(PG8_SA(0, 0), a2, voffA);
;             PG8_BAR; PG8_WAIT_L(0); PG8_MMA(1, 0, At, B0); PG8_BAR; PG8_SCHED;
;             PG8_STAGE(PG8_SB(0, 1), b2 + hstep, voffB);
;             PG8_WAIT_V(6); PG8_BAR; PG8_MMA(1, 1, At, B1); PG8_BAR;
.LBB0_1411:
	ds_read_b128 v[128:131], v162
	ds_read_b128 v[132:135], v162 offset:1024
	ds_read_b128 v[154:157], v162 offset:2048
	ds_read_b128 v[168:171], v162 offset:3072
	s_add_u32 s16, s14, 0xffea8080
	s_addc_u32 s17, s15, -1
	s_cmpk_eq_i32 s63, 0x52
	s_cselect_b32 s19, s1, s17
	s_cselect_b32 s18, s0, s16
	s_cselect_b32 s17, s7, s62
	s_cselect_b32 s16, s6, s61
	v_lshl_add_u64 v[158:159], s[14:15], 0, v[146:147]
	s_add_i32 m0, s30, 0xc000
	ds_read_b128 v[172:175], v163
	ds_read_b128 v[180:183], v163 offset:1024
	ds_read_b128 v[184:187], v163 offset:2048
	ds_read_b128 v[188:191], v163 offset:3072
	ds_read_b128 v[192:195], v163 offset:4096
	ds_read_b128 v[196:199], v163 offset:5120
	ds_read_b128 v[200:203], v163 offset:6144
	ds_read_b128 v[204:207], v163 offset:7168
	global_load_lds_dwordx4 v[158:159], off
	v_lshl_add_u64 v[158:159], s[14:15], 0, v[148:149]
	s_add_i32 m0, s30, 0xe000
	s_nop 0
	global_load_lds_dwordx4 v[158:159], off
	ds_read_b128 v[208:211], v165
	ds_read_b128 v[212:215], v165 offset:1024
	ds_read_b128 v[216:219], v165 offset:2048
	ds_read_b128 v[220:223], v165 offset:3072
	s_waitcnt lgkmcnt(0)
	s_waitcnt vmcnt(8)
	s_setprio 1
	s_barrier
	v_mfma_f32_16x16x32_bf16 v[124:127], v[128:131], v[172:175], v[124:127]
	v_mfma_f32_16x16x32_bf16 v[120:123], v[154:157], v[172:175], v[120:123]
	v_mfma_f32_16x16x32_bf16 v[108:111], v[128:131], v[184:187], v[108:111]
	v_mfma_f32_16x16x32_bf16 v[104:107], v[154:157], v[184:187], v[104:107]
	v_mfma_f32_16x16x32_bf16 v[92:95], v[128:131], v[192:195], v[92:95]
	v_mfma_f32_16x16x32_bf16 v[88:91], v[154:157], v[192:195], v[88:91]
	v_mfma_f32_16x16x32_bf16 v[76:79], v[128:131], v[200:203], v[76:79]
	v_mfma_f32_16x16x32_bf16 v[72:75], v[154:157], v[200:203], v[72:75]
	v_mfma_f32_16x16x32_bf16 v[124:127], v[132:135], v[180:183], v[124:127]
	v_mfma_f32_16x16x32_bf16 v[120:123], v[168:171], v[180:183], v[120:123]
	v_mfma_f32_16x16x32_bf16 v[108:111], v[132:135], v[188:191], v[108:111]
	v_mfma_f32_16x16x32_bf16 v[104:107], v[168:171], v[188:191], v[104:107]
	v_mfma_f32_16x16x32_bf16 v[92:95], v[132:135], v[196:199], v[92:95]
	v_mfma_f32_16x16x32_bf16 v[88:91], v[168:171], v[196:199], v[88:91]
	v_mfma_f32_16x16x32_bf16 v[76:79], v[132:135], v[204:207], v[76:79]
	v_mfma_f32_16x16x32_bf16 v[72:75], v[168:171], v[204:207], v[72:75]
	v_mfma_f32_16x16x32_bf16 v[116:119], v[208:211], v[172:175], v[116:119]
	v_mfma_f32_16x16x32_bf16 v[112:115], v[216:219], v[172:175], v[112:115]
	v_mfma_f32_16x16x32_bf16 v[100:103], v[208:211], v[184:187], v[100:103]
	v_mfma_f32_16x16x32_bf16 v[96:99], v[216:219], v[184:187], v[96:99]
	v_mfma_f32_16x16x32_bf16 v[84:87], v[208:211], v[192:195], v[84:87]
	v_mfma_f32_16x16x32_bf16 v[80:83], v[216:219], v[192:195], v[80:83]
	v_mfma_f32_16x16x32_bf16 v[68:71], v[208:211], v[200:203], v[68:71]
	v_mfma_f32_16x16x32_bf16 v[64:67], v[216:219], v[200:203], v[64:67]
	v_mfma_f32_16x16x32_bf16 v[116:119], v[212:215], v[180:183], v[116:119]
	v_mfma_f32_16x16x32_bf16 v[112:115], v[220:223], v[180:183], v[112:115]
	v_mfma_f32_16x16x32_bf16 v[100:103], v[212:215], v[188:191], v[100:103]
	v_mfma_f32_16x16x32_bf16 v[96:99], v[220:223], v[188:191], v[96:99]
	v_mfma_f32_16x16x32_bf16 v[84:87], v[212:215], v[196:199], v[84:87]
	v_mfma_f32_16x16x32_bf16 v[80:83], v[220:223], v[196:199], v[80:83]
	v_mfma_f32_16x16x32_bf16 v[68:71], v[212:215], v[204:207], v[68:71]
	v_mfma_f32_16x16x32_bf16 v[64:67], v[220:223], v[204:207], v[64:67]
	s_barrier
	s_setprio 0
	s_add_i32 s64, s43, s21
	v_lshl_add_u64 v[158:159], s[16:17], 0, v[140:141]
	s_mov_b32 m0, s64
	s_nop 0
	global_load_lds_dwordx4 v[158:159], off
	v_lshl_add_u64 v[176:177], s[16:17], 0, v[144:145]
	s_add_i32 m0, s64, 0x2000
	s_nop 0
	global_load_lds_dwordx4 v[176:177], off
	s_mov_b32 m0, s30
	v_lshl_add_u64 v[224:225], s[18:19], 0, v[138:139]
	ds_read_b128 v[172:175], v163 offset:16384
	ds_read_b128 v[180:183], v163 offset:17408
	ds_read_b128 v[184:187], v163 offset:18432
	ds_read_b128 v[188:191], v163 offset:19456
	ds_read_b128 v[192:195], v163 offset:20480
	ds_read_b128 v[196:199], v163 offset:21504
	ds_read_b128 v[200:203], v163 offset:22528
	ds_read_b128 v[204:207], v163 offset:23552
	global_load_lds_dwordx4 v[224:225], off
	v_lshl_add_u64 v[226:227], s[18:19], 0, v[142:143]
	s_mov_b32 m0, s31
	s_nop 0
	global_load_lds_dwordx4 v[226:227], off
	s_add_u32 s64, s16, 0x158000
	s_addc_u32 s65, s17, 0
	s_add_i32 s66, s56, s21
	v_lshl_add_u64 v[252:253], s[64:65], 0, v[140:141]
	s_mov_b32 m0, s66
	s_nop 0
	global_load_lds_dwordx4 v[252:253], off
	v_lshl_add_u64 v[252:253], s[64:65], 0, v[144:145]
	s_add_i32 m0, s66, 0x2000
	s_nop 0
	global_load_lds_dwordx4 v[252:253], off
	s_waitcnt lgkmcnt(0)
	s_waitcnt vmcnt(8)
	s_setprio 1
	s_barrier
; #define PG8_STAGE(bufoff, gbase, voff) do { _Pragma("unroll") for (int _i = 0; _i < 2; ++_i) \
;         __builtin_amdgcn_global_load_lds((const unsigned*)((const char*)(gbase) + (voff)[_i]), (LAS unsigned*)(lds + (bufoff) + ldsw + _i * 8192), 16, 0, 0); } while (0)
; #define PG8_LDA(dst, b, h) do { _Pragma("unroll") for (int m = 0; m < 4; ++m) _Pragma("unroll") for (int k = 0; k < 2; ++k) dst[m][k] = *(const LAS bf16x8*)(lds + PG8_SA(b, h) + aoff + m * 2048 + k * 1024); } while (0)
; #define PG8_LDB(dst, b, h) do { _Pragma("unroll") for (int n = 0; n < 2; ++n) _Pragma("unroll") for (int k = 0; k < 2; ++k) dst[n][k] = *(const LAS bf16x8*)(lds + PG8_SB(b, h) + boff + n * 2048 + k * 1024); } while (0)
; #define PG8_MMA(ai, bj, At, Bt) do { __builtin_amdgcn_s_setprio(1); _Pragma("unroll") for (int m = 0; m < 4; ++m) _Pragma("unroll") for (int n = 0; n < 2; ++n) _Pragma("unroll") for (int k = 0; k < 2; ++k) \
;         acc[ai][bj][m][n] = __builtin_amdgcn_mfma_f32_16x16x32_bf16(Bt[n][k], At[m][k], acc[ai][bj][m][n], 0, 0, 0); __builtin_amdgcn_s_setprio(0); } while (0)
; #define PG8_WAIT_V(n) asm volatile("s_waitcnt vmcnt(" #n ")" ::: "memory")
; #define PG8_WAIT_L(n) asm volatile("s_waitcnt lgkmcnt(" #n ")" ::: "memory")
; #define PG8_BAR __builtin_amdgcn_s_barrier()
; #define PG8_SCHED __builtin_amdgcn_sched_barrier(0)
; template <class Epi>
; __device__ __forceinline__ void gemm_phase(LAS unsigned char* lds, const Gemm g, const StaticOrder& S, const Epi& E) {
;     ...
;             PG8_LDA(At, 0, 1); PG8_STAGE(PG8_SA(0, 0), a2, voffA);
;             PG8_BAR; PG8_WAIT_L(0); PG8_MMA(1, 0, At, B0); PG8_BAR; PG8_SCHED;
;             PG8_STAGE(PG8_SB(0, 1), b2 + hstep, voffB);
;             PG8_WAIT_V(6); PG8_BAR; PG8_MMA(1, 1, At, B1); PG8_BAR;
;             PG8_LDB(B0, 1, 0); PG8_SCHED; PG8_LDA(At, 1, 0); PG8_STAGE(PG8_SA(0, 1), a2 + hstep, voffA);
;             PG8_WAIT_L(8); PG8_BAR; PG8_WAIT_L(0); PG8_MMA(0, 0, At, B0); PG8_BAR; PG8_SCHED;
;             PG8_LDB(B1, 1, 1); PG8_STAGE(PG8_SB(1, 0), b3, voffB);
;             PG8_BAR; PG8_WAIT_L(0); PG8_MMA(0, 1, At, B1); PG8_BAR;
	v_mfma_f32_16x16x32_bf16 v[60:63], v[128:131], v[172:175], v[60:63]
	v_mfma_f32_16x16x32_bf16 v[56:59], v[154:157], v[172:175], v[56:59]
	v_mfma_f32_16x16x32_bf16 v[44:47], v[128:131], v[184:187], v[44:47]
	v_mfma_f32_16x16x32_bf16 v[40:43], v[154:157], v[184:187], v[40:43]
	v_mfma_f32_16x16x32_bf16 v[28:31], v[128:131], v[192:195], v[28:31]
	v_mfma_f32_16x16x32_bf16 v[24:27], v[154:157], v[192:195], v[24:27]
	v_mfma_f32_16x16x32_bf16 v[12:15], v[128:131], v[200:203], v[12:15]
	v_mfma_f32_16x16x32_bf16 v[8:11], v[154:157], v[200:203], v[8:11]
	v_mfma_f32_16x16x32_bf16 v[60:63], v[132:135], v[180:183], v[60:63]
	v_mfma_f32_16x16x32_bf16 v[56:59], v[168:171], v[180:183], v[56:59]
	v_mfma_f32_16x16x32_bf16 v[44:47], v[132:135], v[188:191], v[44:47]
	v_mfma_f32_16x16x32_bf16 v[40:43], v[168:171], v[188:191], v[40:43]
	v_mfma_f32_16x16x32_bf16 v[28:31], v[132:135], v[196:199], v[28:31]
	v_mfma_f32_16x16x32_bf16 v[24:27], v[168:171], v[196:199], v[24:27]
	v_mfma_f32_16x16x32_bf16 v[12:15], v[132:135], v[204:207], v[12:15]
	v_mfma_f32_16x16x32_bf16 v[8:11], v[168:171], v[204:207], v[8:11]
	v_mfma_f32_16x16x32_bf16 v[52:55], v[208:211], v[172:175], v[52:55]
	v_mfma_f32_16x16x32_bf16 v[48:51], v[216:219], v[172:175], v[48:51]
	v_mfma_f32_16x16x32_bf16 v[36:39], v[208:211], v[184:187], v[36:39]
	v_mfma_f32_16x16x32_bf16 v[32:35], v[216:219], v[184:187], v[32:35]
	v_mfma_f32_16x16x32_bf16 v[20:23], v[208:211], v[192:195], v[20:23]
	v_mfma_f32_16x16x32_bf16 v[16:19], v[216:219], v[192:195], v[16:19]
	v_mfma_f32_16x16x32_bf16 v[4:7], v[208:211], v[200:203], v[4:7]
	v_mfma_f32_16x16x32_bf16 v[0:3], v[216:219], v[200:203], v[0:3]
	v_mfma_f32_16x16x32_bf16 v[52:55], v[212:215], v[180:183], v[52:55]
	v_mfma_f32_16x16x32_bf16 v[48:51], v[220:223], v[180:183], v[48:51]
	v_mfma_f32_16x16x32_bf16 v[36:39], v[212:215], v[188:191], v[36:39]
	v_mfma_f32_16x16x32_bf16 v[32:35], v[220:223], v[188:191], v[32:35]
	v_mfma_f32_16x16x32_bf16 v[20:23], v[212:215], v[196:199], v[20:23]
	v_mfma_f32_16x16x32_bf16 v[16:19], v[220:223], v[196:199], v[16:19]
	v_mfma_f32_16x16x32_bf16 v[4:7], v[212:215], v[204:207], v[4:7]
	v_mfma_f32_16x16x32_bf16 v[0:3], v[220:223], v[204:207], v[0:3]
	s_barrier
	s_setprio 0
	s_add_i32 s64, 0, 0x18000
	v_add_u32_e32 v167, s64, v137
	ds_read_b128 v[128:131], v167
	ds_read_b128 v[132:135], v167 offset:1024
	ds_read_b128 v[154:157], v167 offset:2048
	ds_read_b128 v[168:171], v167 offset:3072
	s_add_u32 s18, s18, 0x158000
	s_addc_u32 s19, s19, 0
	s_mov_b32 m0, s33
	v_lshl_add_u64 v[208:209], s[18:19], 0, v[138:139]
	ds_read_b128 v[172:175], v163 offset:32768
	ds_read_b128 v[180:183], v163 offset:33792
	ds_read_b128 v[184:187], v163 offset:34816
	ds_read_b128 v[188:191], v163 offset:35840
	ds_read_b128 v[192:195], v163 offset:36864
	ds_read_b128 v[196:199], v163 offset:37888
	ds_read_b128 v[200:203], v163 offset:38912
	ds_read_b128 v[204:207], v163 offset:39936
	global_load_lds_dwordx4 v[208:209], off
	v_lshl_add_u64 v[208:209], s[18:19], 0, v[142:143]
	s_mov_b32 m0, s34
	s_nop 0
	global_load_lds_dwordx4 v[208:209], off
	s_add_i32 s18, 0, 0x1c000
	v_add_u32_e32 v167, s18, v137
	ds_read_b128 v[208:211], v167
	ds_read_b128 v[212:215], v167 offset:1024
	ds_read_b128 v[216:219], v167 offset:2048
	ds_read_b128 v[220:223], v167 offset:3072
	s_waitcnt lgkmcnt(0)
	s_waitcnt vmcnt(8)
	s_setprio 1
	s_barrier
	v_mfma_f32_16x16x32_bf16 v[124:127], v[128:131], v[172:175], v[124:127]
	v_mfma_f32_16x16x32_bf16 v[120:123], v[154:157], v[172:175], v[120:123]
	v_mfma_f32_16x16x32_bf16 v[108:111], v[128:131], v[184:187], v[108:111]
	v_mfma_f32_16x16x32_bf16 v[104:107], v[154:157], v[184:187], v[104:107]
	v_mfma_f32_16x16x32_bf16 v[92:95], v[128:131], v[192:195], v[92:95]
	v_mfma_f32_16x16x32_bf16 v[88:91], v[154:157], v[192:195], v[88:91]
	v_mfma_f32_16x16x32_bf16 v[76:79], v[128:131], v[200:203], v[76:79]
	v_mfma_f32_16x16x32_bf16 v[72:75], v[154:157], v[200:203], v[72:75]
	v_mfma_f32_16x16x32_bf16 v[124:127], v[132:135], v[180:183], v[124:127]
	v_mfma_f32_16x16x32_bf16 v[120:123], v[168:171], v[180:183], v[120:123]
	v_mfma_f32_16x16x32_bf16 v[108:111], v[132:135], v[188:191], v[108:111]
	v_mfma_f32_16x16x32_bf16 v[104:107], v[168:171], v[188:191], v[104:107]
	v_mfma_f32_16x16x32_bf16 v[92:95], v[132:135], v[196:199], v[92:95]
	v_mfma_f32_16x16x32_bf16 v[88:91], v[168:171], v[196:199], v[88:91]
	v_mfma_f32_16x16x32_bf16 v[76:79], v[132:135], v[204:207], v[76:79]
	v_mfma_f32_16x16x32_bf16 v[72:75], v[168:171], v[204:207], v[72:75]
	v_mfma_f32_16x16x32_bf16 v[116:119], v[208:211], v[172:175], v[116:119]
	v_mfma_f32_16x16x32_bf16 v[112:115], v[216:219], v[172:175], v[112:115]
	v_mfma_f32_16x16x32_bf16 v[100:103], v[208:211], v[184:187], v[100:103]
	v_mfma_f32_16x16x32_bf16 v[96:99], v[216:219], v[184:187], v[96:99]
	v_mfma_f32_16x16x32_bf16 v[84:87], v[208:211], v[192:195], v[84:87]
	v_mfma_f32_16x16x32_bf16 v[80:83], v[216:219], v[192:195], v[80:83]
	v_mfma_f32_16x16x32_bf16 v[68:71], v[208:211], v[200:203], v[68:71]
	v_mfma_f32_16x16x32_bf16 v[64:67], v[216:219], v[200:203], v[64:67]
	v_mfma_f32_16x16x32_bf16 v[116:119], v[212:215], v[180:183], v[116:119]
	v_mfma_f32_16x16x32_bf16 v[112:115], v[220:223], v[180:183], v[112:115]
	v_mfma_f32_16x16x32_bf16 v[100:103], v[212:215], v[188:191], v[100:103]
	v_mfma_f32_16x16x32_bf16 v[96:99], v[220:223], v[188:191], v[96:99]
	v_mfma_f32_16x16x32_bf16 v[84:87], v[212:215], v[196:199], v[84:87]
	v_mfma_f32_16x16x32_bf16 v[80:83], v[220:223], v[196:199], v[80:83]
	v_mfma_f32_16x16x32_bf16 v[68:71], v[212:215], v[204:207], v[68:71]
	v_mfma_f32_16x16x32_bf16 v[64:67], v[220:223], v[204:207], v[64:67]
	s_barrier
; #define PG8_STAGE(bufoff, gbase, voff) do { _Pragma("unroll") for (int _i = 0; _i < 2; ++_i) \
;         __builtin_amdgcn_global_load_lds((const unsigned*)((const char*)(gbase) + (voff)[_i]), (LAS unsigned*)(lds + (bufoff) + ldsw + _i * 8192), 16, 0, 0); } while (0)
; #define PG8_LDA(dst, b, h) do { _Pragma("unroll") for (int m = 0; m < 4; ++m) _Pragma("unroll") for (int k = 0; k < 2; ++k) dst[m][k] = *(const LAS bf16x8*)(lds + PG8_SA(b, h) + aoff + m * 2048 + k * 1024); } while (0)
; #define PG8_MMA(ai, bj, At, Bt) do { __builtin_amdgcn_s_setprio(1); _Pragma("unroll") for (int m = 0; m < 4; ++m) _Pragma("unroll") for (int n = 0; n < 2; ++n) _Pragma("unroll") for (int k = 0; k < 2; ++k) \
;         acc[ai][bj][m][n] = __builtin_amdgcn_mfma_f32_16x16x32_bf16(Bt[n][k], At[m][k], acc[ai][bj][m][n], 0, 0, 0); __builtin_amdgcn_s_setprio(0); } while (0)
; #define PG8_WAIT_V(n) asm volatile("s_waitcnt vmcnt(" #n ")" ::: "memory")
; #define PG8_WAIT_L(n) asm volatile("s_waitcnt lgkmcnt(" #n ")" ::: "memory")
; #define PG8_BAR __builtin_amdgcn_s_barrier()
; #define PG8_SCHED __builtin_amdgcn_sched_barrier(0)
; template <class Epi>
; __device__ __forceinline__ void gemm_phase(LAS unsigned char* lds, const Gemm g, const StaticOrder& S, const Epi& E) {
;     ...
;             PG8_LDA(At, 1, 1); PG8_STAGE(PG8_SA(1, 0), a3, voffA);
;             PG8_BAR; PG8_WAIT_L(0); PG8_MMA(1, 0, At, B0); PG8_BAR; PG8_SCHED;
;             PG8_STAGE(PG8_SB(1, 1), b3 + hstep, voffB);
;             PG8_WAIT_V(6); PG8_BAR; PG8_MMA(1, 1, At, B1); PG8_BAR;
;         }
	s_setprio 0
	s_add_i32 s19, s64, s21
	v_lshl_add_u64 v[158:159], v[158:159], 0, s[12:13]
	s_mov_b32 m0, s19
	s_nop 0
	global_load_lds_dwordx4 v[158:159], off
	v_lshl_add_u64 v[158:159], v[176:177], 0, s[12:13]
	s_add_i32 m0, s19, 0x2000
	s_nop 0
	global_load_lds_dwordx4 v[158:159], off
	s_mov_b32 m0, s36
	v_lshl_add_u64 v[158:159], v[224:225], 0, s[12:13]
	ds_read_b128 v[172:175], v163 offset:49152
	ds_read_b128 v[180:183], v163 offset:50176
	ds_read_b128 v[184:187], v163 offset:51200
	ds_read_b128 v[188:191], v163 offset:52224
	ds_read_b128 v[192:195], v163 offset:53248
	ds_read_b128 v[196:199], v163 offset:54272
	ds_read_b128 v[200:203], v163 offset:55296
	ds_read_b128 v[204:207], v163 offset:56320
	global_load_lds_dwordx4 v[158:159], off
	v_lshl_add_u64 v[158:159], v[226:227], 0, s[12:13]
	s_mov_b32 m0, s37
	s_nop 0
	global_load_lds_dwordx4 v[158:159], off
	s_add_u32 s16, s16, 0x158080
	s_addc_u32 s17, s17, 0
	s_add_i32 s18, s18, s21
	v_lshl_add_u64 v[252:253], s[16:17], 0, v[140:141]
	s_mov_b32 m0, s18
	s_nop 0
	global_load_lds_dwordx4 v[252:253], off
	v_lshl_add_u64 v[252:253], s[16:17], 0, v[144:145]
	s_add_i32 m0, s18, 0x2000
	s_nop 0
	global_load_lds_dwordx4 v[252:253], off
	s_waitcnt lgkmcnt(0)
	s_waitcnt vmcnt(8)
	s_setprio 1
	s_barrier
	v_mfma_f32_16x16x32_bf16 v[60:63], v[128:131], v[172:175], v[60:63]
	v_mfma_f32_16x16x32_bf16 v[56:59], v[154:157], v[172:175], v[56:59]
	v_mfma_f32_16x16x32_bf16 v[44:47], v[128:131], v[184:187], v[44:47]
	v_mfma_f32_16x16x32_bf16 v[40:43], v[154:157], v[184:187], v[40:43]
	v_mfma_f32_16x16x32_bf16 v[28:31], v[128:131], v[192:195], v[28:31]
	v_mfma_f32_16x16x32_bf16 v[24:27], v[154:157], v[192:195], v[24:27]
	v_mfma_f32_16x16x32_bf16 v[12:15], v[128:131], v[200:203], v[12:15]
	v_mfma_f32_16x16x32_bf16 v[8:11], v[154:157], v[200:203], v[8:11]
	v_mfma_f32_16x16x32_bf16 v[60:63], v[132:135], v[180:183], v[60:63]
	v_mfma_f32_16x16x32_bf16 v[56:59], v[168:171], v[180:183], v[56:59]
	v_mfma_f32_16x16x32_bf16 v[44:47], v[132:135], v[188:191], v[44:47]
	v_mfma_f32_16x16x32_bf16 v[40:43], v[168:171], v[188:191], v[40:43]
	v_mfma_f32_16x16x32_bf16 v[28:31], v[132:135], v[196:199], v[28:31]
	v_mfma_f32_16x16x32_bf16 v[24:27], v[168:171], v[196:199], v[24:27]
	v_mfma_f32_16x16x32_bf16 v[12:15], v[132:135], v[204:207], v[12:15]
	v_mfma_f32_16x16x32_bf16 v[8:11], v[168:171], v[204:207], v[8:11]
	v_mfma_f32_16x16x32_bf16 v[52:55], v[208:211], v[172:175], v[52:55]
	v_mfma_f32_16x16x32_bf16 v[48:51], v[216:219], v[172:175], v[48:51]
	v_mfma_f32_16x16x32_bf16 v[36:39], v[208:211], v[184:187], v[36:39]
	v_mfma_f32_16x16x32_bf16 v[32:35], v[216:219], v[184:187], v[32:35]
	v_mfma_f32_16x16x32_bf16 v[20:23], v[208:211], v[192:195], v[20:23]
	v_mfma_f32_16x16x32_bf16 v[16:19], v[216:219], v[192:195], v[16:19]
	v_mfma_f32_16x16x32_bf16 v[4:7], v[208:211], v[200:203], v[4:7]
	v_mfma_f32_16x16x32_bf16 v[0:3], v[216:219], v[200:203], v[0:3]
	v_mfma_f32_16x16x32_bf16 v[52:55], v[212:215], v[180:183], v[52:55]
	v_mfma_f32_16x16x32_bf16 v[48:51], v[220:223], v[180:183], v[48:51]
	v_mfma_f32_16x16x32_bf16 v[36:39], v[212:215], v[188:191], v[36:39]
	v_mfma_f32_16x16x32_bf16 v[32:35], v[220:223], v[188:191], v[32:35]
	v_mfma_f32_16x16x32_bf16 v[20:23], v[212:215], v[196:199], v[20:23]
	v_mfma_f32_16x16x32_bf16 v[16:19], v[220:223], v[196:199], v[16:19]
	v_mfma_f32_16x16x32_bf16 v[4:7], v[212:215], v[204:207], v[4:7]
	v_mfma_f32_16x16x32_bf16 v[0:3], v[220:223], v[204:207], v[0:3]
	s_barrier
	s_setprio 0
	s_add_i32 s63, s63, 2
	s_add_u32 s14, s14, 0x100
	s_addc_u32 s15, s15, 0
	s_add_u32 s61, s61, 0x100
	s_addc_u32 s62, s62, 0
	s_cmpk_gt_u32 s63, 0x53
	s_cbranch_scc0 .LBB0_1411
; __device__ __forceinline__ float bflo(unsigned w) { return __uint_as_float(w << 16); }
; __device__ __forceinline__ float bfhi(unsigned w) { return __uint_as_float(w & 0xffff0000u); }
; #define ER_LOAD(g_, set_) do { const size_t off_ = (size_t)(row0 + ((g_) >> 2) * HALF + ((g_) & 3) * 16) * DM + col0; \
;         hv[set_][0] = *(const u32x4*)(HB + off_); hv[set_][1] = *(const u32x4*)(HB + off_ + HALF); } while (0)
;     __device__ __forceinline__ void operator()(const f32x4 (&acc)[2][2][4][2], const Unit& u, int wr, int wc, int fr, int fq, const Pre&) const {
;         const int row0 = ROW_X + u.pm * BM + wr * 64 + fr, col0 = u.pn * BM + wc * 32 + 8 * fq;
;         u32x4 hv[2][2]; float sprev = 0.f;
;     ...
;         ER_LOAD(0, 0);
; #pragma unroll
;         for (int g = 0; g < 8; ++g) { const int ai = g >> 2, m = g & 3; const int r = row0 + ai * HALF + m * 16; const size_t off = (size_t)r * DM + col0; float s = 0.f;
;             if (g + 1 < 8) ER_LOAD(g + 1, (g + 1) & 1);
; #pragma unroll
;             for (int bj = 0; bj < 2; ++bj) { const u32x4 w = hv[g & 1][bj];
;                 const f32x4 h0 = {bflo(w.x), bfhi(w.x), bflo(w.y), bfhi(w.y)}, h1 = {bflo(w.z), bfhi(w.z), bflo(w.w), bfhi(w.w)};
;                 const f32x4 o0 = h0 + acc[ai][bj][m][0] * alpha, o1 = h1 + acc[ai][bj][m][1] * alpha;
;                 if (FINAL) { float* op = OUT + (size_t)(r - ROW_X) * DM + col0 + bj * HALF; *(f32x4*)op = o0; *(f32x4*)(op + 4) = o1; }
;                 else { u32x4 q; q.x = cvtpk(o0[0], o0[1]); q.y = cvtpk(o0[2], o0[3]); q.z = cvtpk(o1[0], o1[1]); q.w = cvtpk(o1[2], o1[3]); *(u32x4*)(HB + off + bj * HALF) = q;
;                        s += ((o0[0] * o0[0] + o0[1] * o0[1]) + (o0[2] * o0[2] + o0[3] * o0[3])) + ((o1[0] * o1[0] + o1[1] * o1[1]) + (o1[2] * o1[2] + o1[3] * o1[3])); } }
;             if (!FINAL) { if (g > 0) { float t = sprev; t += __shfl_xor(t, 16); t += __shfl_xor(t, 32);
;                     if (fq == 0) __hip_atomic_fetch_add(ssq_out + row0 + ((g - 1) >> 2) * HALF + ((g - 1) & 3) * 16, t, __ATOMIC_RELAXED, __HIP_MEMORY_SCOPE_AGENT); }
;                 sprev = s; } }
;     ...
;         if (!FINAL) { float t = sprev; t += __shfl_xor(t, 16); t += __shfl_xor(t, 32);
;             if (fq == 0) __hip_atomic_fetch_add(ssq_out + row0 + HALF + 48, t, __ATOMIC_RELAXED, __HIP_MEMORY_SCOPE_AGENT); }
	v_lshl_add_u32 v156, s59, 8, v160
	v_lshl_or_b32 v154, s60, 8, v161
	v_ashrrev_i32_e32 v157, 31, v156
	v_ashrrev_i32_e32 v155, 31, v154
	v_lshlrev_b64 v[128:129], 12, v[156:157]
	v_lshl_add_u64 v[128:129], s[8:9], 0, v[128:129]
	v_lshlrev_b64 v[130:131], 1, v[154:155]
	v_lshl_add_u64 v[176:177], v[128:129], 0, v[130:131]
	v_or_b32_e32 v128, 16, v156
	v_ashrrev_i32_e32 v129, 31, v128
	global_load_dwordx4 v[168:171], v[176:177], off
	global_load_dwordx4 v[172:175], v[176:177], off offset:256
	v_lshlrev_b64 v[128:129], 12, v[128:129]
	v_lshl_add_u64 v[128:129], s[8:9], 0, v[128:129]
	v_lshl_add_u64 v[188:189], v[128:129], 0, v[130:131]
	global_load_dwordx4 v[180:183], v[188:189], off
	global_load_dwordx4 v[184:187], v[188:189], off offset:256
	v_or_b32_e32 v128, 32, v156
	v_ashrrev_i32_e32 v129, 31, v128
	v_lshlrev_b64 v[128:129], 12, v[128:129]
	v_lshl_add_u64 v[128:129], s[8:9], 0, v[128:129]
	v_lshl_add_u64 v[158:159], v[128:129], 0, v[130:131]
	global_load_dwordx4 v[132:135], v[158:159], off
	global_load_dwordx4 v[128:131], v[158:159], off offset:256
	s_waitcnt vmcnt(0)
	v_lshlrev_b32_e32 v190, 16, v168
	v_and_b32_e32 v191, 0xffff0000, v168
	v_lshlrev_b32_e32 v168, 16, v169
	v_and_b32_e32 v169, 0xffff0000, v169
	v_lshlrev_b32_e32 v192, 16, v170
	v_and_b32_e32 v193, 0xffff0000, v170
	v_lshlrev_b32_e32 v170, 16, v171
	v_and_b32_e32 v171, 0xffff0000, v171
	v_lshlrev_b32_e32 v194, 16, v172
	v_and_b32_e32 v195, 0xffff0000, v172
	v_lshlrev_b32_e32 v172, 16, v173
	v_and_b32_e32 v173, 0xffff0000, v173
	v_lshlrev_b32_e32 v196, 16, v174
	v_and_b32_e32 v197, 0xffff0000, v174
	v_lshlrev_b32_e32 v174, 16, v175
	v_and_b32_e32 v175, 0xffff0000, v175
	v_pk_fma_f32 v[126:127], v[126:127], 0.5, v[168:169] op_sel_hi:[1,0,1]
	v_pk_fma_f32 v[124:125], v[124:125], 0.5, v[190:191] op_sel_hi:[1,0,1]
	v_pk_fma_f32 v[122:123], v[122:123], 0.5, v[170:171] op_sel_hi:[1,0,1]
	v_pk_fma_f32 v[168:169], v[120:121], 0.5, v[192:193] op_sel_hi:[1,0,1]
	v_pk_fma_f32 v[170:171], v[118:119], 0.5, v[172:173] op_sel_hi:[1,0,1]
	v_pk_fma_f32 v[172:173], v[116:117], 0.5, v[194:195] op_sel_hi:[1,0,1]
	v_pk_fma_f32 v[174:175], v[114:115], 0.5, v[174:175] op_sel_hi:[1,0,1]
	v_pk_fma_f32 v[190:191], v[112:113], 0.5, v[196:197] op_sel_hi:[1,0,1]
	v_cvt_pk_bf16_f32 v114, v124, v125
	v_cvt_pk_bf16_f32 v115, v126, v127
	v_cvt_pk_bf16_f32 v116, v168, v169
	v_cvt_pk_bf16_f32 v117, v122, v123
	v_mul_f32_e32 v125, v125, v125
	v_mul_f32_e32 v127, v127, v127
	v_mul_f32_e32 v167, v169, v169
	v_mul_f32_e32 v123, v123, v123
	v_cvt_pk_bf16_f32 v118, v172, v173
	v_cvt_pk_bf16_f32 v119, v170, v171
	v_cvt_pk_bf16_f32 v121, v174, v175
	v_mul_f32_e32 v169, v173, v173
	v_mul_f32_e32 v171, v171, v171
	v_mul_f32_e32 v173, v191, v191
	v_mul_f32_e32 v175, v175, v175
	v_lshlrev_b32_e32 v112, 16, v180
	v_and_b32_e32 v113, 0xffff0000, v180
	v_lshlrev_b32_e32 v192, 16, v182
	v_and_b32_e32 v193, 0xffff0000, v182
	v_lshlrev_b32_e32 v182, 16, v183
	v_and_b32_e32 v183, 0xffff0000, v183
	v_fmac_f32_e32 v125, v124, v124
	v_fmac_f32_e32 v127, v126, v126
	v_fmac_f32_e32 v167, v168, v168
	v_fmac_f32_e32 v123, v122, v122
	v_fmac_f32_e32 v169, v172, v172
	v_fmac_f32_e32 v171, v170, v170
	v_fmac_f32_e32 v173, v190, v190
	v_fmac_f32_e32 v175, v174, v174
	v_lshlrev_b32_e32 v180, 16, v181
	v_and_b32_e32 v181, 0xffff0000, v181
	v_pk_fma_f32 v[112:113], v[108:109], 0.5, v[112:113] op_sel_hi:[1,0,1]
	v_pk_fma_f32 v[108:109], v[106:107], 0.5, v[182:183] op_sel_hi:[1,0,1]
	global_store_dwordx4 v[176:177], v[114:117], off
	v_add_f32_e32 v106, v125, v127
	v_add_f32_e32 v107, v167, v123
	v_add_f32_e32 v114, v169, v171
	v_add_f32_e32 v115, v173, v175
	v_pk_fma_f32 v[110:111], v[110:111], 0.5, v[180:181] op_sel_hi:[1,0,1]
	v_add_f32_e32 v106, v106, v107
	v_add_f32_e32 v107, v114, v115
	v_pk_fma_f32 v[114:115], v[104:105], 0.5, v[192:193] op_sel_hi:[1,0,1]
	v_add_f32_e32 v125, v106, v107
	v_cvt_pk_bf16_f32 v104, v112, v113
	v_cvt_pk_bf16_f32 v105, v110, v111
	v_cvt_pk_bf16_f32 v106, v114, v115
	v_cvt_pk_bf16_f32 v107, v108, v109
	v_cvt_pk_bf16_f32 v120, v190, v191
	global_store_dwordx4 v[188:189], v[104:107], off
	global_store_dwordx4 v[176:177], v[118:121], off offset:256
	v_lshlrev_b32_e32 v122, 16, v186
	v_lshlrev_b32_e32 v104, 16, v184
	v_and_b32_e32 v105, 0xffff0000, v184
	v_pk_fma_f32 v[118:119], v[100:101], 0.5, v[104:105] op_sel_hi:[1,0,1]
	v_and_b32_e32 v101, 64, v166
	v_xor_b32_e32 v100, 16, v166
	v_add_u32_e32 v101, 64, v101
	v_cmp_lt_i32_e32 vcc, v100, v101
	v_and_b32_e32 v123, 0xffff0000, v186
	v_pk_fma_f32 v[122:123], v[96:97], 0.5, v[122:123] op_sel_hi:[1,0,1]
	v_cndmask_b32_e32 v100, v166, v100, vcc
	v_lshlrev_b32_e32 v124, 2, v100
	ds_bpermute_b32 v100, v124, v125
	v_xor_b32_e32 v97, 32, v166
	v_cmp_lt_i32_e32 vcc, v97, v101
	v_lshlrev_b32_e32 v106, 16, v185
	v_and_b32_e32 v107, 0xffff0000, v185
	v_cndmask_b32_e32 v97, v166, v97, vcc
	s_waitcnt lgkmcnt(0)
	v_add_f32_e32 v96, v125, v100
	v_lshlrev_b32_e32 v125, 2, v97
	ds_bpermute_b32 v97, v125, v96
	v_lshlrev_b32_e32 v120, 16, v187
	v_and_b32_e32 v121, 0xffff0000, v187
	v_pk_fma_f32 v[116:117], v[102:103], 0.5, v[106:107] op_sel_hi:[1,0,1]
	v_pk_fma_f32 v[120:121], v[98:99], 0.5, v[120:121] op_sel_hi:[1,0,1]
	v_cvt_pk_bf16_f32 v98, v118, v119
	v_cvt_pk_bf16_f32 v99, v116, v117
	v_cvt_pk_bf16_f32 v100, v122, v123
	v_cvt_pk_bf16_f32 v101, v120, v121
	v_lshl_add_u64 v[104:105], v[156:157], 2, s[10:11]
	global_store_dwordx4 v[188:189], v[98:101], off offset:256
	s_and_saveexec_b64 s[14:15], s[2:3]
	s_cbranch_execz .LBB0_1414
	s_waitcnt lgkmcnt(0)
	v_add_f32_e32 v96, v96, v97
	global_atomic_add_f32 v[104:105], v96, off

; #define PG8_STAGE(bufoff, gbase, voff) do { _Pragma("unroll") for (int _i = 0; _i < 2; ++_i) \
;         __builtin_amdgcn_global_load_lds((const unsigned*)((const char*)(gbase) + (voff)[_i]), (LAS unsigned*)(lds + (bufoff) + ldsw + _i * 8192), 16, 0, 0); } while (0)
; #define PG8_WAIT_V(n) asm volatile("s_waitcnt vmcnt(" #n ")" ::: "memory")
; #define PG8_BAR __builtin_amdgcn_s_barrier()
; template <class Epi>
; __device__ __forceinline__ void gemm_phase(LAS unsigned char* lds, const Gemm g, const StaticOrder& S, const Epi& E) {
;     const int tid = threadIdx.x, wid = __builtin_amdgcn_readfirstlane(tid >> 6), lane = tid & 63, wr = wid >> 2, wc = wid & 3, fr = lane & 15, fq = lane >> 4;
;     const int K = g.K, nt = K / BK;
;     unsigned voffA[2], voffB[2];
; #pragma unroll
;     for (int i = 0; i < 2; ++i) { int R, C; stage_rc(tid * 16 + i * 8192, R, C); const int Rb = Epi::PERM ? ((R & ~31) + perm32(R & 31)) : R;
;         voffA[i] = (unsigned)(R * K + C) * 2u; voffB[i] = (unsigned)(Rb * K + C) * 2u; }
;     const size_t kstep = (size_t)(BK * 2);
;     const size_t hstep = (size_t)HALF * K * 2;
;     const size_t tstep = 2 * hstep;
;     const unsigned ldsw = (unsigned)wid * 1024u;
;     const int aoff = lds_byte(wr * 64 + fr, fq * 8), boff = lds_byte(wc * 32 + fr, fq * 8);
;     ...
;     Unit cur, nxt; int ui = 0;
;     if (!S.next(0, cur)) return;
;     f32x4 acc[2][2][4][2];
; #pragma unroll
;     for (int a = 0; a < 2; ++a)
; #pragma unroll
;         for (int b = 0; b < 2; ++b)
; #pragma unroll
;             for (int m = 0; m < 4; ++m)
; #pragma unroll
;                 for (int n = 0; n < 2; ++n) acc[a][b][m][n] = (f32x4){0.f, 0.f, 0.f, 0.f};
;     bf16x8 At[4][2], B0[2][2], B1[2][2];
;     const char* cA = (const char*)g.A + (size_t)cur.pm * tstep; const char* cB = (const char*)g.Bt + (size_t)cur.pn * tstep;
;     typename Epi::Pre pre = E.pre(cur, wr, fr);
;     PG8_STAGE(PG8_SB(0, 0), cB, voffB); PG8_STAGE(PG8_SA(0, 0), cA, voffA); PG8_STAGE(PG8_SB(0, 1), cB + hstep, voffB); PG8_STAGE(PG8_SA(0, 1), cA + hstep, voffA);
;     if (wr == 1) PG8_BAR;
;     PG8_WAIT_V(4); PG8_BAR;
;     PG8_STAGE(PG8_SB(1, 0), cB + kstep, voffB); PG8_STAGE(PG8_SA(1, 0), cA + kstep, voffA); PG8_STAGE(PG8_SB(1, 1), cB + hstep + kstep, voffB);
;     PG8_WAIT_V(6); PG8_BAR;
.LBB0_1787:
	s_mov_b64 s[24:25], 0x80
	s_and_b32 s1, s2, 3
	s_add_i32 m0, s62, 0x18000
	v_lshl_add_u64 v[6:7], v[6:7], 0, s[24:25]
	s_lshl_b32 s5, s3, 13
	s_lshl_b32 s12, s1, 12
	s_waitcnt vmcnt(2)
	s_barrier
	global_load_lds_dwordx4 v[6:7], off
	v_lshl_add_u64 v[4:5], v[4:5], 0, s[24:25]
	s_add_i32 m0, s62, 0x1a000
	s_add_i32 s67, s62, 0x8000
	s_add_i32 s68, s62, 0xa000
	global_load_lds_dwordx4 v[4:5], off
	v_lshl_add_u64 v[2:3], v[2:3], 0, s[24:25]
	s_mov_b32 m0, s67
	s_add_u32 s2, s10, 0x80080
	global_load_lds_dwordx4 v[2:3], off
	v_lshl_add_u64 v[0:1], v[0:1], 0, s[24:25]
	s_mov_b32 m0, s68
	s_addc_u32 s3, s11, 0
	global_load_lds_dwordx4 v[0:1], off
	s_add_i32 m0, s62, 0x1c000
	v_lshl_add_u64 v[0:1], s[2:3], 0, v[130:131]
	global_load_lds_dwordx4 v[0:1], off
	v_lshl_add_u64 v[0:1], s[2:3], 0, v[134:135]
	s_add_i32 m0, s62, 0x1e000
	v_lshlrev_b32_e32 v2, 6, v12
	global_load_lds_dwordx4 v[0:1], off
	v_lshrrev_b32_e32 v0, 4, v178
	v_and_b32_e32 v0, 3, v0
	v_lshlrev_b32_e32 v1, 3, v0
	v_lshlrev_b32_e32 v3, 4, v0
	s_movk_i32 s2, 0x3c0
	v_lshlrev_b32_e32 v4, 2, v12
	v_cmp_gt_u32_e32 vcc, 2, v0
	v_lshlrev_b32_e32 v136, 5, v0
	v_lshlrev_b32_e32 v0, 9, v178
	v_and_or_b32 v2, v2, s2, v3
	v_and_b32_e32 v4, 32, v4
	v_lshl_or_b32 v156, s1, 5, v1
	v_and_b32_e32 v0, 0x70000, v0
	v_lshlrev_b32_e32 v1, 12, v10
	v_bitop3_b32 v2, v2, s5, v4 bitop3:0xde
	v_lshlrev_b32_e32 v4, 6, v178
	v_or3_b32 v0, v8, v0, v1
	v_and_or_b32 v3, v4, s2, v3
	v_lshlrev_b32_e32 v4, 2, v178
	v_add_u32_e32 v142, v0, v9
	v_lshlrev_b32_e32 v0, 5, v11
	v_and_b32_e32 v4, 32, v4
	s_waitcnt vmcnt(6)
	s_cmp_eq_u32 s1, 0
	v_and_b32_e32 v0, 0xf0000, v0
	v_bitop3_b32 v155, s12, v3, v4 bitop3:0xf6
	s_cselect_b64 s[2:3], -1, 0
	v_or3_b32 v0, v8, v0, v1
	s_add_i32 s72, 0, 0x10000
	s_add_i32 s73, 0, 0x14000
	s_and_b64 s[30:31], s[2:3], vcc
	s_ashr_i32 s69, s54, 31
	s_mov_b32 s70, s54
	s_ashr_i32 s71, s28, 31
	v_lshl_add_u64 v[138:139], s[8:9], 0, v[136:137]
	v_lshl_add_u64 v[140:141], s[40:41], 0, v[136:137]
	v_mov_b32_e32 v143, v137
	v_add_u32_e32 v144, v0, v9
	v_mov_b32_e32 v145, v137
	v_mov_b64_e32 v[146:147], 0x800
	v_mov_b64_e32 v[148:149], 0x7ff
	v_add_u32_e32 v157, s72, v155
	v_add_u32_e32 v158, 0, v2
	v_add_u32_e32 v159, s73, v155
	v_mov_b32_e32 v160, 0x358637bd
	s_mov_b32 s74, 0xbfb8aa3b
	s_mov_b32 s75, 0x800000
	s_mov_b32 s76, 0x3f317217
	s_mov_b32 s77, 0x7f800000
	v_mov_b32_e32 v161, 0x41b17218
	s_barrier
	s_branch .LBB0_1789

; #define PG8_STAGE(bufoff, gbase, voff) do { _Pragma("unroll") for (int _i = 0; _i < 2; ++_i) \
;         __builtin_amdgcn_global_load_lds((const unsigned*)((const char*)(gbase) + (voff)[_i]), (LAS unsigned*)(lds + (bufoff) + ldsw + _i * 8192), 16, 0, 0); } while (0)
; #define PG8_LDA(dst, b, h) do { _Pragma("unroll") for (int m = 0; m < 4; ++m) _Pragma("unroll") for (int k = 0; k < 2; ++k) dst[m][k] = *(const LAS bf16x8*)(lds + PG8_SA(b, h) + aoff + m * 2048 + k * 1024); } while (0)
; #define PG8_LDB(dst, b, h) do { _Pragma("unroll") for (int n = 0; n < 2; ++n) _Pragma("unroll") for (int k = 0; k < 2; ++k) dst[n][k] = *(const LAS bf16x8*)(lds + PG8_SB(b, h) + boff + n * 2048 + k * 1024); } while (0)
; #define PG8_MMA(ai, bj, At, Bt) do { __builtin_amdgcn_s_setprio(1); _Pragma("unroll") for (int m = 0; m < 4; ++m) _Pragma("unroll") for (int n = 0; n < 2; ++n) _Pragma("unroll") for (int k = 0; k < 2; ++k) \
;         acc[ai][bj][m][n] = __builtin_amdgcn_mfma_f32_16x16x32_bf16(Bt[n][k], At[m][k], acc[ai][bj][m][n], 0, 0, 0); __builtin_amdgcn_s_setprio(0); } while (0)
; #define PG8_WAIT_V(n) asm volatile("s_waitcnt vmcnt(" #n ")" ::: "memory")
; #define PG8_WAIT_L(n) asm volatile("s_waitcnt lgkmcnt(" #n ")" ::: "memory")
; template <class Epi>
; __device__ __forceinline__ void gemm_phase(LAS unsigned char* lds, const Gemm g, const StaticOrder& S, const Epi& E) {
;     ...
;         for (int t = 0; t < nt; t += 2) {
;             const bool last = (t == nt - 2);
;             const char* a1 = cA + (size_t)(t + 1) * kstep;
;             const char* a2 = last ? nA : cA + (size_t)(t + 2) * kstep; const char* b2 = last ? nB : cB + (size_t)(t + 2) * kstep;
;             const char* a3 = a2 + kstep; const char* b3 = b2 + kstep;
;             PG8_LDB(B0, 0, 0); PG8_SCHED; PG8_LDA(At, 0, 0); PG8_STAGE(PG8_SA(1, 1), a1 + hstep, voffA);
;             PG8_WAIT_L(8); PG8_BAR; PG8_WAIT_L(0); PG8_MMA(0, 0, At, B0); PG8_BAR; PG8_SCHED;
;             PG8_LDB(B1, 0, 1); PG8_STAGE(PG8_SB(0, 0), b2, voffB);
;             PG8_BAR; PG8_WAIT_L(0); PG8_MMA(0, 1, At, B1); PG8_BAR;
;             PG8_LDA(At, 0, 1); PG8_STAGE(PG8_SA(0, 0), a2, voffA);
;             PG8_BAR; PG8_WAIT_L(0); PG8_MMA(1, 0, At, B0); PG8_BAR; PG8_SCHED;
;             PG8_STAGE(PG8_SB(0, 1), b2 + hstep, voffB);
;             PG8_WAIT_V(6); PG8_BAR; PG8_MMA(1, 1, At, B1); PG8_BAR;
.LBB0_1796:
	ds_read_b128 v[172:175], v157
	ds_read_b128 v[180:183], v157 offset:1024
	ds_read_b128 v[184:187], v157 offset:2048
	ds_read_b128 v[188:191], v157 offset:3072
	s_add_u32 s8, s6, 0xfff80080
	s_addc_u32 s9, s7, -1
	s_cmp_eq_u32 s37, 28
	s_cselect_b32 s11, s1, s9
	s_cselect_b32 s10, s5, s8
	s_cselect_b32 s9, s12, s35
	s_cselect_b32 s8, s13, s33
	v_lshl_add_u64 v[152:153], s[6:7], 0, v[142:143]
	s_add_i32 m0, s62, 0xc000
	ds_read_b128 v[192:195], v158
	ds_read_b128 v[196:199], v158 offset:1024
	ds_read_b128 v[200:203], v158 offset:2048
	ds_read_b128 v[204:207], v158 offset:3072
	ds_read_b128 v[208:211], v158 offset:4096
	ds_read_b128 v[212:215], v158 offset:5120
	ds_read_b128 v[216:219], v158 offset:6144
	ds_read_b128 v[220:223], v158 offset:7168
	global_load_lds_dwordx4 v[152:153], off
	v_lshl_add_u64 v[152:153], s[6:7], 0, v[144:145]
	s_add_i32 m0, s62, 0xe000
	s_nop 0
	global_load_lds_dwordx4 v[152:153], off
	ds_read_b128 v[224:227], v159
	ds_read_b128 v[228:231], v159 offset:1024
	ds_read_b128 v[232:235], v159 offset:2048
	ds_read_b128 v[236:239], v159 offset:3072
	s_waitcnt lgkmcnt(0)
	s_waitcnt vmcnt(8)
	s_setprio 1
	s_barrier
	v_mfma_f32_16x16x32_bf16 v[116:119], v[172:175], v[192:195], v[116:119]
	v_mfma_f32_16x16x32_bf16 v[112:115], v[184:187], v[192:195], v[112:115]
	v_mfma_f32_16x16x32_bf16 v[100:103], v[172:175], v[200:203], v[100:103]
	v_mfma_f32_16x16x32_bf16 v[96:99], v[184:187], v[200:203], v[96:99]
	v_mfma_f32_16x16x32_bf16 v[84:87], v[172:175], v[208:211], v[84:87]
	v_mfma_f32_16x16x32_bf16 v[80:83], v[184:187], v[208:211], v[80:83]
	v_mfma_f32_16x16x32_bf16 v[68:71], v[172:175], v[216:219], v[68:71]
	v_mfma_f32_16x16x32_bf16 v[64:67], v[184:187], v[216:219], v[64:67]
	v_mfma_f32_16x16x32_bf16 v[116:119], v[180:183], v[196:199], v[116:119]
	v_mfma_f32_16x16x32_bf16 v[112:115], v[188:191], v[196:199], v[112:115]
	v_mfma_f32_16x16x32_bf16 v[100:103], v[180:183], v[204:207], v[100:103]
	v_mfma_f32_16x16x32_bf16 v[96:99], v[188:191], v[204:207], v[96:99]
	v_mfma_f32_16x16x32_bf16 v[84:87], v[180:183], v[212:215], v[84:87]
	v_mfma_f32_16x16x32_bf16 v[80:83], v[188:191], v[212:215], v[80:83]
	v_mfma_f32_16x16x32_bf16 v[68:71], v[180:183], v[220:223], v[68:71]
	v_mfma_f32_16x16x32_bf16 v[64:67], v[188:191], v[220:223], v[64:67]
	v_mfma_f32_16x16x32_bf16 v[124:127], v[224:227], v[192:195], v[124:127]
	v_mfma_f32_16x16x32_bf16 v[120:123], v[232:235], v[192:195], v[120:123]
	v_mfma_f32_16x16x32_bf16 v[108:111], v[224:227], v[200:203], v[108:111]
	v_mfma_f32_16x16x32_bf16 v[104:107], v[232:235], v[200:203], v[104:107]
	v_mfma_f32_16x16x32_bf16 v[92:95], v[224:227], v[208:211], v[92:95]
	v_mfma_f32_16x16x32_bf16 v[88:91], v[232:235], v[208:211], v[88:91]
	v_mfma_f32_16x16x32_bf16 v[76:79], v[224:227], v[216:219], v[76:79]
	v_mfma_f32_16x16x32_bf16 v[72:75], v[232:235], v[216:219], v[72:75]
	v_mfma_f32_16x16x32_bf16 v[124:127], v[228:231], v[196:199], v[124:127]
	v_mfma_f32_16x16x32_bf16 v[120:123], v[236:239], v[196:199], v[120:123]
	v_mfma_f32_16x16x32_bf16 v[108:111], v[228:231], v[204:207], v[108:111]
	v_mfma_f32_16x16x32_bf16 v[104:107], v[236:239], v[204:207], v[104:107]
	v_mfma_f32_16x16x32_bf16 v[92:95], v[228:231], v[212:215], v[92:95]
	v_mfma_f32_16x16x32_bf16 v[88:91], v[236:239], v[212:215], v[88:91]
	v_mfma_f32_16x16x32_bf16 v[76:79], v[228:231], v[220:223], v[76:79]
	v_mfma_f32_16x16x32_bf16 v[72:75], v[236:239], v[220:223], v[72:75]
	s_barrier
	s_setprio 0
	s_add_i32 s42, s72, s57
	v_lshl_add_u64 v[152:153], s[8:9], 0, v[130:131]
	s_mov_b32 m0, s42
	s_nop 0
	global_load_lds_dwordx4 v[152:153], off
	v_lshl_add_u64 v[176:177], s[8:9], 0, v[134:135]
	s_add_i32 m0, s42, 0x2000
	s_nop 0
	global_load_lds_dwordx4 v[176:177], off
	s_mov_b32 m0, s62
	v_lshl_add_u64 v[240:241], s[10:11], 0, v[128:129]
	ds_read_b128 v[192:195], v158 offset:16384
	ds_read_b128 v[196:199], v158 offset:17408
	ds_read_b128 v[200:203], v158 offset:18432
	ds_read_b128 v[204:207], v158 offset:19456
	ds_read_b128 v[208:211], v158 offset:20480
	ds_read_b128 v[212:215], v158 offset:21504
	ds_read_b128 v[216:219], v158 offset:22528
	ds_read_b128 v[220:223], v158 offset:23552
	global_load_lds_dwordx4 v[240:241], off
	v_lshl_add_u64 v[242:243], s[10:11], 0, v[132:133]
	s_mov_b32 m0, s63
	s_nop 0
	global_load_lds_dwordx4 v[242:243], off
	s_add_u32 s42, s8, 0x80000
	s_addc_u32 s43, s9, 0
	s_add_i32 s78, s73, s57
	v_lshl_add_u64 v[252:253], s[42:43], 0, v[130:131]
	s_mov_b32 m0, s78
	s_nop 0
	global_load_lds_dwordx4 v[252:253], off
	v_lshl_add_u64 v[252:253], s[42:43], 0, v[134:135]
	s_add_i32 m0, s78, 0x2000
	s_nop 0
	global_load_lds_dwordx4 v[252:253], off
	s_waitcnt lgkmcnt(0)
	s_waitcnt vmcnt(8)
	s_setprio 1
	s_barrier
; #define PG8_STAGE(bufoff, gbase, voff) do { _Pragma("unroll") for (int _i = 0; _i < 2; ++_i) \
;         __builtin_amdgcn_global_load_lds((const unsigned*)((const char*)(gbase) + (voff)[_i]), (LAS unsigned*)(lds + (bufoff) + ldsw + _i * 8192), 16, 0, 0); } while (0)
; #define PG8_LDA(dst, b, h) do { _Pragma("unroll") for (int m = 0; m < 4; ++m) _Pragma("unroll") for (int k = 0; k < 2; ++k) dst[m][k] = *(const LAS bf16x8*)(lds + PG8_SA(b, h) + aoff + m * 2048 + k * 1024); } while (0)
; #define PG8_LDB(dst, b, h) do { _Pragma("unroll") for (int n = 0; n < 2; ++n) _Pragma("unroll") for (int k = 0; k < 2; ++k) dst[n][k] = *(const LAS bf16x8*)(lds + PG8_SB(b, h) + boff + n * 2048 + k * 1024); } while (0)
; #define PG8_MMA(ai, bj, At, Bt) do { __builtin_amdgcn_s_setprio(1); _Pragma("unroll") for (int m = 0; m < 4; ++m) _Pragma("unroll") for (int n = 0; n < 2; ++n) _Pragma("unroll") for (int k = 0; k < 2; ++k) \
;         acc[ai][bj][m][n] = __builtin_amdgcn_mfma_f32_16x16x32_bf16(Bt[n][k], At[m][k], acc[ai][bj][m][n], 0, 0, 0); __builtin_amdgcn_s_setprio(0); } while (0)
; #define PG8_WAIT_V(n) asm volatile("s_waitcnt vmcnt(" #n ")" ::: "memory")
; #define PG8_WAIT_L(n) asm volatile("s_waitcnt lgkmcnt(" #n ")" ::: "memory")
; #define PG8_BAR __builtin_amdgcn_s_barrier()
; #define PG8_SCHED __builtin_amdgcn_sched_barrier(0)
; template <class Epi>
; __device__ __forceinline__ void gemm_phase(LAS unsigned char* lds, const Gemm g, const StaticOrder& S, const Epi& E) {
;     ...
;             PG8_BAR; PG8_WAIT_L(0); PG8_MMA(0, 1, At, B1); PG8_BAR;
;             PG8_LDA(At, 0, 1); PG8_STAGE(PG8_SA(0, 0), a2, voffA);
;             PG8_BAR; PG8_WAIT_L(0); PG8_MMA(1, 0, At, B0); PG8_BAR; PG8_SCHED;
;             PG8_STAGE(PG8_SB(0, 1), b2 + hstep, voffB);
;             PG8_WAIT_V(6); PG8_BAR; PG8_MMA(1, 1, At, B1); PG8_BAR;
;             PG8_LDB(B0, 1, 0); PG8_SCHED; PG8_LDA(At, 1, 0); PG8_STAGE(PG8_SA(0, 1), a2 + hstep, voffA);
;             PG8_WAIT_L(8); PG8_BAR; PG8_WAIT_L(0); PG8_MMA(0, 0, At, B0); PG8_BAR; PG8_SCHED;
;             PG8_LDB(B1, 1, 1); PG8_STAGE(PG8_SB(1, 0), b3, voffB);
;             PG8_BAR; PG8_WAIT_L(0); PG8_MMA(0, 1, At, B1); PG8_BAR;
;             PG8_LDA(At, 1, 1); PG8_STAGE(PG8_SA(1, 0), a3, voffA);
;             PG8_BAR; PG8_WAIT_L(0); PG8_MMA(1, 0, At, B0); PG8_BAR; PG8_SCHED;
	v_mfma_f32_16x16x32_bf16 v[52:55], v[172:175], v[192:195], v[52:55]
	v_mfma_f32_16x16x32_bf16 v[48:51], v[184:187], v[192:195], v[48:51]
	v_mfma_f32_16x16x32_bf16 v[36:39], v[172:175], v[200:203], v[36:39]
	v_mfma_f32_16x16x32_bf16 v[32:35], v[184:187], v[200:203], v[32:35]
	v_mfma_f32_16x16x32_bf16 v[20:23], v[172:175], v[208:211], v[20:23]
	v_mfma_f32_16x16x32_bf16 v[16:19], v[184:187], v[208:211], v[16:19]
	v_mfma_f32_16x16x32_bf16 v[4:7], v[172:175], v[216:219], v[4:7]
	v_mfma_f32_16x16x32_bf16 v[0:3], v[184:187], v[216:219], v[0:3]
	v_mfma_f32_16x16x32_bf16 v[52:55], v[180:183], v[196:199], v[52:55]
	v_mfma_f32_16x16x32_bf16 v[48:51], v[188:191], v[196:199], v[48:51]
	v_mfma_f32_16x16x32_bf16 v[36:39], v[180:183], v[204:207], v[36:39]
	v_mfma_f32_16x16x32_bf16 v[32:35], v[188:191], v[204:207], v[32:35]
	v_mfma_f32_16x16x32_bf16 v[20:23], v[180:183], v[212:215], v[20:23]
	v_mfma_f32_16x16x32_bf16 v[16:19], v[188:191], v[212:215], v[16:19]
	v_mfma_f32_16x16x32_bf16 v[4:7], v[180:183], v[220:223], v[4:7]
	v_mfma_f32_16x16x32_bf16 v[0:3], v[188:191], v[220:223], v[0:3]
	v_mfma_f32_16x16x32_bf16 v[60:63], v[224:227], v[192:195], v[60:63]
	v_mfma_f32_16x16x32_bf16 v[56:59], v[232:235], v[192:195], v[56:59]
	v_mfma_f32_16x16x32_bf16 v[44:47], v[224:227], v[200:203], v[44:47]
	v_mfma_f32_16x16x32_bf16 v[40:43], v[232:235], v[200:203], v[40:43]
	v_mfma_f32_16x16x32_bf16 v[28:31], v[224:227], v[208:211], v[28:31]
	v_mfma_f32_16x16x32_bf16 v[24:27], v[232:235], v[208:211], v[24:27]
	v_mfma_f32_16x16x32_bf16 v[12:15], v[224:227], v[216:219], v[12:15]
	v_mfma_f32_16x16x32_bf16 v[8:11], v[232:235], v[216:219], v[8:11]
	v_mfma_f32_16x16x32_bf16 v[60:63], v[228:231], v[196:199], v[60:63]
	v_mfma_f32_16x16x32_bf16 v[56:59], v[236:239], v[196:199], v[56:59]
	v_mfma_f32_16x16x32_bf16 v[44:47], v[228:231], v[204:207], v[44:47]
	v_mfma_f32_16x16x32_bf16 v[40:43], v[236:239], v[204:207], v[40:43]
	v_mfma_f32_16x16x32_bf16 v[28:31], v[228:231], v[212:215], v[28:31]
	v_mfma_f32_16x16x32_bf16 v[24:27], v[236:239], v[212:215], v[24:27]
	v_mfma_f32_16x16x32_bf16 v[12:15], v[228:231], v[220:223], v[12:15]
	v_mfma_f32_16x16x32_bf16 v[8:11], v[236:239], v[220:223], v[8:11]
	s_barrier
	s_setprio 0
	s_add_i32 s42, 0, 0x18000
	v_add_u32_e32 v136, s42, v155
	ds_read_b128 v[172:175], v136
	ds_read_b128 v[180:183], v136 offset:1024
	ds_read_b128 v[184:187], v136 offset:2048
	ds_read_b128 v[188:191], v136 offset:3072
	s_add_u32 s10, s10, 0x80000
	s_addc_u32 s11, s11, 0
	s_mov_b32 m0, s64
	v_lshl_add_u64 v[224:225], s[10:11], 0, v[128:129]
	ds_read_b128 v[192:195], v158 offset:32768
	ds_read_b128 v[196:199], v158 offset:33792
	ds_read_b128 v[200:203], v158 offset:34816
	ds_read_b128 v[204:207], v158 offset:35840
	ds_read_b128 v[208:211], v158 offset:36864
	ds_read_b128 v[212:215], v158 offset:37888
	ds_read_b128 v[216:219], v158 offset:38912
	ds_read_b128 v[220:223], v158 offset:39936
	global_load_lds_dwordx4 v[224:225], off
	v_lshl_add_u64 v[224:225], s[10:11], 0, v[132:133]
	s_mov_b32 m0, s65
	s_nop 0
	global_load_lds_dwordx4 v[224:225], off
	s_add_i32 s10, 0, 0x1c000
	v_add_u32_e32 v136, s10, v155
	ds_read_b128 v[224:227], v136
	ds_read_b128 v[228:231], v136 offset:1024
	ds_read_b128 v[232:235], v136 offset:2048
	ds_read_b128 v[236:239], v136 offset:3072
	s_waitcnt lgkmcnt(0)
	s_waitcnt vmcnt(8)
	s_setprio 1
	s_barrier
	v_mfma_f32_16x16x32_bf16 v[116:119], v[172:175], v[192:195], v[116:119]
	v_mfma_f32_16x16x32_bf16 v[112:115], v[184:187], v[192:195], v[112:115]
	v_mfma_f32_16x16x32_bf16 v[100:103], v[172:175], v[200:203], v[100:103]
	v_mfma_f32_16x16x32_bf16 v[96:99], v[184:187], v[200:203], v[96:99]
	v_mfma_f32_16x16x32_bf16 v[84:87], v[172:175], v[208:211], v[84:87]
	v_mfma_f32_16x16x32_bf16 v[80:83], v[184:187], v[208:211], v[80:83]
	v_mfma_f32_16x16x32_bf16 v[68:71], v[172:175], v[216:219], v[68:71]
	v_mfma_f32_16x16x32_bf16 v[64:67], v[184:187], v[216:219], v[64:67]
	v_mfma_f32_16x16x32_bf16 v[116:119], v[180:183], v[196:199], v[116:119]
	v_mfma_f32_16x16x32_bf16 v[112:115], v[188:191], v[196:199], v[112:115]
	v_mfma_f32_16x16x32_bf16 v[100:103], v[180:183], v[204:207], v[100:103]
	v_mfma_f32_16x16x32_bf16 v[96:99], v[188:191], v[204:207], v[96:99]
	v_mfma_f32_16x16x32_bf16 v[84:87], v[180:183], v[212:215], v[84:87]
	v_mfma_f32_16x16x32_bf16 v[80:83], v[188:191], v[212:215], v[80:83]
	v_mfma_f32_16x16x32_bf16 v[68:71], v[180:183], v[220:223], v[68:71]
	v_mfma_f32_16x16x32_bf16 v[64:67], v[188:191], v[220:223], v[64:67]
	v_mfma_f32_16x16x32_bf16 v[124:127], v[224:227], v[192:195], v[124:127]
	v_mfma_f32_16x16x32_bf16 v[120:123], v[232:235], v[192:195], v[120:123]
	v_mfma_f32_16x16x32_bf16 v[108:111], v[224:227], v[200:203], v[108:111]
	v_mfma_f32_16x16x32_bf16 v[104:107], v[232:235], v[200:203], v[104:107]
	v_mfma_f32_16x16x32_bf16 v[92:95], v[224:227], v[208:211], v[92:95]
	v_mfma_f32_16x16x32_bf16 v[88:91], v[232:235], v[208:211], v[88:91]
	v_mfma_f32_16x16x32_bf16 v[76:79], v[224:227], v[216:219], v[76:79]
	v_mfma_f32_16x16x32_bf16 v[72:75], v[232:235], v[216:219], v[72:75]
	v_mfma_f32_16x16x32_bf16 v[124:127], v[228:231], v[196:199], v[124:127]
	v_mfma_f32_16x16x32_bf16 v[120:123], v[236:239], v[196:199], v[120:123]
	v_mfma_f32_16x16x32_bf16 v[108:111], v[228:231], v[204:207], v[108:111]
	v_mfma_f32_16x16x32_bf16 v[104:107], v[236:239], v[204:207], v[104:107]
	v_mfma_f32_16x16x32_bf16 v[92:95], v[228:231], v[212:215], v[92:95]
	v_mfma_f32_16x16x32_bf16 v[88:91], v[236:239], v[212:215], v[88:91]
	v_mfma_f32_16x16x32_bf16 v[76:79], v[228:231], v[220:223], v[76:79]
	v_mfma_f32_16x16x32_bf16 v[72:75], v[236:239], v[220:223], v[72:75]
	s_barrier
; #define PG8_STAGE(bufoff, gbase, voff) do { _Pragma("unroll") for (int _i = 0; _i < 2; ++_i) \
;         __builtin_amdgcn_global_load_lds((const unsigned*)((const char*)(gbase) + (voff)[_i]), (LAS unsigned*)(lds + (bufoff) + ldsw + _i * 8192), 16, 0, 0); } while (0)
; #define PG8_LDA(dst, b, h) do { _Pragma("unroll") for (int m = 0; m < 4; ++m) _Pragma("unroll") for (int k = 0; k < 2; ++k) dst[m][k] = *(const LAS bf16x8*)(lds + PG8_SA(b, h) + aoff + m * 2048 + k * 1024); } while (0)
; #define PG8_LDB(dst, b, h) do { _Pragma("unroll") for (int n = 0; n < 2; ++n) _Pragma("unroll") for (int k = 0; k < 2; ++k) dst[n][k] = *(const LAS bf16x8*)(lds + PG8_SB(b, h) + boff + n * 2048 + k * 1024); } while (0)
; #define PG8_MMA(ai, bj, At, Bt) do { __builtin_amdgcn_s_setprio(1); _Pragma("unroll") for (int m = 0; m < 4; ++m) _Pragma("unroll") for (int n = 0; n < 2; ++n) _Pragma("unroll") for (int k = 0; k < 2; ++k) \
;         acc[ai][bj][m][n] = __builtin_amdgcn_mfma_f32_16x16x32_bf16(Bt[n][k], At[m][k], acc[ai][bj][m][n], 0, 0, 0); __builtin_amdgcn_s_setprio(0); } while (0)
; #define PG8_WAIT_V(n) asm volatile("s_waitcnt vmcnt(" #n ")" ::: "memory")
; #define PG8_WAIT_L(n) asm volatile("s_waitcnt lgkmcnt(" #n ")" ::: "memory")
; template <class Epi>
; __device__ __forceinline__ void gemm_phase(LAS unsigned char* lds, const Gemm g, const StaticOrder& S, const Epi& E) {
;     ...
;             PG8_LDB(B1, 1, 1); PG8_STAGE(PG8_SB(1, 0), b3, voffB);
;             PG8_BAR; PG8_WAIT_L(0); PG8_MMA(0, 1, At, B1); PG8_BAR;
;             PG8_LDA(At, 1, 1); PG8_STAGE(PG8_SA(1, 0), a3, voffA);
;             PG8_BAR; PG8_WAIT_L(0); PG8_MMA(1, 0, At, B0); PG8_BAR; PG8_SCHED;
;             PG8_STAGE(PG8_SB(1, 1), b3 + hstep, voffB);
;             PG8_WAIT_V(6); PG8_BAR; PG8_MMA(1, 1, At, B1); PG8_BAR;
;         }
;     __device__ __forceinline__ void operator()(const f32x4 (&acc)[2][2][4][2], const Unit& u, int wr, int wc, int fr, int fq, const Pre& P) const {
;         const int sec = u.pn >> 3, row0 = ROW_X + u.pm * BM + wr * 64 + fr, colb = (u.pn & 7) * BM + wc * 32 + 8 * fq;
; #pragma unroll
;         for (int ai = 0; ai < 2; ++ai)
; #pragma unroll
;             for (int m = 0; m < 4; ++m) { const int r = row0 + ai * HALF + m * 16; const float rs = __builtin_amdgcn_rsqf(P.rs[ai * 4 + m] * (1.0f / DM) + RMS_EPS);
;                 if (sec == 4) {
	s_setprio 0
	s_add_i32 s11, s42, s57
	v_lshl_add_u64 v[152:153], v[152:153], 0, s[24:25]
	s_mov_b32 m0, s11
	s_nop 0
	global_load_lds_dwordx4 v[152:153], off
	v_lshl_add_u64 v[152:153], v[176:177], 0, s[24:25]
	s_add_i32 m0, s11, 0x2000
	s_nop 0
	global_load_lds_dwordx4 v[152:153], off
	s_mov_b32 m0, s67
	v_lshl_add_u64 v[152:153], v[240:241], 0, s[24:25]
	ds_read_b128 v[192:195], v158 offset:49152
	ds_read_b128 v[196:199], v158 offset:50176
	ds_read_b128 v[200:203], v158 offset:51200
	ds_read_b128 v[204:207], v158 offset:52224
	ds_read_b128 v[208:211], v158 offset:53248
	ds_read_b128 v[212:215], v158 offset:54272
	ds_read_b128 v[216:219], v158 offset:55296
	ds_read_b128 v[220:223], v158 offset:56320
	global_load_lds_dwordx4 v[152:153], off
	v_lshl_add_u64 v[152:153], v[242:243], 0, s[24:25]
	s_mov_b32 m0, s68
	s_nop 0
	global_load_lds_dwordx4 v[152:153], off
	s_add_u32 s8, s8, 0x80080
	s_addc_u32 s9, s9, 0
	s_add_i32 s10, s10, s57
	v_lshl_add_u64 v[152:153], s[8:9], 0, v[130:131]
	s_mov_b32 m0, s10
	s_nop 0
	global_load_lds_dwordx4 v[152:153], off
	v_lshl_add_u64 v[152:153], s[8:9], 0, v[134:135]
	s_add_i32 m0, s10, 0x2000
	s_nop 0
	global_load_lds_dwordx4 v[152:153], off
	s_waitcnt lgkmcnt(0)
	s_waitcnt vmcnt(8)
	s_setprio 1
	s_barrier
	v_mfma_f32_16x16x32_bf16 v[52:55], v[172:175], v[192:195], v[52:55]
	v_mfma_f32_16x16x32_bf16 v[48:51], v[184:187], v[192:195], v[48:51]
	v_mfma_f32_16x16x32_bf16 v[36:39], v[172:175], v[200:203], v[36:39]
	v_mfma_f32_16x16x32_bf16 v[32:35], v[184:187], v[200:203], v[32:35]
	v_mfma_f32_16x16x32_bf16 v[20:23], v[172:175], v[208:211], v[20:23]
	v_mfma_f32_16x16x32_bf16 v[16:19], v[184:187], v[208:211], v[16:19]
	v_mfma_f32_16x16x32_bf16 v[4:7], v[172:175], v[216:219], v[4:7]
	v_mfma_f32_16x16x32_bf16 v[0:3], v[184:187], v[216:219], v[0:3]
	v_mfma_f32_16x16x32_bf16 v[52:55], v[180:183], v[196:199], v[52:55]
	v_mfma_f32_16x16x32_bf16 v[48:51], v[188:191], v[196:199], v[48:51]
	v_mfma_f32_16x16x32_bf16 v[36:39], v[180:183], v[204:207], v[36:39]
	v_mfma_f32_16x16x32_bf16 v[32:35], v[188:191], v[204:207], v[32:35]
	v_mfma_f32_16x16x32_bf16 v[20:23], v[180:183], v[212:215], v[20:23]
	v_mfma_f32_16x16x32_bf16 v[16:19], v[188:191], v[212:215], v[16:19]
	v_mfma_f32_16x16x32_bf16 v[4:7], v[180:183], v[220:223], v[4:7]
	v_mfma_f32_16x16x32_bf16 v[0:3], v[188:191], v[220:223], v[0:3]
	v_mfma_f32_16x16x32_bf16 v[60:63], v[224:227], v[192:195], v[60:63]
	v_mfma_f32_16x16x32_bf16 v[56:59], v[232:235], v[192:195], v[56:59]
	v_mfma_f32_16x16x32_bf16 v[44:47], v[224:227], v[200:203], v[44:47]
	v_mfma_f32_16x16x32_bf16 v[40:43], v[232:235], v[200:203], v[40:43]
	v_mfma_f32_16x16x32_bf16 v[28:31], v[224:227], v[208:211], v[28:31]
	v_mfma_f32_16x16x32_bf16 v[24:27], v[232:235], v[208:211], v[24:27]
	v_mfma_f32_16x16x32_bf16 v[12:15], v[224:227], v[216:219], v[12:15]
	v_mfma_f32_16x16x32_bf16 v[8:11], v[232:235], v[216:219], v[8:11]
	v_mfma_f32_16x16x32_bf16 v[60:63], v[228:231], v[196:199], v[60:63]
	v_mfma_f32_16x16x32_bf16 v[56:59], v[236:239], v[196:199], v[56:59]
	v_mfma_f32_16x16x32_bf16 v[44:47], v[228:231], v[204:207], v[44:47]
	v_mfma_f32_16x16x32_bf16 v[40:43], v[236:239], v[204:207], v[40:43]
	v_mfma_f32_16x16x32_bf16 v[28:31], v[228:231], v[212:215], v[28:31]
	v_mfma_f32_16x16x32_bf16 v[24:27], v[236:239], v[212:215], v[24:27]
	v_mfma_f32_16x16x32_bf16 v[12:15], v[228:231], v[220:223], v[12:15]
	v_mfma_f32_16x16x32_bf16 v[8:11], v[236:239], v[220:223], v[8:11]
	s_barrier
	s_setprio 0
	s_add_i32 s37, s37, 2
	s_add_u32 s6, s6, 0x100
	s_addc_u32 s7, s7, 0
	s_add_u32 s33, s33, 0x100
	s_addc_u32 s35, s35, 0
	s_cmp_gt_u32 s37, 29
	s_cbranch_scc0 .LBB0_1796
	s_lshl_b32 s1, s0, 8
	s_ashr_i32 s35, s0, 3
	s_and_b32 s1, s1, 0x700
	s_waitcnt vmcnt(0)
	v_fmamk_f32 v136, v151, 0x3a000000, v160
	s_cmp_lg_u32 s35, 4
	v_rsq_f32_e32 v171, v136
	s_cselect_b64 s[10:11], -1, 0
	s_cmp_eq_u32 s35, 3
	v_lshl_add_u32 v150, s4, 8, v154
	s_cselect_b64 s[4:5], -1, 0
	s_cmp_gt_u32 s0, 7
	v_or_b32_e32 v165, s1, v156
	s_cselect_b64 s[12:13], -1, 0
	s_cmp_eq_u32 s35, 4
	s_mov_b64 s[0:1], -1
	s_cbranch_scc1 .LBB0_1817
	s_and_b64 vcc, exec, s[12:13]
	s_mov_b64 s[0:1], s[14:15]
	s_cbranch_vccz .LBB0_1807
	s_cmp_lt_i32 s35, 2
	s_cbranch_scc1 .LBB0_1803
	s_cmp_eq_u32 s35, 2
	s_mov_b64 s[6:7], -1
	s_cbranch_scc0 .LBB0_1802
	s_mov_b64 s[6:7], 0

; #define PG8_STAGE(bufoff, gbase, voff) do { _Pragma("unroll") for (int _i = 0; _i < 2; ++_i) \
;         __builtin_amdgcn_global_load_lds((const unsigned*)((const char*)(gbase) + (voff)[_i]), (LAS unsigned*)(lds + (bufoff) + ldsw + _i * 8192), 16, 0, 0); } while (0)
; #define PG8_WAIT_V(n) asm volatile("s_waitcnt vmcnt(" #n ")" ::: "memory")
; #define PG8_BAR __builtin_amdgcn_s_barrier()
;     __device__ __forceinline__ Pre pre(const Unit& u, int wr, int fr) const { return load_rs(ssq, u.pm, wr, fr); }
;     __device__ __forceinline__ Pre pre(const Unit& u, int wr, int fr) const { return load_rs(ssq, u.pm, wr, fr); }
;     __device__ __forceinline__ Pre pre(const Unit& u, int wr, int fr) const { return load_rs(ssq, u.pm, wr, fr); }
; template <class Epi>
; __device__ __forceinline__ void gemm_phase(LAS unsigned char* lds, const Gemm g, const StaticOrder& S, const Epi& E) {
;     ...
;     const char* cA = (const char*)g.A + (size_t)cur.pm * tstep; const char* cB = (const char*)g.Bt + (size_t)cur.pn * tstep;
;     typename Epi::Pre pre = E.pre(cur, wr, fr);
;     PG8_STAGE(PG8_SB(0, 0), cB, voffB); PG8_STAGE(PG8_SA(0, 0), cA, voffA); PG8_STAGE(PG8_SB(0, 1), cB + hstep, voffB); PG8_STAGE(PG8_SA(0, 1), cA + hstep, voffA);
;     if (wr == 1) PG8_BAR;
;     PG8_WAIT_V(4); PG8_BAR;
;     PG8_STAGE(PG8_SB(1, 0), cB + kstep, voffB); PG8_STAGE(PG8_SA(1, 0), cA + kstep, voffA); PG8_STAGE(PG8_SB(1, 1), cB + hstep + kstep, voffB);
;     PG8_WAIT_V(6); PG8_BAR;
.LBB0_2451:
	s_add_u32 s0, s50, 0x1d504000
	s_addc_u32 s1, s51, 0
	s_add_u32 s6, s50, 0x21655400
	s_addc_u32 s7, s51, 0
	s_lshl_b32 s3, s3, 5
	s_mov_b64 s[8:9], 0x80
	s_and_b32 s11, s3, 0x60
	s_add_i32 m0, s21, 0x18000
	v_lshl_add_u64 v[6:7], v[6:7], 0, s[8:9]
	s_lshl_b32 s10, s2, 13
	s_lshl_b32 s3, s11, 7
	s_waitcnt vmcnt(2)
	s_barrier
	global_load_lds_dwordx4 v[6:7], off
	v_lshl_add_u64 v[4:5], v[4:5], 0, s[8:9]
	s_add_i32 m0, s21, 0x1a000
	s_add_i32 s43, s21, 0x8000
	s_add_i32 s44, s21, 0xa000
	global_load_lds_dwordx4 v[4:5], off
	v_lshl_add_u64 v[2:3], v[2:3], 0, s[8:9]
	s_mov_b32 m0, s43
	s_add_u32 s4, s24, 0x80080
	global_load_lds_dwordx4 v[2:3], off
	v_lshl_add_u64 v[0:1], v[0:1], 0, s[8:9]
	s_mov_b32 m0, s44
	s_addc_u32 s5, s25, 0
	global_load_lds_dwordx4 v[0:1], off
	s_add_i32 m0, s21, 0x1c000
	v_lshl_add_u64 v[0:1], s[4:5], 0, v[138:139]
	global_load_lds_dwordx4 v[0:1], off
	v_lshl_add_u64 v[0:1], s[4:5], 0, v[142:143]
	s_add_i32 m0, s21, 0x1e000
	v_lshlrev_b32_e32 v4, 2, v178
	global_load_lds_dwordx4 v[0:1], off
	v_and_b32_e32 v0, 15, v178
	v_bfe_u32 v1, v178, 4, 2
	v_lshl_or_b32 v2, s2, 6, v0
	v_lshlrev_b32_e32 v3, 4, v1
	v_lshlrev_b32_e32 v5, 6, v178
	s_movk_i32 s2, 0x3c0
	v_lshl_or_b32 v0, v0, 6, v3
	v_and_b32_e32 v4, 32, v4
	v_and_or_b32 v3, v5, s2, v3
	s_waitcnt vmcnt(0)
	v_bitop3_b32 v158, s3, v3, v4 bitop3:0xf6
	v_cmp_eq_u32_e64 s[2:3], 0, v1
	v_lshl_or_b32 v160, v1, 3, s11
	v_lshlrev_b32_e32 v1, 9, v178
	v_add_u32_e32 v159, 0x100, v2
	v_and_b32_e32 v1, 0x70000, v1
	v_lshlrev_b32_e32 v2, 12, v10
	v_or3_b32 v1, v8, v1, v2
	v_add_u32_e32 v144, v1, v9
	v_lshlrev_b32_e32 v1, 5, v11
	v_bitop3_b32 v0, v0, s10, v4 bitop3:0xde
	s_waitcnt vmcnt(6)
	v_and_b32_e32 v1, 0xf0000, v1
	v_or3_b32 v1, v8, v1, v2
	s_add_i32 s56, 0, 0x10000
	v_add_u32_e32 v162, 0, v0
	s_add_i32 s57, 0, 0x14000
	v_mbcnt_lo_u32_b32 v0, -1, 0
	s_ashr_i32 s45, s54, 31
	s_mov_b32 s46, s54
	s_ashr_i32 s47, s28, 31
	v_mov_b32_e32 v145, v139
	v_add_u32_e32 v146, v1, v9
	v_mov_b32_e32 v147, v139
	v_mov_b64_e32 v[148:149], 0x200
	v_mov_b64_e32 v[150:151], 0x1ff
	v_add_u32_e32 v161, s56, v158
	v_add_u32_e32 v163, s57, v158
	v_mbcnt_hi_u32_b32 v164, -1, v0
	s_barrier
	s_branch .LBB0_2453

; #define PG8_STAGE(bufoff, gbase, voff) do { _Pragma("unroll") for (int _i = 0; _i < 2; ++_i) \
;         __builtin_amdgcn_global_load_lds((const unsigned*)((const char*)(gbase) + (voff)[_i]), (LAS unsigned*)(lds + (bufoff) + ldsw + _i * 8192), 16, 0, 0); } while (0)
; #define PG8_LDA(dst, b, h) do { _Pragma("unroll") for (int m = 0; m < 4; ++m) _Pragma("unroll") for (int k = 0; k < 2; ++k) dst[m][k] = *(const LAS bf16x8*)(lds + PG8_SA(b, h) + aoff + m * 2048 + k * 1024); } while (0)
; #define PG8_LDB(dst, b, h) do { _Pragma("unroll") for (int n = 0; n < 2; ++n) _Pragma("unroll") for (int k = 0; k < 2; ++k) dst[n][k] = *(const LAS bf16x8*)(lds + PG8_SB(b, h) + boff + n * 2048 + k * 1024); } while (0)
; #define PG8_MMA(ai, bj, At, Bt) do { __builtin_amdgcn_s_setprio(1); _Pragma("unroll") for (int m = 0; m < 4; ++m) _Pragma("unroll") for (int n = 0; n < 2; ++n) _Pragma("unroll") for (int k = 0; k < 2; ++k) \
;         acc[ai][bj][m][n] = __builtin_amdgcn_mfma_f32_16x16x32_bf16(Bt[n][k], At[m][k], acc[ai][bj][m][n], 0, 0, 0); __builtin_amdgcn_s_setprio(0); } while (0)
; #define PG8_WAIT_V(n) asm volatile("s_waitcnt vmcnt(" #n ")" ::: "memory")
; #define PG8_WAIT_L(n) asm volatile("s_waitcnt lgkmcnt(" #n ")" ::: "memory")
; template <class Epi>
; __device__ __forceinline__ void gemm_phase(LAS unsigned char* lds, const Gemm g, const StaticOrder& S, const Epi& E) {
;     ...
;         for (int t = 0; t < nt; t += 2) {
;             const bool last = (t == nt - 2);
;             const char* a1 = cA + (size_t)(t + 1) * kstep;
;             const char* a2 = last ? nA : cA + (size_t)(t + 2) * kstep; const char* b2 = last ? nB : cB + (size_t)(t + 2) * kstep;
;             const char* a3 = a2 + kstep; const char* b3 = b2 + kstep;
;             PG8_LDB(B0, 0, 0); PG8_SCHED; PG8_LDA(At, 0, 0); PG8_STAGE(PG8_SA(1, 1), a1 + hstep, voffA);
;             PG8_WAIT_L(8); PG8_BAR; PG8_WAIT_L(0); PG8_MMA(0, 0, At, B0); PG8_BAR; PG8_SCHED;
;             PG8_LDB(B1, 0, 1); PG8_STAGE(PG8_SB(0, 0), b2, voffB);
;             PG8_BAR; PG8_WAIT_L(0); PG8_MMA(0, 1, At, B1); PG8_BAR;
;             PG8_LDA(At, 0, 1); PG8_STAGE(PG8_SA(0, 0), a2, voffA);
;             PG8_BAR; PG8_WAIT_L(0); PG8_MMA(1, 0, At, B0); PG8_BAR; PG8_SCHED;
;             PG8_STAGE(PG8_SB(0, 1), b2 + hstep, voffB);
;             PG8_WAIT_V(6); PG8_BAR; PG8_MMA(1, 1, At, B1); PG8_BAR;
.LBB0_2460:
	ds_read_b128 v[128:131], v161
	ds_read_b128 v[132:135], v161 offset:1024
	ds_read_b128 v[152:155], v161 offset:2048
	ds_read_b128 v[166:169], v161 offset:3072
	s_add_u32 s24, s22, 0xfff80080
	s_addc_u32 s25, s23, -1
	s_cmp_eq_u32 s61, 28
	s_cselect_b32 s31, s13, s25
	s_cselect_b32 s30, s19, s24
	s_cselect_b32 s25, s11, s60
	s_cselect_b32 s24, s58, s59
	v_lshl_add_u64 v[156:157], s[22:23], 0, v[144:145]
	s_add_i32 m0, s21, 0xc000
	ds_read_b128 v[170:173], v162
	ds_read_b128 v[174:177], v162 offset:1024
	ds_read_b128 v[180:183], v162 offset:2048
	ds_read_b128 v[184:187], v162 offset:3072
	ds_read_b128 v[188:191], v162 offset:4096
	ds_read_b128 v[192:195], v162 offset:5120
	ds_read_b128 v[196:199], v162 offset:6144
	ds_read_b128 v[200:203], v162 offset:7168
	global_load_lds_dwordx4 v[156:157], off
	v_lshl_add_u64 v[156:157], s[22:23], 0, v[146:147]
	s_add_i32 m0, s21, 0xe000
	s_nop 0
	global_load_lds_dwordx4 v[156:157], off
	ds_read_b128 v[204:207], v163
	ds_read_b128 v[208:211], v163 offset:1024
	ds_read_b128 v[212:215], v163 offset:2048
	ds_read_b128 v[216:219], v163 offset:3072
	s_waitcnt lgkmcnt(0)
	s_waitcnt vmcnt(8)
	s_setprio 1
	s_barrier
	v_mfma_f32_16x16x32_bf16 v[124:127], v[128:131], v[170:173], v[124:127]
	v_mfma_f32_16x16x32_bf16 v[120:123], v[152:155], v[170:173], v[120:123]
	v_mfma_f32_16x16x32_bf16 v[108:111], v[128:131], v[180:183], v[108:111]
	v_mfma_f32_16x16x32_bf16 v[104:107], v[152:155], v[180:183], v[104:107]
	v_mfma_f32_16x16x32_bf16 v[92:95], v[128:131], v[188:191], v[92:95]
	v_mfma_f32_16x16x32_bf16 v[88:91], v[152:155], v[188:191], v[88:91]
	v_mfma_f32_16x16x32_bf16 v[76:79], v[128:131], v[196:199], v[76:79]
	v_mfma_f32_16x16x32_bf16 v[72:75], v[152:155], v[196:199], v[72:75]
	v_mfma_f32_16x16x32_bf16 v[124:127], v[132:135], v[174:177], v[124:127]
	v_mfma_f32_16x16x32_bf16 v[120:123], v[166:169], v[174:177], v[120:123]
	v_mfma_f32_16x16x32_bf16 v[108:111], v[132:135], v[184:187], v[108:111]
	v_mfma_f32_16x16x32_bf16 v[104:107], v[166:169], v[184:187], v[104:107]
	v_mfma_f32_16x16x32_bf16 v[92:95], v[132:135], v[192:195], v[92:95]
	v_mfma_f32_16x16x32_bf16 v[88:91], v[166:169], v[192:195], v[88:91]
	v_mfma_f32_16x16x32_bf16 v[76:79], v[132:135], v[200:203], v[76:79]
	v_mfma_f32_16x16x32_bf16 v[72:75], v[166:169], v[200:203], v[72:75]
	v_mfma_f32_16x16x32_bf16 v[116:119], v[204:207], v[170:173], v[116:119]
	v_mfma_f32_16x16x32_bf16 v[112:115], v[212:215], v[170:173], v[112:115]
	v_mfma_f32_16x16x32_bf16 v[100:103], v[204:207], v[180:183], v[100:103]
	v_mfma_f32_16x16x32_bf16 v[96:99], v[212:215], v[180:183], v[96:99]
	v_mfma_f32_16x16x32_bf16 v[84:87], v[204:207], v[188:191], v[84:87]
	v_mfma_f32_16x16x32_bf16 v[80:83], v[212:215], v[188:191], v[80:83]
	v_mfma_f32_16x16x32_bf16 v[68:71], v[204:207], v[196:199], v[68:71]
	v_mfma_f32_16x16x32_bf16 v[64:67], v[212:215], v[196:199], v[64:67]
	v_mfma_f32_16x16x32_bf16 v[116:119], v[208:211], v[174:177], v[116:119]
	v_mfma_f32_16x16x32_bf16 v[112:115], v[216:219], v[174:177], v[112:115]
	v_mfma_f32_16x16x32_bf16 v[100:103], v[208:211], v[184:187], v[100:103]
	v_mfma_f32_16x16x32_bf16 v[96:99], v[216:219], v[184:187], v[96:99]
	v_mfma_f32_16x16x32_bf16 v[84:87], v[208:211], v[192:195], v[84:87]
	v_mfma_f32_16x16x32_bf16 v[80:83], v[216:219], v[192:195], v[80:83]
	v_mfma_f32_16x16x32_bf16 v[68:71], v[208:211], v[200:203], v[68:71]
	v_mfma_f32_16x16x32_bf16 v[64:67], v[216:219], v[200:203], v[64:67]
	s_barrier
	s_setprio 0
	s_add_i32 s62, s56, s38
	v_lshl_add_u64 v[156:157], s[24:25], 0, v[138:139]
	s_mov_b32 m0, s62
	s_nop 0
	global_load_lds_dwordx4 v[156:157], off
	v_lshl_add_u64 v[220:221], s[24:25], 0, v[142:143]
	s_add_i32 m0, s62, 0x2000
	s_nop 0
	global_load_lds_dwordx4 v[220:221], off
	s_mov_b32 m0, s21
	v_lshl_add_u64 v[222:223], s[30:31], 0, v[136:137]
	ds_read_b128 v[170:173], v162 offset:16384
	ds_read_b128 v[174:177], v162 offset:17408
	ds_read_b128 v[180:183], v162 offset:18432
	ds_read_b128 v[184:187], v162 offset:19456
	ds_read_b128 v[188:191], v162 offset:20480
	ds_read_b128 v[192:195], v162 offset:21504
	ds_read_b128 v[196:199], v162 offset:22528
	ds_read_b128 v[200:203], v162 offset:23552
	global_load_lds_dwordx4 v[222:223], off
	v_lshl_add_u64 v[224:225], s[30:31], 0, v[140:141]
	s_mov_b32 m0, s39
	s_nop 0
	global_load_lds_dwordx4 v[224:225], off
	s_add_u32 s62, s24, 0x80000
	s_addc_u32 s63, s25, 0
	s_add_i32 s64, s57, s38
	v_lshl_add_u64 v[252:253], s[62:63], 0, v[138:139]
	s_mov_b32 m0, s64
	s_nop 0
	global_load_lds_dwordx4 v[252:253], off
	v_lshl_add_u64 v[252:253], s[62:63], 0, v[142:143]
	s_add_i32 m0, s64, 0x2000
	s_nop 0
	global_load_lds_dwordx4 v[252:253], off
	s_waitcnt lgkmcnt(0)
	s_waitcnt vmcnt(8)
	s_setprio 1
	s_barrier
; #define PG8_STAGE(bufoff, gbase, voff) do { _Pragma("unroll") for (int _i = 0; _i < 2; ++_i) \
;         __builtin_amdgcn_global_load_lds((const unsigned*)((const char*)(gbase) + (voff)[_i]), (LAS unsigned*)(lds + (bufoff) + ldsw + _i * 8192), 16, 0, 0); } while (0)
; #define PG8_LDA(dst, b, h) do { _Pragma("unroll") for (int m = 0; m < 4; ++m) _Pragma("unroll") for (int k = 0; k < 2; ++k) dst[m][k] = *(const LAS bf16x8*)(lds + PG8_SA(b, h) + aoff + m * 2048 + k * 1024); } while (0)
; #define PG8_LDB(dst, b, h) do { _Pragma("unroll") for (int n = 0; n < 2; ++n) _Pragma("unroll") for (int k = 0; k < 2; ++k) dst[n][k] = *(const LAS bf16x8*)(lds + PG8_SB(b, h) + boff + n * 2048 + k * 1024); } while (0)
; #define PG8_MMA(ai, bj, At, Bt) do { __builtin_amdgcn_s_setprio(1); _Pragma("unroll") for (int m = 0; m < 4; ++m) _Pragma("unroll") for (int n = 0; n < 2; ++n) _Pragma("unroll") for (int k = 0; k < 2; ++k) \
;         acc[ai][bj][m][n] = __builtin_amdgcn_mfma_f32_16x16x32_bf16(Bt[n][k], At[m][k], acc[ai][bj][m][n], 0, 0, 0); __builtin_amdgcn_s_setprio(0); } while (0)
; #define PG8_WAIT_V(n) asm volatile("s_waitcnt vmcnt(" #n ")" ::: "memory")
; #define PG8_WAIT_L(n) asm volatile("s_waitcnt lgkmcnt(" #n ")" ::: "memory")
; #define PG8_BAR __builtin_amdgcn_s_barrier()
; #define PG8_SCHED __builtin_amdgcn_sched_barrier(0)
; template <class Epi>
; __device__ __forceinline__ void gemm_phase(LAS unsigned char* lds, const Gemm g, const StaticOrder& S, const Epi& E) {
;     ...
;             PG8_BAR; PG8_WAIT_L(0); PG8_MMA(0, 1, At, B1); PG8_BAR;
;             PG8_LDA(At, 0, 1); PG8_STAGE(PG8_SA(0, 0), a2, voffA);
;             PG8_BAR; PG8_WAIT_L(0); PG8_MMA(1, 0, At, B0); PG8_BAR; PG8_SCHED;
;             PG8_STAGE(PG8_SB(0, 1), b2 + hstep, voffB);
;             PG8_WAIT_V(6); PG8_BAR; PG8_MMA(1, 1, At, B1); PG8_BAR;
;             PG8_LDB(B0, 1, 0); PG8_SCHED; PG8_LDA(At, 1, 0); PG8_STAGE(PG8_SA(0, 1), a2 + hstep, voffA);
;             PG8_WAIT_L(8); PG8_BAR; PG8_WAIT_L(0); PG8_MMA(0, 0, At, B0); PG8_BAR; PG8_SCHED;
;             PG8_LDB(B1, 1, 1); PG8_STAGE(PG8_SB(1, 0), b3, voffB);
;             PG8_BAR; PG8_WAIT_L(0); PG8_MMA(0, 1, At, B1); PG8_BAR;
;             PG8_LDA(At, 1, 1); PG8_STAGE(PG8_SA(1, 0), a3, voffA);
;             PG8_BAR; PG8_WAIT_L(0); PG8_MMA(1, 0, At, B0); PG8_BAR; PG8_SCHED;
	v_mfma_f32_16x16x32_bf16 v[60:63], v[128:131], v[170:173], v[60:63]
	v_mfma_f32_16x16x32_bf16 v[56:59], v[152:155], v[170:173], v[56:59]
	v_mfma_f32_16x16x32_bf16 v[44:47], v[128:131], v[180:183], v[44:47]
	v_mfma_f32_16x16x32_bf16 v[40:43], v[152:155], v[180:183], v[40:43]
	v_mfma_f32_16x16x32_bf16 v[28:31], v[128:131], v[188:191], v[28:31]
	v_mfma_f32_16x16x32_bf16 v[24:27], v[152:155], v[188:191], v[24:27]
	v_mfma_f32_16x16x32_bf16 v[12:15], v[128:131], v[196:199], v[12:15]
	v_mfma_f32_16x16x32_bf16 v[8:11], v[152:155], v[196:199], v[8:11]
	v_mfma_f32_16x16x32_bf16 v[60:63], v[132:135], v[174:177], v[60:63]
	v_mfma_f32_16x16x32_bf16 v[56:59], v[166:169], v[174:177], v[56:59]
	v_mfma_f32_16x16x32_bf16 v[44:47], v[132:135], v[184:187], v[44:47]
	v_mfma_f32_16x16x32_bf16 v[40:43], v[166:169], v[184:187], v[40:43]
	v_mfma_f32_16x16x32_bf16 v[28:31], v[132:135], v[192:195], v[28:31]
	v_mfma_f32_16x16x32_bf16 v[24:27], v[166:169], v[192:195], v[24:27]
	v_mfma_f32_16x16x32_bf16 v[12:15], v[132:135], v[200:203], v[12:15]
	v_mfma_f32_16x16x32_bf16 v[8:11], v[166:169], v[200:203], v[8:11]
	v_mfma_f32_16x16x32_bf16 v[52:55], v[204:207], v[170:173], v[52:55]
	v_mfma_f32_16x16x32_bf16 v[48:51], v[212:215], v[170:173], v[48:51]
	v_mfma_f32_16x16x32_bf16 v[36:39], v[204:207], v[180:183], v[36:39]
	v_mfma_f32_16x16x32_bf16 v[32:35], v[212:215], v[180:183], v[32:35]
	v_mfma_f32_16x16x32_bf16 v[20:23], v[204:207], v[188:191], v[20:23]
	v_mfma_f32_16x16x32_bf16 v[16:19], v[212:215], v[188:191], v[16:19]
	v_mfma_f32_16x16x32_bf16 v[4:7], v[204:207], v[196:199], v[4:7]
	v_mfma_f32_16x16x32_bf16 v[0:3], v[212:215], v[196:199], v[0:3]
	v_mfma_f32_16x16x32_bf16 v[52:55], v[208:211], v[174:177], v[52:55]
	v_mfma_f32_16x16x32_bf16 v[48:51], v[216:219], v[174:177], v[48:51]
	v_mfma_f32_16x16x32_bf16 v[36:39], v[208:211], v[184:187], v[36:39]
	v_mfma_f32_16x16x32_bf16 v[32:35], v[216:219], v[184:187], v[32:35]
	v_mfma_f32_16x16x32_bf16 v[20:23], v[208:211], v[192:195], v[20:23]
	v_mfma_f32_16x16x32_bf16 v[16:19], v[216:219], v[192:195], v[16:19]
	v_mfma_f32_16x16x32_bf16 v[4:7], v[208:211], v[200:203], v[4:7]
	v_mfma_f32_16x16x32_bf16 v[0:3], v[216:219], v[200:203], v[0:3]
	s_barrier
	s_setprio 0
	s_add_i32 s62, 0, 0x18000
	v_add_u32_e32 v165, s62, v158
	ds_read_b128 v[128:131], v165
	ds_read_b128 v[132:135], v165 offset:1024
	ds_read_b128 v[152:155], v165 offset:2048
	ds_read_b128 v[166:169], v165 offset:3072
	s_add_u32 s30, s30, 0x80000
	s_addc_u32 s31, s31, 0
	s_mov_b32 m0, s40
	v_lshl_add_u64 v[204:205], s[30:31], 0, v[136:137]
	ds_read_b128 v[170:173], v162 offset:32768
	ds_read_b128 v[174:177], v162 offset:33792
	ds_read_b128 v[180:183], v162 offset:34816
	ds_read_b128 v[184:187], v162 offset:35840
	ds_read_b128 v[188:191], v162 offset:36864
	ds_read_b128 v[192:195], v162 offset:37888
	ds_read_b128 v[196:199], v162 offset:38912
	ds_read_b128 v[200:203], v162 offset:39936
	global_load_lds_dwordx4 v[204:205], off
	v_lshl_add_u64 v[204:205], s[30:31], 0, v[140:141]
	s_mov_b32 m0, s41
	s_nop 0
	global_load_lds_dwordx4 v[204:205], off
	s_add_i32 s30, 0, 0x1c000
	v_add_u32_e32 v165, s30, v158
	ds_read_b128 v[204:207], v165
	ds_read_b128 v[208:211], v165 offset:1024
	ds_read_b128 v[212:215], v165 offset:2048
	ds_read_b128 v[216:219], v165 offset:3072
	s_waitcnt lgkmcnt(0)
	s_waitcnt vmcnt(8)
	s_setprio 1
	s_barrier
	v_mfma_f32_16x16x32_bf16 v[124:127], v[128:131], v[170:173], v[124:127]
	v_mfma_f32_16x16x32_bf16 v[120:123], v[152:155], v[170:173], v[120:123]
	v_mfma_f32_16x16x32_bf16 v[108:111], v[128:131], v[180:183], v[108:111]
	v_mfma_f32_16x16x32_bf16 v[104:107], v[152:155], v[180:183], v[104:107]
	v_mfma_f32_16x16x32_bf16 v[92:95], v[128:131], v[188:191], v[92:95]
	v_mfma_f32_16x16x32_bf16 v[88:91], v[152:155], v[188:191], v[88:91]
	v_mfma_f32_16x16x32_bf16 v[76:79], v[128:131], v[196:199], v[76:79]
	v_mfma_f32_16x16x32_bf16 v[72:75], v[152:155], v[196:199], v[72:75]
	v_mfma_f32_16x16x32_bf16 v[124:127], v[132:135], v[174:177], v[124:127]
	v_mfma_f32_16x16x32_bf16 v[120:123], v[166:169], v[174:177], v[120:123]
	v_mfma_f32_16x16x32_bf16 v[108:111], v[132:135], v[184:187], v[108:111]
	v_mfma_f32_16x16x32_bf16 v[104:107], v[166:169], v[184:187], v[104:107]
	v_mfma_f32_16x16x32_bf16 v[92:95], v[132:135], v[192:195], v[92:95]
	v_mfma_f32_16x16x32_bf16 v[88:91], v[166:169], v[192:195], v[88:91]
	v_mfma_f32_16x16x32_bf16 v[76:79], v[132:135], v[200:203], v[76:79]
	v_mfma_f32_16x16x32_bf16 v[72:75], v[166:169], v[200:203], v[72:75]
	v_mfma_f32_16x16x32_bf16 v[116:119], v[204:207], v[170:173], v[116:119]
	v_mfma_f32_16x16x32_bf16 v[112:115], v[212:215], v[170:173], v[112:115]
	v_mfma_f32_16x16x32_bf16 v[100:103], v[204:207], v[180:183], v[100:103]
	v_mfma_f32_16x16x32_bf16 v[96:99], v[212:215], v[180:183], v[96:99]
	v_mfma_f32_16x16x32_bf16 v[84:87], v[204:207], v[188:191], v[84:87]
	v_mfma_f32_16x16x32_bf16 v[80:83], v[212:215], v[188:191], v[80:83]
	v_mfma_f32_16x16x32_bf16 v[68:71], v[204:207], v[196:199], v[68:71]
	v_mfma_f32_16x16x32_bf16 v[64:67], v[212:215], v[196:199], v[64:67]
	v_mfma_f32_16x16x32_bf16 v[116:119], v[208:211], v[174:177], v[116:119]
	v_mfma_f32_16x16x32_bf16 v[112:115], v[216:219], v[174:177], v[112:115]
	v_mfma_f32_16x16x32_bf16 v[100:103], v[208:211], v[184:187], v[100:103]
	v_mfma_f32_16x16x32_bf16 v[96:99], v[216:219], v[184:187], v[96:99]
	v_mfma_f32_16x16x32_bf16 v[84:87], v[208:211], v[192:195], v[84:87]
	v_mfma_f32_16x16x32_bf16 v[80:83], v[216:219], v[192:195], v[80:83]
	v_mfma_f32_16x16x32_bf16 v[68:71], v[208:211], v[200:203], v[68:71]
	v_mfma_f32_16x16x32_bf16 v[64:67], v[216:219], v[200:203], v[64:67]
	s_barrier
; #define PG8_STAGE(bufoff, gbase, voff) do { _Pragma("unroll") for (int _i = 0; _i < 2; ++_i) \
;         __builtin_amdgcn_global_load_lds((const unsigned*)((const char*)(gbase) + (voff)[_i]), (LAS unsigned*)(lds + (bufoff) + ldsw + _i * 8192), 16, 0, 0); } while (0)
; #define PG8_LDA(dst, b, h) do { _Pragma("unroll") for (int m = 0; m < 4; ++m) _Pragma("unroll") for (int k = 0; k < 2; ++k) dst[m][k] = *(const LAS bf16x8*)(lds + PG8_SA(b, h) + aoff + m * 2048 + k * 1024); } while (0)
; #define PG8_LDB(dst, b, h) do { _Pragma("unroll") for (int n = 0; n < 2; ++n) _Pragma("unroll") for (int k = 0; k < 2; ++k) dst[n][k] = *(const LAS bf16x8*)(lds + PG8_SB(b, h) + boff + n * 2048 + k * 1024); } while (0)
; #define PG8_MMA(ai, bj, At, Bt) do { __builtin_amdgcn_s_setprio(1); _Pragma("unroll") for (int m = 0; m < 4; ++m) _Pragma("unroll") for (int n = 0; n < 2; ++n) _Pragma("unroll") for (int k = 0; k < 2; ++k) \
;         acc[ai][bj][m][n] = __builtin_amdgcn_mfma_f32_16x16x32_bf16(Bt[n][k], At[m][k], acc[ai][bj][m][n], 0, 0, 0); __builtin_amdgcn_s_setprio(0); } while (0)
; #define PG8_WAIT_V(n) asm volatile("s_waitcnt vmcnt(" #n ")" ::: "memory")
; #define PG8_WAIT_L(n) asm volatile("s_waitcnt lgkmcnt(" #n ")" ::: "memory")
; #define PG8_BAR __builtin_amdgcn_s_barrier()
; #define PG8_SCHED __builtin_amdgcn_sched_barrier(0)
; template <class Epi>
; __device__ __forceinline__ void gemm_phase(LAS unsigned char* lds, const Gemm g, const StaticOrder& S, const Epi& E) {
;     ...
;             PG8_LDB(B1, 1, 1); PG8_STAGE(PG8_SB(1, 0), b3, voffB);
;             PG8_BAR; PG8_WAIT_L(0); PG8_MMA(0, 1, At, B1); PG8_BAR;
;             PG8_LDA(At, 1, 1); PG8_STAGE(PG8_SA(1, 0), a3, voffA);
;             PG8_BAR; PG8_WAIT_L(0); PG8_MMA(1, 0, At, B0); PG8_BAR; PG8_SCHED;
;             PG8_STAGE(PG8_SB(1, 1), b3 + hstep, voffB);
;             PG8_WAIT_V(6); PG8_BAR; PG8_MMA(1, 1, At, B1); PG8_BAR;
;         }
	s_setprio 0
	s_add_i32 s31, s62, s38
	v_lshl_add_u64 v[156:157], v[156:157], 0, s[8:9]
	s_mov_b32 m0, s31
	s_nop 0
	global_load_lds_dwordx4 v[156:157], off
	v_lshl_add_u64 v[156:157], v[220:221], 0, s[8:9]
	s_add_i32 m0, s31, 0x2000
	s_nop 0
	global_load_lds_dwordx4 v[156:157], off
	s_mov_b32 m0, s43
	v_lshl_add_u64 v[156:157], v[222:223], 0, s[8:9]
	ds_read_b128 v[170:173], v162 offset:49152
	ds_read_b128 v[174:177], v162 offset:50176
	ds_read_b128 v[180:183], v162 offset:51200
	ds_read_b128 v[184:187], v162 offset:52224
	ds_read_b128 v[188:191], v162 offset:53248
	ds_read_b128 v[192:195], v162 offset:54272
	ds_read_b128 v[196:199], v162 offset:55296
	ds_read_b128 v[200:203], v162 offset:56320
	global_load_lds_dwordx4 v[156:157], off
	v_lshl_add_u64 v[156:157], v[224:225], 0, s[8:9]
	s_mov_b32 m0, s44
	s_nop 0
	global_load_lds_dwordx4 v[156:157], off
	s_add_u32 s24, s24, 0x80080
	s_addc_u32 s25, s25, 0
	s_add_i32 s30, s30, s38
	v_lshl_add_u64 v[252:253], s[24:25], 0, v[138:139]
	s_mov_b32 m0, s30
	s_nop 0
	global_load_lds_dwordx4 v[252:253], off
	v_lshl_add_u64 v[252:253], s[24:25], 0, v[142:143]
	s_add_i32 m0, s30, 0x2000
	s_nop 0
	global_load_lds_dwordx4 v[252:253], off
	s_waitcnt lgkmcnt(0)
	s_waitcnt vmcnt(8)
	s_setprio 1
	s_barrier
	v_mfma_f32_16x16x32_bf16 v[60:63], v[128:131], v[170:173], v[60:63]
	v_mfma_f32_16x16x32_bf16 v[56:59], v[152:155], v[170:173], v[56:59]
	v_mfma_f32_16x16x32_bf16 v[44:47], v[128:131], v[180:183], v[44:47]
	v_mfma_f32_16x16x32_bf16 v[40:43], v[152:155], v[180:183], v[40:43]
	v_mfma_f32_16x16x32_bf16 v[28:31], v[128:131], v[188:191], v[28:31]
	v_mfma_f32_16x16x32_bf16 v[24:27], v[152:155], v[188:191], v[24:27]
	v_mfma_f32_16x16x32_bf16 v[12:15], v[128:131], v[196:199], v[12:15]
	v_mfma_f32_16x16x32_bf16 v[8:11], v[152:155], v[196:199], v[8:11]
	v_mfma_f32_16x16x32_bf16 v[60:63], v[132:135], v[174:177], v[60:63]
	v_mfma_f32_16x16x32_bf16 v[56:59], v[166:169], v[174:177], v[56:59]
	v_mfma_f32_16x16x32_bf16 v[44:47], v[132:135], v[184:187], v[44:47]
	v_mfma_f32_16x16x32_bf16 v[40:43], v[166:169], v[184:187], v[40:43]
	v_mfma_f32_16x16x32_bf16 v[28:31], v[132:135], v[192:195], v[28:31]
	v_mfma_f32_16x16x32_bf16 v[24:27], v[166:169], v[192:195], v[24:27]
	v_mfma_f32_16x16x32_bf16 v[12:15], v[132:135], v[200:203], v[12:15]
	v_mfma_f32_16x16x32_bf16 v[8:11], v[166:169], v[200:203], v[8:11]
	v_mfma_f32_16x16x32_bf16 v[52:55], v[204:207], v[170:173], v[52:55]
	v_mfma_f32_16x16x32_bf16 v[48:51], v[212:215], v[170:173], v[48:51]
	v_mfma_f32_16x16x32_bf16 v[36:39], v[204:207], v[180:183], v[36:39]
	v_mfma_f32_16x16x32_bf16 v[32:35], v[212:215], v[180:183], v[32:35]
	v_mfma_f32_16x16x32_bf16 v[20:23], v[204:207], v[188:191], v[20:23]
	v_mfma_f32_16x16x32_bf16 v[16:19], v[212:215], v[188:191], v[16:19]
	v_mfma_f32_16x16x32_bf16 v[4:7], v[204:207], v[196:199], v[4:7]
	v_mfma_f32_16x16x32_bf16 v[0:3], v[212:215], v[196:199], v[0:3]
	v_mfma_f32_16x16x32_bf16 v[52:55], v[208:211], v[174:177], v[52:55]
	v_mfma_f32_16x16x32_bf16 v[48:51], v[216:219], v[174:177], v[48:51]
	v_mfma_f32_16x16x32_bf16 v[36:39], v[208:211], v[184:187], v[36:39]
	v_mfma_f32_16x16x32_bf16 v[32:35], v[216:219], v[184:187], v[32:35]
	v_mfma_f32_16x16x32_bf16 v[20:23], v[208:211], v[192:195], v[20:23]
	v_mfma_f32_16x16x32_bf16 v[16:19], v[216:219], v[192:195], v[16:19]
	v_mfma_f32_16x16x32_bf16 v[4:7], v[208:211], v[200:203], v[4:7]
	v_mfma_f32_16x16x32_bf16 v[0:3], v[216:219], v[200:203], v[0:3]
	s_barrier
	s_setprio 0
	s_add_i32 s61, s61, 2
	s_add_u32 s22, s22, 0x100
	s_addc_u32 s23, s23, 0
	s_add_u32 s59, s59, 0x100
	s_addc_u32 s60, s60, 0
	s_cmp_gt_u32 s61, 29
	s_cbranch_scc0 .LBB0_2460
; __device__ __forceinline__ float bflo(unsigned w) { return __uint_as_float(w << 16); }
; __device__ __forceinline__ float bfhi(unsigned w) { return __uint_as_float(w & 0xffff0000u); }
; #define ER_LOAD(g_, set_) do { const size_t off_ = (size_t)(row0 + ((g_) >> 2) * HALF + ((g_) & 3) * 16) * DM + col0; \
;         hv[set_][0] = *(const u32x4*)(HB + off_); hv[set_][1] = *(const u32x4*)(HB + off_ + HALF); } while (0)
;     __device__ __forceinline__ void operator()(const f32x4 (&acc)[2][2][4][2], const Unit& u, int wr, int wc, int fr, int fq, const Pre&) const {
;         const int row0 = ROW_X + u.pm * BM + wr * 64 + fr, col0 = u.pn * BM + wc * 32 + 8 * fq;
;         u32x4 hv[2][2]; float sprev = 0.f;
;     ...
;         ER_LOAD(0, 0);
; #pragma unroll
;         for (int g = 0; g < 8; ++g) { const int ai = g >> 2, m = g & 3; const int r = row0 + ai * HALF + m * 16; const size_t off = (size_t)r * DM + col0; float s = 0.f;
;             if (g + 1 < 8) ER_LOAD(g + 1, (g + 1) & 1);
; #pragma unroll
;             for (int bj = 0; bj < 2; ++bj) { const u32x4 w = hv[g & 1][bj];
;                 const f32x4 h0 = {bflo(w.x), bfhi(w.x), bflo(w.y), bfhi(w.y)}, h1 = {bflo(w.z), bfhi(w.z), bflo(w.w), bfhi(w.w)};
;                 const f32x4 o0 = h0 + acc[ai][bj][m][0] * alpha, o1 = h1 + acc[ai][bj][m][1] * alpha;
;                 if (FINAL) { float* op = OUT + (size_t)(r - ROW_X) * DM + col0 + bj * HALF; *(f32x4*)op = o0; *(f32x4*)(op + 4) = o1; }
;                 else { u32x4 q; q.x = cvtpk(o0[0], o0[1]); q.y = cvtpk(o0[2], o0[3]); q.z = cvtpk(o1[0], o1[1]); q.w = cvtpk(o1[2], o1[3]); *(u32x4*)(HB + off + bj * HALF) = q;
;                        s += ((o0[0] * o0[0] + o0[1] * o0[1]) + (o0[2] * o0[2] + o0[3] * o0[3])) + ((o1[0] * o1[0] + o1[1] * o1[1]) + (o1[2] * o1[2] + o1[3] * o1[3])); } }
;             if (!FINAL) { if (g > 0) { float t = sprev; t += __shfl_xor(t, 16); t += __shfl_xor(t, 32);
;                     if (fq == 0) __hip_atomic_fetch_add(ssq_out + row0 + ((g - 1) >> 2) * HALF + ((g - 1) & 3) * 16, t, __ATOMIC_RELAXED, __HIP_MEMORY_SCOPE_AGENT); }
	v_lshl_add_u32 v154, s18, 8, v159
	v_lshl_or_b32 v152, s20, 8, v160
	v_ashrrev_i32_e32 v155, 31, v154
	v_ashrrev_i32_e32 v153, 31, v152
	v_lshlrev_b64 v[128:129], 12, v[154:155]
	v_lshl_add_u64 v[128:129], s[0:1], 0, v[128:129]
	v_lshlrev_b64 v[130:131], 1, v[152:153]
	v_lshl_add_u64 v[184:185], v[128:129], 0, v[130:131]
	v_or_b32_e32 v128, 16, v154
	v_ashrrev_i32_e32 v129, 31, v128
	global_load_dwordx4 v[166:169], v[184:185], off
	global_load_dwordx4 v[170:173], v[184:185], off offset:256
	v_lshlrev_b64 v[128:129], 12, v[128:129]
	v_lshl_add_u64 v[128:129], s[0:1], 0, v[128:129]
	v_lshl_add_u64 v[186:187], v[128:129], 0, v[130:131]
	global_load_dwordx4 v[174:177], v[186:187], off
	global_load_dwordx4 v[180:183], v[186:187], off offset:256
	v_or_b32_e32 v128, 32, v154
	v_ashrrev_i32_e32 v129, 31, v128
	v_lshlrev_b64 v[128:129], 12, v[128:129]
	v_lshl_add_u64 v[128:129], s[0:1], 0, v[128:129]
	v_lshl_add_u64 v[156:157], v[128:129], 0, v[130:131]
	global_load_dwordx4 v[132:135], v[156:157], off
	global_load_dwordx4 v[128:131], v[156:157], off offset:256
	s_waitcnt vmcnt(0)
	v_lshlrev_b32_e32 v188, 16, v166
	v_and_b32_e32 v189, 0xffff0000, v166
	v_lshlrev_b32_e32 v166, 16, v167
	v_and_b32_e32 v167, 0xffff0000, v167
	v_lshlrev_b32_e32 v190, 16, v168
	v_and_b32_e32 v191, 0xffff0000, v168
	v_lshlrev_b32_e32 v168, 16, v169
	v_and_b32_e32 v169, 0xffff0000, v169
	v_lshlrev_b32_e32 v192, 16, v170
	v_and_b32_e32 v193, 0xffff0000, v170
	v_lshlrev_b32_e32 v170, 16, v171
	v_and_b32_e32 v171, 0xffff0000, v171
	v_lshlrev_b32_e32 v194, 16, v172
	v_and_b32_e32 v195, 0xffff0000, v172
	v_lshlrev_b32_e32 v172, 16, v173
	v_and_b32_e32 v173, 0xffff0000, v173
	v_pk_add_f32 v[126:127], v[126:127], v[166:167]
	v_pk_add_f32 v[124:125], v[124:125], v[188:189]
	v_pk_add_f32 v[122:123], v[122:123], v[168:169]
	v_pk_add_f32 v[166:167], v[120:121], v[190:191]
	v_pk_add_f32 v[168:169], v[118:119], v[170:171]
	v_pk_add_f32 v[170:171], v[116:117], v[192:193]
	v_pk_add_f32 v[172:173], v[114:115], v[172:173]
	v_pk_add_f32 v[188:189], v[112:113], v[194:195]
	v_cvt_pk_bf16_f32 v114, v124, v125
	v_cvt_pk_bf16_f32 v115, v126, v127
	v_cvt_pk_bf16_f32 v116, v166, v167
	v_cvt_pk_bf16_f32 v117, v122, v123
	v_mul_f32_e32 v125, v125, v125
	v_mul_f32_e32 v127, v127, v127
	v_mul_f32_e32 v165, v167, v167
	v_mul_f32_e32 v123, v123, v123
	v_cvt_pk_bf16_f32 v118, v170, v171
	v_cvt_pk_bf16_f32 v119, v168, v169
	v_cvt_pk_bf16_f32 v121, v172, v173
	v_mul_f32_e32 v167, v171, v171
	v_mul_f32_e32 v169, v169, v169
	v_mul_f32_e32 v171, v189, v189
	v_mul_f32_e32 v173, v173, v173
	v_lshlrev_b32_e32 v112, 16, v174
	v_and_b32_e32 v113, 0xffff0000, v174
	v_lshlrev_b32_e32 v190, 16, v176
	v_and_b32_e32 v191, 0xffff0000, v176
	v_lshlrev_b32_e32 v176, 16, v177
	v_and_b32_e32 v177, 0xffff0000, v177
	v_fmac_f32_e32 v125, v124, v124
	v_fmac_f32_e32 v127, v126, v126
	v_fmac_f32_e32 v165, v166, v166
	v_fmac_f32_e32 v123, v122, v122
	v_fmac_f32_e32 v167, v170, v170
	v_fmac_f32_e32 v169, v168, v168
	v_fmac_f32_e32 v171, v188, v188
	v_fmac_f32_e32 v173, v172, v172
	v_lshlrev_b32_e32 v174, 16, v175
	v_and_b32_e32 v175, 0xffff0000, v175
	v_pk_add_f32 v[112:113], v[108:109], v[112:113]
	v_pk_add_f32 v[108:109], v[106:107], v[176:177]
	global_store_dwordx4 v[184:185], v[114:117], off
	v_add_f32_e32 v106, v125, v127
	v_add_f32_e32 v107, v165, v123
	v_add_f32_e32 v114, v167, v169
	v_add_f32_e32 v115, v171, v173
	v_pk_add_f32 v[110:111], v[110:111], v[174:175]
	v_add_f32_e32 v106, v106, v107
	v_add_f32_e32 v107, v114, v115
	v_pk_add_f32 v[114:115], v[104:105], v[190:191]
	v_add_f32_e32 v125, v106, v107
	v_cvt_pk_bf16_f32 v104, v112, v113
	v_cvt_pk_bf16_f32 v105, v110, v111
	v_cvt_pk_bf16_f32 v106, v114, v115
	v_cvt_pk_bf16_f32 v107, v108, v109
	v_cvt_pk_bf16_f32 v120, v188, v189
	global_store_dwordx4 v[186:187], v[104:107], off
	global_store_dwordx4 v[184:185], v[118:121], off offset:256
	v_lshlrev_b32_e32 v122, 16, v182
	v_lshlrev_b32_e32 v104, 16, v180
	v_and_b32_e32 v105, 0xffff0000, v180
	v_pk_add_f32 v[118:119], v[100:101], v[104:105]
	v_and_b32_e32 v101, 64, v164
	v_xor_b32_e32 v100, 16, v164
	v_add_u32_e32 v101, 64, v101
	v_cmp_lt_i32_e32 vcc, v100, v101
	v_and_b32_e32 v123, 0xffff0000, v182
	v_pk_add_f32 v[122:123], v[96:97], v[122:123]
	v_cndmask_b32_e32 v100, v164, v100, vcc
	v_lshlrev_b32_e32 v124, 2, v100
	ds_bpermute_b32 v100, v124, v125
	v_xor_b32_e32 v97, 32, v164
	v_cmp_lt_i32_e32 vcc, v97, v101
	v_lshlrev_b32_e32 v106, 16, v181
	v_and_b32_e32 v107, 0xffff0000, v181
	v_cndmask_b32_e32 v97, v164, v97, vcc
	s_waitcnt lgkmcnt(0)
	v_add_f32_e32 v96, v125, v100
	v_lshlrev_b32_e32 v125, 2, v97
	ds_bpermute_b32 v97, v125, v96
	v_lshlrev_b32_e32 v120, 16, v183
	v_and_b32_e32 v121, 0xffff0000, v183
	v_pk_add_f32 v[116:117], v[102:103], v[106:107]
	v_pk_add_f32 v[120:121], v[98:99], v[120:121]
	v_cvt_pk_bf16_f32 v98, v118, v119
	v_cvt_pk_bf16_f32 v99, v116, v117
	v_cvt_pk_bf16_f32 v100, v122, v123
	v_cvt_pk_bf16_f32 v101, v120, v121
	v_lshl_add_u64 v[104:105], v[154:155], 2, s[6:7]
	global_store_dwordx4 v[186:187], v[98:101], off offset:256
	s_and_saveexec_b64 s[18:19], s[2:3]
	s_cbranch_execz .LBB0_2463
	s_waitcnt lgkmcnt(0)
	v_add_f32_e32 v96, v96, v97
	global_atomic_add_f32 v[104:105], v96, off

; #define PG8_STAGE(bufoff, gbase, voff) do { _Pragma("unroll") for (int _i = 0; _i < 2; ++_i) \
;         __builtin_amdgcn_global_load_lds((const unsigned*)((const char*)(gbase) + (voff)[_i]), (LAS unsigned*)(lds + (bufoff) + ldsw + _i * 8192), 16, 0, 0); } while (0)
; #define PG8_WAIT_V(n) asm volatile("s_waitcnt vmcnt(" #n ")" ::: "memory")
; #define PG8_BAR __builtin_amdgcn_s_barrier()
;     __device__ __forceinline__ Pre pre(const Unit& u, int wr, int fr) const { return load_rs(ssq, u.pm, wr, fr); }
;     __device__ __forceinline__ Pre pre(const Unit& u, int wr, int fr) const { return load_rs(ssq, u.pm, wr, fr); }
;     __device__ __forceinline__ Pre pre(const Unit& u, int wr, int fr) const { return load_rs(ssq, u.pm, wr, fr); }
; template <class Epi>
; __device__ __forceinline__ void gemm_phase(LAS unsigned char* lds, const Gemm g, const StaticOrder& S, const Epi& E) {
;     ...
;     const char* cA = (const char*)g.A + (size_t)cur.pm * tstep; const char* cB = (const char*)g.Bt + (size_t)cur.pn * tstep;
;     typename Epi::Pre pre = E.pre(cur, wr, fr);
;     PG8_STAGE(PG8_SB(0, 0), cB, voffB); PG8_STAGE(PG8_SA(0, 0), cA, voffA); PG8_STAGE(PG8_SB(0, 1), cB + hstep, voffB); PG8_STAGE(PG8_SA(0, 1), cA + hstep, voffA);
;     if (wr == 1) PG8_BAR;
;     PG8_WAIT_V(4); PG8_BAR;
;     PG8_STAGE(PG8_SB(1, 0), cB + kstep, voffB); PG8_STAGE(PG8_SA(1, 0), cA + kstep, voffA); PG8_STAGE(PG8_SB(1, 1), cB + hstep + kstep, voffB);
;     PG8_WAIT_V(6); PG8_BAR;
.LBB0_2541:
	s_add_u32 s2, s50, 0x21667800
	s_addc_u32 s3, s51, 0
	s_lshl_b32 s4, s4, 5
	s_lshl_b32 s7, s5, 13
	s_and_b32 s10, s4, 0x60
	s_mov_b64 s[4:5], 0x80
	s_add_i32 m0, s35, 0x18000
	v_lshl_add_u64 v[6:7], v[6:7], 0, s[4:5]
	s_lshl_b32 s11, s10, 7
	s_waitcnt vmcnt(2)
	s_barrier
	global_load_lds_dwordx4 v[6:7], off
	v_lshl_add_u64 v[4:5], v[4:5], 0, s[4:5]
	s_add_i32 m0, s35, 0x1a000
	s_add_i32 s40, s35, 0x8000
	s_add_i32 s41, s35, 0xa000
	global_load_lds_dwordx4 v[4:5], off
	v_lshl_add_u64 v[2:3], v[2:3], 0, s[4:5]
	s_mov_b32 m0, s40
	s_add_u32 s8, s18, 0x80080
	global_load_lds_dwordx4 v[2:3], off
	v_lshl_add_u64 v[0:1], v[0:1], 0, s[4:5]
	s_mov_b32 m0, s41
	s_addc_u32 s9, s19, 0
	global_load_lds_dwordx4 v[0:1], off
	s_add_i32 m0, s35, 0x1c000
	v_lshl_add_u64 v[0:1], s[8:9], 0, v[132:133]
	global_load_lds_dwordx4 v[0:1], off
	v_lshl_add_u64 v[0:1], s[8:9], 0, v[128:129]
	s_add_i32 m0, s35, 0x1e000
	s_sext_i32_i16 s15, s6
	global_load_lds_dwordx4 v[0:1], off
	v_lshlrev_b32_e32 v0, 6, v13
	v_lshlrev_b32_e32 v1, 1, v11
	s_movk_i32 s6, 0x3c0
	v_lshlrev_b32_e32 v2, 2, v13
	v_and_or_b32 v0, v0, s6, v1
	v_and_b32_e32 v2, 32, v2
	v_bitop3_b32 v0, v0, s7, v2 bitop3:0xde
	v_lshlrev_b32_e32 v2, 6, v178
	v_and_or_b32 v1, v2, s6, v1
	v_lshlrev_b32_e32 v2, 2, v178
	v_and_b32_e32 v2, 32, v2
	v_bitop3_b32 v145, s11, v1, v2 bitop3:0xf6
	v_lshlrev_b32_e32 v1, 9, v178
	v_and_b32_e32 v1, 0x70000, v1
	v_lshlrev_b32_e32 v2, 12, v12
	v_or3_b32 v1, v9, v1, v2
	v_add_u32_e32 v136, v1, v10
	v_lshlrev_b32_e32 v1, 5, v8
	s_waitcnt vmcnt(6)
	v_and_b32_e32 v1, 0xf0000, v1
	v_or3_b32 v1, v9, v1, v2
	s_add_i32 s44, 0, 0x10000
	s_add_i32 s45, 0, 0x14000
	s_ashr_i32 s42, s54, 31
	s_mov_b32 s43, s54
	v_or_b32_e32 v146, s10, v11
	v_mov_b32_e32 v137, v133
	v_add_u32_e32 v138, v1, v10
	v_mov_b32_e32 v139, v133
	v_mov_b64_e32 v[140:141], 0xac0
	v_mov_b64_e32 v[142:143], 0xabf
	v_add_u32_e32 v148, s44, v145
	s_waitcnt vmcnt(0)
	v_add_u32_e32 v149, 0, v0
	v_add_u32_e32 v150, s45, v145
	v_mov_b32_e32 v151, 0x358637bd
	s_movk_i32 s46, 0x2b00
	s_barrier
	s_branch .LBB0_2543

; #define PG8_STAGE(bufoff, gbase, voff) do { _Pragma("unroll") for (int _i = 0; _i < 2; ++_i) \
;         __builtin_amdgcn_global_load_lds((const unsigned*)((const char*)(gbase) + (voff)[_i]), (LAS unsigned*)(lds + (bufoff) + ldsw + _i * 8192), 16, 0, 0); } while (0)
; #define PG8_LDA(dst, b, h) do { _Pragma("unroll") for (int m = 0; m < 4; ++m) _Pragma("unroll") for (int k = 0; k < 2; ++k) dst[m][k] = *(const LAS bf16x8*)(lds + PG8_SA(b, h) + aoff + m * 2048 + k * 1024); } while (0)
; #define PG8_LDB(dst, b, h) do { _Pragma("unroll") for (int n = 0; n < 2; ++n) _Pragma("unroll") for (int k = 0; k < 2; ++k) dst[n][k] = *(const LAS bf16x8*)(lds + PG8_SB(b, h) + boff + n * 2048 + k * 1024); } while (0)
; #define PG8_MMA(ai, bj, At, Bt) do { __builtin_amdgcn_s_setprio(1); _Pragma("unroll") for (int m = 0; m < 4; ++m) _Pragma("unroll") for (int n = 0; n < 2; ++n) _Pragma("unroll") for (int k = 0; k < 2; ++k) \
;         acc[ai][bj][m][n] = __builtin_amdgcn_mfma_f32_16x16x32_bf16(Bt[n][k], At[m][k], acc[ai][bj][m][n], 0, 0, 0); __builtin_amdgcn_s_setprio(0); } while (0)
; #define PG8_WAIT_V(n) asm volatile("s_waitcnt vmcnt(" #n ")" ::: "memory")
; #define PG8_WAIT_L(n) asm volatile("s_waitcnt lgkmcnt(" #n ")" ::: "memory")
; template <class Epi>
; __device__ __forceinline__ void gemm_phase(LAS unsigned char* lds, const Gemm g, const StaticOrder& S, const Epi& E) {
;     ...
;         for (int t = 0; t < nt; t += 2) {
;             const bool last = (t == nt - 2);
;             const char* a1 = cA + (size_t)(t + 1) * kstep;
;             const char* a2 = last ? nA : cA + (size_t)(t + 2) * kstep; const char* b2 = last ? nB : cB + (size_t)(t + 2) * kstep;
;             const char* a3 = a2 + kstep; const char* b3 = b2 + kstep;
;             PG8_LDB(B0, 0, 0); PG8_SCHED; PG8_LDA(At, 0, 0); PG8_STAGE(PG8_SA(1, 1), a1 + hstep, voffA);
;             PG8_WAIT_L(8); PG8_BAR; PG8_WAIT_L(0); PG8_MMA(0, 0, At, B0); PG8_BAR; PG8_SCHED;
;             PG8_LDB(B1, 0, 1); PG8_STAGE(PG8_SB(0, 0), b2, voffB);
;             PG8_BAR; PG8_WAIT_L(0); PG8_MMA(0, 1, At, B1); PG8_BAR;
;             PG8_LDA(At, 0, 1); PG8_STAGE(PG8_SA(0, 0), a2, voffA);
;             PG8_BAR; PG8_WAIT_L(0); PG8_MMA(1, 0, At, B0); PG8_BAR; PG8_SCHED;
;             PG8_STAGE(PG8_SB(0, 1), b2 + hstep, voffB);
;             PG8_WAIT_V(6); PG8_BAR; PG8_MMA(1, 1, At, B1); PG8_BAR;
.LBB0_2546:
	ds_read_b128 v[160:163], v148
	ds_read_b128 v[164:167], v148 offset:1024
	ds_read_b128 v[168:171], v148 offset:2048
	ds_read_b128 v[172:175], v148 offset:3072
	s_add_u32 s18, s16, 0xfff80080
	s_addc_u32 s19, s17, -1
	s_cmp_eq_u32 s59, 28
	s_cselect_b32 s21, s9, s19
	s_cselect_b32 s20, s47, s18
	s_cselect_b32 s19, s7, s58
	s_cselect_b32 s18, s56, s57
	v_lshl_add_u64 v[176:177], s[16:17], 0, v[136:137]
	s_add_i32 m0, s35, 0xc000
	ds_read_b128 v[180:183], v149
	ds_read_b128 v[184:187], v149 offset:1024
	ds_read_b128 v[188:191], v149 offset:2048
	ds_read_b128 v[192:195], v149 offset:3072
	ds_read_b128 v[196:199], v149 offset:4096
	ds_read_b128 v[200:203], v149 offset:5120
	ds_read_b128 v[204:207], v149 offset:6144
	ds_read_b128 v[208:211], v149 offset:7168
	global_load_lds_dwordx4 v[176:177], off
	v_lshl_add_u64 v[176:177], s[16:17], 0, v[138:139]
	s_add_i32 m0, s35, 0xe000
	s_nop 0
	global_load_lds_dwordx4 v[176:177], off
	ds_read_b128 v[212:215], v150
	ds_read_b128 v[216:219], v150 offset:1024
	ds_read_b128 v[220:223], v150 offset:2048
	ds_read_b128 v[224:227], v150 offset:3072
	s_waitcnt lgkmcnt(0)
	s_waitcnt vmcnt(8)
	s_setprio 1
	s_barrier
	v_mfma_f32_16x16x32_bf16 v[124:127], v[160:163], v[180:183], v[124:127]
	v_mfma_f32_16x16x32_bf16 v[116:119], v[168:171], v[180:183], v[116:119]
	v_mfma_f32_16x16x32_bf16 v[108:111], v[160:163], v[188:191], v[108:111]
	v_mfma_f32_16x16x32_bf16 v[100:103], v[168:171], v[188:191], v[100:103]
	v_mfma_f32_16x16x32_bf16 v[92:95], v[160:163], v[196:199], v[92:95]
	v_mfma_f32_16x16x32_bf16 v[84:87], v[168:171], v[196:199], v[84:87]
	v_mfma_f32_16x16x32_bf16 v[76:79], v[160:163], v[204:207], v[76:79]
	v_mfma_f32_16x16x32_bf16 v[68:71], v[168:171], v[204:207], v[68:71]
	v_mfma_f32_16x16x32_bf16 v[124:127], v[164:167], v[184:187], v[124:127]
	v_mfma_f32_16x16x32_bf16 v[116:119], v[172:175], v[184:187], v[116:119]
	v_mfma_f32_16x16x32_bf16 v[108:111], v[164:167], v[192:195], v[108:111]
	v_mfma_f32_16x16x32_bf16 v[100:103], v[172:175], v[192:195], v[100:103]
	v_mfma_f32_16x16x32_bf16 v[92:95], v[164:167], v[200:203], v[92:95]
	v_mfma_f32_16x16x32_bf16 v[84:87], v[172:175], v[200:203], v[84:87]
	v_mfma_f32_16x16x32_bf16 v[76:79], v[164:167], v[208:211], v[76:79]
	v_mfma_f32_16x16x32_bf16 v[68:71], v[172:175], v[208:211], v[68:71]
	v_mfma_f32_16x16x32_bf16 v[120:123], v[212:215], v[180:183], v[120:123]
	v_mfma_f32_16x16x32_bf16 v[112:115], v[220:223], v[180:183], v[112:115]
	v_mfma_f32_16x16x32_bf16 v[104:107], v[212:215], v[188:191], v[104:107]
	v_mfma_f32_16x16x32_bf16 v[96:99], v[220:223], v[188:191], v[96:99]
	v_mfma_f32_16x16x32_bf16 v[88:91], v[212:215], v[196:199], v[88:91]
	v_mfma_f32_16x16x32_bf16 v[80:83], v[220:223], v[196:199], v[80:83]
	v_mfma_f32_16x16x32_bf16 v[72:75], v[212:215], v[204:207], v[72:75]
	v_mfma_f32_16x16x32_bf16 v[64:67], v[220:223], v[204:207], v[64:67]
	v_mfma_f32_16x16x32_bf16 v[120:123], v[216:219], v[184:187], v[120:123]
	v_mfma_f32_16x16x32_bf16 v[112:115], v[224:227], v[184:187], v[112:115]
	v_mfma_f32_16x16x32_bf16 v[104:107], v[216:219], v[192:195], v[104:107]
	v_mfma_f32_16x16x32_bf16 v[96:99], v[224:227], v[192:195], v[96:99]
	v_mfma_f32_16x16x32_bf16 v[88:91], v[216:219], v[200:203], v[88:91]
	v_mfma_f32_16x16x32_bf16 v[80:83], v[224:227], v[200:203], v[80:83]
	v_mfma_f32_16x16x32_bf16 v[72:75], v[216:219], v[208:211], v[72:75]
	v_mfma_f32_16x16x32_bf16 v[64:67], v[224:227], v[208:211], v[64:67]
	s_barrier
	s_setprio 0
	s_add_i32 s60, s44, s31
	v_lshl_add_u64 v[176:177], s[18:19], 0, v[132:133]
	s_mov_b32 m0, s60
	s_nop 0
	global_load_lds_dwordx4 v[176:177], off
	v_lshl_add_u64 v[228:229], s[18:19], 0, v[128:129]
	s_add_i32 m0, s60, 0x2000
	s_nop 0
	global_load_lds_dwordx4 v[228:229], off
	s_mov_b32 m0, s35
	v_lshl_add_u64 v[230:231], s[20:21], 0, v[134:135]
	ds_read_b128 v[180:183], v149 offset:16384
	ds_read_b128 v[184:187], v149 offset:17408
	ds_read_b128 v[188:191], v149 offset:18432
	ds_read_b128 v[192:195], v149 offset:19456
	ds_read_b128 v[196:199], v149 offset:20480
	ds_read_b128 v[200:203], v149 offset:21504
	ds_read_b128 v[204:207], v149 offset:22528
	ds_read_b128 v[208:211], v149 offset:23552
	global_load_lds_dwordx4 v[230:231], off
	v_lshl_add_u64 v[232:233], s[20:21], 0, v[130:131]
	s_mov_b32 m0, s36
	s_nop 0
	global_load_lds_dwordx4 v[232:233], off
	s_add_u32 s60, s18, 0x80000
	s_addc_u32 s61, s19, 0
	s_add_i32 s62, s45, s31
	v_lshl_add_u64 v[252:253], s[60:61], 0, v[132:133]
	s_mov_b32 m0, s62
	s_nop 0
	global_load_lds_dwordx4 v[252:253], off
	v_lshl_add_u64 v[252:253], s[60:61], 0, v[128:129]
	s_add_i32 m0, s62, 0x2000
	s_nop 0
	global_load_lds_dwordx4 v[252:253], off
	s_waitcnt lgkmcnt(0)
	s_waitcnt vmcnt(8)
	s_setprio 1
	s_barrier
; #define PG8_STAGE(bufoff, gbase, voff) do { _Pragma("unroll") for (int _i = 0; _i < 2; ++_i) \
;         __builtin_amdgcn_global_load_lds((const unsigned*)((const char*)(gbase) + (voff)[_i]), (LAS unsigned*)(lds + (bufoff) + ldsw + _i * 8192), 16, 0, 0); } while (0)
; #define PG8_LDA(dst, b, h) do { _Pragma("unroll") for (int m = 0; m < 4; ++m) _Pragma("unroll") for (int k = 0; k < 2; ++k) dst[m][k] = *(const LAS bf16x8*)(lds + PG8_SA(b, h) + aoff + m * 2048 + k * 1024); } while (0)
; #define PG8_LDB(dst, b, h) do { _Pragma("unroll") for (int n = 0; n < 2; ++n) _Pragma("unroll") for (int k = 0; k < 2; ++k) dst[n][k] = *(const LAS bf16x8*)(lds + PG8_SB(b, h) + boff + n * 2048 + k * 1024); } while (0)
; #define PG8_MMA(ai, bj, At, Bt) do { __builtin_amdgcn_s_setprio(1); _Pragma("unroll") for (int m = 0; m < 4; ++m) _Pragma("unroll") for (int n = 0; n < 2; ++n) _Pragma("unroll") for (int k = 0; k < 2; ++k) \
;         acc[ai][bj][m][n] = __builtin_amdgcn_mfma_f32_16x16x32_bf16(Bt[n][k], At[m][k], acc[ai][bj][m][n], 0, 0, 0); __builtin_amdgcn_s_setprio(0); } while (0)
; #define PG8_WAIT_V(n) asm volatile("s_waitcnt vmcnt(" #n ")" ::: "memory")
; #define PG8_WAIT_L(n) asm volatile("s_waitcnt lgkmcnt(" #n ")" ::: "memory")
; #define PG8_BAR __builtin_amdgcn_s_barrier()
; #define PG8_SCHED __builtin_amdgcn_sched_barrier(0)
; template <class Epi>
; __device__ __forceinline__ void gemm_phase(LAS unsigned char* lds, const Gemm g, const StaticOrder& S, const Epi& E) {
;     ...
;             PG8_BAR; PG8_WAIT_L(0); PG8_MMA(0, 1, At, B1); PG8_BAR;
;             PG8_LDA(At, 0, 1); PG8_STAGE(PG8_SA(0, 0), a2, voffA);
;             PG8_BAR; PG8_WAIT_L(0); PG8_MMA(1, 0, At, B0); PG8_BAR; PG8_SCHED;
;             PG8_STAGE(PG8_SB(0, 1), b2 + hstep, voffB);
;             PG8_WAIT_V(6); PG8_BAR; PG8_MMA(1, 1, At, B1); PG8_BAR;
;             PG8_LDB(B0, 1, 0); PG8_SCHED; PG8_LDA(At, 1, 0); PG8_STAGE(PG8_SA(0, 1), a2 + hstep, voffA);
;             PG8_WAIT_L(8); PG8_BAR; PG8_WAIT_L(0); PG8_MMA(0, 0, At, B0); PG8_BAR; PG8_SCHED;
;             PG8_LDB(B1, 1, 1); PG8_STAGE(PG8_SB(1, 0), b3, voffB);
;             PG8_BAR; PG8_WAIT_L(0); PG8_MMA(0, 1, At, B1); PG8_BAR;
;             PG8_LDA(At, 1, 1); PG8_STAGE(PG8_SA(1, 0), a3, voffA);
;             PG8_BAR; PG8_WAIT_L(0); PG8_MMA(1, 0, At, B0); PG8_BAR; PG8_SCHED;
	v_mfma_f32_16x16x32_bf16 v[60:63], v[160:163], v[180:183], v[60:63]
	v_mfma_f32_16x16x32_bf16 v[52:55], v[168:171], v[180:183], v[52:55]
	v_mfma_f32_16x16x32_bf16 v[44:47], v[160:163], v[188:191], v[44:47]
	v_mfma_f32_16x16x32_bf16 v[36:39], v[168:171], v[188:191], v[36:39]
	v_mfma_f32_16x16x32_bf16 v[28:31], v[160:163], v[196:199], v[28:31]
	v_mfma_f32_16x16x32_bf16 v[20:23], v[168:171], v[196:199], v[20:23]
	v_mfma_f32_16x16x32_bf16 v[12:15], v[160:163], v[204:207], v[12:15]
	v_mfma_f32_16x16x32_bf16 v[4:7], v[168:171], v[204:207], v[4:7]
	v_mfma_f32_16x16x32_bf16 v[60:63], v[164:167], v[184:187], v[60:63]
	v_mfma_f32_16x16x32_bf16 v[52:55], v[172:175], v[184:187], v[52:55]
	v_mfma_f32_16x16x32_bf16 v[44:47], v[164:167], v[192:195], v[44:47]
	v_mfma_f32_16x16x32_bf16 v[36:39], v[172:175], v[192:195], v[36:39]
	v_mfma_f32_16x16x32_bf16 v[28:31], v[164:167], v[200:203], v[28:31]
	v_mfma_f32_16x16x32_bf16 v[20:23], v[172:175], v[200:203], v[20:23]
	v_mfma_f32_16x16x32_bf16 v[12:15], v[164:167], v[208:211], v[12:15]
	v_mfma_f32_16x16x32_bf16 v[4:7], v[172:175], v[208:211], v[4:7]
	v_mfma_f32_16x16x32_bf16 v[56:59], v[212:215], v[180:183], v[56:59]
	v_mfma_f32_16x16x32_bf16 v[48:51], v[220:223], v[180:183], v[48:51]
	v_mfma_f32_16x16x32_bf16 v[40:43], v[212:215], v[188:191], v[40:43]
	v_mfma_f32_16x16x32_bf16 v[32:35], v[220:223], v[188:191], v[32:35]
	v_mfma_f32_16x16x32_bf16 v[24:27], v[212:215], v[196:199], v[24:27]
	v_mfma_f32_16x16x32_bf16 v[16:19], v[220:223], v[196:199], v[16:19]
	v_mfma_f32_16x16x32_bf16 v[8:11], v[212:215], v[204:207], v[8:11]
	v_mfma_f32_16x16x32_bf16 v[0:3], v[220:223], v[204:207], v[0:3]
	v_mfma_f32_16x16x32_bf16 v[56:59], v[216:219], v[184:187], v[56:59]
	v_mfma_f32_16x16x32_bf16 v[48:51], v[224:227], v[184:187], v[48:51]
	v_mfma_f32_16x16x32_bf16 v[40:43], v[216:219], v[192:195], v[40:43]
	v_mfma_f32_16x16x32_bf16 v[32:35], v[224:227], v[192:195], v[32:35]
	v_mfma_f32_16x16x32_bf16 v[24:27], v[216:219], v[200:203], v[24:27]
	v_mfma_f32_16x16x32_bf16 v[16:19], v[224:227], v[200:203], v[16:19]
	v_mfma_f32_16x16x32_bf16 v[8:11], v[216:219], v[208:211], v[8:11]
	v_mfma_f32_16x16x32_bf16 v[0:3], v[224:227], v[208:211], v[0:3]
	s_barrier
	s_setprio 0
	s_add_i32 s60, 0, 0x18000
	v_add_u32_e32 v159, s60, v145
	ds_read_b128 v[160:163], v159
	ds_read_b128 v[164:167], v159 offset:1024
	ds_read_b128 v[168:171], v159 offset:2048
	ds_read_b128 v[172:175], v159 offset:3072
	s_add_u32 s20, s20, 0x80000
	s_addc_u32 s21, s21, 0
	s_mov_b32 m0, s37
	v_lshl_add_u64 v[212:213], s[20:21], 0, v[134:135]
	ds_read_b128 v[180:183], v149 offset:32768
	ds_read_b128 v[184:187], v149 offset:33792
	ds_read_b128 v[188:191], v149 offset:34816
	ds_read_b128 v[192:195], v149 offset:35840
	ds_read_b128 v[196:199], v149 offset:36864
	ds_read_b128 v[200:203], v149 offset:37888
	ds_read_b128 v[204:207], v149 offset:38912
	ds_read_b128 v[208:211], v149 offset:39936
	global_load_lds_dwordx4 v[212:213], off
	v_lshl_add_u64 v[212:213], s[20:21], 0, v[130:131]
	s_mov_b32 m0, s38
	s_nop 0
	global_load_lds_dwordx4 v[212:213], off
	s_add_i32 s20, 0, 0x1c000
	v_add_u32_e32 v159, s20, v145
	ds_read_b128 v[212:215], v159
	ds_read_b128 v[216:219], v159 offset:1024
	ds_read_b128 v[220:223], v159 offset:2048
	ds_read_b128 v[224:227], v159 offset:3072
	s_waitcnt lgkmcnt(0)
	s_waitcnt vmcnt(8)
	s_setprio 1
	s_barrier
	v_mfma_f32_16x16x32_bf16 v[124:127], v[160:163], v[180:183], v[124:127]
	v_mfma_f32_16x16x32_bf16 v[116:119], v[168:171], v[180:183], v[116:119]
	v_mfma_f32_16x16x32_bf16 v[108:111], v[160:163], v[188:191], v[108:111]
	v_mfma_f32_16x16x32_bf16 v[100:103], v[168:171], v[188:191], v[100:103]
	v_mfma_f32_16x16x32_bf16 v[92:95], v[160:163], v[196:199], v[92:95]
	v_mfma_f32_16x16x32_bf16 v[84:87], v[168:171], v[196:199], v[84:87]
	v_mfma_f32_16x16x32_bf16 v[76:79], v[160:163], v[204:207], v[76:79]
	v_mfma_f32_16x16x32_bf16 v[68:71], v[168:171], v[204:207], v[68:71]
	v_mfma_f32_16x16x32_bf16 v[124:127], v[164:167], v[184:187], v[124:127]
	v_mfma_f32_16x16x32_bf16 v[116:119], v[172:175], v[184:187], v[116:119]
	v_mfma_f32_16x16x32_bf16 v[108:111], v[164:167], v[192:195], v[108:111]
	v_mfma_f32_16x16x32_bf16 v[100:103], v[172:175], v[192:195], v[100:103]
	v_mfma_f32_16x16x32_bf16 v[92:95], v[164:167], v[200:203], v[92:95]
	v_mfma_f32_16x16x32_bf16 v[84:87], v[172:175], v[200:203], v[84:87]
	v_mfma_f32_16x16x32_bf16 v[76:79], v[164:167], v[208:211], v[76:79]
	v_mfma_f32_16x16x32_bf16 v[68:71], v[172:175], v[208:211], v[68:71]
	v_mfma_f32_16x16x32_bf16 v[120:123], v[212:215], v[180:183], v[120:123]
	v_mfma_f32_16x16x32_bf16 v[112:115], v[220:223], v[180:183], v[112:115]
	v_mfma_f32_16x16x32_bf16 v[104:107], v[212:215], v[188:191], v[104:107]
	v_mfma_f32_16x16x32_bf16 v[96:99], v[220:223], v[188:191], v[96:99]
	v_mfma_f32_16x16x32_bf16 v[88:91], v[212:215], v[196:199], v[88:91]
	v_mfma_f32_16x16x32_bf16 v[80:83], v[220:223], v[196:199], v[80:83]
	v_mfma_f32_16x16x32_bf16 v[72:75], v[212:215], v[204:207], v[72:75]
	v_mfma_f32_16x16x32_bf16 v[64:67], v[220:223], v[204:207], v[64:67]
	v_mfma_f32_16x16x32_bf16 v[120:123], v[216:219], v[184:187], v[120:123]
	v_mfma_f32_16x16x32_bf16 v[112:115], v[224:227], v[184:187], v[112:115]
	v_mfma_f32_16x16x32_bf16 v[104:107], v[216:219], v[192:195], v[104:107]
	v_mfma_f32_16x16x32_bf16 v[96:99], v[224:227], v[192:195], v[96:99]
	v_mfma_f32_16x16x32_bf16 v[88:91], v[216:219], v[200:203], v[88:91]
	v_mfma_f32_16x16x32_bf16 v[80:83], v[224:227], v[200:203], v[80:83]
	v_mfma_f32_16x16x32_bf16 v[72:75], v[216:219], v[208:211], v[72:75]
	v_mfma_f32_16x16x32_bf16 v[64:67], v[224:227], v[208:211], v[64:67]
	s_barrier
; __device__ __forceinline__ float sigmoidf_(float x) { return __builtin_amdgcn_rcpf(1.0f + fexp(-x)); }
; #define PG8_STAGE(bufoff, gbase, voff) do { _Pragma("unroll") for (int _i = 0; _i < 2; ++_i) \
;         __builtin_amdgcn_global_load_lds((const unsigned*)((const char*)(gbase) + (voff)[_i]), (LAS unsigned*)(lds + (bufoff) + ldsw + _i * 8192), 16, 0, 0); } while (0)
; #define PG8_LDA(dst, b, h) do { _Pragma("unroll") for (int m = 0; m < 4; ++m) _Pragma("unroll") for (int k = 0; k < 2; ++k) dst[m][k] = *(const LAS bf16x8*)(lds + PG8_SA(b, h) + aoff + m * 2048 + k * 1024); } while (0)
; #define PG8_LDB(dst, b, h) do { _Pragma("unroll") for (int n = 0; n < 2; ++n) _Pragma("unroll") for (int k = 0; k < 2; ++k) dst[n][k] = *(const LAS bf16x8*)(lds + PG8_SB(b, h) + boff + n * 2048 + k * 1024); } while (0)
; #define PG8_BAR __builtin_amdgcn_s_barrier()
; template <class Epi>
; __device__ __forceinline__ void gemm_phase(LAS unsigned char* lds, const Gemm g, const StaticOrder& S, const Epi& E) {
;     ...
;             PG8_LDB(B1, 1, 1); PG8_STAGE(PG8_SB(1, 0), b3, voffB);
;             PG8_BAR; PG8_WAIT_L(0); PG8_MMA(0, 1, At, B1); PG8_BAR;
;             PG8_LDA(At, 1, 1); PG8_STAGE(PG8_SA(1, 0), a3, voffA);
;             PG8_BAR; PG8_WAIT_L(0); PG8_MMA(1, 0, At, B0); PG8_BAR; PG8_SCHED;
;             PG8_STAGE(PG8_SB(1, 1), b3 + hstep, voffB);
;             PG8_WAIT_V(6); PG8_BAR; PG8_MMA(1, 1, At, B1); PG8_BAR;
;         }
;     __device__ __forceinline__ void operator()(const f32x4 (&acc)[2][2][4][2], const Unit& u, int wr, int wc, int fr, int fq, const Pre& P) const {
;         const int row0 = ROW_X + u.pm * BM + wr * 64 + fr, col0 = u.pn * HALF + wc * 32 + 8 * fq;
; #pragma unroll
;         for (int ai = 0; ai < 2; ++ai)
; #pragma unroll
;             for (int m = 0; m < 4; ++m) { const int r = row0 + ai * HALF + m * 16; const float rs = __builtin_amdgcn_rsqf(P.rs[ai * 4 + m] * (1.0f / DM) + RMS_EPS);
;                 float y[8];
; #pragma unroll
;                 for (int n = 0; n < 2; ++n)
; #pragma unroll
;                     for (int j = 0; j < 4; ++j) { const float a = acc[ai][0][m][n][j] * rs, b = acc[ai][1][m][n][j] * rs; y[n * 4 + j] = a * b * sigmoidf_(a); }
;                 u32x4 w; w.x = cvtpk(y[0], y[1]); w.y = cvtpk(y[2], y[3]); w.z = cvtpk(y[4], y[5]); w.w = cvtpk(y[6], y[7]);
;                 *(u32x4*)(O + (size_t)r * FF + col0) = w; }
	s_setprio 0
	s_add_i32 s21, s60, s31
	v_lshl_add_u64 v[176:177], v[176:177], 0, s[4:5]
	s_mov_b32 m0, s21
	s_nop 0
	global_load_lds_dwordx4 v[176:177], off
	v_lshl_add_u64 v[176:177], v[228:229], 0, s[4:5]
	s_add_i32 m0, s21, 0x2000
	s_nop 0
	global_load_lds_dwordx4 v[176:177], off
	s_mov_b32 m0, s40
	v_lshl_add_u64 v[176:177], v[230:231], 0, s[4:5]
	ds_read_b128 v[180:183], v149 offset:49152
	ds_read_b128 v[184:187], v149 offset:50176
	ds_read_b128 v[188:191], v149 offset:51200
	ds_read_b128 v[192:195], v149 offset:52224
	ds_read_b128 v[196:199], v149 offset:53248
	ds_read_b128 v[200:203], v149 offset:54272
	ds_read_b128 v[204:207], v149 offset:55296
	ds_read_b128 v[208:211], v149 offset:56320
	global_load_lds_dwordx4 v[176:177], off
	v_lshl_add_u64 v[176:177], v[232:233], 0, s[4:5]
	s_mov_b32 m0, s41
	s_nop 0
	global_load_lds_dwordx4 v[176:177], off
	s_add_u32 s18, s18, 0x80080
	s_addc_u32 s19, s19, 0
	s_add_i32 s20, s20, s31
	v_lshl_add_u64 v[252:253], s[18:19], 0, v[132:133]
	s_mov_b32 m0, s20
	s_nop 0
	global_load_lds_dwordx4 v[252:253], off
	v_lshl_add_u64 v[252:253], s[18:19], 0, v[128:129]
	s_add_i32 m0, s20, 0x2000
	s_nop 0
	global_load_lds_dwordx4 v[252:253], off
	s_waitcnt lgkmcnt(0)
	s_waitcnt vmcnt(8)
	s_setprio 1
	s_barrier
	v_mfma_f32_16x16x32_bf16 v[60:63], v[160:163], v[180:183], v[60:63]
	v_mfma_f32_16x16x32_bf16 v[52:55], v[168:171], v[180:183], v[52:55]
	v_mfma_f32_16x16x32_bf16 v[44:47], v[160:163], v[188:191], v[44:47]
	v_mfma_f32_16x16x32_bf16 v[36:39], v[168:171], v[188:191], v[36:39]
	v_mfma_f32_16x16x32_bf16 v[28:31], v[160:163], v[196:199], v[28:31]
	v_mfma_f32_16x16x32_bf16 v[20:23], v[168:171], v[196:199], v[20:23]
	v_mfma_f32_16x16x32_bf16 v[12:15], v[160:163], v[204:207], v[12:15]
	v_mfma_f32_16x16x32_bf16 v[4:7], v[168:171], v[204:207], v[4:7]
	v_mfma_f32_16x16x32_bf16 v[60:63], v[164:167], v[184:187], v[60:63]
	v_mfma_f32_16x16x32_bf16 v[52:55], v[172:175], v[184:187], v[52:55]
	v_mfma_f32_16x16x32_bf16 v[44:47], v[164:167], v[192:195], v[44:47]
	v_mfma_f32_16x16x32_bf16 v[36:39], v[172:175], v[192:195], v[36:39]
	v_mfma_f32_16x16x32_bf16 v[28:31], v[164:167], v[200:203], v[28:31]
	v_mfma_f32_16x16x32_bf16 v[20:23], v[172:175], v[200:203], v[20:23]
	v_mfma_f32_16x16x32_bf16 v[12:15], v[164:167], v[208:211], v[12:15]
	v_mfma_f32_16x16x32_bf16 v[4:7], v[172:175], v[208:211], v[4:7]
	v_mfma_f32_16x16x32_bf16 v[56:59], v[212:215], v[180:183], v[56:59]
	v_mfma_f32_16x16x32_bf16 v[48:51], v[220:223], v[180:183], v[48:51]
	v_mfma_f32_16x16x32_bf16 v[40:43], v[212:215], v[188:191], v[40:43]
	v_mfma_f32_16x16x32_bf16 v[32:35], v[220:223], v[188:191], v[32:35]
	v_mfma_f32_16x16x32_bf16 v[24:27], v[212:215], v[196:199], v[24:27]
	v_mfma_f32_16x16x32_bf16 v[16:19], v[220:223], v[196:199], v[16:19]
	v_mfma_f32_16x16x32_bf16 v[8:11], v[212:215], v[204:207], v[8:11]
	v_mfma_f32_16x16x32_bf16 v[0:3], v[220:223], v[204:207], v[0:3]
	v_mfma_f32_16x16x32_bf16 v[56:59], v[216:219], v[184:187], v[56:59]
	v_mfma_f32_16x16x32_bf16 v[48:51], v[224:227], v[184:187], v[48:51]
	v_mfma_f32_16x16x32_bf16 v[40:43], v[216:219], v[192:195], v[40:43]
	v_mfma_f32_16x16x32_bf16 v[32:35], v[224:227], v[192:195], v[32:35]
	v_mfma_f32_16x16x32_bf16 v[24:27], v[216:219], v[200:203], v[24:27]
	v_mfma_f32_16x16x32_bf16 v[16:19], v[224:227], v[200:203], v[16:19]
	v_mfma_f32_16x16x32_bf16 v[8:11], v[216:219], v[208:211], v[8:11]
	v_mfma_f32_16x16x32_bf16 v[0:3], v[224:227], v[208:211], v[0:3]
	s_barrier
	s_setprio 0
	s_add_i32 s59, s59, 2
	s_add_u32 s16, s16, 0x100
	s_addc_u32 s17, s17, 0
	s_add_u32 s57, s57, 0x100
	s_addc_u32 s58, s58, 0
	s_cmp_gt_u32 s59, 29
	s_cbranch_scc0 .LBB0_2546
	s_waitcnt vmcnt(0)
	v_fmamk_f32 v158, v158, 0x3a000000, v151
	v_rsq_f32_e32 v158, v158
	v_lshl_or_b32 v162, s15, 7, v146
	v_ashrrev_i32_e32 v163, 31, v162
	s_and_b64 vcc, vcc, exec
	v_pk_mul_f32 v[160:161], v[158:159], v[124:125] op_sel_hi:[0,1]
	v_mul_f32_e32 v124, 0xbfb8aa3b, v160
	v_mul_f32_e32 v125, 0xbfb8aa3b, v161
	v_exp_f32_e32 v159, v124
	v_exp_f32_e32 v125, v125
	v_lshl_add_u32 v124, s14, 8, v144
	v_add_f32_e32 v159, 1.0, v159
	v_add_f32_e32 v125, 1.0, v125
	v_rcp_f32_e32 v164, v159
	v_rcp_f32_e32 v165, v125
	v_pk_mul_f32 v[120:121], v[158:159], v[120:121] op_sel_hi:[0,1]
	v_pk_mul_f32 v[120:121], v[160:161], v[120:121]
	v_pk_mul_f32 v[126:127], v[158:159], v[126:127] op_sel_hi:[0,1]
	v_pk_mul_f32 v[120:121], v[164:165], v[120:121]
	v_mul_f32_e32 v125, 0xbfb8aa3b, v126
	v_cvt_pk_bf16_f32 v120, v120, v121
	v_mul_f32_e32 v121, 0xbfb8aa3b, v127
	v_exp_f32_e32 v125, v125
	v_exp_f32_e32 v121, v121
	v_pk_mul_f32 v[122:123], v[158:159], v[122:123] op_sel_hi:[0,1]
	v_pk_mul_f32 v[116:117], v[158:159], v[116:117] op_sel_hi:[0,1]
	v_add_f32_e32 v125, 1.0, v125
	v_add_f32_e32 v121, 1.0, v121
	v_rcp_f32_e32 v160, v125
	v_rcp_f32_e32 v161, v121
	v_pk_mul_f32 v[122:123], v[126:127], v[122:123]
	v_mul_f32_e32 v121, 0xbfb8aa3b, v116
	v_exp_f32_e32 v125, v121
	v_pk_mul_f32 v[122:123], v[160:161], v[122:123]
	v_pk_mul_f32 v[112:113], v[158:159], v[112:113] op_sel_hi:[0,1]
	v_cvt_pk_bf16_f32 v121, v122, v123
	v_mul_f32_e32 v123, 0xbfb8aa3b, v117
	v_exp_f32_e32 v123, v123
	v_add_f32_e32 v122, 1.0, v125
	v_pk_mul_f32 v[112:113], v[116:117], v[112:113]
	v_rcp_f32_e32 v122, v122
	v_add_f32_e32 v116, 1.0, v123
	v_rcp_f32_e32 v123, v116
	v_pk_mul_f32 v[116:117], v[158:159], v[118:119] op_sel_hi:[0,1]
	v_mul_f32_e32 v118, 0xbfb8aa3b, v116
	v_mul_f32_e32 v119, 0xbfb8aa3b, v117
	v_exp_f32_e32 v118, v118
	v_exp_f32_e32 v119, v119
	v_pk_mul_f32 v[112:113], v[122:123], v[112:113]
	v_add_f32_e32 v118, 1.0, v118
	v_cvt_pk_bf16_f32 v122, v112, v113
	v_pk_mul_f32 v[112:113], v[158:159], v[114:115] op_sel_hi:[0,1]
; __device__ __forceinline__ float sigmoidf_(float x) { return __builtin_amdgcn_rcpf(1.0f + fexp(-x)); }
;     __device__ __forceinline__ void operator()(const f32x4 (&acc)[2][2][4][2], const Unit& u, int wr, int wc, int fr, int fq, const Pre& P) const {
;         const int row0 = ROW_X + u.pm * BM + wr * 64 + fr, col0 = u.pn * HALF + wc * 32 + 8 * fq;
; #pragma unroll
;         for (int ai = 0; ai < 2; ++ai)
; #pragma unroll
;             for (int m = 0; m < 4; ++m) { const int r = row0 + ai * HALF + m * 16; const float rs = __builtin_amdgcn_rsqf(P.rs[ai * 4 + m] * (1.0f / DM) + RMS_EPS);
;                 float y[8];
; #pragma unroll
;                 for (int n = 0; n < 2; ++n)
; #pragma unroll
;                     for (int j = 0; j < 4; ++j) { const float a = acc[ai][0][m][n][j] * rs, b = acc[ai][1][m][n][j] * rs; y[n * 4 + j] = a * b * sigmoidf_(a); }
;                 u32x4 w; w.x = cvtpk(y[0], y[1]); w.y = cvtpk(y[2], y[3]); w.z = cvtpk(y[4], y[5]); w.w = cvtpk(y[6], y[7]);
;                 *(u32x4*)(O + (size_t)r * FF + col0) = w; }
	v_fmamk_f32 v114, v157, 0x3a000000, v151
	v_pk_mul_f32 v[112:113], v[116:117], v[112:113]
	v_rsq_f32_e32 v116, v114
	v_add_f32_e32 v119, 1.0, v119
	v_rcp_f32_e32 v118, v118
	v_rcp_f32_e32 v119, v119
	v_pk_mul_f32 v[108:109], v[116:117], v[108:109] op_sel_hi:[0,1]
	v_mul_f32_e32 v117, 0xbfb8aa3b, v108
	v_exp_f32_e32 v117, v117
	v_mul_f32_e32 v125, 0xbfb8aa3b, v109
	v_pk_mul_f32 v[112:113], v[118:119], v[112:113]
	v_exp_f32_e32 v125, v125
	v_cvt_pk_bf16_f32 v123, v112, v113
	v_mov_b64_e32 v[112:113], s[2:3]
	v_mad_i64_i32 v[118:119], s[14:15], v124, s46, v[112:113]
	v_lshlrev_b64 v[114:115], 1, v[162:163]
	v_lshl_add_u64 v[118:119], v[118:119], 0, v[114:115]
	v_add_f32_e32 v117, 1.0, v117
	global_store_dwordx4 v[118:119], v[120:123], off
	v_rcp_f32_e32 v118, v117
	v_add_f32_e32 v117, 1.0, v125
	v_rcp_f32_e32 v119, v117
	v_or_b32_e32 v117, 16, v124
	v_pk_mul_f32 v[104:105], v[116:117], v[104:105] op_sel_hi:[0,1]
	v_pk_mul_f32 v[104:105], v[108:109], v[104:105]
	v_pk_mul_f32 v[108:109], v[116:117], v[110:111] op_sel_hi:[0,1]
	v_pk_mul_f32 v[104:105], v[118:119], v[104:105]
	v_mul_f32_e32 v110, 0xbfb8aa3b, v108
	v_cvt_pk_bf16_f32 v104, v104, v105
	v_mul_f32_e32 v105, 0xbfb8aa3b, v109
	v_exp_f32_e32 v110, v110
	v_exp_f32_e32 v105, v105
	v_pk_mul_f32 v[106:107], v[116:117], v[106:107] op_sel_hi:[0,1]
	v_pk_mul_f32 v[100:101], v[116:117], v[100:101] op_sel_hi:[0,1]
	v_add_f32_e32 v110, 1.0, v110
	v_add_f32_e32 v105, 1.0, v105
	v_rcp_f32_e32 v110, v110
	v_rcp_f32_e32 v111, v105
	v_pk_mul_f32 v[106:107], v[108:109], v[106:107]
	v_mul_f32_e32 v105, 0xbfb8aa3b, v100
	v_exp_f32_e32 v118, v105
	v_pk_mul_f32 v[106:107], v[110:111], v[106:107]
	v_pk_mul_f32 v[96:97], v[116:117], v[96:97] op_sel_hi:[0,1]
	v_cvt_pk_bf16_f32 v105, v106, v107
	v_mul_f32_e32 v107, 0xbfb8aa3b, v101
	v_exp_f32_e32 v107, v107
	v_pk_mul_f32 v[96:97], v[100:101], v[96:97]
	v_add_f32_e32 v106, 1.0, v118
	v_rcp_f32_e32 v106, v106
	v_add_f32_e32 v100, 1.0, v107
	v_rcp_f32_e32 v107, v100
	v_pk_mul_f32 v[100:101], v[116:117], v[102:103] op_sel_hi:[0,1]
	v_mul_f32_e32 v102, 0xbfb8aa3b, v100
	v_mul_f32_e32 v103, 0xbfb8aa3b, v101
	v_exp_f32_e32 v102, v102
	v_exp_f32_e32 v103, v103
	v_pk_mul_f32 v[96:97], v[106:107], v[96:97]
	v_add_f32_e32 v102, 1.0, v102
	v_add_f32_e32 v103, 1.0, v103
	v_rcp_f32_e32 v102, v102
	v_rcp_f32_e32 v103, v103
	v_cvt_pk_bf16_f32 v106, v96, v97
	v_pk_mul_f32 v[96:97], v[116:117], v[98:99] op_sel_hi:[0,1]
	v_pk_mul_f32 v[96:97], v[100:101], v[96:97]
	v_mad_i64_i32 v[98:99], s[14:15], v117, s46, v[112:113]
	v_pk_mul_f32 v[96:97], v[102:103], v[96:97]
	v_lshl_add_u64 v[98:99], v[98:99], 0, v[114:115]
	v_cvt_pk_bf16_f32 v107, v96, v97
	v_fmamk_f32 v96, v156, 0x3a000000, v151
	v_rsq_f32_e32 v96, v96
	global_store_dwordx4 v[98:99], v[104:107], off
	v_pk_mul_f32 v[92:93], v[96:97], v[92:93] op_sel_hi:[0,1]
	v_mul_f32_e32 v97, 0xbfb8aa3b, v92
	v_exp_f32_e32 v97, v97
	v_mul_f32_e32 v100, 0xbfb8aa3b, v93
	v_exp_f32_e32 v100, v100
	v_add_f32_e32 v97, 1.0, v97
	v_rcp_f32_e32 v98, v97
	v_add_f32_e32 v97, 1.0, v100
	v_rcp_f32_e32 v99, v97
	v_or_b32_e32 v97, 32, v124
	v_pk_mul_f32 v[88:89], v[96:97], v[88:89] op_sel_hi:[0,1]
	v_pk_mul_f32 v[88:89], v[92:93], v[88:89]
	v_pk_mul_f32 v[92:93], v[96:97], v[94:95] op_sel_hi:[0,1]
	v_pk_mul_f32 v[88:89], v[98:99], v[88:89]
	v_mul_f32_e32 v94, 0xbfb8aa3b, v92
	v_cvt_pk_bf16_f32 v88, v88, v89
	v_mul_f32_e32 v89, 0xbfb8aa3b, v93
	v_exp_f32_e32 v94, v94
	v_exp_f32_e32 v89, v89
	v_pk_mul_f32 v[90:91], v[96:97], v[90:91] op_sel_hi:[0,1]
	v_pk_mul_f32 v[84:85], v[96:97], v[84:85] op_sel_hi:[0,1]
	v_add_f32_e32 v94, 1.0, v94
	v_add_f32_e32 v89, 1.0, v89
	v_rcp_f32_e32 v94, v94
	v_rcp_f32_e32 v95, v89
	v_pk_mul_f32 v[90:91], v[92:93], v[90:91]
	v_mul_f32_e32 v89, 0xbfb8aa3b, v84
	v_exp_f32_e32 v98, v89
	v_pk_mul_f32 v[90:91], v[94:95], v[90:91]
	v_pk_mul_f32 v[80:81], v[96:97], v[80:81] op_sel_hi:[0,1]
	v_cvt_pk_bf16_f32 v89, v90, v91
	v_mul_f32_e32 v91, 0xbfb8aa3b, v85
	v_exp_f32_e32 v91, v91
	v_pk_mul_f32 v[80:81], v[84:85], v[80:81]
	v_add_f32_e32 v90, 1.0, v98
	v_rcp_f32_e32 v90, v90
	v_add_f32_e32 v84, 1.0, v91
	v_rcp_f32_e32 v91, v84
	v_pk_mul_f32 v[84:85], v[96:97], v[86:87] op_sel_hi:[0,1]
	v_mul_f32_e32 v86, 0xbfb8aa3b, v84
	v_mul_f32_e32 v87, 0xbfb8aa3b, v85
	v_exp_f32_e32 v86, v86
	v_exp_f32_e32 v87, v87
	v_pk_mul_f32 v[80:81], v[90:91], v[80:81]
	v_add_f32_e32 v86, 1.0, v86
	v_add_f32_e32 v87, 1.0, v87
	v_rcp_f32_e32 v86, v86
	v_rcp_f32_e32 v87, v87
	v_cvt_pk_bf16_f32 v90, v80, v81
	v_pk_mul_f32 v[80:81], v[96:97], v[82:83] op_sel_hi:[0,1]
	v_pk_mul_f32 v[80:81], v[84:85], v[80:81]
	v_mad_i64_i32 v[82:83], s[14:15], v97, s46, v[112:113]
	v_pk_mul_f32 v[80:81], v[86:87], v[80:81]
	v_lshl_add_u64 v[82:83], v[82:83], 0, v[114:115]
	v_cvt_pk_bf16_f32 v91, v80, v81
	v_fmamk_f32 v80, v155, 0x3a000000, v151
	v_rsq_f32_e32 v80, v80
	global_store_dwordx4 v[82:83], v[88:91], off
	v_pk_mul_f32 v[76:77], v[80:81], v[76:77] op_sel_hi:[0,1]
	v_mul_f32_e32 v81, 0xbfb8aa3b, v76
	v_exp_f32_e32 v81, v81
	v_mul_f32_e32 v84, 0xbfb8aa3b, v77
	v_exp_f32_e32 v84, v84
	v_add_f32_e32 v81, 1.0, v81
	v_rcp_f32_e32 v82, v81
	v_add_f32_e32 v81, 1.0, v84
	v_rcp_f32_e32 v83, v81
	v_or_b32_e32 v81, 48, v124
	v_pk_mul_f32 v[72:73], v[80:81], v[72:73] op_sel_hi:[0,1]
	v_pk_mul_f32 v[72:73], v[76:77], v[72:73]
	v_pk_mul_f32 v[76:77], v[80:81], v[78:79] op_sel_hi:[0,1]
	v_pk_mul_f32 v[72:73], v[82:83], v[72:73]
	v_mul_f32_e32 v78, 0xbfb8aa3b, v76
	v_cvt_pk_bf16_f32 v72, v72, v73
	v_mul_f32_e32 v73, 0xbfb8aa3b, v77
	v_exp_f32_e32 v78, v78
	v_exp_f32_e32 v73, v73
	v_pk_mul_f32 v[74:75], v[80:81], v[74:75] op_sel_hi:[0,1]
	v_pk_mul_f32 v[68:69], v[80:81], v[68:69] op_sel_hi:[0,1]
; __device__ __forceinline__ float sigmoidf_(float x) { return __builtin_amdgcn_rcpf(1.0f + fexp(-x)); }
;     __device__ __forceinline__ void operator()(const f32x4 (&acc)[2][2][4][2], const Unit& u, int wr, int wc, int fr, int fq, const Pre& P) const {
;         const int row0 = ROW_X + u.pm * BM + wr * 64 + fr, col0 = u.pn * HALF + wc * 32 + 8 * fq;
; #pragma unroll
;         for (int ai = 0; ai < 2; ++ai)
; #pragma unroll
;             for (int m = 0; m < 4; ++m) { const int r = row0 + ai * HALF + m * 16; const float rs = __builtin_amdgcn_rsqf(P.rs[ai * 4 + m] * (1.0f / DM) + RMS_EPS);
;                 float y[8];
; #pragma unroll
;                 for (int n = 0; n < 2; ++n)
; #pragma unroll
;                     for (int j = 0; j < 4; ++j) { const float a = acc[ai][0][m][n][j] * rs, b = acc[ai][1][m][n][j] * rs; y[n * 4 + j] = a * b * sigmoidf_(a); }
;                 u32x4 w; w.x = cvtpk(y[0], y[1]); w.y = cvtpk(y[2], y[3]); w.z = cvtpk(y[4], y[5]); w.w = cvtpk(y[6], y[7]);
;                 *(u32x4*)(O + (size_t)r * FF + col0) = w; }
	v_add_f32_e32 v78, 1.0, v78
	v_add_f32_e32 v73, 1.0, v73
	v_rcp_f32_e32 v78, v78
	v_rcp_f32_e32 v79, v73
	v_pk_mul_f32 v[74:75], v[76:77], v[74:75]
	v_mul_f32_e32 v73, 0xbfb8aa3b, v68
	v_exp_f32_e32 v82, v73
	v_pk_mul_f32 v[74:75], v[78:79], v[74:75]
	v_pk_mul_f32 v[64:65], v[80:81], v[64:65] op_sel_hi:[0,1]
	v_cvt_pk_bf16_f32 v73, v74, v75
	v_mul_f32_e32 v75, 0xbfb8aa3b, v69
	v_exp_f32_e32 v75, v75
	v_pk_mul_f32 v[64:65], v[68:69], v[64:65]
	v_add_f32_e32 v74, 1.0, v82
	v_rcp_f32_e32 v74, v74
	v_add_f32_e32 v68, 1.0, v75
	v_rcp_f32_e32 v75, v68
	v_pk_mul_f32 v[68:69], v[80:81], v[70:71] op_sel_hi:[0,1]
	v_mul_f32_e32 v70, 0xbfb8aa3b, v68
	v_mul_f32_e32 v71, 0xbfb8aa3b, v69
	v_exp_f32_e32 v70, v70
	v_exp_f32_e32 v71, v71
	v_pk_mul_f32 v[64:65], v[74:75], v[64:65]
	v_add_f32_e32 v70, 1.0, v70
	v_add_f32_e32 v71, 1.0, v71
	v_rcp_f32_e32 v70, v70
	v_rcp_f32_e32 v71, v71
	v_cvt_pk_bf16_f32 v74, v64, v65
	v_pk_mul_f32 v[64:65], v[80:81], v[66:67] op_sel_hi:[0,1]
	v_pk_mul_f32 v[64:65], v[68:69], v[64:65]
	v_mad_i64_i32 v[66:67], s[14:15], v81, s46, v[112:113]
	v_pk_mul_f32 v[64:65], v[70:71], v[64:65]
	v_lshl_add_u64 v[66:67], v[66:67], 0, v[114:115]
	v_cvt_pk_bf16_f32 v75, v64, v65
	v_fmamk_f32 v64, v154, 0x3a000000, v151
	v_rsq_f32_e32 v64, v64
	global_store_dwordx4 v[66:67], v[72:75], off
	v_pk_mul_f32 v[60:61], v[64:65], v[60:61] op_sel_hi:[0,1]
	v_mul_f32_e32 v65, 0xbfb8aa3b, v60
	v_exp_f32_e32 v65, v65
	v_mul_f32_e32 v68, 0xbfb8aa3b, v61
	v_exp_f32_e32 v68, v68
	v_add_f32_e32 v65, 1.0, v65
	v_rcp_f32_e32 v66, v65
	v_add_f32_e32 v65, 1.0, v68
	v_rcp_f32_e32 v67, v65
	v_add_u32_e32 v65, 0x80, v124
	v_pk_mul_f32 v[56:57], v[64:65], v[56:57] op_sel_hi:[0,1]
	v_pk_mul_f32 v[56:57], v[60:61], v[56:57]
	v_pk_mul_f32 v[60:61], v[64:65], v[62:63] op_sel_hi:[0,1]
	v_pk_mul_f32 v[56:57], v[66:67], v[56:57]
	v_mul_f32_e32 v62, 0xbfb8aa3b, v60
	v_cvt_pk_bf16_f32 v56, v56, v57
	v_mul_f32_e32 v57, 0xbfb8aa3b, v61
	v_exp_f32_e32 v62, v62
	v_exp_f32_e32 v57, v57
	v_pk_mul_f32 v[58:59], v[64:65], v[58:59] op_sel_hi:[0,1]
	v_pk_mul_f32 v[52:53], v[64:65], v[52:53] op_sel_hi:[0,1]
	v_add_f32_e32 v62, 1.0, v62
	v_add_f32_e32 v57, 1.0, v57
	v_rcp_f32_e32 v62, v62
	v_rcp_f32_e32 v63, v57
	v_pk_mul_f32 v[58:59], v[60:61], v[58:59]
	v_mul_f32_e32 v57, 0xbfb8aa3b, v52
	v_exp_f32_e32 v66, v57
	v_pk_mul_f32 v[58:59], v[62:63], v[58:59]
	v_pk_mul_f32 v[48:49], v[64:65], v[48:49] op_sel_hi:[0,1]
	v_cvt_pk_bf16_f32 v57, v58, v59
	v_mul_f32_e32 v59, 0xbfb8aa3b, v53
	v_exp_f32_e32 v59, v59
	v_pk_mul_f32 v[48:49], v[52:53], v[48:49]
	v_add_f32_e32 v58, 1.0, v66
	v_rcp_f32_e32 v58, v58
	v_add_f32_e32 v52, 1.0, v59
	v_rcp_f32_e32 v59, v52
	v_pk_mul_f32 v[52:53], v[64:65], v[54:55] op_sel_hi:[0,1]
	v_mul_f32_e32 v54, 0xbfb8aa3b, v52
	v_mul_f32_e32 v55, 0xbfb8aa3b, v53
	v_exp_f32_e32 v54, v54
	v_exp_f32_e32 v55, v55
	v_pk_mul_f32 v[48:49], v[58:59], v[48:49]
	v_add_f32_e32 v54, 1.0, v54
	v_add_f32_e32 v55, 1.0, v55
	v_rcp_f32_e32 v54, v54
	v_rcp_f32_e32 v55, v55
	v_cvt_pk_bf16_f32 v58, v48, v49
	v_pk_mul_f32 v[48:49], v[64:65], v[50:51] op_sel_hi:[0,1]
	v_pk_mul_f32 v[48:49], v[52:53], v[48:49]
	v_mad_i64_i32 v[50:51], s[14:15], v65, s46, v[112:113]
	v_pk_mul_f32 v[48:49], v[54:55], v[48:49]
	v_lshl_add_u64 v[50:51], v[50:51], 0, v[114:115]
	v_cvt_pk_bf16_f32 v59, v48, v49
	v_fmamk_f32 v48, v153, 0x3a000000, v151
	v_rsq_f32_e32 v48, v48
	global_store_dwordx4 v[50:51], v[56:59], off
	v_pk_mul_f32 v[44:45], v[48:49], v[44:45] op_sel_hi:[0,1]
	v_mul_f32_e32 v49, 0xbfb8aa3b, v44
	v_exp_f32_e32 v49, v49
	v_mul_f32_e32 v52, 0xbfb8aa3b, v45
	v_exp_f32_e32 v52, v52
	v_add_f32_e32 v49, 1.0, v49
	v_rcp_f32_e32 v50, v49
	v_add_f32_e32 v49, 1.0, v52
	v_rcp_f32_e32 v51, v49
	v_add_u32_e32 v49, 0x90, v124
	v_pk_mul_f32 v[40:41], v[48:49], v[40:41] op_sel_hi:[0,1]
	v_pk_mul_f32 v[40:41], v[44:45], v[40:41]
	v_pk_mul_f32 v[44:45], v[48:49], v[46:47] op_sel_hi:[0,1]
	v_pk_mul_f32 v[40:41], v[50:51], v[40:41]
	v_mul_f32_e32 v46, 0xbfb8aa3b, v44
	v_cvt_pk_bf16_f32 v40, v40, v41
	v_mul_f32_e32 v41, 0xbfb8aa3b, v45
	v_exp_f32_e32 v46, v46
	v_exp_f32_e32 v41, v41
	v_pk_mul_f32 v[42:43], v[48:49], v[42:43] op_sel_hi:[0,1]
	v_pk_mul_f32 v[36:37], v[48:49], v[36:37] op_sel_hi:[0,1]
	v_add_f32_e32 v46, 1.0, v46
	v_add_f32_e32 v41, 1.0, v41
	v_rcp_f32_e32 v46, v46
	v_rcp_f32_e32 v47, v41
	v_pk_mul_f32 v[42:43], v[44:45], v[42:43]
	v_mul_f32_e32 v41, 0xbfb8aa3b, v36
	v_exp_f32_e32 v50, v41
	v_pk_mul_f32 v[42:43], v[46:47], v[42:43]
	v_pk_mul_f32 v[32:33], v[48:49], v[32:33] op_sel_hi:[0,1]
	v_cvt_pk_bf16_f32 v41, v42, v43
	v_mul_f32_e32 v43, 0xbfb8aa3b, v37
	v_exp_f32_e32 v43, v43
	v_pk_mul_f32 v[32:33], v[36:37], v[32:33]
	v_add_f32_e32 v42, 1.0, v50
	v_rcp_f32_e32 v42, v42
	v_add_f32_e32 v36, 1.0, v43
	v_rcp_f32_e32 v43, v36
	v_pk_mul_f32 v[36:37], v[48:49], v[38:39] op_sel_hi:[0,1]
	v_mul_f32_e32 v38, 0xbfb8aa3b, v36
	v_mul_f32_e32 v39, 0xbfb8aa3b, v37
	v_exp_f32_e32 v38, v38
	v_exp_f32_e32 v39, v39
	v_pk_mul_f32 v[32:33], v[42:43], v[32:33]
	v_add_f32_e32 v38, 1.0, v38
	v_add_f32_e32 v39, 1.0, v39
	v_rcp_f32_e32 v38, v38
	v_rcp_f32_e32 v39, v39
	v_cvt_pk_bf16_f32 v42, v32, v33
	v_pk_mul_f32 v[32:33], v[48:49], v[34:35] op_sel_hi:[0,1]
	v_pk_mul_f32 v[32:33], v[36:37], v[32:33]
	v_mad_i64_i32 v[34:35], s[14:15], v49, s46, v[112:113]
; __device__ __forceinline__ float sigmoidf_(float x) { return __builtin_amdgcn_rcpf(1.0f + fexp(-x)); }
; __device__ __forceinline__ PreRs load_rs(const float* ssq, int pm, int wr, int fr) { PreRs p;
; #pragma unroll
;     for (int ai = 0; ai < 2; ++ai)
; #pragma unroll
;         for (int m = 0; m < 4; ++m) p.rs[ai * 4 + m] = ssq[ROW_X + pm * BM + ai * HALF + wr * 64 + m * 16 + fr];
;     return p; }
;     __device__ __forceinline__ void operator()(const f32x4 (&acc)[2][2][4][2], const Unit& u, int wr, int wc, int fr, int fq, const Pre& P) const {
;     ...
;         for (int ai = 0; ai < 2; ++ai)
; #pragma unroll
;             for (int m = 0; m < 4; ++m) { const int r = row0 + ai * HALF + m * 16; const float rs = __builtin_amdgcn_rsqf(P.rs[ai * 4 + m] * (1.0f / DM) + RMS_EPS);
;                 float y[8];
; #pragma unroll
;                 for (int n = 0; n < 2; ++n)
; #pragma unroll
;                     for (int j = 0; j < 4; ++j) { const float a = acc[ai][0][m][n][j] * rs, b = acc[ai][1][m][n][j] * rs; y[n * 4 + j] = a * b * sigmoidf_(a); }
;                 u32x4 w; w.x = cvtpk(y[0], y[1]); w.y = cvtpk(y[2], y[3]); w.z = cvtpk(y[4], y[5]); w.w = cvtpk(y[6], y[7]);
;                 *(u32x4*)(O + (size_t)r * FF + col0) = w; }
	v_pk_mul_f32 v[32:33], v[38:39], v[32:33]
	v_lshl_add_u64 v[34:35], v[34:35], 0, v[114:115]
	v_cvt_pk_bf16_f32 v43, v32, v33
	v_fmamk_f32 v32, v152, 0x3a000000, v151
	v_rsq_f32_e32 v32, v32
	global_store_dwordx4 v[34:35], v[40:43], off
	v_pk_mul_f32 v[28:29], v[32:33], v[28:29] op_sel_hi:[0,1]
	v_mul_f32_e32 v33, 0xbfb8aa3b, v28
	v_exp_f32_e32 v33, v33
	v_mul_f32_e32 v36, 0xbfb8aa3b, v29
	v_exp_f32_e32 v36, v36
	v_add_f32_e32 v33, 1.0, v33
	v_rcp_f32_e32 v34, v33
	v_add_f32_e32 v33, 1.0, v36
	v_rcp_f32_e32 v35, v33
	v_add_u32_e32 v33, 0xa0, v124
	v_pk_mul_f32 v[24:25], v[32:33], v[24:25] op_sel_hi:[0,1]
	v_pk_mul_f32 v[24:25], v[28:29], v[24:25]
	v_pk_mul_f32 v[28:29], v[32:33], v[30:31] op_sel_hi:[0,1]
	v_pk_mul_f32 v[24:25], v[34:35], v[24:25]
	v_mul_f32_e32 v30, 0xbfb8aa3b, v28
	v_cvt_pk_bf16_f32 v24, v24, v25
	v_mul_f32_e32 v25, 0xbfb8aa3b, v29
	v_exp_f32_e32 v30, v30
	v_exp_f32_e32 v25, v25
	v_pk_mul_f32 v[26:27], v[32:33], v[26:27] op_sel_hi:[0,1]
	v_pk_mul_f32 v[20:21], v[32:33], v[20:21] op_sel_hi:[0,1]
	v_add_f32_e32 v30, 1.0, v30
	v_add_f32_e32 v25, 1.0, v25
	v_rcp_f32_e32 v30, v30
	v_rcp_f32_e32 v31, v25
	v_pk_mul_f32 v[26:27], v[28:29], v[26:27]
	v_mul_f32_e32 v25, 0xbfb8aa3b, v20
	v_exp_f32_e32 v34, v25
	v_pk_mul_f32 v[26:27], v[30:31], v[26:27]
	v_pk_mul_f32 v[16:17], v[32:33], v[16:17] op_sel_hi:[0,1]
	v_cvt_pk_bf16_f32 v25, v26, v27
	v_mul_f32_e32 v27, 0xbfb8aa3b, v21
	v_exp_f32_e32 v27, v27
	v_pk_mul_f32 v[16:17], v[20:21], v[16:17]
	v_add_f32_e32 v26, 1.0, v34
	v_rcp_f32_e32 v26, v26
	v_add_f32_e32 v20, 1.0, v27
	v_rcp_f32_e32 v27, v20
	v_pk_mul_f32 v[20:21], v[32:33], v[22:23] op_sel_hi:[0,1]
	v_mul_f32_e32 v22, 0xbfb8aa3b, v20
	v_mul_f32_e32 v23, 0xbfb8aa3b, v21
	v_exp_f32_e32 v22, v22
	v_exp_f32_e32 v23, v23
	v_pk_mul_f32 v[16:17], v[26:27], v[16:17]
	v_add_f32_e32 v22, 1.0, v22
	v_add_f32_e32 v23, 1.0, v23
	v_rcp_f32_e32 v22, v22
	v_rcp_f32_e32 v23, v23
	v_cvt_pk_bf16_f32 v26, v16, v17
	v_pk_mul_f32 v[16:17], v[32:33], v[18:19] op_sel_hi:[0,1]
	v_pk_mul_f32 v[16:17], v[20:21], v[16:17]
	v_mad_i64_i32 v[18:19], s[14:15], v33, s46, v[112:113]
	v_pk_mul_f32 v[16:17], v[22:23], v[16:17]
	v_lshl_add_u64 v[18:19], v[18:19], 0, v[114:115]
	v_cvt_pk_bf16_f32 v27, v16, v17
	v_fmamk_f32 v16, v147, 0x3a000000, v151
	v_rsq_f32_e32 v16, v16
	global_store_dwordx4 v[18:19], v[24:27], off
	v_pk_mul_f32 v[12:13], v[16:17], v[12:13] op_sel_hi:[0,1]
	v_mul_f32_e32 v17, 0xbfb8aa3b, v12
	v_exp_f32_e32 v17, v17
	v_mul_f32_e32 v20, 0xbfb8aa3b, v13
	v_exp_f32_e32 v20, v20
	v_add_f32_e32 v17, 1.0, v17
	v_rcp_f32_e32 v18, v17
	v_add_f32_e32 v17, 1.0, v20
	v_rcp_f32_e32 v19, v17
	v_add_u32_e32 v17, 0xb0, v124
	v_pk_mul_f32 v[8:9], v[16:17], v[8:9] op_sel_hi:[0,1]
	v_pk_mul_f32 v[8:9], v[12:13], v[8:9]
	v_pk_mul_f32 v[12:13], v[16:17], v[14:15] op_sel_hi:[0,1]
	v_pk_mul_f32 v[8:9], v[18:19], v[8:9]
	v_mul_f32_e32 v14, 0xbfb8aa3b, v12
	v_cvt_pk_bf16_f32 v8, v8, v9
	v_mul_f32_e32 v9, 0xbfb8aa3b, v13
	v_exp_f32_e32 v14, v14
	v_exp_f32_e32 v9, v9
	v_pk_mul_f32 v[10:11], v[16:17], v[10:11] op_sel_hi:[0,1]
	v_pk_mul_f32 v[4:5], v[16:17], v[4:5] op_sel_hi:[0,1]
	v_add_f32_e32 v14, 1.0, v14
	v_add_f32_e32 v9, 1.0, v9
	v_rcp_f32_e32 v14, v14
	v_rcp_f32_e32 v15, v9
	v_pk_mul_f32 v[10:11], v[12:13], v[10:11]
	v_mul_f32_e32 v9, 0xbfb8aa3b, v4
	v_exp_f32_e32 v18, v9
	v_pk_mul_f32 v[10:11], v[14:15], v[10:11]
	v_pk_mul_f32 v[0:1], v[16:17], v[0:1] op_sel_hi:[0,1]
	v_cvt_pk_bf16_f32 v9, v10, v11
	v_mul_f32_e32 v11, 0xbfb8aa3b, v5
	v_exp_f32_e32 v11, v11
	v_pk_mul_f32 v[0:1], v[4:5], v[0:1]
	v_add_f32_e32 v10, 1.0, v18
	v_rcp_f32_e32 v10, v10
	v_add_f32_e32 v4, 1.0, v11
	v_rcp_f32_e32 v11, v4
	v_pk_mul_f32 v[4:5], v[16:17], v[6:7] op_sel_hi:[0,1]
	v_mul_f32_e32 v6, 0xbfb8aa3b, v4
	v_mul_f32_e32 v7, 0xbfb8aa3b, v5
	v_exp_f32_e32 v6, v6
	v_exp_f32_e32 v7, v7
	v_pk_mul_f32 v[0:1], v[10:11], v[0:1]
	v_add_f32_e32 v6, 1.0, v6
	v_add_f32_e32 v7, 1.0, v7
	v_rcp_f32_e32 v6, v6
	v_rcp_f32_e32 v7, v7
	v_cvt_pk_bf16_f32 v10, v0, v1
	v_pk_mul_f32 v[0:1], v[16:17], v[2:3] op_sel_hi:[0,1]
	v_pk_mul_f32 v[0:1], v[4:5], v[0:1]
	s_nop 0
	v_pk_mul_f32 v[0:1], v[6:7], v[0:1]
	s_nop 0
	v_cvt_pk_bf16_f32 v11, v0, v1
	v_mad_i64_i32 v[0:1], s[14:15], v17, s46, v[112:113]
	v_lshl_add_u64 v[0:1], v[0:1], 0, v[114:115]
	s_mov_b64 s[14:15], -1
	global_store_dwordx4 v[0:1], v[8:11], off
	s_cbranch_vccz .LBB0_2542
	v_lshl_add_u32 v0, s8, 8, v144
	v_ashrrev_i32_e32 v1, 31, v0
	v_lshl_add_u64 v[2:3], v[0:1], 2, s[0:1]
	v_add_u32_e32 v4, 0x80, v0
	v_add_u32_e32 v6, 0x90, v0
	v_add_u32_e32 v8, 0xa0, v0
	v_add_u32_e32 v0, 0xb0, v0
	v_ashrrev_i32_e32 v5, 31, v4
	v_ashrrev_i32_e32 v7, 31, v6
	v_ashrrev_i32_e32 v9, 31, v8
	v_ashrrev_i32_e32 v1, 31, v0
	v_lshl_add_u64 v[4:5], v[4:5], 2, s[0:1]
	v_lshl_add_u64 v[6:7], v[6:7], 2, s[0:1]
	v_lshl_add_u64 v[8:9], v[8:9], 2, s[0:1]
	v_lshl_add_u64 v[0:1], v[0:1], 2, s[0:1]
	global_load_dword v158, v[2:3], off
	global_load_dword v157, v[2:3], off offset:64
	global_load_dword v156, v[2:3], off offset:128
	global_load_dword v155, v[2:3], off offset:192
	global_load_dword v154, v[4:5], off
	global_load_dword v153, v[6:7], off
	global_load_dword v152, v[8:9], off
	global_load_dword v147, v[0:1], off
	s_mov_b64 s[14:15], 0
	s_branch .LBB0_2542

; #define PG8_STAGE(bufoff, gbase, voff) do { _Pragma("unroll") for (int _i = 0; _i < 2; ++_i) \
;         __builtin_amdgcn_global_load_lds((const unsigned*)((const char*)(gbase) + (voff)[_i]), (LAS unsigned*)(lds + (bufoff) + ldsw + _i * 8192), 16, 0, 0); } while (0)
; #define PG8_WAIT_V(n) asm volatile("s_waitcnt vmcnt(" #n ")" ::: "memory")
; #define PG8_BAR __builtin_amdgcn_s_barrier()
;     __device__ __forceinline__ Pre pre(const Unit& u, int wr, int fr) const { return load_rs(ssq, u.pm, wr, fr); }
;     __device__ __forceinline__ Pre pre(const Unit& u, int wr, int fr) const { return load_rs(ssq, u.pm, wr, fr); }
;     __device__ __forceinline__ Pre pre(const Unit& u, int wr, int fr) const { return load_rs(ssq, u.pm, wr, fr); }
; template <class Epi>
; __device__ __forceinline__ void gemm_phase(LAS unsigned char* lds, const Gemm g, const StaticOrder& S, const Epi& E) {
;     ...
;     const char* cA = (const char*)g.A + (size_t)cur.pm * tstep; const char* cB = (const char*)g.Bt + (size_t)cur.pn * tstep;
;     typename Epi::Pre pre = E.pre(cur, wr, fr);
;     PG8_STAGE(PG8_SB(0, 0), cB, voffB); PG8_STAGE(PG8_SA(0, 0), cA, voffA); PG8_STAGE(PG8_SB(0, 1), cB + hstep, voffB); PG8_STAGE(PG8_SA(0, 1), cA + hstep, voffA);
;     if (wr == 1) PG8_BAR;
;     PG8_WAIT_V(4); PG8_BAR;
;     PG8_STAGE(PG8_SB(1, 0), cB + kstep, voffB); PG8_STAGE(PG8_SA(1, 0), cA + kstep, voffA); PG8_STAGE(PG8_SB(1, 1), cB + hstep + kstep, voffB);
;     PG8_WAIT_V(6); PG8_BAR;
.LBB0_2614:
	s_add_u32 s6, s50, 0x1d504000
	s_addc_u32 s7, s51, 0
	s_lshl_b32 s2, s2, 5
	s_mov_b64 s[8:9], 0x80
	s_and_b32 s5, s2, 0x60
	s_add_i32 m0, s36, 0x18000
	v_lshl_add_u64 v[6:7], v[6:7], 0, s[8:9]
	s_lshl_b32 s4, s0, 13
	s_lshl_b32 s10, s5, 7
	s_waitcnt vmcnt(2)
	s_barrier
	global_load_lds_dwordx4 v[6:7], off
	v_lshl_add_u64 v[4:5], v[4:5], 0, s[8:9]
	s_add_i32 m0, s36, 0x1a000
	s_add_i32 s41, s36, 0x8000
	s_add_i32 s42, s36, 0xa000
	global_load_lds_dwordx4 v[4:5], off
	v_lshl_add_u64 v[2:3], v[2:3], 0, s[8:9]
	s_mov_b32 m0, s41
	s_add_u32 s2, s20, 0x158080
	global_load_lds_dwordx4 v[2:3], off
	v_lshl_add_u64 v[0:1], v[0:1], 0, s[8:9]
	s_mov_b32 m0, s42
	s_addc_u32 s3, s21, 0
	global_load_lds_dwordx4 v[0:1], off
	s_add_i32 m0, s36, 0x1c000
	v_lshl_add_u64 v[0:1], s[2:3], 0, v[130:131]
	global_load_lds_dwordx4 v[0:1], off
	v_lshl_add_u64 v[0:1], s[2:3], 0, v[134:135]
	s_add_i32 m0, s36, 0x1e000
	v_lshlrev_b32_e32 v2, 1, v10
	global_load_lds_dwordx4 v[0:1], off
	v_and_b32_e32 v0, 15, v178
	v_lshl_or_b32 v1, s0, 6, v0
	v_lshlrev_b32_e32 v3, 2, v178
	v_lshlrev_b32_e32 v4, 6, v178
	s_movk_i32 s0, 0x3c0
	v_lshl_or_b32 v0, v0, 6, v2
	v_and_b32_e32 v3, 32, v3
	v_and_or_b32 v2, v4, s0, v2
	s_waitcnt vmcnt(6)
	s_waitcnt vmcnt(0)
	v_add_u32_e32 v151, 0x100, v1
	v_add_u16_e32 v1, v8, v9
	v_bitop3_b32 v0, v0, s4, v3 bitop3:0xde
	v_bitop3_b32 v150, s10, v2, v3 bitop3:0xf6
	v_lshrrev_b16_e32 v1, 1, v1
	s_add_i32 s45, 0, 0x10000
	s_add_i32 s46, 0, 0x14000
	s_sext_i32_i8 s61, s1
	s_ashr_i32 s43, s54, 31
	s_mov_b32 s44, s54
	v_or_b32_e32 v152, s5, v10
	v_add_lshl_u32 v136, v11, v1, 1
	v_mov_b32_e32 v137, v131
	v_add_lshl_u32 v138, v12, v1, 1
	v_mov_b32_e32 v139, v131
	v_mov_b64_e32 v[140:141], 0x200
	v_mov_b64_e32 v[142:143], 0x1ff
	v_add_u32_e32 v153, s45, v150
	v_add_u32_e32 v154, 0, v0
	v_add_u32_e32 v155, s46, v150
	s_mov_b64 s[10:11], 0x80000
	s_mov_b32 s47, 0x80000
	s_mov_b64 s[12:13], 0x90000
	s_mov_b32 s52, 0x90000
	s_mov_b64 s[14:15], 0xa0000
	s_mov_b32 s56, 0xa0000
	s_mov_b64 s[16:17], 0xb0000
	s_mov_b32 s57, 0xb0000
	s_barrier

; #define PG8_STAGE(bufoff, gbase, voff) do { _Pragma("unroll") for (int _i = 0; _i < 2; ++_i) \
;         __builtin_amdgcn_global_load_lds((const unsigned*)((const char*)(gbase) + (voff)[_i]), (LAS unsigned*)(lds + (bufoff) + ldsw + _i * 8192), 16, 0, 0); } while (0)
; #define PG8_LDA(dst, b, h) do { _Pragma("unroll") for (int m = 0; m < 4; ++m) _Pragma("unroll") for (int k = 0; k < 2; ++k) dst[m][k] = *(const LAS bf16x8*)(lds + PG8_SA(b, h) + aoff + m * 2048 + k * 1024); } while (0)
; #define PG8_LDB(dst, b, h) do { _Pragma("unroll") for (int n = 0; n < 2; ++n) _Pragma("unroll") for (int k = 0; k < 2; ++k) dst[n][k] = *(const LAS bf16x8*)(lds + PG8_SB(b, h) + boff + n * 2048 + k * 1024); } while (0)
; #define PG8_MMA(ai, bj, At, Bt) do { __builtin_amdgcn_s_setprio(1); _Pragma("unroll") for (int m = 0; m < 4; ++m) _Pragma("unroll") for (int n = 0; n < 2; ++n) _Pragma("unroll") for (int k = 0; k < 2; ++k) \
;         acc[ai][bj][m][n] = __builtin_amdgcn_mfma_f32_16x16x32_bf16(Bt[n][k], At[m][k], acc[ai][bj][m][n], 0, 0, 0); __builtin_amdgcn_s_setprio(0); } while (0)
; #define PG8_WAIT_V(n) asm volatile("s_waitcnt vmcnt(" #n ")" ::: "memory")
; #define PG8_WAIT_L(n) asm volatile("s_waitcnt lgkmcnt(" #n ")" ::: "memory")
; template <class Epi>
; __device__ __forceinline__ void gemm_phase(LAS unsigned char* lds, const Gemm g, const StaticOrder& S, const Epi& E) {
;     ...
;         for (int t = 0; t < nt; t += 2) {
;             const bool last = (t == nt - 2);
;             const char* a1 = cA + (size_t)(t + 1) * kstep;
;             const char* a2 = last ? nA : cA + (size_t)(t + 2) * kstep; const char* b2 = last ? nB : cB + (size_t)(t + 2) * kstep;
;             const char* a3 = a2 + kstep; const char* b3 = b2 + kstep;
;             PG8_LDB(B0, 0, 0); PG8_SCHED; PG8_LDA(At, 0, 0); PG8_STAGE(PG8_SA(1, 1), a1 + hstep, voffA);
;             PG8_WAIT_L(8); PG8_BAR; PG8_WAIT_L(0); PG8_MMA(0, 0, At, B0); PG8_BAR; PG8_SCHED;
;             PG8_LDB(B1, 0, 1); PG8_STAGE(PG8_SB(0, 0), b2, voffB);
;             PG8_BAR; PG8_WAIT_L(0); PG8_MMA(0, 1, At, B1); PG8_BAR;
;             PG8_LDA(At, 0, 1); PG8_STAGE(PG8_SA(0, 0), a2, voffA);
;             PG8_BAR; PG8_WAIT_L(0); PG8_MMA(1, 0, At, B0); PG8_BAR; PG8_SCHED;
;             PG8_STAGE(PG8_SB(0, 1), b2 + hstep, voffB);
;             PG8_WAIT_V(6); PG8_BAR; PG8_MMA(1, 1, At, B1); PG8_BAR;
.LBB0_2626:
	ds_read_b128 v[144:147], v153
	ds_read_b128 v[156:159], v153 offset:1024
	ds_read_b128 v[160:163], v153 offset:2048
	ds_read_b128 v[164:167], v153 offset:3072
	s_add_u32 s20, s18, 0xffea8080
	s_addc_u32 s21, s19, -1
	s_cmpk_eq_i32 s64, 0x52
	s_cselect_b32 s23, s1, s21
	s_cselect_b32 s22, s0, s20
	s_cselect_b32 s21, s5, s63
	s_cselect_b32 s20, s4, s62
	v_lshl_add_u64 v[148:149], s[18:19], 0, v[136:137]
	s_add_i32 m0, s36, 0xc000
	ds_read_b128 v[168:171], v154
	ds_read_b128 v[172:175], v154 offset:1024
	ds_read_b128 v[176:179], v154 offset:2048
	ds_read_b128 v[180:183], v154 offset:3072
	ds_read_b128 v[184:187], v154 offset:4096
	ds_read_b128 v[188:191], v154 offset:5120
	ds_read_b128 v[192:195], v154 offset:6144
	ds_read_b128 v[196:199], v154 offset:7168
	global_load_lds_dwordx4 v[148:149], off
	v_lshl_add_u64 v[148:149], s[18:19], 0, v[138:139]
	s_add_i32 m0, s36, 0xe000
	s_nop 0
	global_load_lds_dwordx4 v[148:149], off
	ds_read_b128 v[200:203], v155
	ds_read_b128 v[204:207], v155 offset:1024
	ds_read_b128 v[208:211], v155 offset:2048
	ds_read_b128 v[212:215], v155 offset:3072
	s_waitcnt lgkmcnt(0)
	s_waitcnt vmcnt(8)
	s_setprio 1
	s_barrier
	v_mfma_f32_16x16x32_bf16 v[124:127], v[144:147], v[168:171], v[124:127]
	v_mfma_f32_16x16x32_bf16 v[120:123], v[160:163], v[168:171], v[120:123]
	v_mfma_f32_16x16x32_bf16 v[112:115], v[144:147], v[176:179], v[112:115]
	v_mfma_f32_16x16x32_bf16 v[104:107], v[160:163], v[176:179], v[104:107]
	v_mfma_f32_16x16x32_bf16 v[92:95], v[144:147], v[184:187], v[92:95]
	v_mfma_f32_16x16x32_bf16 v[88:91], v[160:163], v[184:187], v[88:91]
	v_mfma_f32_16x16x32_bf16 v[80:83], v[144:147], v[192:195], v[80:83]
	v_mfma_f32_16x16x32_bf16 v[72:75], v[160:163], v[192:195], v[72:75]
	v_mfma_f32_16x16x32_bf16 v[124:127], v[156:159], v[172:175], v[124:127]
	v_mfma_f32_16x16x32_bf16 v[120:123], v[164:167], v[172:175], v[120:123]
	v_mfma_f32_16x16x32_bf16 v[112:115], v[156:159], v[180:183], v[112:115]
	v_mfma_f32_16x16x32_bf16 v[104:107], v[164:167], v[180:183], v[104:107]
	v_mfma_f32_16x16x32_bf16 v[92:95], v[156:159], v[188:191], v[92:95]
	v_mfma_f32_16x16x32_bf16 v[88:91], v[164:167], v[188:191], v[88:91]
	v_mfma_f32_16x16x32_bf16 v[80:83], v[156:159], v[196:199], v[80:83]
	v_mfma_f32_16x16x32_bf16 v[72:75], v[164:167], v[196:199], v[72:75]
	v_mfma_f32_16x16x32_bf16 v[116:119], v[200:203], v[168:171], v[116:119]
	v_mfma_f32_16x16x32_bf16 v[108:111], v[208:211], v[168:171], v[108:111]
	v_mfma_f32_16x16x32_bf16 v[100:103], v[200:203], v[176:179], v[100:103]
	v_mfma_f32_16x16x32_bf16 v[96:99], v[208:211], v[176:179], v[96:99]
	v_mfma_f32_16x16x32_bf16 v[84:87], v[200:203], v[184:187], v[84:87]
	v_mfma_f32_16x16x32_bf16 v[76:79], v[208:211], v[184:187], v[76:79]
	v_mfma_f32_16x16x32_bf16 v[68:71], v[200:203], v[192:195], v[68:71]
	v_mfma_f32_16x16x32_bf16 v[64:67], v[208:211], v[192:195], v[64:67]
	v_mfma_f32_16x16x32_bf16 v[116:119], v[204:207], v[172:175], v[116:119]
	v_mfma_f32_16x16x32_bf16 v[108:111], v[212:215], v[172:175], v[108:111]
	v_mfma_f32_16x16x32_bf16 v[100:103], v[204:207], v[180:183], v[100:103]
	v_mfma_f32_16x16x32_bf16 v[96:99], v[212:215], v[180:183], v[96:99]
	v_mfma_f32_16x16x32_bf16 v[84:87], v[204:207], v[188:191], v[84:87]
	v_mfma_f32_16x16x32_bf16 v[76:79], v[212:215], v[188:191], v[76:79]
	v_mfma_f32_16x16x32_bf16 v[68:71], v[204:207], v[196:199], v[68:71]
	v_mfma_f32_16x16x32_bf16 v[64:67], v[212:215], v[196:199], v[64:67]
	s_barrier
	s_setprio 0
	s_add_i32 s65, s45, s35
	v_lshl_add_u64 v[148:149], s[20:21], 0, v[130:131]
	s_mov_b32 m0, s65
	s_nop 0
	global_load_lds_dwordx4 v[148:149], off
	v_lshl_add_u64 v[216:217], s[20:21], 0, v[134:135]
	s_add_i32 m0, s65, 0x2000
	s_nop 0
	global_load_lds_dwordx4 v[216:217], off
	s_mov_b32 m0, s36
	v_lshl_add_u64 v[218:219], s[22:23], 0, v[128:129]
	ds_read_b128 v[168:171], v154 offset:16384
	ds_read_b128 v[172:175], v154 offset:17408
	ds_read_b128 v[176:179], v154 offset:18432
	ds_read_b128 v[180:183], v154 offset:19456
	ds_read_b128 v[184:187], v154 offset:20480
	ds_read_b128 v[188:191], v154 offset:21504
	ds_read_b128 v[192:195], v154 offset:22528
	ds_read_b128 v[196:199], v154 offset:23552
	global_load_lds_dwordx4 v[218:219], off
	v_lshl_add_u64 v[220:221], s[22:23], 0, v[132:133]
	s_mov_b32 m0, s37
	s_nop 0
	global_load_lds_dwordx4 v[220:221], off
	s_add_u32 s66, s20, 0x158000
	s_addc_u32 s67, s21, 0
	s_add_i32 s65, s46, s35
	v_lshl_add_u64 v[252:253], s[66:67], 0, v[130:131]
	s_mov_b32 m0, s65
	s_nop 0
	global_load_lds_dwordx4 v[252:253], off
	v_lshl_add_u64 v[252:253], s[66:67], 0, v[134:135]
	s_add_i32 m0, s65, 0x2000
	s_nop 0
	global_load_lds_dwordx4 v[252:253], off
	s_waitcnt lgkmcnt(0)
	s_waitcnt vmcnt(8)
	s_setprio 1
	s_barrier
; #define PG8_STAGE(bufoff, gbase, voff) do { _Pragma("unroll") for (int _i = 0; _i < 2; ++_i) \
;         __builtin_amdgcn_global_load_lds((const unsigned*)((const char*)(gbase) + (voff)[_i]), (LAS unsigned*)(lds + (bufoff) + ldsw + _i * 8192), 16, 0, 0); } while (0)
; #define PG8_LDA(dst, b, h) do { _Pragma("unroll") for (int m = 0; m < 4; ++m) _Pragma("unroll") for (int k = 0; k < 2; ++k) dst[m][k] = *(const LAS bf16x8*)(lds + PG8_SA(b, h) + aoff + m * 2048 + k * 1024); } while (0)
; #define PG8_LDB(dst, b, h) do { _Pragma("unroll") for (int n = 0; n < 2; ++n) _Pragma("unroll") for (int k = 0; k < 2; ++k) dst[n][k] = *(const LAS bf16x8*)(lds + PG8_SB(b, h) + boff + n * 2048 + k * 1024); } while (0)
; #define PG8_MMA(ai, bj, At, Bt) do { __builtin_amdgcn_s_setprio(1); _Pragma("unroll") for (int m = 0; m < 4; ++m) _Pragma("unroll") for (int n = 0; n < 2; ++n) _Pragma("unroll") for (int k = 0; k < 2; ++k) \
;         acc[ai][bj][m][n] = __builtin_amdgcn_mfma_f32_16x16x32_bf16(Bt[n][k], At[m][k], acc[ai][bj][m][n], 0, 0, 0); __builtin_amdgcn_s_setprio(0); } while (0)
; #define PG8_WAIT_V(n) asm volatile("s_waitcnt vmcnt(" #n ")" ::: "memory")
; #define PG8_WAIT_L(n) asm volatile("s_waitcnt lgkmcnt(" #n ")" ::: "memory")
; #define PG8_BAR __builtin_amdgcn_s_barrier()
; #define PG8_SCHED __builtin_amdgcn_sched_barrier(0)
; template <class Epi>
; __device__ __forceinline__ void gemm_phase(LAS unsigned char* lds, const Gemm g, const StaticOrder& S, const Epi& E) {
;     ...
;             PG8_BAR; PG8_WAIT_L(0); PG8_MMA(0, 1, At, B1); PG8_BAR;
;             PG8_LDA(At, 0, 1); PG8_STAGE(PG8_SA(0, 0), a2, voffA);
;             PG8_BAR; PG8_WAIT_L(0); PG8_MMA(1, 0, At, B0); PG8_BAR; PG8_SCHED;
;             PG8_STAGE(PG8_SB(0, 1), b2 + hstep, voffB);
;             PG8_WAIT_V(6); PG8_BAR; PG8_MMA(1, 1, At, B1); PG8_BAR;
;             PG8_LDB(B0, 1, 0); PG8_SCHED; PG8_LDA(At, 1, 0); PG8_STAGE(PG8_SA(0, 1), a2 + hstep, voffA);
;             PG8_WAIT_L(8); PG8_BAR; PG8_WAIT_L(0); PG8_MMA(0, 0, At, B0); PG8_BAR; PG8_SCHED;
;             PG8_LDB(B1, 1, 1); PG8_STAGE(PG8_SB(1, 0), b3, voffB);
;             PG8_BAR; PG8_WAIT_L(0); PG8_MMA(0, 1, At, B1); PG8_BAR;
;             PG8_LDA(At, 1, 1); PG8_STAGE(PG8_SA(1, 0), a3, voffA);
;             PG8_BAR; PG8_WAIT_L(0); PG8_MMA(1, 0, At, B0); PG8_BAR; PG8_SCHED;
	v_mfma_f32_16x16x32_bf16 v[60:63], v[144:147], v[168:171], v[60:63]
	v_mfma_f32_16x16x32_bf16 v[56:59], v[160:163], v[168:171], v[56:59]
	v_mfma_f32_16x16x32_bf16 v[48:51], v[144:147], v[176:179], v[48:51]
	v_mfma_f32_16x16x32_bf16 v[40:43], v[160:163], v[176:179], v[40:43]
	v_mfma_f32_16x16x32_bf16 v[28:31], v[144:147], v[184:187], v[28:31]
	v_mfma_f32_16x16x32_bf16 v[24:27], v[160:163], v[184:187], v[24:27]
	v_mfma_f32_16x16x32_bf16 v[20:23], v[144:147], v[192:195], v[20:23]
	v_mfma_f32_16x16x32_bf16 v[12:15], v[160:163], v[192:195], v[12:15]
	v_mfma_f32_16x16x32_bf16 v[60:63], v[156:159], v[172:175], v[60:63]
	v_mfma_f32_16x16x32_bf16 v[56:59], v[164:167], v[172:175], v[56:59]
	v_mfma_f32_16x16x32_bf16 v[48:51], v[156:159], v[180:183], v[48:51]
	v_mfma_f32_16x16x32_bf16 v[40:43], v[164:167], v[180:183], v[40:43]
	v_mfma_f32_16x16x32_bf16 v[28:31], v[156:159], v[188:191], v[28:31]
	v_mfma_f32_16x16x32_bf16 v[24:27], v[164:167], v[188:191], v[24:27]
	v_mfma_f32_16x16x32_bf16 v[20:23], v[156:159], v[196:199], v[20:23]
	v_mfma_f32_16x16x32_bf16 v[12:15], v[164:167], v[196:199], v[12:15]
	v_mfma_f32_16x16x32_bf16 v[52:55], v[200:203], v[168:171], v[52:55]
	v_mfma_f32_16x16x32_bf16 v[44:47], v[208:211], v[168:171], v[44:47]
	v_mfma_f32_16x16x32_bf16 v[36:39], v[200:203], v[176:179], v[36:39]
	v_mfma_f32_16x16x32_bf16 v[32:35], v[208:211], v[176:179], v[32:35]
	v_mfma_f32_16x16x32_bf16 v[16:19], v[200:203], v[184:187], v[16:19]
	v_mfma_f32_16x16x32_bf16 v[8:11], v[208:211], v[184:187], v[8:11]
	v_mfma_f32_16x16x32_bf16 v[4:7], v[200:203], v[192:195], v[4:7]
	v_mfma_f32_16x16x32_bf16 v[0:3], v[208:211], v[192:195], v[0:3]
	v_mfma_f32_16x16x32_bf16 v[52:55], v[204:207], v[172:175], v[52:55]
	v_mfma_f32_16x16x32_bf16 v[44:47], v[212:215], v[172:175], v[44:47]
	v_mfma_f32_16x16x32_bf16 v[36:39], v[204:207], v[180:183], v[36:39]
	v_mfma_f32_16x16x32_bf16 v[32:35], v[212:215], v[180:183], v[32:35]
	v_mfma_f32_16x16x32_bf16 v[16:19], v[204:207], v[188:191], v[16:19]
	v_mfma_f32_16x16x32_bf16 v[8:11], v[212:215], v[188:191], v[8:11]
	v_mfma_f32_16x16x32_bf16 v[4:7], v[204:207], v[196:199], v[4:7]
	v_mfma_f32_16x16x32_bf16 v[0:3], v[212:215], v[196:199], v[0:3]
	s_barrier
	s_setprio 0
	s_add_i32 s65, 0, 0x18000
	v_add_u32_e32 v164, s65, v150
	ds_read_b128 v[144:147], v164
	ds_read_b128 v[156:159], v164 offset:1024
	ds_read_b128 v[160:163], v164 offset:2048
	ds_read_b128 v[164:167], v164 offset:3072
	s_add_u32 s22, s22, 0x158000
	s_addc_u32 s23, s23, 0
	s_mov_b32 m0, s38
	v_lshl_add_u64 v[200:201], s[22:23], 0, v[128:129]
	ds_read_b128 v[168:171], v154 offset:32768
	ds_read_b128 v[172:175], v154 offset:33792
	ds_read_b128 v[176:179], v154 offset:34816
	ds_read_b128 v[180:183], v154 offset:35840
	ds_read_b128 v[184:187], v154 offset:36864
	ds_read_b128 v[188:191], v154 offset:37888
	ds_read_b128 v[192:195], v154 offset:38912
	ds_read_b128 v[196:199], v154 offset:39936
	global_load_lds_dwordx4 v[200:201], off
	v_lshl_add_u64 v[200:201], s[22:23], 0, v[132:133]
	s_mov_b32 m0, s39
	s_nop 0
	global_load_lds_dwordx4 v[200:201], off
	s_add_i32 s22, 0, 0x1c000
	v_add_u32_e32 v212, s22, v150
	ds_read_b128 v[200:203], v212
	ds_read_b128 v[204:207], v212 offset:1024
	ds_read_b128 v[208:211], v212 offset:2048
	ds_read_b128 v[212:215], v212 offset:3072
	s_waitcnt lgkmcnt(0)
	s_waitcnt vmcnt(8)
	s_setprio 1
	s_barrier
	v_mfma_f32_16x16x32_bf16 v[124:127], v[144:147], v[168:171], v[124:127]
	v_mfma_f32_16x16x32_bf16 v[120:123], v[160:163], v[168:171], v[120:123]
	v_mfma_f32_16x16x32_bf16 v[112:115], v[144:147], v[176:179], v[112:115]
	v_mfma_f32_16x16x32_bf16 v[104:107], v[160:163], v[176:179], v[104:107]
	v_mfma_f32_16x16x32_bf16 v[92:95], v[144:147], v[184:187], v[92:95]
	v_mfma_f32_16x16x32_bf16 v[88:91], v[160:163], v[184:187], v[88:91]
	v_mfma_f32_16x16x32_bf16 v[80:83], v[144:147], v[192:195], v[80:83]
	v_mfma_f32_16x16x32_bf16 v[72:75], v[160:163], v[192:195], v[72:75]
	v_mfma_f32_16x16x32_bf16 v[124:127], v[156:159], v[172:175], v[124:127]
	v_mfma_f32_16x16x32_bf16 v[120:123], v[164:167], v[172:175], v[120:123]
	v_mfma_f32_16x16x32_bf16 v[112:115], v[156:159], v[180:183], v[112:115]
	v_mfma_f32_16x16x32_bf16 v[104:107], v[164:167], v[180:183], v[104:107]
	v_mfma_f32_16x16x32_bf16 v[92:95], v[156:159], v[188:191], v[92:95]
	v_mfma_f32_16x16x32_bf16 v[88:91], v[164:167], v[188:191], v[88:91]
	v_mfma_f32_16x16x32_bf16 v[80:83], v[156:159], v[196:199], v[80:83]
	v_mfma_f32_16x16x32_bf16 v[72:75], v[164:167], v[196:199], v[72:75]
	v_mfma_f32_16x16x32_bf16 v[116:119], v[200:203], v[168:171], v[116:119]
	v_mfma_f32_16x16x32_bf16 v[108:111], v[208:211], v[168:171], v[108:111]
	v_mfma_f32_16x16x32_bf16 v[100:103], v[200:203], v[176:179], v[100:103]
	v_mfma_f32_16x16x32_bf16 v[96:99], v[208:211], v[176:179], v[96:99]
	v_mfma_f32_16x16x32_bf16 v[84:87], v[200:203], v[184:187], v[84:87]
	v_mfma_f32_16x16x32_bf16 v[76:79], v[208:211], v[184:187], v[76:79]
	v_mfma_f32_16x16x32_bf16 v[68:71], v[200:203], v[192:195], v[68:71]
	v_mfma_f32_16x16x32_bf16 v[64:67], v[208:211], v[192:195], v[64:67]
	v_mfma_f32_16x16x32_bf16 v[116:119], v[204:207], v[172:175], v[116:119]
	v_mfma_f32_16x16x32_bf16 v[108:111], v[212:215], v[172:175], v[108:111]
	v_mfma_f32_16x16x32_bf16 v[100:103], v[204:207], v[180:183], v[100:103]
	v_mfma_f32_16x16x32_bf16 v[96:99], v[212:215], v[180:183], v[96:99]
	v_mfma_f32_16x16x32_bf16 v[84:87], v[204:207], v[188:191], v[84:87]
	v_mfma_f32_16x16x32_bf16 v[76:79], v[212:215], v[188:191], v[76:79]
	v_mfma_f32_16x16x32_bf16 v[68:71], v[204:207], v[196:199], v[68:71]
	v_mfma_f32_16x16x32_bf16 v[64:67], v[212:215], v[196:199], v[64:67]
	s_barrier
; #define PG8_STAGE(bufoff, gbase, voff) do { _Pragma("unroll") for (int _i = 0; _i < 2; ++_i) \
;         __builtin_amdgcn_global_load_lds((const unsigned*)((const char*)(gbase) + (voff)[_i]), (LAS unsigned*)(lds + (bufoff) + ldsw + _i * 8192), 16, 0, 0); } while (0)
; #define PG8_LDA(dst, b, h) do { _Pragma("unroll") for (int m = 0; m < 4; ++m) _Pragma("unroll") for (int k = 0; k < 2; ++k) dst[m][k] = *(const LAS bf16x8*)(lds + PG8_SA(b, h) + aoff + m * 2048 + k * 1024); } while (0)
; #define PG8_LDB(dst, b, h) do { _Pragma("unroll") for (int n = 0; n < 2; ++n) _Pragma("unroll") for (int k = 0; k < 2; ++k) dst[n][k] = *(const LAS bf16x8*)(lds + PG8_SB(b, h) + boff + n * 2048 + k * 1024); } while (0)
; #define PG8_MMA(ai, bj, At, Bt) do { __builtin_amdgcn_s_setprio(1); _Pragma("unroll") for (int m = 0; m < 4; ++m) _Pragma("unroll") for (int n = 0; n < 2; ++n) _Pragma("unroll") for (int k = 0; k < 2; ++k) \
;         acc[ai][bj][m][n] = __builtin_amdgcn_mfma_f32_16x16x32_bf16(Bt[n][k], At[m][k], acc[ai][bj][m][n], 0, 0, 0); __builtin_amdgcn_s_setprio(0); } while (0)
; #define PG8_WAIT_V(n) asm volatile("s_waitcnt vmcnt(" #n ")" ::: "memory")
; #define PG8_WAIT_L(n) asm volatile("s_waitcnt lgkmcnt(" #n ")" ::: "memory")
; #define PG8_BAR __builtin_amdgcn_s_barrier()
; #define PG8_SCHED __builtin_amdgcn_sched_barrier(0)
; template <class Epi>
; __device__ __forceinline__ void gemm_phase(LAS unsigned char* lds, const Gemm g, const StaticOrder& S, const Epi& E) {
;     ...
;             PG8_LDB(B1, 1, 1); PG8_STAGE(PG8_SB(1, 0), b3, voffB);
;             PG8_BAR; PG8_WAIT_L(0); PG8_MMA(0, 1, At, B1); PG8_BAR;
;             PG8_LDA(At, 1, 1); PG8_STAGE(PG8_SA(1, 0), a3, voffA);
;             PG8_BAR; PG8_WAIT_L(0); PG8_MMA(1, 0, At, B0); PG8_BAR; PG8_SCHED;
;             PG8_STAGE(PG8_SB(1, 1), b3 + hstep, voffB);
;             PG8_WAIT_V(6); PG8_BAR; PG8_MMA(1, 1, At, B1); PG8_BAR;
;         }
;     __device__ __forceinline__ void operator()(const f32x4 (&acc)[2][2][4][2], const Unit& u, int wr, int wc, int fr, int fq, const Pre&) const {
;         const int row0 = ROW_X + u.pm * BM + wr * 64 + fr, col0 = u.pn * BM + wc * 32 + 8 * fq;
;         u32x4 hv[2][2]; float sprev = 0.f;
	s_setprio 0
	s_add_i32 s23, s65, s35
	v_lshl_add_u64 v[148:149], v[148:149], 0, s[8:9]
	s_mov_b32 m0, s23
	s_nop 0
	global_load_lds_dwordx4 v[148:149], off
	v_lshl_add_u64 v[148:149], v[216:217], 0, s[8:9]
	s_add_i32 m0, s23, 0x2000
	s_nop 0
	global_load_lds_dwordx4 v[148:149], off
	s_mov_b32 m0, s41
	v_lshl_add_u64 v[148:149], v[218:219], 0, s[8:9]
	ds_read_b128 v[168:171], v154 offset:49152
	ds_read_b128 v[172:175], v154 offset:50176
	ds_read_b128 v[176:179], v154 offset:51200
	ds_read_b128 v[180:183], v154 offset:52224
	ds_read_b128 v[184:187], v154 offset:53248
	ds_read_b128 v[188:191], v154 offset:54272
	ds_read_b128 v[192:195], v154 offset:55296
	ds_read_b128 v[196:199], v154 offset:56320
	global_load_lds_dwordx4 v[148:149], off
	v_lshl_add_u64 v[148:149], v[220:221], 0, s[8:9]
	s_mov_b32 m0, s42
	s_nop 0
	global_load_lds_dwordx4 v[148:149], off
	s_add_u32 s20, s20, 0x158080
	s_addc_u32 s21, s21, 0
	s_add_i32 s22, s22, s35
	v_lshl_add_u64 v[252:253], s[20:21], 0, v[130:131]
	s_mov_b32 m0, s22
	s_nop 0
	global_load_lds_dwordx4 v[252:253], off
	v_lshl_add_u64 v[252:253], s[20:21], 0, v[134:135]
	s_add_i32 m0, s22, 0x2000
	s_nop 0
	global_load_lds_dwordx4 v[252:253], off
	s_waitcnt lgkmcnt(0)
	s_waitcnt vmcnt(8)
	s_setprio 1
	s_barrier
	v_mfma_f32_16x16x32_bf16 v[60:63], v[144:147], v[168:171], v[60:63]
	v_mfma_f32_16x16x32_bf16 v[56:59], v[160:163], v[168:171], v[56:59]
	v_mfma_f32_16x16x32_bf16 v[48:51], v[144:147], v[176:179], v[48:51]
	v_mfma_f32_16x16x32_bf16 v[40:43], v[160:163], v[176:179], v[40:43]
	v_mfma_f32_16x16x32_bf16 v[28:31], v[144:147], v[184:187], v[28:31]
	v_mfma_f32_16x16x32_bf16 v[24:27], v[160:163], v[184:187], v[24:27]
	v_mfma_f32_16x16x32_bf16 v[20:23], v[144:147], v[192:195], v[20:23]
	v_mfma_f32_16x16x32_bf16 v[12:15], v[160:163], v[192:195], v[12:15]
	v_mfma_f32_16x16x32_bf16 v[60:63], v[156:159], v[172:175], v[60:63]
	v_mfma_f32_16x16x32_bf16 v[56:59], v[164:167], v[172:175], v[56:59]
	v_mfma_f32_16x16x32_bf16 v[48:51], v[156:159], v[180:183], v[48:51]
	v_mfma_f32_16x16x32_bf16 v[40:43], v[164:167], v[180:183], v[40:43]
	v_mfma_f32_16x16x32_bf16 v[28:31], v[156:159], v[188:191], v[28:31]
	v_mfma_f32_16x16x32_bf16 v[24:27], v[164:167], v[188:191], v[24:27]
	v_mfma_f32_16x16x32_bf16 v[20:23], v[156:159], v[196:199], v[20:23]
	v_mfma_f32_16x16x32_bf16 v[12:15], v[164:167], v[196:199], v[12:15]
	v_mfma_f32_16x16x32_bf16 v[52:55], v[200:203], v[168:171], v[52:55]
	v_mfma_f32_16x16x32_bf16 v[44:47], v[208:211], v[168:171], v[44:47]
	v_mfma_f32_16x16x32_bf16 v[36:39], v[200:203], v[176:179], v[36:39]
	v_mfma_f32_16x16x32_bf16 v[32:35], v[208:211], v[176:179], v[32:35]
	v_mfma_f32_16x16x32_bf16 v[16:19], v[200:203], v[184:187], v[16:19]
	v_mfma_f32_16x16x32_bf16 v[8:11], v[208:211], v[184:187], v[8:11]
	v_mfma_f32_16x16x32_bf16 v[4:7], v[200:203], v[192:195], v[4:7]
	v_mfma_f32_16x16x32_bf16 v[0:3], v[208:211], v[192:195], v[0:3]
	v_mfma_f32_16x16x32_bf16 v[52:55], v[204:207], v[172:175], v[52:55]
	v_mfma_f32_16x16x32_bf16 v[44:47], v[212:215], v[172:175], v[44:47]
	v_mfma_f32_16x16x32_bf16 v[36:39], v[204:207], v[180:183], v[36:39]
	v_mfma_f32_16x16x32_bf16 v[32:35], v[212:215], v[180:183], v[32:35]
	v_mfma_f32_16x16x32_bf16 v[16:19], v[204:207], v[188:191], v[16:19]
	v_mfma_f32_16x16x32_bf16 v[8:11], v[212:215], v[188:191], v[8:11]
	v_mfma_f32_16x16x32_bf16 v[4:7], v[204:207], v[196:199], v[4:7]
	v_mfma_f32_16x16x32_bf16 v[0:3], v[212:215], v[196:199], v[0:3]
	s_barrier
	s_setprio 0
	s_add_i32 s64, s64, 2
	s_add_u32 s18, s18, 0x100
	s_addc_u32 s19, s19, 0
	s_add_u32 s62, s62, 0x100
	s_addc_u32 s63, s63, 0
	s_cmpk_gt_u32 s64, 0x53
	s_cbranch_scc0 .LBB0_2626
	v_lshl_add_u32 v144, s60, 8, v151
	v_lshl_or_b32 v148, s61, 8, v152
	v_ashrrev_i32_e32 v145, 31, v144
	v_ashrrev_i32_e32 v149, 31, v148
	v_lshlrev_b64 v[146:147], 12, v[144:145]
	v_or_b32_e32 v164, 16, v144
	v_lshl_add_u64 v[146:147], s[6:7], 0, v[146:147]
	v_lshlrev_b64 v[172:173], 1, v[148:149]
	v_ashrrev_i32_e32 v165, 31, v164
	v_lshl_add_u64 v[146:147], v[146:147], 0, v[172:173]
	v_lshlrev_b64 v[164:165], 12, v[164:165]
	global_load_dwordx4 v[156:159], v[146:147], off
	global_load_dwordx4 v[160:163], v[146:147], off offset:256
	v_lshl_add_u64 v[164:165], s[6:7], 0, v[164:165]
	v_lshl_add_u64 v[168:169], v[164:165], 0, v[172:173]
	global_load_dwordx4 v[164:167], v[168:169], off
	s_nop 0
	global_load_dwordx4 v[168:171], v[168:169], off offset:256
	v_or_b32_e32 v176, 32, v144
	v_or_b32_e32 v180, 48, v144
	v_add_u32_e32 v174, 0xffffff00, v144
	v_ashrrev_i32_e32 v177, 31, v176
	v_ashrrev_i32_e32 v181, 31, v180
	v_ashrrev_i32_e32 v175, 31, v174
	v_lshlrev_b64 v[176:177], 12, v[176:177]
	v_lshlrev_b64 v[180:181], 12, v[180:181]
	v_add_u32_e32 v178, 0xffffff10, v144
	v_lshlrev_b64 v[174:175], 13, v[174:175]
	v_lshl_add_u64 v[176:177], s[6:7], 0, v[176:177]
	v_lshl_add_u64 v[180:181], s[6:7], 0, v[180:181]
	v_lshlrev_b64 v[148:149], 2, v[148:149]
	v_ashrrev_i32_e32 v179, 31, v178
	v_lshl_add_u64 v[174:175], s[48:49], 0, v[174:175]
	v_lshl_add_u64 v[176:177], v[176:177], 0, v[172:173]
	v_lshl_add_u64 v[172:173], v[180:181], 0, v[172:173]
	v_lshlrev_b64 v[178:179], 13, v[178:179]
	v_lshl_add_u64 v[174:175], v[174:175], 0, v[148:149]
	v_lshl_add_u64 v[178:179], s[48:49], 0, v[178:179]
	v_lshl_add_u64 v[178:179], v[178:179], 0, v[148:149]
	s_mov_b32 s60, s59
	s_mov_b32 s61, s58
	s_mov_b64 s[20:21], s[4:5]
	s_mov_b64 s[18:19], s[0:1]
	s_waitcnt vmcnt(0)
; __device__ __forceinline__ float bflo(unsigned w) { return __uint_as_float(w << 16); }
; __device__ __forceinline__ float bfhi(unsigned w) { return __uint_as_float(w & 0xffff0000u); }
; #define ER_LOAD(g_, set_) do { const size_t off_ = (size_t)(row0 + ((g_) >> 2) * HALF + ((g_) & 3) * 16) * DM + col0; \
;         hv[set_][0] = *(const u32x4*)(HB + off_); hv[set_][1] = *(const u32x4*)(HB + off_ + HALF); } while (0)
;     __device__ __forceinline__ void operator()(const f32x4 (&acc)[2][2][4][2], const Unit& u, int wr, int wc, int fr, int fq, const Pre&) const {
;         const int row0 = ROW_X + u.pm * BM + wr * 64 + fr, col0 = u.pn * BM + wc * 32 + 8 * fq;
;         u32x4 hv[2][2]; float sprev = 0.f;
;     ...
;         ER_LOAD(0, 0);
; #pragma unroll
;         for (int g = 0; g < 8; ++g) { const int ai = g >> 2, m = g & 3; const int r = row0 + ai * HALF + m * 16; const size_t off = (size_t)r * DM + col0; float s = 0.f;
;             if (g + 1 < 8) ER_LOAD(g + 1, (g + 1) & 1);
; #pragma unroll
;             for (int bj = 0; bj < 2; ++bj) { const u32x4 w = hv[g & 1][bj];
;                 const f32x4 h0 = {bflo(w.x), bfhi(w.x), bflo(w.y), bfhi(w.y)}, h1 = {bflo(w.z), bfhi(w.z), bflo(w.w), bfhi(w.w)};
;                 const f32x4 o0 = h0 + acc[ai][bj][m][0] * alpha, o1 = h1 + acc[ai][bj][m][1] * alpha;
;                 if (FINAL) { float* op = OUT + (size_t)(r - ROW_X) * DM + col0 + bj * HALF; *(f32x4*)op = o0; *(f32x4*)(op + 4) = o1; }
;                 else { u32x4 q; q.x = cvtpk(o0[0], o0[1]); q.y = cvtpk(o0[2], o0[3]); q.z = cvtpk(o1[0], o1[1]); q.w = cvtpk(o1[2], o1[3]); *(u32x4*)(HB + off + bj * HALF) = q;
;                        s += ((o0[0] * o0[0] + o0[1] * o0[1]) + (o0[2] * o0[2] + o0[3] * o0[3])) + ((o1[0] * o1[0] + o1[1] * o1[1]) + (o1[2] * o1[2] + o1[3] * o1[3])); } }
	v_lshlrev_b32_e32 v180, 16, v156
	v_and_b32_e32 v181, 0xffff0000, v156
	v_lshlrev_b32_e32 v156, 16, v157
	v_and_b32_e32 v157, 0xffff0000, v157
	v_lshlrev_b32_e32 v182, 16, v158
	v_and_b32_e32 v183, 0xffff0000, v158
	v_lshlrev_b32_e32 v158, 16, v159
	v_and_b32_e32 v159, 0xffff0000, v159
	v_lshlrev_b32_e32 v184, 16, v160
	v_and_b32_e32 v185, 0xffff0000, v160
	v_lshlrev_b32_e32 v160, 16, v161
	v_and_b32_e32 v161, 0xffff0000, v161
	v_lshlrev_b32_e32 v186, 16, v162
	v_and_b32_e32 v187, 0xffff0000, v162
	v_lshlrev_b32_e32 v162, 16, v163
	v_and_b32_e32 v163, 0xffff0000, v163
	v_pk_fma_f32 v[126:127], v[126:127], 0.5, v[156:157] op_sel_hi:[1,0,1]
	v_pk_fma_f32 v[124:125], v[124:125], 0.5, v[180:181] op_sel_hi:[1,0,1]
	v_pk_fma_f32 v[122:123], v[122:123], 0.5, v[158:159] op_sel_hi:[1,0,1]
	v_pk_fma_f32 v[120:121], v[120:121], 0.5, v[182:183] op_sel_hi:[1,0,1]
	v_pk_fma_f32 v[118:119], v[118:119], 0.5, v[160:161] op_sel_hi:[1,0,1]
	v_pk_fma_f32 v[116:117], v[116:117], 0.5, v[184:185] op_sel_hi:[1,0,1]
	v_pk_fma_f32 v[110:111], v[110:111], 0.5, v[162:163] op_sel_hi:[1,0,1]
	v_pk_fma_f32 v[108:109], v[108:109], 0.5, v[186:187] op_sel_hi:[1,0,1]
	v_lshlrev_b32_e32 v156, 16, v164
	v_and_b32_e32 v157, 0xffff0000, v164
	v_lshlrev_b32_e32 v158, 16, v165
	v_and_b32_e32 v159, 0xffff0000, v165
	global_store_dwordx4 v[174:175], v[124:127], off
	global_store_dwordx4 v[174:175], v[120:123], off offset:16
	global_store_dwordx4 v[174:175], v[116:119], off offset:512
	global_store_dwordx4 v[174:175], v[108:111], off offset:528
	v_lshlrev_b32_e32 v160, 16, v166
	v_and_b32_e32 v161, 0xffff0000, v166
	global_load_dwordx4 v[108:111], v[176:177], off
	global_load_dwordx4 v[116:119], v[176:177], off offset:256
	v_lshlrev_b32_e32 v120, 16, v167
	v_and_b32_e32 v121, 0xffff0000, v167
	v_lshlrev_b32_e32 v122, 16, v168
	v_and_b32_e32 v123, 0xffff0000, v168
	v_lshlrev_b32_e32 v124, 16, v169
	v_and_b32_e32 v125, 0xffff0000, v169
	v_lshlrev_b32_e32 v126, 16, v170
	v_and_b32_e32 v127, 0xffff0000, v170
	v_lshlrev_b32_e32 v162, 16, v171
	v_and_b32_e32 v163, 0xffff0000, v171
	v_pk_fma_f32 v[114:115], v[114:115], 0.5, v[158:159] op_sel_hi:[1,0,1]
	v_pk_fma_f32 v[112:113], v[112:113], 0.5, v[156:157] op_sel_hi:[1,0,1]
	v_pk_fma_f32 v[106:107], v[106:107], 0.5, v[120:121] op_sel_hi:[1,0,1]
	v_pk_fma_f32 v[104:105], v[104:105], 0.5, v[160:161] op_sel_hi:[1,0,1]
	v_pk_fma_f32 v[102:103], v[102:103], 0.5, v[124:125] op_sel_hi:[1,0,1]
	v_pk_fma_f32 v[100:101], v[100:101], 0.5, v[122:123] op_sel_hi:[1,0,1]
	v_pk_fma_f32 v[98:99], v[98:99], 0.5, v[162:163] op_sel_hi:[1,0,1]
	v_pk_fma_f32 v[96:97], v[96:97], 0.5, v[126:127] op_sel_hi:[1,0,1]
	global_store_dwordx4 v[178:179], v[112:115], off
	global_store_dwordx4 v[178:179], v[104:107], off offset:16
	global_store_dwordx4 v[178:179], v[100:103], off offset:512
	global_store_dwordx4 v[178:179], v[96:99], off offset:528
	global_load_dwordx4 v[96:99], v[172:173], off
	s_nop 0
	global_load_dwordx4 v[100:103], v[172:173], off offset:256
	v_add_u32_e32 v104, 0xffffff20, v144
	v_add_u32_e32 v106, 0xffffff30, v144
	v_ashrrev_i32_e32 v105, 31, v104
	v_ashrrev_i32_e32 v107, 31, v106
	v_lshlrev_b64 v[104:105], 13, v[104:105]
	v_lshlrev_b64 v[106:107], 13, v[106:107]
	v_lshl_add_u64 v[104:105], s[48:49], 0, v[104:105]
	v_add_co_u32_e32 v114, vcc, s47, v146
	v_lshl_add_u64 v[106:107], s[48:49], 0, v[106:107]
	v_lshl_add_u64 v[104:105], v[104:105], 0, v[148:149]
	v_addc_co_u32_e32 v115, vcc, 0, v147, vcc
	v_lshl_add_u64 v[112:113], v[146:147], 0, s[10:11]
	v_lshl_add_u64 v[106:107], v[106:107], 0, v[148:149]
	v_add_co_u32_e32 v120, vcc, s52, v146
	s_waitcnt vmcnt(0)
	v_lshlrev_b32_e32 v122, 16, v108
	v_and_b32_e32 v123, 0xffff0000, v108
	v_lshlrev_b32_e32 v108, 16, v109
	v_and_b32_e32 v109, 0xffff0000, v109
	v_lshlrev_b32_e32 v124, 16, v110
	v_and_b32_e32 v125, 0xffff0000, v110
	v_lshlrev_b32_e32 v110, 16, v111
	v_and_b32_e32 v111, 0xffff0000, v111
	v_lshlrev_b32_e32 v126, 16, v116
	v_and_b32_e32 v127, 0xffff0000, v116
	v_lshlrev_b32_e32 v116, 16, v117
	v_and_b32_e32 v117, 0xffff0000, v117
	v_lshlrev_b32_e32 v156, 16, v118
	v_and_b32_e32 v157, 0xffff0000, v118
	v_lshlrev_b32_e32 v118, 16, v119
	v_and_b32_e32 v119, 0xffff0000, v119
	v_pk_fma_f32 v[94:95], v[94:95], 0.5, v[108:109] op_sel_hi:[1,0,1]
	v_pk_fma_f32 v[92:93], v[92:93], 0.5, v[122:123] op_sel_hi:[1,0,1]
	v_pk_fma_f32 v[90:91], v[90:91], 0.5, v[110:111] op_sel_hi:[1,0,1]
	v_pk_fma_f32 v[88:89], v[88:89], 0.5, v[124:125] op_sel_hi:[1,0,1]
	v_lshlrev_b32_e32 v108, 16, v96
	v_and_b32_e32 v109, 0xffff0000, v96
	v_lshlrev_b32_e32 v96, 16, v97
	v_and_b32_e32 v97, 0xffff0000, v97
	v_pk_fma_f32 v[86:87], v[86:87], 0.5, v[116:117] op_sel_hi:[1,0,1]
	v_pk_fma_f32 v[84:85], v[84:85], 0.5, v[126:127] op_sel_hi:[1,0,1]
	v_pk_fma_f32 v[78:79], v[78:79], 0.5, v[118:119] op_sel_hi:[1,0,1]
	v_pk_fma_f32 v[76:77], v[76:77], 0.5, v[156:157] op_sel_hi:[1,0,1]
	v_lshlrev_b32_e32 v110, 16, v98
	v_and_b32_e32 v111, 0xffff0000, v98
	global_store_dwordx4 v[104:105], v[92:95], off
	global_store_dwordx4 v[104:105], v[88:91], off offset:16
	global_store_dwordx4 v[104:105], v[84:87], off offset:512
	global_store_dwordx4 v[104:105], v[76:79], off offset:528
	v_lshlrev_b32_e32 v88, 16, v99
	v_and_b32_e32 v89, 0xffff0000, v99
	v_lshlrev_b32_e32 v90, 16, v100
	v_and_b32_e32 v91, 0xffff0000, v100
	v_lshlrev_b32_e32 v92, 16, v101
	v_and_b32_e32 v93, 0xffff0000, v101
	v_lshlrev_b32_e32 v94, 16, v102
	v_and_b32_e32 v95, 0xffff0000, v102
	v_lshlrev_b32_e32 v98, 16, v103
	v_and_b32_e32 v99, 0xffff0000, v103
	v_pk_fma_f32 v[82:83], v[82:83], 0.5, v[96:97] op_sel_hi:[1,0,1]
	v_pk_fma_f32 v[80:81], v[80:81], 0.5, v[108:109] op_sel_hi:[1,0,1]
; __device__ __forceinline__ float bflo(unsigned w) { return __uint_as_float(w << 16); }
; __device__ __forceinline__ float bfhi(unsigned w) { return __uint_as_float(w & 0xffff0000u); }
; #define ER_LOAD(g_, set_) do { const size_t off_ = (size_t)(row0 + ((g_) >> 2) * HALF + ((g_) & 3) * 16) * DM + col0; \
;         hv[set_][0] = *(const u32x4*)(HB + off_); hv[set_][1] = *(const u32x4*)(HB + off_ + HALF); } while (0)
;     __device__ __forceinline__ void operator()(const f32x4 (&acc)[2][2][4][2], const Unit& u, int wr, int wc, int fr, int fq, const Pre&) const {
;     ...
;         ER_LOAD(0, 0);
; #pragma unroll
;         for (int g = 0; g < 8; ++g) { const int ai = g >> 2, m = g & 3; const int r = row0 + ai * HALF + m * 16; const size_t off = (size_t)r * DM + col0; float s = 0.f;
;             if (g + 1 < 8) ER_LOAD(g + 1, (g + 1) & 1);
; #pragma unroll
;             for (int bj = 0; bj < 2; ++bj) { const u32x4 w = hv[g & 1][bj];
;                 const f32x4 h0 = {bflo(w.x), bfhi(w.x), bflo(w.y), bfhi(w.y)}, h1 = {bflo(w.z), bfhi(w.z), bflo(w.w), bfhi(w.w)};
;                 const f32x4 o0 = h0 + acc[ai][bj][m][0] * alpha, o1 = h1 + acc[ai][bj][m][1] * alpha;
;                 if (FINAL) { float* op = OUT + (size_t)(r - ROW_X) * DM + col0 + bj * HALF; *(f32x4*)op = o0; *(f32x4*)(op + 4) = o1; }
	v_addc_co_u32_e32 v121, vcc, 0, v147, vcc
	global_load_dwordx4 v[76:79], v[114:115], off
	global_load_dwordx4 v[84:87], v[112:113], off offset:256
	v_pk_fma_f32 v[74:75], v[74:75], 0.5, v[88:89] op_sel_hi:[1,0,1]
	v_pk_fma_f32 v[72:73], v[72:73], 0.5, v[110:111] op_sel_hi:[1,0,1]
	v_pk_fma_f32 v[70:71], v[70:71], 0.5, v[92:93] op_sel_hi:[1,0,1]
	v_pk_fma_f32 v[68:69], v[68:69], 0.5, v[90:91] op_sel_hi:[1,0,1]
	v_pk_fma_f32 v[66:67], v[66:67], 0.5, v[98:99] op_sel_hi:[1,0,1]
	v_pk_fma_f32 v[64:65], v[64:65], 0.5, v[94:95] op_sel_hi:[1,0,1]
	global_store_dwordx4 v[106:107], v[80:83], off
	global_store_dwordx4 v[106:107], v[72:75], off offset:16
	global_store_dwordx4 v[106:107], v[68:71], off offset:512
	global_store_dwordx4 v[106:107], v[64:67], off offset:528
	global_load_dwordx4 v[64:67], v[120:121], off
	v_lshl_add_u64 v[68:69], v[146:147], 0, s[12:13]
	global_load_dwordx4 v[68:71], v[68:69], off offset:256
	v_add_u32_e32 v72, 0xffffff80, v144
	v_add_u32_e32 v74, 0xffffff90, v144
	v_ashrrev_i32_e32 v73, 31, v72
	v_ashrrev_i32_e32 v75, 31, v74
	v_lshlrev_b64 v[72:73], 13, v[72:73]
	v_lshlrev_b64 v[74:75], 13, v[74:75]
	v_lshl_add_u64 v[72:73], s[48:49], 0, v[72:73]
	v_add_co_u32_e32 v82, vcc, s56, v146
	v_lshl_add_u64 v[74:75], s[48:49], 0, v[74:75]
	v_lshl_add_u64 v[72:73], v[72:73], 0, v[148:149]
	v_addc_co_u32_e32 v83, vcc, 0, v147, vcc
	v_lshl_add_u64 v[80:81], v[146:147], 0, s[14:15]
	v_lshl_add_u64 v[74:75], v[74:75], 0, v[148:149]
	v_add_co_u32_e32 v88, vcc, s57, v146
	s_waitcnt vmcnt(0)
	v_lshlrev_b32_e32 v90, 16, v76
	v_and_b32_e32 v91, 0xffff0000, v76
	v_lshlrev_b32_e32 v76, 16, v77
	v_and_b32_e32 v77, 0xffff0000, v77
	v_lshlrev_b32_e32 v92, 16, v78
	v_and_b32_e32 v93, 0xffff0000, v78
	v_lshlrev_b32_e32 v78, 16, v79
	v_and_b32_e32 v79, 0xffff0000, v79
	v_lshlrev_b32_e32 v94, 16, v84
	v_and_b32_e32 v95, 0xffff0000, v84
	v_lshlrev_b32_e32 v84, 16, v85
	v_and_b32_e32 v85, 0xffff0000, v85
	v_lshlrev_b32_e32 v96, 16, v86
	v_and_b32_e32 v97, 0xffff0000, v86
	v_lshlrev_b32_e32 v86, 16, v87
	v_and_b32_e32 v87, 0xffff0000, v87
	v_pk_fma_f32 v[62:63], v[62:63], 0.5, v[76:77] op_sel_hi:[1,0,1]
	v_pk_fma_f32 v[60:61], v[60:61], 0.5, v[90:91] op_sel_hi:[1,0,1]
	v_pk_fma_f32 v[58:59], v[58:59], 0.5, v[78:79] op_sel_hi:[1,0,1]
	v_pk_fma_f32 v[56:57], v[56:57], 0.5, v[92:93] op_sel_hi:[1,0,1]
	v_lshlrev_b32_e32 v76, 16, v64
	v_and_b32_e32 v77, 0xffff0000, v64
	v_lshlrev_b32_e32 v64, 16, v65
	v_and_b32_e32 v65, 0xffff0000, v65
	v_pk_fma_f32 v[54:55], v[54:55], 0.5, v[84:85] op_sel_hi:[1,0,1]
	v_pk_fma_f32 v[52:53], v[52:53], 0.5, v[94:95] op_sel_hi:[1,0,1]
	v_pk_fma_f32 v[46:47], v[46:47], 0.5, v[86:87] op_sel_hi:[1,0,1]
	v_pk_fma_f32 v[44:45], v[44:45], 0.5, v[96:97] op_sel_hi:[1,0,1]
	v_lshlrev_b32_e32 v78, 16, v66
	v_and_b32_e32 v79, 0xffff0000, v66
	global_store_dwordx4 v[72:73], v[60:63], off
	global_store_dwordx4 v[72:73], v[56:59], off offset:16
	global_store_dwordx4 v[72:73], v[52:55], off offset:512
	global_store_dwordx4 v[72:73], v[44:47], off offset:528
	v_lshlrev_b32_e32 v56, 16, v67
	v_and_b32_e32 v57, 0xffff0000, v67
	v_lshlrev_b32_e32 v58, 16, v68
	v_and_b32_e32 v59, 0xffff0000, v68
	v_lshlrev_b32_e32 v60, 16, v69
	v_and_b32_e32 v61, 0xffff0000, v69
	v_lshlrev_b32_e32 v62, 16, v70
	v_and_b32_e32 v63, 0xffff0000, v70
	v_lshlrev_b32_e32 v66, 16, v71
	v_and_b32_e32 v67, 0xffff0000, v71
	v_pk_fma_f32 v[50:51], v[50:51], 0.5, v[64:65] op_sel_hi:[1,0,1]
	v_pk_fma_f32 v[48:49], v[48:49], 0.5, v[76:77] op_sel_hi:[1,0,1]
	v_addc_co_u32_e32 v89, vcc, 0, v147, vcc
	global_load_dwordx4 v[44:47], v[82:83], off
	global_load_dwordx4 v[52:55], v[80:81], off offset:256
	v_pk_fma_f32 v[42:43], v[42:43], 0.5, v[56:57] op_sel_hi:[1,0,1]
	v_pk_fma_f32 v[40:41], v[40:41], 0.5, v[78:79] op_sel_hi:[1,0,1]
	v_pk_fma_f32 v[38:39], v[38:39], 0.5, v[60:61] op_sel_hi:[1,0,1]
	v_pk_fma_f32 v[36:37], v[36:37], 0.5, v[58:59] op_sel_hi:[1,0,1]
	v_pk_fma_f32 v[34:35], v[34:35], 0.5, v[66:67] op_sel_hi:[1,0,1]
	v_pk_fma_f32 v[32:33], v[32:33], 0.5, v[62:63] op_sel_hi:[1,0,1]
	global_store_dwordx4 v[74:75], v[48:51], off
	global_store_dwordx4 v[74:75], v[40:43], off offset:16
	global_store_dwordx4 v[74:75], v[36:39], off offset:512
	global_store_dwordx4 v[74:75], v[32:35], off offset:528
	global_load_dwordx4 v[32:35], v[88:89], off
	v_lshl_add_u64 v[36:37], v[146:147], 0, s[16:17]
	global_load_dwordx4 v[36:39], v[36:37], off offset:256
	v_add_u32_e32 v40, 0xffffffa0, v144
	v_add_u32_e32 v42, 0xffffffb0, v144
	v_ashrrev_i32_e32 v41, 31, v40
	v_ashrrev_i32_e32 v43, 31, v42
	v_lshlrev_b64 v[40:41], 13, v[40:41]
	v_lshlrev_b64 v[42:43], 13, v[42:43]
	v_lshl_add_u64 v[40:41], s[48:49], 0, v[40:41]
	v_lshl_add_u64 v[42:43], s[48:49], 0, v[42:43]
	v_lshl_add_u64 v[40:41], v[40:41], 0, v[148:149]
	s_and_b64 vcc, exec, s[2:3]
	v_lshl_add_u64 v[42:43], v[42:43], 0, v[148:149]
	s_waitcnt vmcnt(0)
; __device__ __forceinline__ float bflo(unsigned w) { return __uint_as_float(w << 16); }
; __device__ __forceinline__ float bfhi(unsigned w) { return __uint_as_float(w & 0xffff0000u); }
; #define ER_LOAD(g_, set_) do { const size_t off_ = (size_t)(row0 + ((g_) >> 2) * HALF + ((g_) & 3) * 16) * DM + col0; \
;         hv[set_][0] = *(const u32x4*)(HB + off_); hv[set_][1] = *(const u32x4*)(HB + off_ + HALF); } while (0)
;     __device__ __forceinline__ void operator()(const f32x4 (&acc)[2][2][4][2], const Unit& u, int wr, int wc, int fr, int fq, const Pre&) const {
;     ...
;         for (int g = 0; g < 8; ++g) { const int ai = g >> 2, m = g & 3; const int r = row0 + ai * HALF + m * 16; const size_t off = (size_t)r * DM + col0; float s = 0.f;
;             if (g + 1 < 8) ER_LOAD(g + 1, (g + 1) & 1);
; #pragma unroll
;             for (int bj = 0; bj < 2; ++bj) { const u32x4 w = hv[g & 1][bj];
;                 const f32x4 h0 = {bflo(w.x), bfhi(w.x), bflo(w.y), bfhi(w.y)}, h1 = {bflo(w.z), bfhi(w.z), bflo(w.w), bfhi(w.w)};
;                 const f32x4 o0 = h0 + acc[ai][bj][m][0] * alpha, o1 = h1 + acc[ai][bj][m][1] * alpha;
;                 if (FINAL) { float* op = OUT + (size_t)(r - ROW_X) * DM + col0 + bj * HALF; *(f32x4*)op = o0; *(f32x4*)(op + 4) = o1; }
	v_lshlrev_b32_e32 v48, 16, v44
	v_and_b32_e32 v49, 0xffff0000, v44
	v_lshlrev_b32_e32 v44, 16, v45
	v_and_b32_e32 v45, 0xffff0000, v45
	v_lshlrev_b32_e32 v58, 16, v54
	v_and_b32_e32 v59, 0xffff0000, v54
	v_lshlrev_b32_e32 v54, 16, v55
	v_and_b32_e32 v55, 0xffff0000, v55
	v_lshlrev_b32_e32 v50, 16, v46
	v_and_b32_e32 v51, 0xffff0000, v46
	v_lshlrev_b32_e32 v46, 16, v47
	v_and_b32_e32 v47, 0xffff0000, v47
	v_lshlrev_b32_e32 v56, 16, v52
	v_and_b32_e32 v57, 0xffff0000, v52
	v_lshlrev_b32_e32 v52, 16, v53
	v_and_b32_e32 v53, 0xffff0000, v53
	v_pk_fma_f32 v[30:31], v[30:31], 0.5, v[44:45] op_sel_hi:[1,0,1]
	v_pk_fma_f32 v[28:29], v[28:29], 0.5, v[48:49] op_sel_hi:[1,0,1]
	v_pk_fma_f32 v[10:11], v[10:11], 0.5, v[54:55] op_sel_hi:[1,0,1]
	v_pk_fma_f32 v[8:9], v[8:9], 0.5, v[58:59] op_sel_hi:[1,0,1]
	v_lshlrev_b32_e32 v44, 16, v32
	v_and_b32_e32 v45, 0xffff0000, v32
	v_lshlrev_b32_e32 v32, 16, v33
	v_and_b32_e32 v33, 0xffff0000, v33
	v_pk_fma_f32 v[26:27], v[26:27], 0.5, v[46:47] op_sel_hi:[1,0,1]
	v_pk_fma_f32 v[24:25], v[24:25], 0.5, v[50:51] op_sel_hi:[1,0,1]
	v_pk_fma_f32 v[18:19], v[18:19], 0.5, v[52:53] op_sel_hi:[1,0,1]
	v_pk_fma_f32 v[16:17], v[16:17], 0.5, v[56:57] op_sel_hi:[1,0,1]
	v_lshlrev_b32_e32 v46, 16, v34
	v_and_b32_e32 v47, 0xffff0000, v34
	v_lshlrev_b32_e32 v34, 16, v35
	v_and_b32_e32 v35, 0xffff0000, v35
	v_lshlrev_b32_e32 v48, 16, v36
	v_and_b32_e32 v49, 0xffff0000, v36
	v_lshlrev_b32_e32 v36, 16, v37
	v_and_b32_e32 v37, 0xffff0000, v37
	v_lshlrev_b32_e32 v50, 16, v38
	v_and_b32_e32 v51, 0xffff0000, v38
	v_lshlrev_b32_e32 v38, 16, v39
	v_and_b32_e32 v39, 0xffff0000, v39
	global_store_dwordx4 v[40:41], v[28:31], off
	global_store_dwordx4 v[40:41], v[24:27], off offset:16
	global_store_dwordx4 v[40:41], v[16:19], off offset:512
	global_store_dwordx4 v[40:41], v[8:11], off offset:528
	v_pk_fma_f32 v[14:15], v[14:15], 0.5, v[34:35] op_sel_hi:[1,0,1]
	v_pk_fma_f32 v[12:13], v[12:13], 0.5, v[46:47] op_sel_hi:[1,0,1]
	v_pk_fma_f32 v[10:11], v[22:23], 0.5, v[32:33] op_sel_hi:[1,0,1]
	v_pk_fma_f32 v[8:9], v[20:21], 0.5, v[44:45] op_sel_hi:[1,0,1]
	v_pk_fma_f32 v[6:7], v[6:7], 0.5, v[36:37] op_sel_hi:[1,0,1]
	v_pk_fma_f32 v[4:5], v[4:5], 0.5, v[48:49] op_sel_hi:[1,0,1]
	v_pk_fma_f32 v[2:3], v[2:3], 0.5, v[38:39] op_sel_hi:[1,0,1]
	v_pk_fma_f32 v[0:1], v[0:1], 0.5, v[50:51] op_sel_hi:[1,0,1]
	global_store_dwordx4 v[42:43], v[8:11], off
	global_store_dwordx4 v[42:43], v[12:15], off offset:16
	global_store_dwordx4 v[42:43], v[4:7], off offset:512
	global_store_dwordx4 v[42:43], v[0:3], off offset:528
	s_cbranch_vccz .LBB0_2615
	s_waitcnt vmcnt(0)
	s_cmpk_gt_u32 s24, 0xff
	s_cbranch_scc1 .LBB0_2630
	s_barrier
